# U and V passes fused per wave (no grid barrier 9, expert lists stay in LDS), wo epilogue loads batched
# speedup vs baseline: 1.0826x; 1.0134x over previous
; template <int WM, class AF, class BF>
; DI void gemm512(f32x16 (&acc)[WM][2], AF arow, int a_kstep, BF brow, int b_kstep, int KT, char* smem) {
;     ...
; #pragma unroll 1
;   for (int kt = 0; kt < KT; kt += 2) {
;     GEMM_STEP(A0, B0, A1, B1, ra0, rb0, ra1, rb1, kt + 2)
;     if (kt + 1 < KT) GEMM_STEP(A1, B1, A0, B0, ra1, rb1, ra0, rb0, kt + 3)
;   }
.LBB0_866:
	ds_read_b128 v[160:163], v220
	ds_read_b128 v[164:167], v219 offset:36864
	ds_read_b128 v[168:171], v219 offset:36896
	ds_read_b128 v[172:175], v220 offset:32
	ds_read_b128 v[176:179], v219 offset:41472
	ds_read_b128 v[180:183], v219 offset:41504
	s_add_i32 s16, s15, 2
	s_waitcnt lgkmcnt(4)
	v_mfma_f32_32x32x16_bf16 v[112:127], v[160:163], v[164:167], v[112:127]
	s_cmp_lt_u32 s15, 14
	s_cselect_b64 s[22:23], -1, 0
	s_and_b64 vcc, s[22:23], exec
	s_cselect_b32 s4, s14, 0x3c0
	s_lshl_b64 s[22:23], s[4:5], 1
	s_min_u32 s4, s15, 12
	s_lshl_b32 s4, s4, 7
	s_waitcnt lgkmcnt(1)
	v_mfma_f32_32x32x16_bf16 v[96:111], v[160:163], v[176:179], v[96:111]
	ds_read_b128 v[160:163], v220 offset:4608
	ds_read_b128 v[184:187], v220 offset:4640
	v_lshl_add_u64 v[240:241], v[206:207], 0, s[4:5]
	v_lshl_add_u64 v[242:243], v[208:209], 0, s[4:5]
	s_addk_i32 s14, 0x80
	s_mov_b32 s15, s16
	s_waitcnt lgkmcnt(1)
	v_mfma_f32_32x32x16_bf16 v[80:95], v[160:163], v[164:167], v[80:95]
	v_mfma_f32_32x32x16_bf16 v[64:79], v[160:163], v[176:179], v[64:79]
	ds_read_b128 v[160:163], v220 offset:9216
	ds_read_b128 v[188:191], v220 offset:9248
	s_waitcnt lgkmcnt(1)
	v_mfma_f32_32x32x16_bf16 v[48:63], v[160:163], v[164:167], v[48:63]
	v_mfma_f32_32x32x16_bf16 v[32:47], v[160:163], v[176:179], v[32:47]
	ds_read_b128 v[160:163], v220 offset:13824
	ds_read_b128 v[232:235], v220 offset:13856
	s_waitcnt lgkmcnt(1)
	v_mfma_f32_32x32x16_bf16 v[16:31], v[160:163], v[164:167], v[16:31]
	v_mfma_f32_32x32x16_bf16 v[0:15], v[160:163], v[176:179], v[0:15]
	v_mfma_f32_32x32x16_bf16 v[112:127], v[172:175], v[168:171], v[112:127]
	v_mfma_f32_32x32x16_bf16 v[96:111], v[172:175], v[180:183], v[96:111]
	v_mfma_f32_32x32x16_bf16 v[80:95], v[184:187], v[168:171], v[80:95]
	v_mfma_f32_32x32x16_bf16 v[64:79], v[184:187], v[180:183], v[64:79]
	v_mfma_f32_32x32x16_bf16 v[48:63], v[188:191], v[168:171], v[48:63]
	s_waitcnt lgkmcnt(0)
	v_mfma_f32_32x32x16_bf16 v[16:31], v[232:235], v[168:171], v[16:31]
	ds_read_b128 v[160:163], v220 offset:64
	ds_read_b128 v[164:167], v219 offset:36928
	ds_read_b128 v[176:179], v219 offset:36960
	ds_read_b128 v[168:171], v220 offset:96
	v_mfma_f32_32x32x16_bf16 v[0:15], v[232:235], v[180:183], v[0:15]
	ds_read_b128 v[172:175], v219 offset:41536
	ds_read_b128 v[232:235], v219 offset:41568
	v_mfma_f32_32x32x16_bf16 v[32:47], v[188:191], v[180:183], v[32:47]
	s_waitcnt lgkmcnt(4)
	v_mfma_f32_32x32x16_bf16 v[112:127], v[160:163], v[164:167], v[112:127]
	s_waitcnt lgkmcnt(1)
	v_mfma_f32_32x32x16_bf16 v[96:111], v[160:163], v[172:175], v[96:111]
	ds_read_b128 v[160:163], v220 offset:4672
	ds_read_b128 v[180:183], v220 offset:4704
	s_waitcnt lgkmcnt(1)
	v_mfma_f32_32x32x16_bf16 v[80:95], v[160:163], v[164:167], v[80:95]
	v_mfma_f32_32x32x16_bf16 v[64:79], v[160:163], v[172:175], v[64:79]
	ds_read_b128 v[160:163], v220 offset:9280
	ds_read_b128 v[184:187], v220 offset:9312
	s_waitcnt lgkmcnt(1)
	v_mfma_f32_32x32x16_bf16 v[48:63], v[160:163], v[164:167], v[48:63]
	v_mfma_f32_32x32x16_bf16 v[32:47], v[160:163], v[172:175], v[32:47]
	ds_read_b128 v[160:163], v220 offset:13888
	ds_read_b128 v[236:239], v220 offset:13920
	s_waitcnt vmcnt(7)
	ds_write_b128 v223, v[128:131]
	s_waitcnt vmcnt(5)
	ds_write_b128 v224, v[136:139]
	s_waitcnt vmcnt(4)
	ds_write_b128 v225, v[140:143]
	s_waitcnt vmcnt(3)
	ds_write_b128 v226, v[144:147]
	ds_write_b128 v227, v[132:135]
	s_waitcnt vmcnt(2)
	ds_write_b128 v228, v[148:151]
	s_waitcnt vmcnt(1)
	ds_write_b128 v229, v[152:155]
	s_waitcnt vmcnt(0)
	ds_write_b128 v230, v[156:159]
	v_lshl_add_u64 v[128:129], v[194:195], 0, s[22:23]
	v_lshl_add_u64 v[130:131], v[196:197], 0, s[22:23]
	v_lshl_add_u64 v[132:133], v[198:199], 0, s[22:23]
	v_lshl_add_u64 v[134:135], v[200:201], 0, s[22:23]
	s_waitcnt lgkmcnt(9)
	v_mfma_f32_32x32x16_bf16 v[16:31], v[160:163], v[164:167], v[16:31]
	v_lshl_add_u64 v[136:137], v[202:203], 0, s[22:23]
	v_lshl_add_u64 v[138:139], v[204:205], 0, s[22:23]
	v_lshl_add_u64 v[140:141], v[206:207], 0, s[22:23]
	v_lshl_add_u64 v[142:143], v[208:209], 0, s[22:23]
	v_mfma_f32_32x32x16_bf16 v[112:127], v[168:171], v[176:179], v[112:127]
	v_mfma_f32_32x32x16_bf16 v[96:111], v[168:171], v[232:235], v[96:111]
	v_mfma_f32_32x32x16_bf16 v[0:15], v[160:163], v[172:175], v[0:15]
	global_load_dwordx4 v[160:163], v[128:129], off
	global_load_dwordx4 v[164:167], v[130:131], off
	global_load_dwordx4 v[168:171], v[132:133], off
	global_load_dwordx4 v[172:175], v[134:135], off
	v_mfma_f32_32x32x16_bf16 v[80:95], v[180:183], v[176:179], v[80:95]
	v_mfma_f32_32x32x16_bf16 v[64:79], v[180:183], v[232:235], v[64:79]
	v_mfma_f32_32x32x16_bf16 v[48:63], v[184:187], v[176:179], v[48:63]
	v_mfma_f32_32x32x16_bf16 v[32:47], v[184:187], v[232:235], v[32:47]
	s_waitcnt lgkmcnt(8)
	v_mfma_f32_32x32x16_bf16 v[16:31], v[236:239], v[176:179], v[16:31]
	global_load_dwordx4 v[176:179], v[136:137], off
	global_load_dwordx4 v[180:183], v[138:139], off
	global_load_dwordx4 v[184:187], v[140:141], off
	global_load_dwordx4 v[188:191], v[142:143], off
	s_waitcnt lgkmcnt(0)
	s_barrier
; template <int WM, class AF, class BF>
; DI void gemm512(f32x16 (&acc)[WM][2], AF arow, int a_kstep, BF brow, int b_kstep, int KT, char* smem) {
;     ...
; #pragma unroll 1
;   for (int kt = 0; kt < KT; kt += 2) {
;     GEMM_STEP(A0, B0, A1, B1, ra0, rb0, ra1, rb1, kt + 2)
;     if (kt + 1 < KT) GEMM_STEP(A1, B1, A0, B0, ra1, rb1, ra0, rb0, kt + 3)
;   }
	ds_read_b128 v[128:131], v222
	ds_read_b128 v[132:135], v221
	ds_read_b128 v[136:139], v221 offset:32
	ds_read_b128 v[140:143], v222 offset:32
	ds_read_b128 v[144:147], v221 offset:4608
	ds_read_b128 v[148:151], v221 offset:4640
	s_waitcnt lgkmcnt(4)
	v_mfma_f32_32x32x16_bf16 v[112:127], v[128:131], v[132:135], v[112:127]
	s_waitcnt lgkmcnt(1)
	v_mfma_f32_32x32x16_bf16 v[96:111], v[128:131], v[144:147], v[96:111]
	ds_read_b128 v[128:131], v222 offset:4608
	ds_read_b128 v[152:155], v222 offset:4640
	v_mfma_f32_32x32x16_bf16 v[0:15], v[236:239], v[232:235], v[0:15]
	s_waitcnt lgkmcnt(1)
	v_mfma_f32_32x32x16_bf16 v[80:95], v[128:131], v[132:135], v[80:95]
	v_mfma_f32_32x32x16_bf16 v[64:79], v[128:131], v[144:147], v[64:79]
	ds_read_b128 v[128:131], v222 offset:9216
	ds_read_b128 v[156:159], v222 offset:9248
	s_waitcnt lgkmcnt(1)
	v_mfma_f32_32x32x16_bf16 v[48:63], v[128:131], v[132:135], v[48:63]
	v_mfma_f32_32x32x16_bf16 v[32:47], v[128:131], v[144:147], v[32:47]
	ds_read_b128 v[128:131], v222 offset:13824
	ds_read_b128 v[232:235], v222 offset:13856
	s_waitcnt lgkmcnt(1)
	v_mfma_f32_32x32x16_bf16 v[16:31], v[128:131], v[132:135], v[16:31]
	v_mfma_f32_32x32x16_bf16 v[0:15], v[128:131], v[144:147], v[0:15]
	v_mfma_f32_32x32x16_bf16 v[112:127], v[140:143], v[136:139], v[112:127]
	v_mfma_f32_32x32x16_bf16 v[96:111], v[140:143], v[148:151], v[96:111]
	v_mfma_f32_32x32x16_bf16 v[80:95], v[152:155], v[136:139], v[80:95]
	v_mfma_f32_32x32x16_bf16 v[64:79], v[152:155], v[148:151], v[64:79]
	v_lshl_add_u64 v[152:153], v[202:203], 0, s[4:5]
	v_lshl_add_u64 v[154:155], v[204:205], 0, s[4:5]
	v_mfma_f32_32x32x16_bf16 v[48:63], v[156:159], v[136:139], v[48:63]
	v_mfma_f32_32x32x16_bf16 v[32:47], v[156:159], v[148:151], v[32:47]
	s_waitcnt lgkmcnt(0)
	v_mfma_f32_32x32x16_bf16 v[16:31], v[232:235], v[136:139], v[16:31]
	ds_read_b128 v[128:131], v222 offset:64
	ds_read_b128 v[132:135], v221 offset:64
	ds_read_b128 v[156:159], v221 offset:96
	ds_read_b128 v[136:139], v222 offset:96
	v_mfma_f32_32x32x16_bf16 v[0:15], v[232:235], v[148:151], v[0:15]
	ds_read_b128 v[140:143], v221 offset:4672
	ds_read_b128 v[232:235], v221 offset:4704
	s_waitcnt lgkmcnt(4)
	v_mfma_f32_32x32x16_bf16 v[112:127], v[128:131], v[132:135], v[112:127]
	s_waitcnt lgkmcnt(1)
	v_mfma_f32_32x32x16_bf16 v[96:111], v[128:131], v[140:143], v[96:111]
	ds_read_b128 v[128:131], v222 offset:4672
	ds_read_b128 v[144:147], v222 offset:4704
	s_waitcnt lgkmcnt(1)
	v_mfma_f32_32x32x16_bf16 v[80:95], v[128:131], v[132:135], v[80:95]
	v_mfma_f32_32x32x16_bf16 v[64:79], v[128:131], v[140:143], v[64:79]
	ds_read_b128 v[128:131], v222 offset:9280
	ds_read_b128 v[148:151], v222 offset:9312
	s_waitcnt lgkmcnt(1)
	v_mfma_f32_32x32x16_bf16 v[48:63], v[128:131], v[132:135], v[48:63]
	v_mfma_f32_32x32x16_bf16 v[32:47], v[128:131], v[140:143], v[32:47]
	ds_read_b128 v[128:131], v222 offset:13888
	ds_read_b128 v[236:239], v222 offset:13920
	s_waitcnt lgkmcnt(1)
	v_mfma_f32_32x32x16_bf16 v[16:31], v[128:131], v[132:135], v[16:31]
	v_lshl_add_u64 v[132:133], v[196:197], 0, s[4:5]
	v_lshl_add_u64 v[134:135], v[198:199], 0, s[4:5]
	v_mfma_f32_32x32x16_bf16 v[0:15], v[128:131], v[140:143], v[0:15]
	v_lshl_add_u64 v[128:129], v[194:195], 0, s[4:5]
	v_mfma_f32_32x32x16_bf16 v[80:95], v[144:147], v[156:159], v[80:95]
	v_mfma_f32_32x32x16_bf16 v[64:79], v[144:147], v[232:235], v[64:79]
	v_lshl_add_u64 v[144:145], v[200:201], 0, s[4:5]
	v_mfma_f32_32x32x16_bf16 v[112:127], v[136:139], v[156:159], v[112:127]
	v_mfma_f32_32x32x16_bf16 v[96:111], v[136:139], v[232:235], v[96:111]
	v_mfma_f32_32x32x16_bf16 v[48:63], v[148:151], v[156:159], v[48:63]
	v_mfma_f32_32x32x16_bf16 v[32:47], v[148:151], v[232:235], v[32:47]
	global_load_dwordx4 v[128:131], v[128:129], off offset:384
	s_nop 0
	global_load_dwordx4 v[136:139], v[132:133], off offset:384
	global_load_dwordx4 v[140:143], v[134:135], off offset:384
	s_nop 0
	global_load_dwordx4 v[144:147], v[144:145], off offset:384
	s_nop 0
	global_load_dwordx4 v[132:135], v[152:153], off offset:384
	global_load_dwordx4 v[148:151], v[154:155], off offset:384
	s_nop 0
	global_load_dwordx4 v[152:155], v[240:241], off offset:384
	s_waitcnt lgkmcnt(0)
	v_mfma_f32_32x32x16_bf16 v[16:31], v[236:239], v[156:159], v[16:31]
	global_load_dwordx4 v[156:159], v[242:243], off offset:384
	s_waitcnt vmcnt(15)
	ds_write_b128 v192, v[160:163]
	s_waitcnt vmcnt(14)
	ds_write_b128 v216, v[164:167]
	s_waitcnt vmcnt(13)
	ds_write_b128 v217, v[168:171]
	s_waitcnt vmcnt(12)
	ds_write_b128 v218, v[172:175]
	s_waitcnt vmcnt(11)
	ds_write_b128 v192, v[176:179] offset:36864
	s_waitcnt vmcnt(10)
	ds_write_b128 v216, v[180:183] offset:36864
	s_waitcnt vmcnt(9)
	ds_write_b128 v217, v[184:187] offset:36864
	s_waitcnt vmcnt(8)
	ds_write_b128 v218, v[188:191] offset:36864
	s_waitcnt lgkmcnt(0)
	s_barrier
	v_mfma_f32_32x32x16_bf16 v[0:15], v[236:239], v[232:235], v[0:15]
	s_cbranch_vccnz .LBB0_866
; DI void phase_wo(const Params& p, char* smem) {
;     ...
; #pragma unroll
;     for (int i = 0; i < 4; ++i)
; #pragma unroll
;       for (int j = 0; j < 2; ++j)
; #pragma unroll
;         for (int q4 = 0; q4 < 4; ++q4) {
;           const int f = n0 + wm * 128 + i * 32 + q4 * 8 + hh * 4;
;           const size_t t = m0 + wn * 64 + j * 32 + lr;
;           float4 xv = *(const float4*)(p.x + t * 1024 + f);
;           xv.x += acc[i][j][q4 * 4 + 0]; xv.y += acc[i][j][q4 * 4 + 1];
;           xv.z += acc[i][j][q4 * 4 + 2]; xv.w += acc[i][j][q4 * 4 + 3];
;           *(float4*)(X1 + t * 1024 + f) = xv;
;         }
	v_readlane_b32 s80, v253, 0
	s_waitcnt vmcnt(7)
	v_add_u32_e32 v128, s13, v214
	v_or_b32_e32 v129, s12, v215
	v_readlane_b32 s81, v253, 1
	v_lshlrev_b32_e32 v192, 12, v129
	s_mov_b64 s[12:13], s[80:81]
	v_ashrrev_i32_e32 v129, 31, v128
	v_lshl_add_u64 v[130:131], s[12:13], 0, v[192:193]
	s_waitcnt vmcnt(6)
	v_lshlrev_b64 v[136:137], 2, v[128:129]
	v_lshl_add_u64 v[130:131], v[130:131], 0, v[136:137]
	v_lshl_add_u64 v[128:129], s[76:77], 0, v[192:193]
	v_lshl_add_u64 v[128:129], v[128:129], 0, v[136:137]
	v_or_b32_e32 v192, 0x20000, v192
	s_add_i32 s11, s11, 1
	s_mul_i32 s4, s11, s51
	s_add_i32 s4, s4, s50
	s_cmp_lt_u32 s4, 32
	v_readlane_b32 s82, v253, 2
	v_readlane_b32 s83, v253, 3
	v_readlane_b32 s84, v253, 4
	v_readlane_b32 s85, v253, 5
	v_readlane_b32 s86, v253, 6
	v_readlane_b32 s87, v253, 7
	v_readlane_b32 s88, v253, 8
	v_readlane_b32 s89, v253, 9
	v_readlane_b32 s90, v253, 10
	v_readlane_b32 s91, v253, 11
	v_readlane_b32 s92, v253, 12
	v_readlane_b32 s93, v253, 13
	v_readlane_b32 s94, v253, 14
	v_readlane_b32 s95, v253, 15
	s_waitcnt vmcnt(0)
	v_lshl_add_u64 v[138:139], s[12:13], 0, v[192:193]
	v_lshl_add_u64 v[138:139], v[138:139], 0, v[136:137]
	v_lshl_add_u64 v[140:141], s[76:77], 0, v[192:193]
	v_lshl_add_u64 v[140:141], v[140:141], 0, v[136:137]
	global_load_dwordx4 v[144:147], v[130:131], off
	global_load_dwordx4 v[148:151], v[130:131], off offset:32
	global_load_dwordx4 v[152:155], v[130:131], off offset:64
	global_load_dwordx4 v[156:159], v[130:131], off offset:96
	global_load_dwordx4 v[160:163], v[138:139], off
	global_load_dwordx4 v[164:167], v[138:139], off offset:32
	global_load_dwordx4 v[168:171], v[138:139], off offset:64
	global_load_dwordx4 v[172:175], v[138:139], off offset:96
	global_load_dwordx4 v[216:219], v[130:131], off offset:128
	global_load_dwordx4 v[220:223], v[130:131], off offset:160
	global_load_dwordx4 v[224:227], v[130:131], off offset:192
	global_load_dwordx4 v[228:231], v[130:131], off offset:224
	global_load_dwordx4 v[232:235], v[138:139], off offset:128
	global_load_dwordx4 v[236:239], v[138:139], off offset:160
	global_load_dwordx4 v[240:243], v[138:139], off offset:192
	global_load_dwordx4 v[244:247], v[138:139], off offset:224
	s_waitcnt vmcnt(8)
	v_pk_add_f32 v[112:113], v[112:113], v[144:145]
	v_pk_add_f32 v[114:115], v[114:115], v[146:147]
	v_pk_add_f32 v[116:117], v[116:117], v[148:149]
	v_pk_add_f32 v[118:119], v[118:119], v[150:151]
	v_pk_add_f32 v[120:121], v[120:121], v[152:153]
	v_pk_add_f32 v[122:123], v[122:123], v[154:155]
	v_pk_add_f32 v[124:125], v[124:125], v[156:157]
	v_pk_add_f32 v[126:127], v[126:127], v[158:159]
	global_store_dwordx4 v[128:129], v[112:115], off
	global_store_dwordx4 v[128:129], v[116:119], off offset:32
	global_store_dwordx4 v[128:129], v[120:123], off offset:64
	global_store_dwordx4 v[128:129], v[124:127], off offset:96
	v_pk_add_f32 v[96:97], v[96:97], v[160:161]
	v_pk_add_f32 v[98:99], v[98:99], v[162:163]
	v_pk_add_f32 v[100:101], v[100:101], v[164:165]
	v_pk_add_f32 v[102:103], v[102:103], v[166:167]
	v_pk_add_f32 v[104:105], v[104:105], v[168:169]
	v_pk_add_f32 v[106:107], v[106:107], v[170:171]
	v_pk_add_f32 v[108:109], v[108:109], v[172:173]
	v_pk_add_f32 v[110:111], v[110:111], v[174:175]
	global_store_dwordx4 v[140:141], v[96:99], off
	global_store_dwordx4 v[140:141], v[100:103], off offset:32
	global_store_dwordx4 v[140:141], v[104:107], off offset:64
	global_store_dwordx4 v[140:141], v[108:111], off offset:96
	global_load_dwordx4 v[144:147], v[130:131], off offset:256
	global_load_dwordx4 v[148:151], v[130:131], off offset:288
	global_load_dwordx4 v[152:155], v[130:131], off offset:320
	global_load_dwordx4 v[156:159], v[130:131], off offset:352
	global_load_dwordx4 v[160:163], v[138:139], off offset:256
	global_load_dwordx4 v[164:167], v[138:139], off offset:288
	global_load_dwordx4 v[168:171], v[138:139], off offset:320
	global_load_dwordx4 v[172:175], v[138:139], off offset:352
	s_waitcnt vmcnt(16)
; DI void phase_wo(const Params& p, char* smem) {
;     ...
; #pragma unroll
;     for (int i = 0; i < 4; ++i)
; #pragma unroll
;       for (int j = 0; j < 2; ++j)
; #pragma unroll
;         for (int q4 = 0; q4 < 4; ++q4) {
;           const int f = n0 + wm * 128 + i * 32 + q4 * 8 + hh * 4;
;           const size_t t = m0 + wn * 64 + j * 32 + lr;
;           float4 xv = *(const float4*)(p.x + t * 1024 + f);
;           xv.x += acc[i][j][q4 * 4 + 0]; xv.y += acc[i][j][q4 * 4 + 1];
;           xv.z += acc[i][j][q4 * 4 + 2]; xv.w += acc[i][j][q4 * 4 + 3];
;           *(float4*)(X1 + t * 1024 + f) = xv;
;         }
	v_pk_add_f32 v[80:81], v[80:81], v[216:217]
	v_pk_add_f32 v[82:83], v[82:83], v[218:219]
	v_pk_add_f32 v[84:85], v[84:85], v[220:221]
	v_pk_add_f32 v[86:87], v[86:87], v[222:223]
	v_pk_add_f32 v[88:89], v[88:89], v[224:225]
	v_pk_add_f32 v[90:91], v[90:91], v[226:227]
	v_pk_add_f32 v[92:93], v[92:93], v[228:229]
	v_pk_add_f32 v[94:95], v[94:95], v[230:231]
	global_store_dwordx4 v[128:129], v[80:83], off offset:128
	global_store_dwordx4 v[128:129], v[84:87], off offset:160
	global_store_dwordx4 v[128:129], v[88:91], off offset:192
	global_store_dwordx4 v[128:129], v[92:95], off offset:224
	v_pk_add_f32 v[64:65], v[64:65], v[232:233]
	v_pk_add_f32 v[66:67], v[66:67], v[234:235]
	v_pk_add_f32 v[68:69], v[68:69], v[236:237]
	v_pk_add_f32 v[70:71], v[70:71], v[238:239]
	v_pk_add_f32 v[72:73], v[72:73], v[240:241]
	v_pk_add_f32 v[74:75], v[74:75], v[242:243]
	v_pk_add_f32 v[76:77], v[76:77], v[244:245]
	v_pk_add_f32 v[78:79], v[78:79], v[246:247]
	global_store_dwordx4 v[140:141], v[64:67], off offset:128
	global_store_dwordx4 v[140:141], v[68:71], off offset:160
	global_store_dwordx4 v[140:141], v[72:75], off offset:192
	global_store_dwordx4 v[140:141], v[76:79], off offset:224
	global_load_dwordx4 v[216:219], v[130:131], off offset:384
	global_load_dwordx4 v[220:223], v[130:131], off offset:416
	global_load_dwordx4 v[224:227], v[130:131], off offset:448
	global_load_dwordx4 v[228:231], v[130:131], off offset:480
	global_load_dwordx4 v[232:235], v[138:139], off offset:384
	global_load_dwordx4 v[236:239], v[138:139], off offset:416
	global_load_dwordx4 v[240:243], v[138:139], off offset:448
	global_load_dwordx4 v[244:247], v[138:139], off offset:480
	s_waitcnt vmcnt(16)
	v_pk_add_f32 v[48:49], v[48:49], v[144:145]
	v_pk_add_f32 v[50:51], v[50:51], v[146:147]
	v_pk_add_f32 v[52:53], v[52:53], v[148:149]
	v_pk_add_f32 v[54:55], v[54:55], v[150:151]
	v_pk_add_f32 v[56:57], v[56:57], v[152:153]
	v_pk_add_f32 v[58:59], v[58:59], v[154:155]
	v_pk_add_f32 v[60:61], v[60:61], v[156:157]
	v_pk_add_f32 v[62:63], v[62:63], v[158:159]
	global_store_dwordx4 v[128:129], v[48:51], off offset:256
	global_store_dwordx4 v[128:129], v[52:55], off offset:288
	global_store_dwordx4 v[128:129], v[56:59], off offset:320
	global_store_dwordx4 v[128:129], v[60:63], off offset:352
	v_pk_add_f32 v[32:33], v[32:33], v[160:161]
	v_pk_add_f32 v[34:35], v[34:35], v[162:163]
	v_pk_add_f32 v[36:37], v[36:37], v[164:165]
	v_pk_add_f32 v[38:39], v[38:39], v[166:167]
	v_pk_add_f32 v[40:41], v[40:41], v[168:169]
	v_pk_add_f32 v[42:43], v[42:43], v[170:171]
	v_pk_add_f32 v[44:45], v[44:45], v[172:173]
	v_pk_add_f32 v[46:47], v[46:47], v[174:175]
	global_store_dwordx4 v[140:141], v[32:35], off offset:256
	global_store_dwordx4 v[140:141], v[36:39], off offset:288
	global_store_dwordx4 v[140:141], v[40:43], off offset:320
	global_store_dwordx4 v[140:141], v[44:47], off offset:352
	s_waitcnt vmcnt(8)
	v_pk_add_f32 v[16:17], v[16:17], v[216:217]
	v_pk_add_f32 v[18:19], v[18:19], v[218:219]
	v_pk_add_f32 v[20:21], v[20:21], v[220:221]
	v_pk_add_f32 v[22:23], v[22:23], v[222:223]
	v_pk_add_f32 v[24:25], v[24:25], v[224:225]
	v_pk_add_f32 v[26:27], v[26:27], v[226:227]
	v_pk_add_f32 v[28:29], v[28:29], v[228:229]
	v_pk_add_f32 v[30:31], v[30:31], v[230:231]
	global_store_dwordx4 v[128:129], v[16:19], off offset:384
	global_store_dwordx4 v[128:129], v[20:23], off offset:416
	global_store_dwordx4 v[128:129], v[24:27], off offset:448
	global_store_dwordx4 v[128:129], v[28:31], off offset:480
	v_pk_add_f32 v[0:1], v[0:1], v[232:233]
	v_pk_add_f32 v[2:3], v[2:3], v[234:235]
	v_pk_add_f32 v[4:5], v[4:5], v[236:237]
	v_pk_add_f32 v[6:7], v[6:7], v[238:239]
	v_pk_add_f32 v[8:9], v[8:9], v[240:241]
	v_pk_add_f32 v[10:11], v[10:11], v[242:243]
	v_pk_add_f32 v[12:13], v[12:13], v[244:245]
	v_pk_add_f32 v[14:15], v[14:15], v[246:247]
	global_store_dwordx4 v[140:141], v[0:3], off offset:384
	global_store_dwordx4 v[140:141], v[4:7], off offset:416
	global_store_dwordx4 v[140:141], v[8:11], off offset:448
	global_store_dwordx4 v[140:141], v[12:15], off offset:480
	s_cbranch_scc1 .LBB0_865
	s_mov_b32 s88, s17

; DI float bflo(unsigned u) { return __uint_as_float(u << 16); }
; DI float bfhi(unsigned u) { return __uint_as_float(u & 0xffff0000u); }
; template <bool STORE>
; DI void peer_item(const Params& p, int item, char* smem) {
;     ...
;   const unsigned char* U8 = (const unsigned char*)(ws + WS_UBF);
;   const float* SU = (const float*)(ws + WS_SU);
;   const float* SV = (const float*)(ws + WS_SV);
;   int* EG = (int*)(ws + WS_XN);
;   float* AG = (float*)(ws + WS_XN + (size_t)T_TOK * 128 * 4);
;   const bool b5 = (lane & 32) != 0, b4 = (lane & 16) != 0, b3 = (lane & 8) != 0;
; #pragma unroll 1
;   for (int ti = 0; ti < 8; ++ti) {
;     const int tl = wave * 8 + ti;
;     const size_t tok = (size_t)tok0 + tl;
;     float xf[16];
;     {
; #pragma unroll
;       for (int i = 0; i < 4; ++i) {
;         const uint2 xv = *(const uint2*)(XN2 + tok * 1024 + 256 * i + lane * 4);
;         xf[4 * i] = bflo(xv.x); xf[4 * i + 1] = bfhi(xv.x); xf[4 * i + 2] = bflo(xv.y); xf[4 * i + 3] = bfhi(xv.y);
;       }
;     }
.LBB0_1058:
	s_or_b64 exec, exec, s[0:1]
	s_waitcnt vmcnt(0) lgkmcnt(0)
	v_writelane_b32 v254, s6, 0
	v_writelane_b32 v254, s7, 1
	v_writelane_b32 v254, s12, 2
	v_writelane_b32 v254, s13, 3
	v_writelane_b32 v254, s14, 4
	v_writelane_b32 v254, s15, 5
	v_writelane_b32 v254, s16, 6
	v_writelane_b32 v254, s17, 7
	v_writelane_b32 v254, s18, 8
	v_writelane_b32 v254, s19, 9
	v_writelane_b32 v254, s20, 10
	v_writelane_b32 v254, s21, 11
	v_writelane_b32 v254, s22, 12
	v_writelane_b32 v254, s23, 13
	v_writelane_b32 v254, s24, 14
	v_writelane_b32 v254, s25, 15
	v_writelane_b32 v254, s26, 16
	v_writelane_b32 v254, s27, 17
	v_writelane_b32 v254, s28, 18
	v_writelane_b32 v254, s29, 19
	v_writelane_b32 v254, s30, 20
	v_writelane_b32 v254, s31, 21
	v_writelane_b32 v254, s33, 22
	v_writelane_b32 v254, s34, 23
	v_writelane_b32 v254, s35, 24
	v_writelane_b32 v254, s36, 25
	v_writelane_b32 v254, s37, 26
	v_writelane_b32 v254, s38, 27
	v_writelane_b32 v254, s39, 28
	v_writelane_b32 v254, s40, 29
	v_writelane_b32 v254, s41, 30
	v_writelane_b32 v254, s42, 31
	v_writelane_b32 v254, s44, 32
	v_writelane_b32 v254, s45, 33
	v_writelane_b32 v254, s48, 34
	v_writelane_b32 v254, s49, 35
	v_writelane_b32 v254, s50, 36
	v_writelane_b32 v254, s51, 37
	v_writelane_b32 v254, s52, 38
	v_writelane_b32 v254, s53, 39
	v_writelane_b32 v254, s55, 40
	v_writelane_b32 v254, s60, 41
	v_writelane_b32 v254, s61, 42
	v_writelane_b32 v254, s62, 43
	v_writelane_b32 v254, s63, 44
	v_writelane_b32 v254, s66, 45
	v_writelane_b32 v254, s67, 46
	v_writelane_b32 v254, s68, 47
	v_writelane_b32 v254, s69, 48
	v_writelane_b32 v254, s74, 49
	v_writelane_b32 v254, s75, 50
	v_writelane_b32 v254, s76, 51
	v_writelane_b32 v254, s77, 52
	v_writelane_b32 v254, s78, 53
	v_writelane_b32 v254, s79, 54
	v_writelane_b32 v254, s88, 55
	s_mov_b32 s16, s33
	s_mov_b32 s14, s42
	v_readlane_b32 s56, v253, 48
	v_readlane_b32 s57, v253, 49
	v_readfirstlane_b32 s13, v211
	v_mbcnt_lo_u32_b32 v213, -1, 0
	v_mbcnt_hi_u32_b32 v213, -1, v213
	s_nop 3
	s_bfe_u32 s17, s13, 0x20006
	s_add_u32 s0, s56, 0x1200200
	s_addc_u32 s1, s57, 0
	s_add_u32 s2, s56, 0x7200200
	s_addc_u32 s3, s57, 0
	s_add_u32 s4, s56, 0x5200200
	s_addc_u32 s5, s57, 0
	s_add_u32 s6, s56, 0x5a00200
	s_addc_u32 s7, s57, 0
	s_add_u32 s8, s56, 0x2200200
	s_addc_u32 s9, s57, 0
	s_add_u32 s10, s56, 0x4200200
	s_addc_u32 s11, s57, 0
	s_lshl_b32 s13, s17, 3
	s_add_u32 s14, s14, s13
	s_mul_i32 s18, s17, 7168
	s_add_u32 s18, s18, s16
	s_add_u32 s18, s18, 49152
	s_lshl_b32 s19, s17, 12
	s_add_u32 s19, s19, s16
	v_lshlrev_b32_e32 v238, 2, v213
	v_lshlrev_b32_e32 v234, 4, v213
	v_add_u32_e32 v236, s18, v238
	v_add_u32_e32 v237, s19, v238
	ds_write_b32 v236, v3 offset:512
	ds_write_b32 v236, v53 offset:768
	ds_write_b32 v236, v64 offset:1024
	ds_write_b32 v236, v65 offset:1280
	ds_write_b32 v236, v66 offset:1536
	ds_write_b32 v236, v67 offset:1792
	ds_write_b32 v236, v68 offset:2048
	ds_write_b32 v236, v69 offset:2304
	ds_write_b32 v236, v70 offset:2560
	ds_write_b32 v236, v71 offset:2816
	ds_write_b32 v236, v72 offset:3072
	ds_write_b32 v236, v73 offset:3328
	ds_write_b32 v236, v74 offset:3584
	ds_write_b32 v236, v75 offset:3840
	ds_write_b32 v236, v76 offset:4096
	ds_write_b32 v236, v77 offset:4352
	ds_write_b32 v236, v78 offset:4608
	ds_write_b32 v236, v79 offset:4864
	ds_write_b32 v236, v80 offset:5120
	ds_write_b32 v236, v81 offset:5376
	ds_write_b32 v236, v82 offset:5632
	ds_write_b32 v236, v83 offset:5888
	ds_write_b32 v236, v96 offset:6144
	ds_write_b32 v236, v210 offset:6400
	ds_write_b32 v236, v211 offset:6656
	ds_write_b32 v236, v212 offset:6912
	s_mov_b32 s24, 0xff00ff00
	s_mov_b32 s25, 0xff00ff00
	s_mov_b32 s80, 0x378e98ab
	s_mov_b32 s81, 0x3b7cd369
	s_mov_b32 s82, 0xbcc618b2
	s_mov_b32 s83, 0x3dda74e4
	s_mov_b32 s84, 0x3f228afd
	s_mov_b32 s85, 0x3e03c728
	s_mov_b32 s86, 0xbfb8aa3b
	s_mov_b32 s87, 0x42ce8ed0
	s_mov_b32 s88, 0xc2b17218
	s_mov_b32 s89, 0x7fffffff
	s_waitcnt lgkmcnt(0)
	s_lshl_b32 s13, s14, 11
	s_add_u32 s32, s2, s13
	s_addc_u32 s33, s3, 0
	v_lshlrev_b32_e32 v239, 3, v213
	global_load_dwordx2 v[2:3], v239, s[32:33] offset:0
	global_load_dwordx2 v[6:7], v239, s[32:33] offset:512
	global_load_dwordx2 v[10:11], v239, s[32:33] offset:1024
	global_load_dwordx2 v[14:15], v239, s[32:33] offset:1536
	global_load_dwordx2 v[18:19], v239, s[32:33] offset:2048
	global_load_dwordx2 v[22:23], v239, s[32:33] offset:2560
	global_load_dwordx2 v[26:27], v239, s[32:33] offset:3072
	global_load_dwordx2 v[30:31], v239, s[32:33] offset:3584
	s_add_u32 s32, s32, 4096
	s_addc_u32 s33, s33, 0
	global_load_dwordx2 v[34:35], v239, s[32:33] offset:0
	global_load_dwordx2 v[38:39], v239, s[32:33] offset:512
	global_load_dwordx2 v[42:43], v239, s[32:33] offset:1024
	global_load_dwordx2 v[46:47], v239, s[32:33] offset:1536
	global_load_dwordx2 v[50:51], v239, s[32:33] offset:2048
	global_load_dwordx2 v[54:55], v239, s[32:33] offset:2560
	global_load_dwordx2 v[58:59], v239, s[32:33] offset:3072
	global_load_dwordx2 v[62:63], v239, s[32:33] offset:3584
	s_add_u32 s32, s32, 4096
	s_addc_u32 s33, s33, 0
	global_load_dwordx2 v[66:67], v239, s[32:33] offset:0
	global_load_dwordx2 v[70:71], v239, s[32:33] offset:512
	global_load_dwordx2 v[74:75], v239, s[32:33] offset:1024
	global_load_dwordx2 v[78:79], v239, s[32:33] offset:1536
	global_load_dwordx2 v[82:83], v239, s[32:33] offset:2048
	global_load_dwordx2 v[86:87], v239, s[32:33] offset:2560
	global_load_dwordx2 v[90:91], v239, s[32:33] offset:3072
	global_load_dwordx2 v[94:95], v239, s[32:33] offset:3584
	s_add_u32 s32, s32, 4096
	s_addc_u32 s33, s33, 0
	global_load_dwordx2 v[98:99], v239, s[32:33] offset:0
	global_load_dwordx2 v[102:103], v239, s[32:33] offset:512
	global_load_dwordx2 v[106:107], v239, s[32:33] offset:1024
	global_load_dwordx2 v[110:111], v239, s[32:33] offset:1536
	global_load_dwordx2 v[114:115], v239, s[32:33] offset:2048
	global_load_dwordx2 v[118:119], v239, s[32:33] offset:2560
	global_load_dwordx2 v[122:123], v239, s[32:33] offset:3072
	global_load_dwordx2 v[126:127], v239, s[32:33] offset:3584
	v_mov_b32_e32 v144, v236
	v_mov_b32_e32 v145, 0
	v_mov_b32_e32 v146, 1
	v_lshrrev_b32_e32 v147, 3, v213
	v_and_b32_e32 v148, 7, v213
	v_lshlrev_b32_e32 v147, 6, v147
	v_lshl_add_u32 v147, v148, 2, v147
	v_add_u32_e32 v147, s19, v147
	v_subrev_u32_e32 v149, 1, v213
	v_subrev_u32_e32 v150, 2, v213
	v_subrev_u32_e32 v151, 4, v213
	v_subrev_u32_e32 v152, 8, v213
	v_subrev_u32_e32 v153, 16, v213
	v_subrev_u32_e32 v154, 32, v213
	v_lshlrev_b32_e32 v149, 2, v149
	v_lshlrev_b32_e32 v150, 2, v150
	v_lshlrev_b32_e32 v151, 2, v151
	v_lshlrev_b32_e32 v152, 2, v152
	v_lshlrev_b32_e32 v153, 2, v153
	v_lshlrev_b32_e32 v154, 2, v154
	ds_read_b32 v166, v237 offset:0
	ds_read_b32 v167, v237 offset:256
	ds_read_b32 v168, v237 offset:16384
	ds_read_b32 v169, v237 offset:16640
	ds_write_b32 v144, v145
	ds_write_b32 v144, v145 offset:256
	s_waitcnt lgkmcnt(0)
; template <bool STORE>
; DI void peer_item(const Params& p, int item, char* smem) {
;     ...
; #pragma unroll 2
;     for (int k = 0; k < 128; k += 8) {
;       u32x4 uq[8];
;       const int emine = e_s[tl * 128 + k + (lane >> 3)];
;       const float gmine = g_s[tl * 128 + k + (lane >> 3)];
;       const float su = SU[emine], sv = SV[emine];
; #pragma unroll
;       for (int u = 0; u < 8; ++u) {
;         int e = e_s[tl * 128 + k + u];
;         uq[u] = *(const u32x4*)(U8 + (size_t)e * 1024 + lane * 16);
	v_lshrrev_b32_e32 v156, 5, v166
	v_lshrrev_b32_e32 v157, 5, v167
	v_and_b32_e32 v156, 0x1fc, v156
	v_and_b32_e32 v157, 0x1fc, v157
	v_add_u32_e32 v156, s18, v156
	v_add_u32_e32 v157, s18, v157
	ds_add_rtn_u32 v158, v156, v146
	ds_add_rtn_u32 v159, v157, v146
	ds_read_b32 v160, v144
	ds_read_b32 v161, v144 offset:256
	s_waitcnt lgkmcnt(0)
	v_mov_b32_e32 v164, v160
	v_mov_b32_e32 v165, v161
	v_cmp_le_u32_e32 vcc, 1, v213
	ds_bpermute_b32 v162, v149, v164
	ds_bpermute_b32 v163, v149, v165
	s_waitcnt lgkmcnt(0)
	v_cndmask_b32_e32 v162, 0, v162, vcc
	v_cndmask_b32_e32 v163, 0, v163, vcc
	v_add_u32_e32 v164, v164, v162
	v_add_u32_e32 v165, v165, v163
	v_cmp_le_u32_e32 vcc, 2, v213
	ds_bpermute_b32 v162, v150, v164
	ds_bpermute_b32 v163, v150, v165
	s_waitcnt lgkmcnt(0)
	v_cndmask_b32_e32 v162, 0, v162, vcc
	v_cndmask_b32_e32 v163, 0, v163, vcc
	v_add_u32_e32 v164, v164, v162
	v_add_u32_e32 v165, v165, v163
	v_cmp_le_u32_e32 vcc, 4, v213
	ds_bpermute_b32 v162, v151, v164
	ds_bpermute_b32 v163, v151, v165
	s_waitcnt lgkmcnt(0)
	v_cndmask_b32_e32 v162, 0, v162, vcc
	v_cndmask_b32_e32 v163, 0, v163, vcc
	v_add_u32_e32 v164, v164, v162
	v_add_u32_e32 v165, v165, v163
	v_cmp_le_u32_e32 vcc, 8, v213
	ds_bpermute_b32 v162, v152, v164
	ds_bpermute_b32 v163, v152, v165
	s_waitcnt lgkmcnt(0)
	v_cndmask_b32_e32 v162, 0, v162, vcc
	v_cndmask_b32_e32 v163, 0, v163, vcc
	v_add_u32_e32 v164, v164, v162
	v_add_u32_e32 v165, v165, v163
	v_cmp_le_u32_e32 vcc, 16, v213
	ds_bpermute_b32 v162, v153, v164
	ds_bpermute_b32 v163, v153, v165
	s_waitcnt lgkmcnt(0)
	v_cndmask_b32_e32 v162, 0, v162, vcc
	v_cndmask_b32_e32 v163, 0, v163, vcc
	v_add_u32_e32 v164, v164, v162
	v_add_u32_e32 v165, v165, v163
	v_cmp_le_u32_e32 vcc, 32, v213
	ds_bpermute_b32 v162, v154, v164
	ds_bpermute_b32 v163, v154, v165
	s_waitcnt lgkmcnt(0)
	v_cndmask_b32_e32 v162, 0, v162, vcc
	v_cndmask_b32_e32 v163, 0, v163, vcc
	v_add_u32_e32 v164, v164, v162
	v_add_u32_e32 v165, v165, v163
	v_readlane_b32 s13, v164, 63
	v_sub_u32_e32 v164, v164, v160
	v_sub_u32_e32 v165, v165, v161
	s_nop 0
	v_add_u32_e32 v165, s13, v165
	ds_write_b32 v144, v164
	ds_write_b32 v144, v165 offset:256
	ds_read_b32 v160, v156
	ds_read_b32 v161, v157
	s_waitcnt lgkmcnt(0)
	v_add_u32_e32 v160, v160, v158
	v_add_u32_e32 v161, v161, v159
	v_lshl_add_u32 v160, v160, 2, s19
	v_lshl_add_u32 v161, v161, 2, s19
	ds_write_b32 v160, v166 offset:0
	ds_write_b32 v160, v168 offset:16384
	ds_write_b32 v161, v167 offset:0
	ds_write_b32 v161, v169 offset:16384
	ds_read_b32 v128, v147 offset:0
	ds_read_b32 v129, v147 offset:32
	s_waitcnt lgkmcnt(0)
	v_lshlrev_b32_e32 v128, 10, v128
	v_lshlrev_b32_e32 v129, 10, v129
	ds_read_b32 v166, v237 offset:512
	ds_read_b32 v167, v237 offset:768
	ds_read_b32 v168, v237 offset:16896
	ds_read_b32 v169, v237 offset:17152
	ds_write_b32 v144, v145
	ds_write_b32 v144, v145 offset:256
	s_waitcnt lgkmcnt(0)
	v_lshrrev_b32_e32 v156, 5, v166
	v_lshrrev_b32_e32 v157, 5, v167
	v_and_b32_e32 v156, 0x1fc, v156
	v_and_b32_e32 v157, 0x1fc, v157
	v_add_u32_e32 v156, s18, v156
	v_add_u32_e32 v157, s18, v157
	ds_add_rtn_u32 v158, v156, v146
	ds_add_rtn_u32 v159, v157, v146
	ds_read_b32 v160, v144
	ds_read_b32 v161, v144 offset:256
	s_waitcnt lgkmcnt(0)
	v_mov_b32_e32 v164, v160
	v_mov_b32_e32 v165, v161
	v_cmp_le_u32_e32 vcc, 1, v213
	ds_bpermute_b32 v162, v149, v164
	ds_bpermute_b32 v163, v149, v165
	s_waitcnt lgkmcnt(0)
	v_cndmask_b32_e32 v162, 0, v162, vcc
	v_cndmask_b32_e32 v163, 0, v163, vcc
	v_add_u32_e32 v164, v164, v162
	v_add_u32_e32 v165, v165, v163
	v_cmp_le_u32_e32 vcc, 2, v213
	ds_bpermute_b32 v162, v150, v164
	ds_bpermute_b32 v163, v150, v165
	s_waitcnt lgkmcnt(0)
	v_cndmask_b32_e32 v162, 0, v162, vcc
	v_cndmask_b32_e32 v163, 0, v163, vcc
	v_add_u32_e32 v164, v164, v162
	v_add_u32_e32 v165, v165, v163
	v_cmp_le_u32_e32 vcc, 4, v213
	ds_bpermute_b32 v162, v151, v164
	ds_bpermute_b32 v163, v151, v165
	s_waitcnt lgkmcnt(0)
	v_cndmask_b32_e32 v162, 0, v162, vcc
	v_cndmask_b32_e32 v163, 0, v163, vcc
	v_add_u32_e32 v164, v164, v162
	v_add_u32_e32 v165, v165, v163
	v_cmp_le_u32_e32 vcc, 8, v213
	ds_bpermute_b32 v162, v152, v164
	ds_bpermute_b32 v163, v152, v165
	s_waitcnt lgkmcnt(0)
	v_cndmask_b32_e32 v162, 0, v162, vcc
	v_cndmask_b32_e32 v163, 0, v163, vcc
	v_add_u32_e32 v164, v164, v162
	v_add_u32_e32 v165, v165, v163
	v_cmp_le_u32_e32 vcc, 16, v213
	ds_bpermute_b32 v162, v153, v164
	ds_bpermute_b32 v163, v153, v165
	s_waitcnt lgkmcnt(0)
	v_cndmask_b32_e32 v162, 0, v162, vcc
	v_cndmask_b32_e32 v163, 0, v163, vcc
	v_add_u32_e32 v164, v164, v162
	v_add_u32_e32 v165, v165, v163
	v_cmp_le_u32_e32 vcc, 32, v213
	ds_bpermute_b32 v162, v154, v164
	ds_bpermute_b32 v163, v154, v165
	s_waitcnt lgkmcnt(0)
	v_cndmask_b32_e32 v162, 0, v162, vcc
	v_cndmask_b32_e32 v163, 0, v163, vcc
	v_add_u32_e32 v164, v164, v162
	v_add_u32_e32 v165, v165, v163
	v_readlane_b32 s13, v164, 63
	v_sub_u32_e32 v164, v164, v160
	v_sub_u32_e32 v165, v165, v161
	s_nop 0
	v_add_u32_e32 v165, s13, v165
	ds_write_b32 v144, v164
	ds_write_b32 v144, v165 offset:256
	ds_read_b32 v160, v156
	ds_read_b32 v161, v157
	s_waitcnt lgkmcnt(0)
	v_add_u32_e32 v160, v160, v158
	v_add_u32_e32 v161, v161, v159
	v_lshl_add_u32 v160, v160, 2, s19
	v_lshl_add_u32 v161, v161, 2, s19
	ds_write_b32 v160, v166 offset:512
	ds_write_b32 v160, v168 offset:16896
	ds_write_b32 v161, v167 offset:512
	ds_write_b32 v161, v169 offset:16896
	ds_read_b32 v130, v147 offset:512
	ds_read_b32 v131, v147 offset:544
	s_waitcnt lgkmcnt(0)
	v_lshlrev_b32_e32 v130, 10, v130
	v_lshlrev_b32_e32 v131, 10, v131
	ds_read_b32 v166, v237 offset:1024
	ds_read_b32 v167, v237 offset:1280
	ds_read_b32 v168, v237 offset:17408
	ds_read_b32 v169, v237 offset:17664
	ds_write_b32 v144, v145
	ds_write_b32 v144, v145 offset:256
	s_waitcnt lgkmcnt(0)
; template <bool STORE>
; DI void peer_item(const Params& p, int item, char* smem) {
;     ...
; #pragma unroll 2
;     for (int k = 0; k < 128; k += 8) {
;       u32x4 uq[8];
;       const int emine = e_s[tl * 128 + k + (lane >> 3)];
;       const float gmine = g_s[tl * 128 + k + (lane >> 3)];
;       const float su = SU[emine], sv = SV[emine];
; #pragma unroll
;       for (int u = 0; u < 8; ++u) {
;         int e = e_s[tl * 128 + k + u];
;         uq[u] = *(const u32x4*)(U8 + (size_t)e * 1024 + lane * 16);
	v_lshrrev_b32_e32 v156, 5, v166
	v_lshrrev_b32_e32 v157, 5, v167
	v_and_b32_e32 v156, 0x1fc, v156
	v_and_b32_e32 v157, 0x1fc, v157
	v_add_u32_e32 v156, s18, v156
	v_add_u32_e32 v157, s18, v157
	ds_add_rtn_u32 v158, v156, v146
	ds_add_rtn_u32 v159, v157, v146
	ds_read_b32 v160, v144
	ds_read_b32 v161, v144 offset:256
	s_waitcnt lgkmcnt(0)
	v_mov_b32_e32 v164, v160
	v_mov_b32_e32 v165, v161
	v_cmp_le_u32_e32 vcc, 1, v213
	ds_bpermute_b32 v162, v149, v164
	ds_bpermute_b32 v163, v149, v165
	s_waitcnt lgkmcnt(0)
	v_cndmask_b32_e32 v162, 0, v162, vcc
	v_cndmask_b32_e32 v163, 0, v163, vcc
	v_add_u32_e32 v164, v164, v162
	v_add_u32_e32 v165, v165, v163
	v_cmp_le_u32_e32 vcc, 2, v213
	ds_bpermute_b32 v162, v150, v164
	ds_bpermute_b32 v163, v150, v165
	s_waitcnt lgkmcnt(0)
	v_cndmask_b32_e32 v162, 0, v162, vcc
	v_cndmask_b32_e32 v163, 0, v163, vcc
	v_add_u32_e32 v164, v164, v162
	v_add_u32_e32 v165, v165, v163
	v_cmp_le_u32_e32 vcc, 4, v213
	ds_bpermute_b32 v162, v151, v164
	ds_bpermute_b32 v163, v151, v165
	s_waitcnt lgkmcnt(0)
	v_cndmask_b32_e32 v162, 0, v162, vcc
	v_cndmask_b32_e32 v163, 0, v163, vcc
	v_add_u32_e32 v164, v164, v162
	v_add_u32_e32 v165, v165, v163
	v_cmp_le_u32_e32 vcc, 8, v213
	ds_bpermute_b32 v162, v152, v164
	ds_bpermute_b32 v163, v152, v165
	s_waitcnt lgkmcnt(0)
	v_cndmask_b32_e32 v162, 0, v162, vcc
	v_cndmask_b32_e32 v163, 0, v163, vcc
	v_add_u32_e32 v164, v164, v162
	v_add_u32_e32 v165, v165, v163
	v_cmp_le_u32_e32 vcc, 16, v213
	ds_bpermute_b32 v162, v153, v164
	ds_bpermute_b32 v163, v153, v165
	s_waitcnt lgkmcnt(0)
	v_cndmask_b32_e32 v162, 0, v162, vcc
	v_cndmask_b32_e32 v163, 0, v163, vcc
	v_add_u32_e32 v164, v164, v162
	v_add_u32_e32 v165, v165, v163
	v_cmp_le_u32_e32 vcc, 32, v213
	ds_bpermute_b32 v162, v154, v164
	ds_bpermute_b32 v163, v154, v165
	s_waitcnt lgkmcnt(0)
	v_cndmask_b32_e32 v162, 0, v162, vcc
	v_cndmask_b32_e32 v163, 0, v163, vcc
	v_add_u32_e32 v164, v164, v162
	v_add_u32_e32 v165, v165, v163
	v_readlane_b32 s13, v164, 63
	v_sub_u32_e32 v164, v164, v160
	v_sub_u32_e32 v165, v165, v161
	s_nop 0
	v_add_u32_e32 v165, s13, v165
	ds_write_b32 v144, v164
	ds_write_b32 v144, v165 offset:256
	ds_read_b32 v160, v156
	ds_read_b32 v161, v157
	s_waitcnt lgkmcnt(0)
	v_add_u32_e32 v160, v160, v158
	v_add_u32_e32 v161, v161, v159
	v_lshl_add_u32 v160, v160, 2, s19
	v_lshl_add_u32 v161, v161, 2, s19
	ds_write_b32 v160, v166 offset:1024
	ds_write_b32 v160, v168 offset:17408
	ds_write_b32 v161, v167 offset:1024
	ds_write_b32 v161, v169 offset:17408
	ds_read_b32 v132, v147 offset:1024
	ds_read_b32 v133, v147 offset:1056
	s_waitcnt lgkmcnt(0)
	v_lshlrev_b32_e32 v132, 10, v132
	v_lshlrev_b32_e32 v133, 10, v133
	ds_read_b32 v166, v237 offset:1536
	ds_read_b32 v167, v237 offset:1792
	ds_read_b32 v168, v237 offset:17920
	ds_read_b32 v169, v237 offset:18176
	ds_write_b32 v144, v145
	ds_write_b32 v144, v145 offset:256
	s_waitcnt lgkmcnt(0)
	v_lshrrev_b32_e32 v156, 5, v166
	v_lshrrev_b32_e32 v157, 5, v167
	v_and_b32_e32 v156, 0x1fc, v156
	v_and_b32_e32 v157, 0x1fc, v157
	v_add_u32_e32 v156, s18, v156
	v_add_u32_e32 v157, s18, v157
	ds_add_rtn_u32 v158, v156, v146
	ds_add_rtn_u32 v159, v157, v146
	ds_read_b32 v160, v144
	ds_read_b32 v161, v144 offset:256
	s_waitcnt lgkmcnt(0)
	v_mov_b32_e32 v164, v160
	v_mov_b32_e32 v165, v161
	v_cmp_le_u32_e32 vcc, 1, v213
	ds_bpermute_b32 v162, v149, v164
	ds_bpermute_b32 v163, v149, v165
	s_waitcnt lgkmcnt(0)
	v_cndmask_b32_e32 v162, 0, v162, vcc
	v_cndmask_b32_e32 v163, 0, v163, vcc
	v_add_u32_e32 v164, v164, v162
	v_add_u32_e32 v165, v165, v163
	v_cmp_le_u32_e32 vcc, 2, v213
	ds_bpermute_b32 v162, v150, v164
	ds_bpermute_b32 v163, v150, v165
	s_waitcnt lgkmcnt(0)
	v_cndmask_b32_e32 v162, 0, v162, vcc
	v_cndmask_b32_e32 v163, 0, v163, vcc
	v_add_u32_e32 v164, v164, v162
	v_add_u32_e32 v165, v165, v163
	v_cmp_le_u32_e32 vcc, 4, v213
	ds_bpermute_b32 v162, v151, v164
	ds_bpermute_b32 v163, v151, v165
	s_waitcnt lgkmcnt(0)
	v_cndmask_b32_e32 v162, 0, v162, vcc
	v_cndmask_b32_e32 v163, 0, v163, vcc
	v_add_u32_e32 v164, v164, v162
	v_add_u32_e32 v165, v165, v163
	v_cmp_le_u32_e32 vcc, 8, v213
	ds_bpermute_b32 v162, v152, v164
	ds_bpermute_b32 v163, v152, v165
	s_waitcnt lgkmcnt(0)
	v_cndmask_b32_e32 v162, 0, v162, vcc
	v_cndmask_b32_e32 v163, 0, v163, vcc
	v_add_u32_e32 v164, v164, v162
	v_add_u32_e32 v165, v165, v163
	v_cmp_le_u32_e32 vcc, 16, v213
	ds_bpermute_b32 v162, v153, v164
	ds_bpermute_b32 v163, v153, v165
	s_waitcnt lgkmcnt(0)
	v_cndmask_b32_e32 v162, 0, v162, vcc
	v_cndmask_b32_e32 v163, 0, v163, vcc
	v_add_u32_e32 v164, v164, v162
	v_add_u32_e32 v165, v165, v163
	v_cmp_le_u32_e32 vcc, 32, v213
	ds_bpermute_b32 v162, v154, v164
	ds_bpermute_b32 v163, v154, v165
	s_waitcnt lgkmcnt(0)
	v_cndmask_b32_e32 v162, 0, v162, vcc
	v_cndmask_b32_e32 v163, 0, v163, vcc
	v_add_u32_e32 v164, v164, v162
	v_add_u32_e32 v165, v165, v163
	v_readlane_b32 s13, v164, 63
	v_sub_u32_e32 v164, v164, v160
	v_sub_u32_e32 v165, v165, v161
	s_nop 0
	v_add_u32_e32 v165, s13, v165
	ds_write_b32 v144, v164
	ds_write_b32 v144, v165 offset:256
	ds_read_b32 v160, v156
	ds_read_b32 v161, v157
	s_waitcnt lgkmcnt(0)
	v_add_u32_e32 v160, v160, v158
	v_add_u32_e32 v161, v161, v159
	v_lshl_add_u32 v160, v160, 2, s19
	v_lshl_add_u32 v161, v161, 2, s19
	ds_write_b32 v160, v166 offset:1536
	ds_write_b32 v160, v168 offset:17920
	ds_write_b32 v161, v167 offset:1536
	ds_write_b32 v161, v169 offset:17920
	ds_read_b32 v134, v147 offset:1536
	ds_read_b32 v135, v147 offset:1568
	s_waitcnt lgkmcnt(0)
; template <bool STORE>
; DI void peer_item(const Params& p, int item, char* smem) {
;     ...
; #pragma unroll 2
;     for (int k = 0; k < 128; k += 8) {
;       u32x4 uq[8];
;       const int emine = e_s[tl * 128 + k + (lane >> 3)];
;       const float gmine = g_s[tl * 128 + k + (lane >> 3)];
;       const float su = SU[emine], sv = SV[emine];
; #pragma unroll
;       for (int u = 0; u < 8; ++u) {
;         int e = e_s[tl * 128 + k + u];
;         uq[u] = *(const u32x4*)(U8 + (size_t)e * 1024 + lane * 16);
	v_lshlrev_b32_e32 v134, 10, v134
	v_lshlrev_b32_e32 v135, 10, v135
	ds_read_b32 v166, v237 offset:2048
	ds_read_b32 v167, v237 offset:2304
	ds_read_b32 v168, v237 offset:18432
	ds_read_b32 v169, v237 offset:18688
	ds_write_b32 v144, v145
	ds_write_b32 v144, v145 offset:256
	s_waitcnt lgkmcnt(0)
	v_lshrrev_b32_e32 v156, 5, v166
	v_lshrrev_b32_e32 v157, 5, v167
	v_and_b32_e32 v156, 0x1fc, v156
	v_and_b32_e32 v157, 0x1fc, v157
	v_add_u32_e32 v156, s18, v156
	v_add_u32_e32 v157, s18, v157
	ds_add_rtn_u32 v158, v156, v146
	ds_add_rtn_u32 v159, v157, v146
	ds_read_b32 v160, v144
	ds_read_b32 v161, v144 offset:256
	s_waitcnt lgkmcnt(0)
	v_mov_b32_e32 v164, v160
	v_mov_b32_e32 v165, v161
	v_cmp_le_u32_e32 vcc, 1, v213
	ds_bpermute_b32 v162, v149, v164
	ds_bpermute_b32 v163, v149, v165
	s_waitcnt lgkmcnt(0)
	v_cndmask_b32_e32 v162, 0, v162, vcc
	v_cndmask_b32_e32 v163, 0, v163, vcc
	v_add_u32_e32 v164, v164, v162
	v_add_u32_e32 v165, v165, v163
	v_cmp_le_u32_e32 vcc, 2, v213
	ds_bpermute_b32 v162, v150, v164
	ds_bpermute_b32 v163, v150, v165
	s_waitcnt lgkmcnt(0)
	v_cndmask_b32_e32 v162, 0, v162, vcc
	v_cndmask_b32_e32 v163, 0, v163, vcc
	v_add_u32_e32 v164, v164, v162
	v_add_u32_e32 v165, v165, v163
	v_cmp_le_u32_e32 vcc, 4, v213
	ds_bpermute_b32 v162, v151, v164
	ds_bpermute_b32 v163, v151, v165
	s_waitcnt lgkmcnt(0)
	v_cndmask_b32_e32 v162, 0, v162, vcc
	v_cndmask_b32_e32 v163, 0, v163, vcc
	v_add_u32_e32 v164, v164, v162
	v_add_u32_e32 v165, v165, v163
	v_cmp_le_u32_e32 vcc, 8, v213
	ds_bpermute_b32 v162, v152, v164
	ds_bpermute_b32 v163, v152, v165
	s_waitcnt lgkmcnt(0)
	v_cndmask_b32_e32 v162, 0, v162, vcc
	v_cndmask_b32_e32 v163, 0, v163, vcc
	v_add_u32_e32 v164, v164, v162
	v_add_u32_e32 v165, v165, v163
	v_cmp_le_u32_e32 vcc, 16, v213
	ds_bpermute_b32 v162, v153, v164
	ds_bpermute_b32 v163, v153, v165
	s_waitcnt lgkmcnt(0)
	v_cndmask_b32_e32 v162, 0, v162, vcc
	v_cndmask_b32_e32 v163, 0, v163, vcc
	v_add_u32_e32 v164, v164, v162
	v_add_u32_e32 v165, v165, v163
	v_cmp_le_u32_e32 vcc, 32, v213
	ds_bpermute_b32 v162, v154, v164
	ds_bpermute_b32 v163, v154, v165
	s_waitcnt lgkmcnt(0)
	v_cndmask_b32_e32 v162, 0, v162, vcc
	v_cndmask_b32_e32 v163, 0, v163, vcc
	v_add_u32_e32 v164, v164, v162
	v_add_u32_e32 v165, v165, v163
	v_readlane_b32 s13, v164, 63
	v_sub_u32_e32 v164, v164, v160
	v_sub_u32_e32 v165, v165, v161
	s_nop 0
	v_add_u32_e32 v165, s13, v165
	ds_write_b32 v144, v164
	ds_write_b32 v144, v165 offset:256
	ds_read_b32 v160, v156
	ds_read_b32 v161, v157
	s_waitcnt lgkmcnt(0)
	v_add_u32_e32 v160, v160, v158
	v_add_u32_e32 v161, v161, v159
	v_lshl_add_u32 v160, v160, 2, s19
	v_lshl_add_u32 v161, v161, 2, s19
	ds_write_b32 v160, v166 offset:2048
	ds_write_b32 v160, v168 offset:18432
	ds_write_b32 v161, v167 offset:2048
	ds_write_b32 v161, v169 offset:18432
	ds_read_b32 v136, v147 offset:2048
	ds_read_b32 v137, v147 offset:2080
	s_waitcnt lgkmcnt(0)
	v_lshlrev_b32_e32 v136, 10, v136
	v_lshlrev_b32_e32 v137, 10, v137
	ds_read_b32 v166, v237 offset:2560
	ds_read_b32 v167, v237 offset:2816
	ds_read_b32 v168, v237 offset:18944
	ds_read_b32 v169, v237 offset:19200
	ds_write_b32 v144, v145
	ds_write_b32 v144, v145 offset:256
	s_waitcnt lgkmcnt(0)
	v_lshrrev_b32_e32 v156, 5, v166
	v_lshrrev_b32_e32 v157, 5, v167
	v_and_b32_e32 v156, 0x1fc, v156
	v_and_b32_e32 v157, 0x1fc, v157
	v_add_u32_e32 v156, s18, v156
	v_add_u32_e32 v157, s18, v157
	ds_add_rtn_u32 v158, v156, v146
	ds_add_rtn_u32 v159, v157, v146
	ds_read_b32 v160, v144
	ds_read_b32 v161, v144 offset:256
	s_waitcnt lgkmcnt(0)
	v_mov_b32_e32 v164, v160
	v_mov_b32_e32 v165, v161
	v_cmp_le_u32_e32 vcc, 1, v213
	ds_bpermute_b32 v162, v149, v164
	ds_bpermute_b32 v163, v149, v165
	s_waitcnt lgkmcnt(0)
	v_cndmask_b32_e32 v162, 0, v162, vcc
	v_cndmask_b32_e32 v163, 0, v163, vcc
	v_add_u32_e32 v164, v164, v162
	v_add_u32_e32 v165, v165, v163
	v_cmp_le_u32_e32 vcc, 2, v213
	ds_bpermute_b32 v162, v150, v164
	ds_bpermute_b32 v163, v150, v165
	s_waitcnt lgkmcnt(0)
	v_cndmask_b32_e32 v162, 0, v162, vcc
	v_cndmask_b32_e32 v163, 0, v163, vcc
	v_add_u32_e32 v164, v164, v162
	v_add_u32_e32 v165, v165, v163
	v_cmp_le_u32_e32 vcc, 4, v213
	ds_bpermute_b32 v162, v151, v164
	ds_bpermute_b32 v163, v151, v165
	s_waitcnt lgkmcnt(0)
	v_cndmask_b32_e32 v162, 0, v162, vcc
	v_cndmask_b32_e32 v163, 0, v163, vcc
	v_add_u32_e32 v164, v164, v162
	v_add_u32_e32 v165, v165, v163
	v_cmp_le_u32_e32 vcc, 8, v213
	ds_bpermute_b32 v162, v152, v164
	ds_bpermute_b32 v163, v152, v165
	s_waitcnt lgkmcnt(0)
	v_cndmask_b32_e32 v162, 0, v162, vcc
	v_cndmask_b32_e32 v163, 0, v163, vcc
	v_add_u32_e32 v164, v164, v162
	v_add_u32_e32 v165, v165, v163
	v_cmp_le_u32_e32 vcc, 16, v213
	ds_bpermute_b32 v162, v153, v164
	ds_bpermute_b32 v163, v153, v165
	s_waitcnt lgkmcnt(0)
	v_cndmask_b32_e32 v162, 0, v162, vcc
	v_cndmask_b32_e32 v163, 0, v163, vcc
	v_add_u32_e32 v164, v164, v162
	v_add_u32_e32 v165, v165, v163
	v_cmp_le_u32_e32 vcc, 32, v213
	ds_bpermute_b32 v162, v154, v164
	ds_bpermute_b32 v163, v154, v165
	s_waitcnt lgkmcnt(0)
	v_cndmask_b32_e32 v162, 0, v162, vcc
	v_cndmask_b32_e32 v163, 0, v163, vcc
	v_add_u32_e32 v164, v164, v162
	v_add_u32_e32 v165, v165, v163
	v_readlane_b32 s13, v164, 63
	v_sub_u32_e32 v164, v164, v160
	v_sub_u32_e32 v165, v165, v161
	s_nop 0
	v_add_u32_e32 v165, s13, v165
	ds_write_b32 v144, v164
	ds_write_b32 v144, v165 offset:256
	ds_read_b32 v160, v156
	ds_read_b32 v161, v157
	s_waitcnt lgkmcnt(0)
	v_add_u32_e32 v160, v160, v158
	v_add_u32_e32 v161, v161, v159
	v_lshl_add_u32 v160, v160, 2, s19
	v_lshl_add_u32 v161, v161, 2, s19
	ds_write_b32 v160, v166 offset:2560
	ds_write_b32 v160, v168 offset:18944
	ds_write_b32 v161, v167 offset:2560
	ds_write_b32 v161, v169 offset:18944
	ds_read_b32 v138, v147 offset:2560
	ds_read_b32 v139, v147 offset:2592
	s_waitcnt lgkmcnt(0)
; template <bool STORE>
; DI void peer_item(const Params& p, int item, char* smem) {
;     ...
; #pragma unroll 2
;     for (int k = 0; k < 128; k += 8) {
;       u32x4 uq[8];
;       const int emine = e_s[tl * 128 + k + (lane >> 3)];
;       const float gmine = g_s[tl * 128 + k + (lane >> 3)];
;       const float su = SU[emine], sv = SV[emine];
; #pragma unroll
;       for (int u = 0; u < 8; ++u) {
;         int e = e_s[tl * 128 + k + u];
;         uq[u] = *(const u32x4*)(U8 + (size_t)e * 1024 + lane * 16);
	v_lshlrev_b32_e32 v138, 10, v138
	v_lshlrev_b32_e32 v139, 10, v139
	ds_read_b32 v166, v237 offset:3072
	ds_read_b32 v167, v237 offset:3328
	ds_read_b32 v168, v237 offset:19456
	ds_read_b32 v169, v237 offset:19712
	ds_write_b32 v144, v145
	ds_write_b32 v144, v145 offset:256
	s_waitcnt lgkmcnt(0)
	v_lshrrev_b32_e32 v156, 5, v166
	v_lshrrev_b32_e32 v157, 5, v167
	v_and_b32_e32 v156, 0x1fc, v156
	v_and_b32_e32 v157, 0x1fc, v157
	v_add_u32_e32 v156, s18, v156
	v_add_u32_e32 v157, s18, v157
	ds_add_rtn_u32 v158, v156, v146
	ds_add_rtn_u32 v159, v157, v146
	ds_read_b32 v160, v144
	ds_read_b32 v161, v144 offset:256
	s_waitcnt lgkmcnt(0)
	v_mov_b32_e32 v164, v160
	v_mov_b32_e32 v165, v161
	v_cmp_le_u32_e32 vcc, 1, v213
	ds_bpermute_b32 v162, v149, v164
	ds_bpermute_b32 v163, v149, v165
	s_waitcnt lgkmcnt(0)
	v_cndmask_b32_e32 v162, 0, v162, vcc
	v_cndmask_b32_e32 v163, 0, v163, vcc
	v_add_u32_e32 v164, v164, v162
	v_add_u32_e32 v165, v165, v163
	v_cmp_le_u32_e32 vcc, 2, v213
	ds_bpermute_b32 v162, v150, v164
	ds_bpermute_b32 v163, v150, v165
	s_waitcnt lgkmcnt(0)
	v_cndmask_b32_e32 v162, 0, v162, vcc
	v_cndmask_b32_e32 v163, 0, v163, vcc
	v_add_u32_e32 v164, v164, v162
	v_add_u32_e32 v165, v165, v163
	v_cmp_le_u32_e32 vcc, 4, v213
	ds_bpermute_b32 v162, v151, v164
	ds_bpermute_b32 v163, v151, v165
	s_waitcnt lgkmcnt(0)
	v_cndmask_b32_e32 v162, 0, v162, vcc
	v_cndmask_b32_e32 v163, 0, v163, vcc
	v_add_u32_e32 v164, v164, v162
	v_add_u32_e32 v165, v165, v163
	v_cmp_le_u32_e32 vcc, 8, v213
	ds_bpermute_b32 v162, v152, v164
	ds_bpermute_b32 v163, v152, v165
	s_waitcnt lgkmcnt(0)
	v_cndmask_b32_e32 v162, 0, v162, vcc
	v_cndmask_b32_e32 v163, 0, v163, vcc
	v_add_u32_e32 v164, v164, v162
	v_add_u32_e32 v165, v165, v163
	v_cmp_le_u32_e32 vcc, 16, v213
	ds_bpermute_b32 v162, v153, v164
	ds_bpermute_b32 v163, v153, v165
	s_waitcnt lgkmcnt(0)
	v_cndmask_b32_e32 v162, 0, v162, vcc
	v_cndmask_b32_e32 v163, 0, v163, vcc
	v_add_u32_e32 v164, v164, v162
	v_add_u32_e32 v165, v165, v163
	v_cmp_le_u32_e32 vcc, 32, v213
	ds_bpermute_b32 v162, v154, v164
	ds_bpermute_b32 v163, v154, v165
	s_waitcnt lgkmcnt(0)
	v_cndmask_b32_e32 v162, 0, v162, vcc
	v_cndmask_b32_e32 v163, 0, v163, vcc
	v_add_u32_e32 v164, v164, v162
	v_add_u32_e32 v165, v165, v163
	v_readlane_b32 s13, v164, 63
	v_sub_u32_e32 v164, v164, v160
	v_sub_u32_e32 v165, v165, v161
	s_nop 0
	v_add_u32_e32 v165, s13, v165
	ds_write_b32 v144, v164
	ds_write_b32 v144, v165 offset:256
	ds_read_b32 v160, v156
	ds_read_b32 v161, v157
	s_waitcnt lgkmcnt(0)
	v_add_u32_e32 v160, v160, v158
	v_add_u32_e32 v161, v161, v159
	v_lshl_add_u32 v160, v160, 2, s19
	v_lshl_add_u32 v161, v161, 2, s19
	ds_write_b32 v160, v166 offset:3072
	ds_write_b32 v160, v168 offset:19456
	ds_write_b32 v161, v167 offset:3072
	ds_write_b32 v161, v169 offset:19456
	ds_read_b32 v140, v147 offset:3072
	ds_read_b32 v141, v147 offset:3104
	s_waitcnt lgkmcnt(0)
	v_lshlrev_b32_e32 v140, 10, v140
	v_lshlrev_b32_e32 v141, 10, v141
	ds_read_b32 v166, v237 offset:3584
	ds_read_b32 v167, v237 offset:3840
	ds_read_b32 v168, v237 offset:19968
	ds_read_b32 v169, v237 offset:20224
	ds_write_b32 v144, v145
	ds_write_b32 v144, v145 offset:256
	s_waitcnt lgkmcnt(0)
	v_lshrrev_b32_e32 v156, 5, v166
	v_lshrrev_b32_e32 v157, 5, v167
	v_and_b32_e32 v156, 0x1fc, v156
	v_and_b32_e32 v157, 0x1fc, v157
	v_add_u32_e32 v156, s18, v156
	v_add_u32_e32 v157, s18, v157
	ds_add_rtn_u32 v158, v156, v146
	ds_add_rtn_u32 v159, v157, v146
	ds_read_b32 v160, v144
	ds_read_b32 v161, v144 offset:256
	s_waitcnt lgkmcnt(0)
	v_mov_b32_e32 v164, v160
	v_mov_b32_e32 v165, v161
	v_cmp_le_u32_e32 vcc, 1, v213
	ds_bpermute_b32 v162, v149, v164
	ds_bpermute_b32 v163, v149, v165
	s_waitcnt lgkmcnt(0)
	v_cndmask_b32_e32 v162, 0, v162, vcc
	v_cndmask_b32_e32 v163, 0, v163, vcc
	v_add_u32_e32 v164, v164, v162
	v_add_u32_e32 v165, v165, v163
	v_cmp_le_u32_e32 vcc, 2, v213
	ds_bpermute_b32 v162, v150, v164
	ds_bpermute_b32 v163, v150, v165
	s_waitcnt lgkmcnt(0)
	v_cndmask_b32_e32 v162, 0, v162, vcc
	v_cndmask_b32_e32 v163, 0, v163, vcc
	v_add_u32_e32 v164, v164, v162
	v_add_u32_e32 v165, v165, v163
	v_cmp_le_u32_e32 vcc, 4, v213
	ds_bpermute_b32 v162, v151, v164
	ds_bpermute_b32 v163, v151, v165
	s_waitcnt lgkmcnt(0)
	v_cndmask_b32_e32 v162, 0, v162, vcc
	v_cndmask_b32_e32 v163, 0, v163, vcc
	v_add_u32_e32 v164, v164, v162
	v_add_u32_e32 v165, v165, v163
	v_cmp_le_u32_e32 vcc, 8, v213
	ds_bpermute_b32 v162, v152, v164
	ds_bpermute_b32 v163, v152, v165
	s_waitcnt lgkmcnt(0)
	v_cndmask_b32_e32 v162, 0, v162, vcc
	v_cndmask_b32_e32 v163, 0, v163, vcc
	v_add_u32_e32 v164, v164, v162
	v_add_u32_e32 v165, v165, v163
	v_cmp_le_u32_e32 vcc, 16, v213
	ds_bpermute_b32 v162, v153, v164
	ds_bpermute_b32 v163, v153, v165
	s_waitcnt lgkmcnt(0)
	v_cndmask_b32_e32 v162, 0, v162, vcc
	v_cndmask_b32_e32 v163, 0, v163, vcc
	v_add_u32_e32 v164, v164, v162
	v_add_u32_e32 v165, v165, v163
	v_cmp_le_u32_e32 vcc, 32, v213
	ds_bpermute_b32 v162, v154, v164
	ds_bpermute_b32 v163, v154, v165
	s_waitcnt lgkmcnt(0)
	v_cndmask_b32_e32 v162, 0, v162, vcc
	v_cndmask_b32_e32 v163, 0, v163, vcc
	v_add_u32_e32 v164, v164, v162
	v_add_u32_e32 v165, v165, v163
	v_readlane_b32 s13, v164, 63
	v_sub_u32_e32 v164, v164, v160
	v_sub_u32_e32 v165, v165, v161
	s_nop 0
	v_add_u32_e32 v165, s13, v165
	ds_write_b32 v144, v164
	ds_write_b32 v144, v165 offset:256
	ds_read_b32 v160, v156
	ds_read_b32 v161, v157
	s_waitcnt lgkmcnt(0)
	v_add_u32_e32 v160, v160, v158
	v_add_u32_e32 v161, v161, v159
	v_lshl_add_u32 v160, v160, 2, s19
	v_lshl_add_u32 v161, v161, 2, s19
	ds_write_b32 v160, v166 offset:3584
	ds_write_b32 v160, v168 offset:19968
	ds_write_b32 v161, v167 offset:3584
	ds_write_b32 v161, v169 offset:19968
	ds_read_b32 v142, v147 offset:3584
	ds_read_b32 v143, v147 offset:3616
	s_waitcnt lgkmcnt(0)
; DI float bflo(unsigned u) { return __uint_as_float(u << 16); }
; DI float bfhi(unsigned u) { return __uint_as_float(u & 0xffff0000u); }
; template <bool STORE>
; DI void peer_item(const Params& p, int item, char* smem) {
;     ...
;     {
; #pragma unroll
;       for (int i = 0; i < 4; ++i) {
;         const uint2 xv = *(const uint2*)(XN2 + tok * 1024 + 256 * i + lane * 4);
;         xf[4 * i] = bflo(xv.x); xf[4 * i + 1] = bfhi(xv.x); xf[4 * i + 2] = bflo(xv.y); xf[4 * i + 3] = bfhi(xv.y);
;       }
;     }
; #pragma unroll 2
;     for (int k = 0; k < 128; k += 8) {
;       u32x4 uq[8];
;       const int emine = e_s[tl * 128 + k + (lane >> 3)];
;       const float gmine = g_s[tl * 128 + k + (lane >> 3)];
;       const float su = SU[emine], sv = SV[emine];
; #pragma unroll
;       for (int u = 0; u < 8; ++u) {
;         int e = e_s[tl * 128 + k + u];
;         uq[u] = *(const u32x4*)(U8 + (size_t)e * 1024 + lane * 16);
;       }
	v_lshlrev_b32_e32 v142, 10, v142
	v_lshlrev_b32_e32 v143, 10, v143
	s_waitcnt vmcnt(0)
	v_lshlrev_b32_e32 v0, 16, v2
	v_and_b32_e32 v1, 0xffff0000, v2
	v_lshlrev_b32_e32 v2, 16, v3
	v_and_b32_e32 v3, 0xffff0000, v3
	v_lshlrev_b32_e32 v4, 16, v6
	v_and_b32_e32 v5, 0xffff0000, v6
	v_lshlrev_b32_e32 v6, 16, v7
	v_and_b32_e32 v7, 0xffff0000, v7
	v_lshlrev_b32_e32 v8, 16, v10
	v_and_b32_e32 v9, 0xffff0000, v10
	v_lshlrev_b32_e32 v10, 16, v11
	v_and_b32_e32 v11, 0xffff0000, v11
	v_lshlrev_b32_e32 v12, 16, v14
	v_and_b32_e32 v13, 0xffff0000, v14
	v_lshlrev_b32_e32 v14, 16, v15
	v_and_b32_e32 v15, 0xffff0000, v15
	v_lshlrev_b32_e32 v16, 16, v18
	v_and_b32_e32 v17, 0xffff0000, v18
	v_lshlrev_b32_e32 v18, 16, v19
	v_and_b32_e32 v19, 0xffff0000, v19
	v_lshlrev_b32_e32 v20, 16, v22
	v_and_b32_e32 v21, 0xffff0000, v22
	v_lshlrev_b32_e32 v22, 16, v23
	v_and_b32_e32 v23, 0xffff0000, v23
	v_lshlrev_b32_e32 v24, 16, v26
	v_and_b32_e32 v25, 0xffff0000, v26
	v_lshlrev_b32_e32 v26, 16, v27
	v_and_b32_e32 v27, 0xffff0000, v27
	v_lshlrev_b32_e32 v28, 16, v30
	v_and_b32_e32 v29, 0xffff0000, v30
	v_lshlrev_b32_e32 v30, 16, v31
	v_and_b32_e32 v31, 0xffff0000, v31
	v_lshlrev_b32_e32 v32, 16, v34
	v_and_b32_e32 v33, 0xffff0000, v34
	v_lshlrev_b32_e32 v34, 16, v35
	v_and_b32_e32 v35, 0xffff0000, v35
	v_lshlrev_b32_e32 v36, 16, v38
	v_and_b32_e32 v37, 0xffff0000, v38
	v_lshlrev_b32_e32 v38, 16, v39
	v_and_b32_e32 v39, 0xffff0000, v39
	v_lshlrev_b32_e32 v40, 16, v42
	v_and_b32_e32 v41, 0xffff0000, v42
	v_lshlrev_b32_e32 v42, 16, v43
	v_and_b32_e32 v43, 0xffff0000, v43
	v_lshlrev_b32_e32 v44, 16, v46
	v_and_b32_e32 v45, 0xffff0000, v46
	v_lshlrev_b32_e32 v46, 16, v47
	v_and_b32_e32 v47, 0xffff0000, v47
	v_lshlrev_b32_e32 v48, 16, v50
	v_and_b32_e32 v49, 0xffff0000, v50
	v_lshlrev_b32_e32 v50, 16, v51
	v_and_b32_e32 v51, 0xffff0000, v51
	v_lshlrev_b32_e32 v52, 16, v54
	v_and_b32_e32 v53, 0xffff0000, v54
	v_lshlrev_b32_e32 v54, 16, v55
	v_and_b32_e32 v55, 0xffff0000, v55
	v_lshlrev_b32_e32 v56, 16, v58
	v_and_b32_e32 v57, 0xffff0000, v58
	v_lshlrev_b32_e32 v58, 16, v59
	v_and_b32_e32 v59, 0xffff0000, v59
	v_lshlrev_b32_e32 v60, 16, v62
	v_and_b32_e32 v61, 0xffff0000, v62
	v_lshlrev_b32_e32 v62, 16, v63
	v_and_b32_e32 v63, 0xffff0000, v63
	v_lshlrev_b32_e32 v64, 16, v66
	v_and_b32_e32 v65, 0xffff0000, v66
	v_lshlrev_b32_e32 v66, 16, v67
	v_and_b32_e32 v67, 0xffff0000, v67
	v_lshlrev_b32_e32 v68, 16, v70
	v_and_b32_e32 v69, 0xffff0000, v70
	v_lshlrev_b32_e32 v70, 16, v71
	v_and_b32_e32 v71, 0xffff0000, v71
	v_lshlrev_b32_e32 v72, 16, v74
	v_and_b32_e32 v73, 0xffff0000, v74
	v_lshlrev_b32_e32 v74, 16, v75
	v_and_b32_e32 v75, 0xffff0000, v75
	v_lshlrev_b32_e32 v76, 16, v78
	v_and_b32_e32 v77, 0xffff0000, v78
	v_lshlrev_b32_e32 v78, 16, v79
	v_and_b32_e32 v79, 0xffff0000, v79
	v_lshlrev_b32_e32 v80, 16, v82
	v_and_b32_e32 v81, 0xffff0000, v82
	v_lshlrev_b32_e32 v82, 16, v83
	v_and_b32_e32 v83, 0xffff0000, v83
	v_lshlrev_b32_e32 v84, 16, v86
	v_and_b32_e32 v85, 0xffff0000, v86
	v_lshlrev_b32_e32 v86, 16, v87
	v_and_b32_e32 v87, 0xffff0000, v87
	v_lshlrev_b32_e32 v88, 16, v90
	v_and_b32_e32 v89, 0xffff0000, v90
	v_lshlrev_b32_e32 v90, 16, v91
	v_and_b32_e32 v91, 0xffff0000, v91
	v_lshlrev_b32_e32 v92, 16, v94
	v_and_b32_e32 v93, 0xffff0000, v94
	v_lshlrev_b32_e32 v94, 16, v95
	v_and_b32_e32 v95, 0xffff0000, v95
	v_lshlrev_b32_e32 v96, 16, v98
	v_and_b32_e32 v97, 0xffff0000, v98
	v_lshlrev_b32_e32 v98, 16, v99
	v_and_b32_e32 v99, 0xffff0000, v99
	v_lshlrev_b32_e32 v100, 16, v102
	v_and_b32_e32 v101, 0xffff0000, v102
	v_lshlrev_b32_e32 v102, 16, v103
	v_and_b32_e32 v103, 0xffff0000, v103
	v_lshlrev_b32_e32 v104, 16, v106
	v_and_b32_e32 v105, 0xffff0000, v106
	v_lshlrev_b32_e32 v106, 16, v107
	v_and_b32_e32 v107, 0xffff0000, v107
	v_lshlrev_b32_e32 v108, 16, v110
	v_and_b32_e32 v109, 0xffff0000, v110
	v_lshlrev_b32_e32 v110, 16, v111
	v_and_b32_e32 v111, 0xffff0000, v111
	v_lshlrev_b32_e32 v112, 16, v114
	v_and_b32_e32 v113, 0xffff0000, v114
	v_lshlrev_b32_e32 v114, 16, v115
	v_and_b32_e32 v115, 0xffff0000, v115
	v_lshlrev_b32_e32 v116, 16, v118
	v_and_b32_e32 v117, 0xffff0000, v118
	v_lshlrev_b32_e32 v118, 16, v119
	v_and_b32_e32 v119, 0xffff0000, v119
	v_lshlrev_b32_e32 v120, 16, v122
	v_and_b32_e32 v121, 0xffff0000, v122
	v_lshlrev_b32_e32 v122, 16, v123
	v_and_b32_e32 v123, 0xffff0000, v123
	v_lshlrev_b32_e32 v124, 16, v126
	v_and_b32_e32 v125, 0xffff0000, v126
	v_lshlrev_b32_e32 v126, 16, v127
	v_and_b32_e32 v127, 0xffff0000, v127
	v_lshrrev_b32_e32 v235, 3, v213
	v_lshl_add_u32 v235, v235, 2, s19
	s_mov_b32 s72, 0
	s_mov_b32 s73, 1
	s_mov_b32 s74, 2
	s_mov_b32 s75, 3
	s_mov_b32 s76, 4
	s_mov_b32 s77, 5
	s_mov_b32 s78, 6
	s_mov_b32 s79, 7
	s_nop 0
	v_readlane_b32 s48, v128, s72
	v_readlane_b32 s49, v128, s73
	v_readlane_b32 s50, v128, s74
	v_readlane_b32 s51, v128, s75
	v_readlane_b32 s52, v128, s76
	v_readlane_b32 s53, v128, s77
	v_readlane_b32 s54, v128, s78
	v_readlane_b32 s55, v128, s79
	s_add_u32 s32, s0, s48
	s_addc_u32 s33, s1, 0
	s_add_u32 s34, s0, s49
	s_addc_u32 s35, s1, 0
	s_add_u32 s36, s0, s50
	s_addc_u32 s37, s1, 0
	s_add_u32 s38, s0, s51
	s_addc_u32 s39, s1, 0
	s_add_u32 s40, s0, s52
	s_addc_u32 s41, s1, 0
	s_add_u32 s42, s0, s53
	s_addc_u32 s43, s1, 0
	s_add_u32 s44, s0, s54
	s_addc_u32 s45, s1, 0
	s_add_u32 s46, s0, s55
	s_addc_u32 s47, s1, 0
	global_load_dwordx4 v[144:147], v234, s[32:33]
	global_load_dwordx4 v[148:151], v234, s[34:35]
	global_load_dwordx4 v[152:155], v234, s[36:37]
	global_load_dwordx4 v[156:159], v234, s[38:39]
	global_load_dwordx4 v[160:163], v234, s[40:41]
	global_load_dwordx4 v[164:167], v234, s[42:43]
	global_load_dwordx4 v[168:171], v234, s[44:45]
	global_load_dwordx4 v[172:175], v234, s[46:47]
	s_mov_b32 s12, 0
; template <bool STORE>
; DI void peer_item(const Params& p, int item, char* smem) {
;     ...
;       for (int u = 0; u < 8; ++u) {
;         int e = e_s[tl * 128 + k + u];
;         uq[u] = *(const u32x4*)(U8 + (size_t)e * 1024 + lane * 16);
;       }
;       float part[8];
; #pragma unroll
;       for (int u = 0; u < 8; ++u) {
;         float d = 0.f;
; #pragma unroll
;         for (int i = 0; i < 4; ++i) {
;           f32x2_t lo = __builtin_amdgcn_cvt_pk_f32_fp8((int)uq[u][i], false);
;           f32x2_t hi = __builtin_amdgcn_cvt_pk_f32_fp8((int)uq[u][i], true);
;           d += xf[4 * i] * lo.x + xf[4 * i + 1] * lo.y + xf[4 * i + 2] * hi.x + xf[4 * i + 3] * hi.y;
;         }
;         part[u] = d;
;       }
;       float q4[4], r2[2], h;
; #pragma unroll
;       for (int j = 0; j < 4; ++j) {
;         float mine = b5 ? part[j + 4] : part[j];
;         float other = b5 ? part[j] : part[j + 4];
;         q4[j] = mine + __shfl_xor(other, 32);
;       }
; #pragma unroll
;       for (int j = 0; j < 2; ++j) {
;         float mine = b4 ? q4[j + 2] : q4[j];
;         float other = b4 ? q4[j] : q4[j + 2];
;         r2[j] = mine + __shfl_xor(other, 16);
;       }
;       {
;         float mine = b3 ? r2[1] : r2[0];
;         float other = b3 ? r2[0] : r2[1];
;         h = mine + __shfl_xor(other, 8);
;       }
;       h += __shfl_xor(h, 4);
;       h += __shfl_xor(h, 2);
;       h += __shfl_xor(h, 1);
.Lup_k:
	v_readlane_b32 s48, v130, s72
	v_readlane_b32 s49, v130, s73
	v_readlane_b32 s50, v130, s74
	v_readlane_b32 s51, v130, s75
	v_readlane_b32 s52, v130, s76
	v_readlane_b32 s53, v130, s77
	v_readlane_b32 s54, v130, s78
	v_readlane_b32 s55, v130, s79
	s_add_u32 s32, s0, s48
	s_addc_u32 s33, s1, 0
	s_add_u32 s34, s0, s49
	s_addc_u32 s35, s1, 0
	s_add_u32 s36, s0, s50
	s_addc_u32 s37, s1, 0
	s_add_u32 s38, s0, s51
	s_addc_u32 s39, s1, 0
	s_add_u32 s40, s0, s52
	s_addc_u32 s41, s1, 0
	s_add_u32 s42, s0, s53
	s_addc_u32 s43, s1, 0
	s_add_u32 s44, s0, s54
	s_addc_u32 s45, s1, 0
	s_add_u32 s46, s0, s55
	s_addc_u32 s47, s1, 0
	global_load_dwordx4 v[176:179], v234, s[32:33]
	global_load_dwordx4 v[180:183], v234, s[34:35]
	global_load_dwordx4 v[184:187], v234, s[36:37]
	global_load_dwordx4 v[188:191], v234, s[38:39]
	global_load_dwordx4 v[192:195], v234, s[40:41]
	global_load_dwordx4 v[196:199], v234, s[42:43]
	global_load_dwordx4 v[200:203], v234, s[44:45]
	global_load_dwordx4 v[204:207], v234, s[46:47]
	s_waitcnt vmcnt(8)
	v_cvt_pk_f32_fp8_e32 v[214:215], v144
	v_cvt_pk_f32_fp8_sdwa v[216:217], v144 src0_sel:WORD_1
	v_cvt_pk_f32_fp8_e32 v[218:219], v145
	v_cvt_pk_f32_fp8_sdwa v[220:221], v145 src0_sel:WORD_1
	v_pk_mul_f32 v[222:223], v[0:1], v[214:215]
	v_pk_mul_f32 v[224:225], v[2:3], v[216:217]
	v_cvt_pk_f32_fp8_e32 v[214:215], v146
	v_cvt_pk_f32_fp8_sdwa v[216:217], v146 src0_sel:WORD_1
	v_pk_fma_f32 v[222:223], v[4:5], v[218:219], v[222:223]
	v_pk_fma_f32 v[224:225], v[6:7], v[220:221], v[224:225]
	v_cvt_pk_f32_fp8_e32 v[218:219], v147
	v_cvt_pk_f32_fp8_sdwa v[220:221], v147 src0_sel:WORD_1
	v_pk_fma_f32 v[222:223], v[8:9], v[214:215], v[222:223]
	v_pk_fma_f32 v[224:225], v[10:11], v[216:217], v[224:225]
	v_pk_fma_f32 v[222:223], v[12:13], v[218:219], v[222:223]
	v_pk_fma_f32 v[224:225], v[14:15], v[220:221], v[224:225]
	v_pk_add_f32 v[222:223], v[222:223], v[224:225]
	s_nop 0
	v_add_f32_e32 v226, v222, v223
	v_cvt_pk_f32_fp8_e32 v[214:215], v148
	v_cvt_pk_f32_fp8_sdwa v[216:217], v148 src0_sel:WORD_1
	v_cvt_pk_f32_fp8_e32 v[218:219], v149
	v_cvt_pk_f32_fp8_sdwa v[220:221], v149 src0_sel:WORD_1
	v_pk_mul_f32 v[222:223], v[0:1], v[214:215]
	v_pk_mul_f32 v[224:225], v[2:3], v[216:217]
	v_cvt_pk_f32_fp8_e32 v[214:215], v150
	v_cvt_pk_f32_fp8_sdwa v[216:217], v150 src0_sel:WORD_1
	v_pk_fma_f32 v[222:223], v[4:5], v[218:219], v[222:223]
	v_pk_fma_f32 v[224:225], v[6:7], v[220:221], v[224:225]
	v_cvt_pk_f32_fp8_e32 v[218:219], v151
	v_cvt_pk_f32_fp8_sdwa v[220:221], v151 src0_sel:WORD_1
	v_pk_fma_f32 v[222:223], v[8:9], v[214:215], v[222:223]
	v_pk_fma_f32 v[224:225], v[10:11], v[216:217], v[224:225]
	v_pk_fma_f32 v[222:223], v[12:13], v[218:219], v[222:223]
	v_pk_fma_f32 v[224:225], v[14:15], v[220:221], v[224:225]
	v_pk_add_f32 v[222:223], v[222:223], v[224:225]
	s_nop 0
	v_add_f32_e32 v227, v222, v223
	v_cvt_pk_f32_fp8_e32 v[214:215], v152
	v_cvt_pk_f32_fp8_sdwa v[216:217], v152 src0_sel:WORD_1
	v_cvt_pk_f32_fp8_e32 v[218:219], v153
	v_cvt_pk_f32_fp8_sdwa v[220:221], v153 src0_sel:WORD_1
	v_pk_mul_f32 v[222:223], v[0:1], v[214:215]
	v_pk_mul_f32 v[224:225], v[2:3], v[216:217]
	v_cvt_pk_f32_fp8_e32 v[214:215], v154
	v_cvt_pk_f32_fp8_sdwa v[216:217], v154 src0_sel:WORD_1
	v_pk_fma_f32 v[222:223], v[4:5], v[218:219], v[222:223]
	v_pk_fma_f32 v[224:225], v[6:7], v[220:221], v[224:225]
	v_cvt_pk_f32_fp8_e32 v[218:219], v155
	v_cvt_pk_f32_fp8_sdwa v[220:221], v155 src0_sel:WORD_1
	v_pk_fma_f32 v[222:223], v[8:9], v[214:215], v[222:223]
	v_pk_fma_f32 v[224:225], v[10:11], v[216:217], v[224:225]
	v_pk_fma_f32 v[222:223], v[12:13], v[218:219], v[222:223]
	v_pk_fma_f32 v[224:225], v[14:15], v[220:221], v[224:225]
	v_pk_add_f32 v[222:223], v[222:223], v[224:225]
	s_nop 0
	v_add_f32_e32 v228, v222, v223
	v_cvt_pk_f32_fp8_e32 v[214:215], v156
	v_cvt_pk_f32_fp8_sdwa v[216:217], v156 src0_sel:WORD_1
	v_cvt_pk_f32_fp8_e32 v[218:219], v157
	v_cvt_pk_f32_fp8_sdwa v[220:221], v157 src0_sel:WORD_1
	v_pk_mul_f32 v[222:223], v[0:1], v[214:215]
	v_pk_mul_f32 v[224:225], v[2:3], v[216:217]
	v_cvt_pk_f32_fp8_e32 v[214:215], v158
	v_cvt_pk_f32_fp8_sdwa v[216:217], v158 src0_sel:WORD_1
	v_pk_fma_f32 v[222:223], v[4:5], v[218:219], v[222:223]
	v_pk_fma_f32 v[224:225], v[6:7], v[220:221], v[224:225]
	v_cvt_pk_f32_fp8_e32 v[218:219], v159
	v_cvt_pk_f32_fp8_sdwa v[220:221], v159 src0_sel:WORD_1
	v_pk_fma_f32 v[222:223], v[8:9], v[214:215], v[222:223]
	v_pk_fma_f32 v[224:225], v[10:11], v[216:217], v[224:225]
	v_pk_fma_f32 v[222:223], v[12:13], v[218:219], v[222:223]
	v_pk_fma_f32 v[224:225], v[14:15], v[220:221], v[224:225]
	v_pk_add_f32 v[222:223], v[222:223], v[224:225]
	s_nop 0
	v_add_f32_e32 v229, v222, v223
	v_cvt_pk_f32_fp8_e32 v[214:215], v160
	v_cvt_pk_f32_fp8_sdwa v[216:217], v160 src0_sel:WORD_1
	v_cvt_pk_f32_fp8_e32 v[218:219], v161
	v_cvt_pk_f32_fp8_sdwa v[220:221], v161 src0_sel:WORD_1
	v_pk_mul_f32 v[222:223], v[0:1], v[214:215]
	v_pk_mul_f32 v[224:225], v[2:3], v[216:217]
	v_cvt_pk_f32_fp8_e32 v[214:215], v162
	v_cvt_pk_f32_fp8_sdwa v[216:217], v162 src0_sel:WORD_1
	v_pk_fma_f32 v[222:223], v[4:5], v[218:219], v[222:223]
	v_pk_fma_f32 v[224:225], v[6:7], v[220:221], v[224:225]
	v_cvt_pk_f32_fp8_e32 v[218:219], v163
	v_cvt_pk_f32_fp8_sdwa v[220:221], v163 src0_sel:WORD_1
	v_pk_fma_f32 v[222:223], v[8:9], v[214:215], v[222:223]
	v_pk_fma_f32 v[224:225], v[10:11], v[216:217], v[224:225]
	v_pk_fma_f32 v[222:223], v[12:13], v[218:219], v[222:223]
	v_pk_fma_f32 v[224:225], v[14:15], v[220:221], v[224:225]
	v_pk_add_f32 v[222:223], v[222:223], v[224:225]
	s_nop 0
	v_add_f32_e32 v230, v222, v223
	v_cvt_pk_f32_fp8_e32 v[214:215], v164
; template <bool STORE>
; DI void peer_item(const Params& p, int item, char* smem) {
;     ...
;       for (int u = 0; u < 8; ++u) {
;         int e = e_s[tl * 128 + k + u];
;         uq[u] = *(const u32x4*)(U8 + (size_t)e * 1024 + lane * 16);
;       }
;       float part[8];
; #pragma unroll
;       for (int u = 0; u < 8; ++u) {
;         float d = 0.f;
; #pragma unroll
;         for (int i = 0; i < 4; ++i) {
;           f32x2_t lo = __builtin_amdgcn_cvt_pk_f32_fp8((int)uq[u][i], false);
;           f32x2_t hi = __builtin_amdgcn_cvt_pk_f32_fp8((int)uq[u][i], true);
;           d += xf[4 * i] * lo.x + xf[4 * i + 1] * lo.y + xf[4 * i + 2] * hi.x + xf[4 * i + 3] * hi.y;
;         }
;         part[u] = d;
;       }
;       float q4[4], r2[2], h;
; #pragma unroll
;       for (int j = 0; j < 4; ++j) {
;         float mine = b5 ? part[j + 4] : part[j];
;         float other = b5 ? part[j] : part[j + 4];
;         q4[j] = mine + __shfl_xor(other, 32);
;       }
; #pragma unroll
;       for (int j = 0; j < 2; ++j) {
;         float mine = b4 ? q4[j + 2] : q4[j];
;         float other = b4 ? q4[j] : q4[j + 2];
;         r2[j] = mine + __shfl_xor(other, 16);
;       }
;       {
;         float mine = b3 ? r2[1] : r2[0];
;         float other = b3 ? r2[0] : r2[1];
;         h = mine + __shfl_xor(other, 8);
;       }
;       h += __shfl_xor(h, 4);
;       h += __shfl_xor(h, 2);
;       h += __shfl_xor(h, 1);
	v_cvt_pk_f32_fp8_sdwa v[216:217], v164 src0_sel:WORD_1
	v_cvt_pk_f32_fp8_e32 v[218:219], v165
	v_cvt_pk_f32_fp8_sdwa v[220:221], v165 src0_sel:WORD_1
	v_pk_mul_f32 v[222:223], v[0:1], v[214:215]
	v_pk_mul_f32 v[224:225], v[2:3], v[216:217]
	v_cvt_pk_f32_fp8_e32 v[214:215], v166
	v_cvt_pk_f32_fp8_sdwa v[216:217], v166 src0_sel:WORD_1
	v_pk_fma_f32 v[222:223], v[4:5], v[218:219], v[222:223]
	v_pk_fma_f32 v[224:225], v[6:7], v[220:221], v[224:225]
	v_cvt_pk_f32_fp8_e32 v[218:219], v167
	v_cvt_pk_f32_fp8_sdwa v[220:221], v167 src0_sel:WORD_1
	v_pk_fma_f32 v[222:223], v[8:9], v[214:215], v[222:223]
	v_pk_fma_f32 v[224:225], v[10:11], v[216:217], v[224:225]
	v_pk_fma_f32 v[222:223], v[12:13], v[218:219], v[222:223]
	v_pk_fma_f32 v[224:225], v[14:15], v[220:221], v[224:225]
	v_pk_add_f32 v[222:223], v[222:223], v[224:225]
	s_nop 0
	v_add_f32_e32 v231, v222, v223
	v_cvt_pk_f32_fp8_e32 v[214:215], v168
	v_cvt_pk_f32_fp8_sdwa v[216:217], v168 src0_sel:WORD_1
	v_cvt_pk_f32_fp8_e32 v[218:219], v169
	v_cvt_pk_f32_fp8_sdwa v[220:221], v169 src0_sel:WORD_1
	v_pk_mul_f32 v[222:223], v[0:1], v[214:215]
	v_pk_mul_f32 v[224:225], v[2:3], v[216:217]
	v_cvt_pk_f32_fp8_e32 v[214:215], v170
	v_cvt_pk_f32_fp8_sdwa v[216:217], v170 src0_sel:WORD_1
	v_pk_fma_f32 v[222:223], v[4:5], v[218:219], v[222:223]
	v_pk_fma_f32 v[224:225], v[6:7], v[220:221], v[224:225]
	v_cvt_pk_f32_fp8_e32 v[218:219], v171
	v_cvt_pk_f32_fp8_sdwa v[220:221], v171 src0_sel:WORD_1
	v_pk_fma_f32 v[222:223], v[8:9], v[214:215], v[222:223]
	v_pk_fma_f32 v[224:225], v[10:11], v[216:217], v[224:225]
	v_pk_fma_f32 v[222:223], v[12:13], v[218:219], v[222:223]
	v_pk_fma_f32 v[224:225], v[14:15], v[220:221], v[224:225]
	v_pk_add_f32 v[222:223], v[222:223], v[224:225]
	s_nop 0
	v_add_f32_e32 v232, v222, v223
	v_cvt_pk_f32_fp8_e32 v[214:215], v172
	v_cvt_pk_f32_fp8_sdwa v[216:217], v172 src0_sel:WORD_1
	v_cvt_pk_f32_fp8_e32 v[218:219], v173
	v_cvt_pk_f32_fp8_sdwa v[220:221], v173 src0_sel:WORD_1
	v_pk_mul_f32 v[222:223], v[0:1], v[214:215]
	v_pk_mul_f32 v[224:225], v[2:3], v[216:217]
	v_cvt_pk_f32_fp8_e32 v[214:215], v174
	v_cvt_pk_f32_fp8_sdwa v[216:217], v174 src0_sel:WORD_1
	v_pk_fma_f32 v[222:223], v[4:5], v[218:219], v[222:223]
	v_pk_fma_f32 v[224:225], v[6:7], v[220:221], v[224:225]
	v_cvt_pk_f32_fp8_e32 v[218:219], v175
	v_cvt_pk_f32_fp8_sdwa v[220:221], v175 src0_sel:WORD_1
	v_pk_fma_f32 v[222:223], v[8:9], v[214:215], v[222:223]
	v_pk_fma_f32 v[224:225], v[10:11], v[216:217], v[224:225]
	v_pk_fma_f32 v[222:223], v[12:13], v[218:219], v[222:223]
	v_pk_fma_f32 v[224:225], v[14:15], v[220:221], v[224:225]
	v_pk_add_f32 v[222:223], v[222:223], v[224:225]
	s_nop 0
	v_add_f32_e32 v233, v222, v223
	v_permlane32_swap_b32_e32 v226, v230
	v_permlane32_swap_b32_e32 v227, v231
	v_permlane32_swap_b32_e32 v228, v232
	v_permlane32_swap_b32_e32 v229, v233
	v_add_f32_e32 v226, v226, v230
	v_add_f32_e32 v228, v228, v232
	v_add_f32_e32 v227, v227, v231
	v_add_f32_e32 v229, v229, v233
	s_nop 1
	v_permlane16_swap_b32_e32 v226, v228
	v_permlane16_swap_b32_e32 v227, v229
	v_add_f32_e32 v226, v226, v228
	v_add_f32_e32 v227, v227, v229
	s_nop 0
	v_cndmask_b32_e64 v230, v226, v227, s[24:25]
	v_cndmask_b32_e64 v231, v227, v226, s[24:25]
	s_nop 1
	v_add_f32_dpp v232, v231, v230 row_ror:8 row_mask:0xf bank_mask:0xf
	s_nop 1
	v_add_f32_dpp v233, v232, v232 quad_perm:[1,0,3,2] row_mask:0xf bank_mask:0xf
	s_nop 1
	v_add_f32_dpp v232, v233, v233 quad_perm:[2,3,0,1] row_mask:0xf bank_mask:0xf
	s_nop 1
	v_add_f32_dpp v233, v232, v232 row_half_mirror row_mask:0xf bank_mask:0xf
	ds_write_b32 v235, v233 offset:32768
	v_readlane_b32 s48, v132, s72
	v_readlane_b32 s49, v132, s73
	v_readlane_b32 s50, v132, s74
	v_readlane_b32 s51, v132, s75
	v_readlane_b32 s52, v132, s76
	v_readlane_b32 s53, v132, s77
	v_readlane_b32 s54, v132, s78
	v_readlane_b32 s55, v132, s79
	s_add_u32 s32, s0, s48
	s_addc_u32 s33, s1, 0
	s_add_u32 s34, s0, s49
	s_addc_u32 s35, s1, 0
	s_add_u32 s36, s0, s50
	s_addc_u32 s37, s1, 0
	s_add_u32 s38, s0, s51
	s_addc_u32 s39, s1, 0
	s_add_u32 s40, s0, s52
	s_addc_u32 s41, s1, 0
	s_add_u32 s42, s0, s53
	s_addc_u32 s43, s1, 0
	s_add_u32 s44, s0, s54
	s_addc_u32 s45, s1, 0
	s_add_u32 s46, s0, s55
	s_addc_u32 s47, s1, 0
	global_load_dwordx4 v[144:147], v234, s[32:33]
	global_load_dwordx4 v[148:151], v234, s[34:35]
	global_load_dwordx4 v[152:155], v234, s[36:37]
	global_load_dwordx4 v[156:159], v234, s[38:39]
	global_load_dwordx4 v[160:163], v234, s[40:41]
	global_load_dwordx4 v[164:167], v234, s[42:43]
	global_load_dwordx4 v[168:171], v234, s[44:45]
	global_load_dwordx4 v[172:175], v234, s[46:47]
	s_waitcnt vmcnt(8)
; template <bool STORE>
; DI void peer_item(const Params& p, int item, char* smem) {
;     ...
;       float part[8];
; #pragma unroll
;       for (int u = 0; u < 8; ++u) {
;         float d = 0.f;
; #pragma unroll
;         for (int i = 0; i < 4; ++i) {
;           f32x2_t lo = __builtin_amdgcn_cvt_pk_f32_fp8((int)uq[u][i], false);
;           f32x2_t hi = __builtin_amdgcn_cvt_pk_f32_fp8((int)uq[u][i], true);
;           d += xf[4 * i] * lo.x + xf[4 * i + 1] * lo.y + xf[4 * i + 2] * hi.x + xf[4 * i + 3] * hi.y;
;         }
;         part[u] = d;
;       }
	v_cvt_pk_f32_fp8_e32 v[214:215], v176
	v_cvt_pk_f32_fp8_sdwa v[216:217], v176 src0_sel:WORD_1
	v_cvt_pk_f32_fp8_e32 v[218:219], v177
	v_cvt_pk_f32_fp8_sdwa v[220:221], v177 src0_sel:WORD_1
	v_pk_mul_f32 v[222:223], v[16:17], v[214:215]
	v_pk_mul_f32 v[224:225], v[18:19], v[216:217]
	v_cvt_pk_f32_fp8_e32 v[214:215], v178
	v_cvt_pk_f32_fp8_sdwa v[216:217], v178 src0_sel:WORD_1
	v_pk_fma_f32 v[222:223], v[20:21], v[218:219], v[222:223]
	v_pk_fma_f32 v[224:225], v[22:23], v[220:221], v[224:225]
	v_cvt_pk_f32_fp8_e32 v[218:219], v179
	v_cvt_pk_f32_fp8_sdwa v[220:221], v179 src0_sel:WORD_1
	v_pk_fma_f32 v[222:223], v[24:25], v[214:215], v[222:223]
	v_pk_fma_f32 v[224:225], v[26:27], v[216:217], v[224:225]
	v_pk_fma_f32 v[222:223], v[28:29], v[218:219], v[222:223]
	v_pk_fma_f32 v[224:225], v[30:31], v[220:221], v[224:225]
	v_pk_add_f32 v[222:223], v[222:223], v[224:225]
	s_nop 0
	v_add_f32_e32 v226, v222, v223
	v_cvt_pk_f32_fp8_e32 v[214:215], v180
	v_cvt_pk_f32_fp8_sdwa v[216:217], v180 src0_sel:WORD_1
	v_cvt_pk_f32_fp8_e32 v[218:219], v181
	v_cvt_pk_f32_fp8_sdwa v[220:221], v181 src0_sel:WORD_1
	v_pk_mul_f32 v[222:223], v[16:17], v[214:215]
	v_pk_mul_f32 v[224:225], v[18:19], v[216:217]
	v_cvt_pk_f32_fp8_e32 v[214:215], v182
	v_cvt_pk_f32_fp8_sdwa v[216:217], v182 src0_sel:WORD_1
	v_pk_fma_f32 v[222:223], v[20:21], v[218:219], v[222:223]
	v_pk_fma_f32 v[224:225], v[22:23], v[220:221], v[224:225]
	v_cvt_pk_f32_fp8_e32 v[218:219], v183
	v_cvt_pk_f32_fp8_sdwa v[220:221], v183 src0_sel:WORD_1
	v_pk_fma_f32 v[222:223], v[24:25], v[214:215], v[222:223]
	v_pk_fma_f32 v[224:225], v[26:27], v[216:217], v[224:225]
	v_pk_fma_f32 v[222:223], v[28:29], v[218:219], v[222:223]
	v_pk_fma_f32 v[224:225], v[30:31], v[220:221], v[224:225]
	v_pk_add_f32 v[222:223], v[222:223], v[224:225]
	s_nop 0
	v_add_f32_e32 v227, v222, v223
	v_cvt_pk_f32_fp8_e32 v[214:215], v184
	v_cvt_pk_f32_fp8_sdwa v[216:217], v184 src0_sel:WORD_1
	v_cvt_pk_f32_fp8_e32 v[218:219], v185
	v_cvt_pk_f32_fp8_sdwa v[220:221], v185 src0_sel:WORD_1
	v_pk_mul_f32 v[222:223], v[16:17], v[214:215]
	v_pk_mul_f32 v[224:225], v[18:19], v[216:217]
	v_cvt_pk_f32_fp8_e32 v[214:215], v186
	v_cvt_pk_f32_fp8_sdwa v[216:217], v186 src0_sel:WORD_1
	v_pk_fma_f32 v[222:223], v[20:21], v[218:219], v[222:223]
	v_pk_fma_f32 v[224:225], v[22:23], v[220:221], v[224:225]
	v_cvt_pk_f32_fp8_e32 v[218:219], v187
	v_cvt_pk_f32_fp8_sdwa v[220:221], v187 src0_sel:WORD_1
	v_pk_fma_f32 v[222:223], v[24:25], v[214:215], v[222:223]
	v_pk_fma_f32 v[224:225], v[26:27], v[216:217], v[224:225]
	v_pk_fma_f32 v[222:223], v[28:29], v[218:219], v[222:223]
	v_pk_fma_f32 v[224:225], v[30:31], v[220:221], v[224:225]
	v_pk_add_f32 v[222:223], v[222:223], v[224:225]
	s_nop 0
	v_add_f32_e32 v228, v222, v223
	v_cvt_pk_f32_fp8_e32 v[214:215], v188
	v_cvt_pk_f32_fp8_sdwa v[216:217], v188 src0_sel:WORD_1
	v_cvt_pk_f32_fp8_e32 v[218:219], v189
	v_cvt_pk_f32_fp8_sdwa v[220:221], v189 src0_sel:WORD_1
	v_pk_mul_f32 v[222:223], v[16:17], v[214:215]
	v_pk_mul_f32 v[224:225], v[18:19], v[216:217]
	v_cvt_pk_f32_fp8_e32 v[214:215], v190
	v_cvt_pk_f32_fp8_sdwa v[216:217], v190 src0_sel:WORD_1
	v_pk_fma_f32 v[222:223], v[20:21], v[218:219], v[222:223]
	v_pk_fma_f32 v[224:225], v[22:23], v[220:221], v[224:225]
	v_cvt_pk_f32_fp8_e32 v[218:219], v191
	v_cvt_pk_f32_fp8_sdwa v[220:221], v191 src0_sel:WORD_1
	v_pk_fma_f32 v[222:223], v[24:25], v[214:215], v[222:223]
	v_pk_fma_f32 v[224:225], v[26:27], v[216:217], v[224:225]
	v_pk_fma_f32 v[222:223], v[28:29], v[218:219], v[222:223]
	v_pk_fma_f32 v[224:225], v[30:31], v[220:221], v[224:225]
	v_pk_add_f32 v[222:223], v[222:223], v[224:225]
	s_nop 0
	v_add_f32_e32 v229, v222, v223
	v_cvt_pk_f32_fp8_e32 v[214:215], v192
	v_cvt_pk_f32_fp8_sdwa v[216:217], v192 src0_sel:WORD_1
	v_cvt_pk_f32_fp8_e32 v[218:219], v193
	v_cvt_pk_f32_fp8_sdwa v[220:221], v193 src0_sel:WORD_1
	v_pk_mul_f32 v[222:223], v[16:17], v[214:215]
	v_pk_mul_f32 v[224:225], v[18:19], v[216:217]
	v_cvt_pk_f32_fp8_e32 v[214:215], v194
	v_cvt_pk_f32_fp8_sdwa v[216:217], v194 src0_sel:WORD_1
	v_pk_fma_f32 v[222:223], v[20:21], v[218:219], v[222:223]
	v_pk_fma_f32 v[224:225], v[22:23], v[220:221], v[224:225]
	v_cvt_pk_f32_fp8_e32 v[218:219], v195
	v_cvt_pk_f32_fp8_sdwa v[220:221], v195 src0_sel:WORD_1
	v_pk_fma_f32 v[222:223], v[24:25], v[214:215], v[222:223]
	v_pk_fma_f32 v[224:225], v[26:27], v[216:217], v[224:225]
	v_pk_fma_f32 v[222:223], v[28:29], v[218:219], v[222:223]
	v_pk_fma_f32 v[224:225], v[30:31], v[220:221], v[224:225]
	v_pk_add_f32 v[222:223], v[222:223], v[224:225]
	s_nop 0
	v_add_f32_e32 v230, v222, v223
	v_cvt_pk_f32_fp8_e32 v[214:215], v196
	v_cvt_pk_f32_fp8_sdwa v[216:217], v196 src0_sel:WORD_1
	v_cvt_pk_f32_fp8_e32 v[218:219], v197
	v_cvt_pk_f32_fp8_sdwa v[220:221], v197 src0_sel:WORD_1
	v_pk_mul_f32 v[222:223], v[16:17], v[214:215]
	v_pk_mul_f32 v[224:225], v[18:19], v[216:217]
	v_cvt_pk_f32_fp8_e32 v[214:215], v198
	v_cvt_pk_f32_fp8_sdwa v[216:217], v198 src0_sel:WORD_1
	v_pk_fma_f32 v[222:223], v[20:21], v[218:219], v[222:223]
	v_pk_fma_f32 v[224:225], v[22:23], v[220:221], v[224:225]
	v_cvt_pk_f32_fp8_e32 v[218:219], v199
	v_cvt_pk_f32_fp8_sdwa v[220:221], v199 src0_sel:WORD_1
	v_pk_fma_f32 v[222:223], v[24:25], v[214:215], v[222:223]
	v_pk_fma_f32 v[224:225], v[26:27], v[216:217], v[224:225]
	v_pk_fma_f32 v[222:223], v[28:29], v[218:219], v[222:223]
	v_pk_fma_f32 v[224:225], v[30:31], v[220:221], v[224:225]
	v_pk_add_f32 v[222:223], v[222:223], v[224:225]
	s_nop 0
	v_add_f32_e32 v231, v222, v223
	v_cvt_pk_f32_fp8_e32 v[214:215], v200
	v_cvt_pk_f32_fp8_sdwa v[216:217], v200 src0_sel:WORD_1
	v_cvt_pk_f32_fp8_e32 v[218:219], v201
; template <bool STORE>
; DI void peer_item(const Params& p, int item, char* smem) {
;     ...
;       float part[8];
; #pragma unroll
;       for (int u = 0; u < 8; ++u) {
;         float d = 0.f;
; #pragma unroll
;         for (int i = 0; i < 4; ++i) {
;           f32x2_t lo = __builtin_amdgcn_cvt_pk_f32_fp8((int)uq[u][i], false);
;           f32x2_t hi = __builtin_amdgcn_cvt_pk_f32_fp8((int)uq[u][i], true);
;           d += xf[4 * i] * lo.x + xf[4 * i + 1] * lo.y + xf[4 * i + 2] * hi.x + xf[4 * i + 3] * hi.y;
;         }
;         part[u] = d;
;       }
;       float q4[4], r2[2], h;
; #pragma unroll
;       for (int j = 0; j < 4; ++j) {
;         float mine = b5 ? part[j + 4] : part[j];
;         float other = b5 ? part[j] : part[j + 4];
;         q4[j] = mine + __shfl_xor(other, 32);
;       }
; #pragma unroll
;       for (int j = 0; j < 2; ++j) {
;         float mine = b4 ? q4[j + 2] : q4[j];
;         float other = b4 ? q4[j] : q4[j + 2];
;         r2[j] = mine + __shfl_xor(other, 16);
;       }
;       {
;         float mine = b3 ? r2[1] : r2[0];
;         float other = b3 ? r2[0] : r2[1];
;         h = mine + __shfl_xor(other, 8);
;       }
;       h += __shfl_xor(h, 4);
;       h += __shfl_xor(h, 2);
;       h += __shfl_xor(h, 1);
	v_cvt_pk_f32_fp8_sdwa v[220:221], v201 src0_sel:WORD_1
	v_pk_mul_f32 v[222:223], v[16:17], v[214:215]
	v_pk_mul_f32 v[224:225], v[18:19], v[216:217]
	v_cvt_pk_f32_fp8_e32 v[214:215], v202
	v_cvt_pk_f32_fp8_sdwa v[216:217], v202 src0_sel:WORD_1
	v_pk_fma_f32 v[222:223], v[20:21], v[218:219], v[222:223]
	v_pk_fma_f32 v[224:225], v[22:23], v[220:221], v[224:225]
	v_cvt_pk_f32_fp8_e32 v[218:219], v203
	v_cvt_pk_f32_fp8_sdwa v[220:221], v203 src0_sel:WORD_1
	v_pk_fma_f32 v[222:223], v[24:25], v[214:215], v[222:223]
	v_pk_fma_f32 v[224:225], v[26:27], v[216:217], v[224:225]
	v_pk_fma_f32 v[222:223], v[28:29], v[218:219], v[222:223]
	v_pk_fma_f32 v[224:225], v[30:31], v[220:221], v[224:225]
	v_pk_add_f32 v[222:223], v[222:223], v[224:225]
	s_nop 0
	v_add_f32_e32 v232, v222, v223
	v_cvt_pk_f32_fp8_e32 v[214:215], v204
	v_cvt_pk_f32_fp8_sdwa v[216:217], v204 src0_sel:WORD_1
	v_cvt_pk_f32_fp8_e32 v[218:219], v205
	v_cvt_pk_f32_fp8_sdwa v[220:221], v205 src0_sel:WORD_1
	v_pk_mul_f32 v[222:223], v[16:17], v[214:215]
	v_pk_mul_f32 v[224:225], v[18:19], v[216:217]
	v_cvt_pk_f32_fp8_e32 v[214:215], v206
	v_cvt_pk_f32_fp8_sdwa v[216:217], v206 src0_sel:WORD_1
	v_pk_fma_f32 v[222:223], v[20:21], v[218:219], v[222:223]
	v_pk_fma_f32 v[224:225], v[22:23], v[220:221], v[224:225]
	v_cvt_pk_f32_fp8_e32 v[218:219], v207
	v_cvt_pk_f32_fp8_sdwa v[220:221], v207 src0_sel:WORD_1
	v_pk_fma_f32 v[222:223], v[24:25], v[214:215], v[222:223]
	v_pk_fma_f32 v[224:225], v[26:27], v[216:217], v[224:225]
	v_pk_fma_f32 v[222:223], v[28:29], v[218:219], v[222:223]
	v_pk_fma_f32 v[224:225], v[30:31], v[220:221], v[224:225]
	v_pk_add_f32 v[222:223], v[222:223], v[224:225]
	s_nop 0
	v_add_f32_e32 v233, v222, v223
	v_permlane32_swap_b32_e32 v226, v230
	v_permlane32_swap_b32_e32 v227, v231
	v_permlane32_swap_b32_e32 v228, v232
	v_permlane32_swap_b32_e32 v229, v233
	v_add_f32_e32 v226, v226, v230
	v_add_f32_e32 v228, v228, v232
	v_add_f32_e32 v227, v227, v231
	v_add_f32_e32 v229, v229, v233
	s_nop 1
	v_permlane16_swap_b32_e32 v226, v228
	v_permlane16_swap_b32_e32 v227, v229
	v_add_f32_e32 v226, v226, v228
	v_add_f32_e32 v227, v227, v229
	s_nop 0
	v_cndmask_b32_e64 v230, v226, v227, s[24:25]
	v_cndmask_b32_e64 v231, v227, v226, s[24:25]
	s_nop 1
	v_add_f32_dpp v232, v231, v230 row_ror:8 row_mask:0xf bank_mask:0xf
	s_nop 1
	v_add_f32_dpp v233, v232, v232 quad_perm:[1,0,3,2] row_mask:0xf bank_mask:0xf
	s_nop 1
	v_add_f32_dpp v232, v233, v233 quad_perm:[2,3,0,1] row_mask:0xf bank_mask:0xf
	s_nop 1
	v_add_f32_dpp v233, v232, v232 row_half_mirror row_mask:0xf bank_mask:0xf
	ds_write_b32 v235, v233 offset:33280
	v_readlane_b32 s48, v134, s72
	v_readlane_b32 s49, v134, s73
	v_readlane_b32 s50, v134, s74
	v_readlane_b32 s51, v134, s75
	v_readlane_b32 s52, v134, s76
	v_readlane_b32 s53, v134, s77
	v_readlane_b32 s54, v134, s78
	v_readlane_b32 s55, v134, s79
	s_add_u32 s32, s0, s48
	s_addc_u32 s33, s1, 0
	s_add_u32 s34, s0, s49
	s_addc_u32 s35, s1, 0
	s_add_u32 s36, s0, s50
	s_addc_u32 s37, s1, 0
	s_add_u32 s38, s0, s51
	s_addc_u32 s39, s1, 0
	s_add_u32 s40, s0, s52
	s_addc_u32 s41, s1, 0
	s_add_u32 s42, s0, s53
	s_addc_u32 s43, s1, 0
	s_add_u32 s44, s0, s54
	s_addc_u32 s45, s1, 0
	s_add_u32 s46, s0, s55
	s_addc_u32 s47, s1, 0
	global_load_dwordx4 v[176:179], v234, s[32:33]
	global_load_dwordx4 v[180:183], v234, s[34:35]
	global_load_dwordx4 v[184:187], v234, s[36:37]
	global_load_dwordx4 v[188:191], v234, s[38:39]
	global_load_dwordx4 v[192:195], v234, s[40:41]
	global_load_dwordx4 v[196:199], v234, s[42:43]
	global_load_dwordx4 v[200:203], v234, s[44:45]
	global_load_dwordx4 v[204:207], v234, s[46:47]
	s_waitcnt vmcnt(8)
	v_cvt_pk_f32_fp8_e32 v[214:215], v144
	v_cvt_pk_f32_fp8_sdwa v[216:217], v144 src0_sel:WORD_1
	v_cvt_pk_f32_fp8_e32 v[218:219], v145
	v_cvt_pk_f32_fp8_sdwa v[220:221], v145 src0_sel:WORD_1
	v_pk_mul_f32 v[222:223], v[32:33], v[214:215]
	v_pk_mul_f32 v[224:225], v[34:35], v[216:217]
	v_cvt_pk_f32_fp8_e32 v[214:215], v146
	v_cvt_pk_f32_fp8_sdwa v[216:217], v146 src0_sel:WORD_1
	v_pk_fma_f32 v[222:223], v[36:37], v[218:219], v[222:223]
	v_pk_fma_f32 v[224:225], v[38:39], v[220:221], v[224:225]
	v_cvt_pk_f32_fp8_e32 v[218:219], v147
	v_cvt_pk_f32_fp8_sdwa v[220:221], v147 src0_sel:WORD_1
	v_pk_fma_f32 v[222:223], v[40:41], v[214:215], v[222:223]
	v_pk_fma_f32 v[224:225], v[42:43], v[216:217], v[224:225]
	v_pk_fma_f32 v[222:223], v[44:45], v[218:219], v[222:223]
	v_pk_fma_f32 v[224:225], v[46:47], v[220:221], v[224:225]
	v_pk_add_f32 v[222:223], v[222:223], v[224:225]
	s_nop 0
	v_add_f32_e32 v226, v222, v223
	v_cvt_pk_f32_fp8_e32 v[214:215], v148
	v_cvt_pk_f32_fp8_sdwa v[216:217], v148 src0_sel:WORD_1
	v_cvt_pk_f32_fp8_e32 v[218:219], v149
	v_cvt_pk_f32_fp8_sdwa v[220:221], v149 src0_sel:WORD_1
	v_pk_mul_f32 v[222:223], v[32:33], v[214:215]
	v_pk_mul_f32 v[224:225], v[34:35], v[216:217]
	v_cvt_pk_f32_fp8_e32 v[214:215], v150
	v_cvt_pk_f32_fp8_sdwa v[216:217], v150 src0_sel:WORD_1
	v_pk_fma_f32 v[222:223], v[36:37], v[218:219], v[222:223]
	v_pk_fma_f32 v[224:225], v[38:39], v[220:221], v[224:225]
	v_cvt_pk_f32_fp8_e32 v[218:219], v151
	v_cvt_pk_f32_fp8_sdwa v[220:221], v151 src0_sel:WORD_1
	v_pk_fma_f32 v[222:223], v[40:41], v[214:215], v[222:223]
	v_pk_fma_f32 v[224:225], v[42:43], v[216:217], v[224:225]
	v_pk_fma_f32 v[222:223], v[44:45], v[218:219], v[222:223]
	v_pk_fma_f32 v[224:225], v[46:47], v[220:221], v[224:225]
	v_pk_add_f32 v[222:223], v[222:223], v[224:225]
	s_nop 0
	v_add_f32_e32 v227, v222, v223
	v_cvt_pk_f32_fp8_e32 v[214:215], v152
	v_cvt_pk_f32_fp8_sdwa v[216:217], v152 src0_sel:WORD_1
	v_cvt_pk_f32_fp8_e32 v[218:219], v153
	v_cvt_pk_f32_fp8_sdwa v[220:221], v153 src0_sel:WORD_1
; template <bool STORE>
; DI void peer_item(const Params& p, int item, char* smem) {
;     ...
;       float part[8];
; #pragma unroll
;       for (int u = 0; u < 8; ++u) {
;         float d = 0.f;
; #pragma unroll
;         for (int i = 0; i < 4; ++i) {
;           f32x2_t lo = __builtin_amdgcn_cvt_pk_f32_fp8((int)uq[u][i], false);
;           f32x2_t hi = __builtin_amdgcn_cvt_pk_f32_fp8((int)uq[u][i], true);
;           d += xf[4 * i] * lo.x + xf[4 * i + 1] * lo.y + xf[4 * i + 2] * hi.x + xf[4 * i + 3] * hi.y;
;         }
;         part[u] = d;
;       }
;       float q4[4], r2[2], h;
; #pragma unroll
;       for (int j = 0; j < 4; ++j) {
;         float mine = b5 ? part[j + 4] : part[j];
;         float other = b5 ? part[j] : part[j + 4];
;         q4[j] = mine + __shfl_xor(other, 32);
;       }
; #pragma unroll
;       for (int j = 0; j < 2; ++j) {
;         float mine = b4 ? q4[j + 2] : q4[j];
;         float other = b4 ? q4[j] : q4[j + 2];
;         r2[j] = mine + __shfl_xor(other, 16);
;       }
;       {
;         float mine = b3 ? r2[1] : r2[0];
;         float other = b3 ? r2[0] : r2[1];
;         h = mine + __shfl_xor(other, 8);
;       }
;       h += __shfl_xor(h, 4);
;       h += __shfl_xor(h, 2);
;       h += __shfl_xor(h, 1);
	v_pk_mul_f32 v[222:223], v[32:33], v[214:215]
	v_pk_mul_f32 v[224:225], v[34:35], v[216:217]
	v_cvt_pk_f32_fp8_e32 v[214:215], v154
	v_cvt_pk_f32_fp8_sdwa v[216:217], v154 src0_sel:WORD_1
	v_pk_fma_f32 v[222:223], v[36:37], v[218:219], v[222:223]
	v_pk_fma_f32 v[224:225], v[38:39], v[220:221], v[224:225]
	v_cvt_pk_f32_fp8_e32 v[218:219], v155
	v_cvt_pk_f32_fp8_sdwa v[220:221], v155 src0_sel:WORD_1
	v_pk_fma_f32 v[222:223], v[40:41], v[214:215], v[222:223]
	v_pk_fma_f32 v[224:225], v[42:43], v[216:217], v[224:225]
	v_pk_fma_f32 v[222:223], v[44:45], v[218:219], v[222:223]
	v_pk_fma_f32 v[224:225], v[46:47], v[220:221], v[224:225]
	v_pk_add_f32 v[222:223], v[222:223], v[224:225]
	s_nop 0
	v_add_f32_e32 v228, v222, v223
	v_cvt_pk_f32_fp8_e32 v[214:215], v156
	v_cvt_pk_f32_fp8_sdwa v[216:217], v156 src0_sel:WORD_1
	v_cvt_pk_f32_fp8_e32 v[218:219], v157
	v_cvt_pk_f32_fp8_sdwa v[220:221], v157 src0_sel:WORD_1
	v_pk_mul_f32 v[222:223], v[32:33], v[214:215]
	v_pk_mul_f32 v[224:225], v[34:35], v[216:217]
	v_cvt_pk_f32_fp8_e32 v[214:215], v158
	v_cvt_pk_f32_fp8_sdwa v[216:217], v158 src0_sel:WORD_1
	v_pk_fma_f32 v[222:223], v[36:37], v[218:219], v[222:223]
	v_pk_fma_f32 v[224:225], v[38:39], v[220:221], v[224:225]
	v_cvt_pk_f32_fp8_e32 v[218:219], v159
	v_cvt_pk_f32_fp8_sdwa v[220:221], v159 src0_sel:WORD_1
	v_pk_fma_f32 v[222:223], v[40:41], v[214:215], v[222:223]
	v_pk_fma_f32 v[224:225], v[42:43], v[216:217], v[224:225]
	v_pk_fma_f32 v[222:223], v[44:45], v[218:219], v[222:223]
	v_pk_fma_f32 v[224:225], v[46:47], v[220:221], v[224:225]
	v_pk_add_f32 v[222:223], v[222:223], v[224:225]
	s_nop 0
	v_add_f32_e32 v229, v222, v223
	v_cvt_pk_f32_fp8_e32 v[214:215], v160
	v_cvt_pk_f32_fp8_sdwa v[216:217], v160 src0_sel:WORD_1
	v_cvt_pk_f32_fp8_e32 v[218:219], v161
	v_cvt_pk_f32_fp8_sdwa v[220:221], v161 src0_sel:WORD_1
	v_pk_mul_f32 v[222:223], v[32:33], v[214:215]
	v_pk_mul_f32 v[224:225], v[34:35], v[216:217]
	v_cvt_pk_f32_fp8_e32 v[214:215], v162
	v_cvt_pk_f32_fp8_sdwa v[216:217], v162 src0_sel:WORD_1
	v_pk_fma_f32 v[222:223], v[36:37], v[218:219], v[222:223]
	v_pk_fma_f32 v[224:225], v[38:39], v[220:221], v[224:225]
	v_cvt_pk_f32_fp8_e32 v[218:219], v163
	v_cvt_pk_f32_fp8_sdwa v[220:221], v163 src0_sel:WORD_1
	v_pk_fma_f32 v[222:223], v[40:41], v[214:215], v[222:223]
	v_pk_fma_f32 v[224:225], v[42:43], v[216:217], v[224:225]
	v_pk_fma_f32 v[222:223], v[44:45], v[218:219], v[222:223]
	v_pk_fma_f32 v[224:225], v[46:47], v[220:221], v[224:225]
	v_pk_add_f32 v[222:223], v[222:223], v[224:225]
	s_nop 0
	v_add_f32_e32 v230, v222, v223
	v_cvt_pk_f32_fp8_e32 v[214:215], v164
	v_cvt_pk_f32_fp8_sdwa v[216:217], v164 src0_sel:WORD_1
	v_cvt_pk_f32_fp8_e32 v[218:219], v165
	v_cvt_pk_f32_fp8_sdwa v[220:221], v165 src0_sel:WORD_1
	v_pk_mul_f32 v[222:223], v[32:33], v[214:215]
	v_pk_mul_f32 v[224:225], v[34:35], v[216:217]
	v_cvt_pk_f32_fp8_e32 v[214:215], v166
	v_cvt_pk_f32_fp8_sdwa v[216:217], v166 src0_sel:WORD_1
	v_pk_fma_f32 v[222:223], v[36:37], v[218:219], v[222:223]
	v_pk_fma_f32 v[224:225], v[38:39], v[220:221], v[224:225]
	v_cvt_pk_f32_fp8_e32 v[218:219], v167
	v_cvt_pk_f32_fp8_sdwa v[220:221], v167 src0_sel:WORD_1
	v_pk_fma_f32 v[222:223], v[40:41], v[214:215], v[222:223]
	v_pk_fma_f32 v[224:225], v[42:43], v[216:217], v[224:225]
	v_pk_fma_f32 v[222:223], v[44:45], v[218:219], v[222:223]
	v_pk_fma_f32 v[224:225], v[46:47], v[220:221], v[224:225]
	v_pk_add_f32 v[222:223], v[222:223], v[224:225]
	s_nop 0
	v_add_f32_e32 v231, v222, v223
	v_cvt_pk_f32_fp8_e32 v[214:215], v168
	v_cvt_pk_f32_fp8_sdwa v[216:217], v168 src0_sel:WORD_1
	v_cvt_pk_f32_fp8_e32 v[218:219], v169
	v_cvt_pk_f32_fp8_sdwa v[220:221], v169 src0_sel:WORD_1
	v_pk_mul_f32 v[222:223], v[32:33], v[214:215]
	v_pk_mul_f32 v[224:225], v[34:35], v[216:217]
	v_cvt_pk_f32_fp8_e32 v[214:215], v170
	v_cvt_pk_f32_fp8_sdwa v[216:217], v170 src0_sel:WORD_1
	v_pk_fma_f32 v[222:223], v[36:37], v[218:219], v[222:223]
	v_pk_fma_f32 v[224:225], v[38:39], v[220:221], v[224:225]
	v_cvt_pk_f32_fp8_e32 v[218:219], v171
	v_cvt_pk_f32_fp8_sdwa v[220:221], v171 src0_sel:WORD_1
	v_pk_fma_f32 v[222:223], v[40:41], v[214:215], v[222:223]
	v_pk_fma_f32 v[224:225], v[42:43], v[216:217], v[224:225]
	v_pk_fma_f32 v[222:223], v[44:45], v[218:219], v[222:223]
	v_pk_fma_f32 v[224:225], v[46:47], v[220:221], v[224:225]
	v_pk_add_f32 v[222:223], v[222:223], v[224:225]
	s_nop 0
	v_add_f32_e32 v232, v222, v223
	v_cvt_pk_f32_fp8_e32 v[214:215], v172
	v_cvt_pk_f32_fp8_sdwa v[216:217], v172 src0_sel:WORD_1
	v_cvt_pk_f32_fp8_e32 v[218:219], v173
	v_cvt_pk_f32_fp8_sdwa v[220:221], v173 src0_sel:WORD_1
	v_pk_mul_f32 v[222:223], v[32:33], v[214:215]
	v_pk_mul_f32 v[224:225], v[34:35], v[216:217]
	v_cvt_pk_f32_fp8_e32 v[214:215], v174
	v_cvt_pk_f32_fp8_sdwa v[216:217], v174 src0_sel:WORD_1
	v_pk_fma_f32 v[222:223], v[36:37], v[218:219], v[222:223]
	v_pk_fma_f32 v[224:225], v[38:39], v[220:221], v[224:225]
	v_cvt_pk_f32_fp8_e32 v[218:219], v175
	v_cvt_pk_f32_fp8_sdwa v[220:221], v175 src0_sel:WORD_1
	v_pk_fma_f32 v[222:223], v[40:41], v[214:215], v[222:223]
	v_pk_fma_f32 v[224:225], v[42:43], v[216:217], v[224:225]
	v_pk_fma_f32 v[222:223], v[44:45], v[218:219], v[222:223]
	v_pk_fma_f32 v[224:225], v[46:47], v[220:221], v[224:225]
	v_pk_add_f32 v[222:223], v[222:223], v[224:225]
	s_nop 0
	v_add_f32_e32 v233, v222, v223
	v_permlane32_swap_b32_e32 v226, v230
	v_permlane32_swap_b32_e32 v227, v231
	v_permlane32_swap_b32_e32 v228, v232
	v_permlane32_swap_b32_e32 v229, v233
	v_add_f32_e32 v226, v226, v230
	v_add_f32_e32 v228, v228, v232
	v_add_f32_e32 v227, v227, v231
	v_add_f32_e32 v229, v229, v233
	s_nop 1
	v_permlane16_swap_b32_e32 v226, v228
; template <bool STORE>
; DI void peer_item(const Params& p, int item, char* smem) {
;     ...
;       float q4[4], r2[2], h;
; #pragma unroll
;       for (int j = 0; j < 4; ++j) {
;         float mine = b5 ? part[j + 4] : part[j];
;         float other = b5 ? part[j] : part[j + 4];
;         q4[j] = mine + __shfl_xor(other, 32);
;       }
; #pragma unroll
;       for (int j = 0; j < 2; ++j) {
;         float mine = b4 ? q4[j + 2] : q4[j];
;         float other = b4 ? q4[j] : q4[j + 2];
;         r2[j] = mine + __shfl_xor(other, 16);
;       }
;       {
;         float mine = b3 ? r2[1] : r2[0];
;         float other = b3 ? r2[0] : r2[1];
;         h = mine + __shfl_xor(other, 8);
;       }
;       h += __shfl_xor(h, 4);
;       h += __shfl_xor(h, 2);
;       h += __shfl_xor(h, 1);
	v_permlane16_swap_b32_e32 v227, v229
	v_add_f32_e32 v226, v226, v228
	v_add_f32_e32 v227, v227, v229
	s_nop 0
	v_cndmask_b32_e64 v230, v226, v227, s[24:25]
	v_cndmask_b32_e64 v231, v227, v226, s[24:25]
	s_nop 1
	v_add_f32_dpp v232, v231, v230 row_ror:8 row_mask:0xf bank_mask:0xf
	s_nop 1
	v_add_f32_dpp v233, v232, v232 quad_perm:[1,0,3,2] row_mask:0xf bank_mask:0xf
	s_nop 1
	v_add_f32_dpp v232, v233, v233 quad_perm:[2,3,0,1] row_mask:0xf bank_mask:0xf
	s_nop 1
	v_add_f32_dpp v233, v232, v232 row_half_mirror row_mask:0xf bank_mask:0xf
	ds_write_b32 v235, v233 offset:33792
	v_readlane_b32 s48, v136, s72
	v_readlane_b32 s49, v136, s73
	v_readlane_b32 s50, v136, s74
	v_readlane_b32 s51, v136, s75
	v_readlane_b32 s52, v136, s76
	v_readlane_b32 s53, v136, s77
	v_readlane_b32 s54, v136, s78
	v_readlane_b32 s55, v136, s79
	s_add_u32 s32, s0, s48
	s_addc_u32 s33, s1, 0
	s_add_u32 s34, s0, s49
	s_addc_u32 s35, s1, 0
	s_add_u32 s36, s0, s50
	s_addc_u32 s37, s1, 0
	s_add_u32 s38, s0, s51
	s_addc_u32 s39, s1, 0
	s_add_u32 s40, s0, s52
	s_addc_u32 s41, s1, 0
	s_add_u32 s42, s0, s53
	s_addc_u32 s43, s1, 0
	s_add_u32 s44, s0, s54
	s_addc_u32 s45, s1, 0
	s_add_u32 s46, s0, s55
	s_addc_u32 s47, s1, 0
	global_load_dwordx4 v[144:147], v234, s[32:33]
	global_load_dwordx4 v[148:151], v234, s[34:35]
	global_load_dwordx4 v[152:155], v234, s[36:37]
	global_load_dwordx4 v[156:159], v234, s[38:39]
	global_load_dwordx4 v[160:163], v234, s[40:41]
	global_load_dwordx4 v[164:167], v234, s[42:43]
	global_load_dwordx4 v[168:171], v234, s[44:45]
	global_load_dwordx4 v[172:175], v234, s[46:47]
	s_waitcnt vmcnt(8)
	v_cvt_pk_f32_fp8_e32 v[214:215], v176
	v_cvt_pk_f32_fp8_sdwa v[216:217], v176 src0_sel:WORD_1
	v_cvt_pk_f32_fp8_e32 v[218:219], v177
	v_cvt_pk_f32_fp8_sdwa v[220:221], v177 src0_sel:WORD_1
	v_pk_mul_f32 v[222:223], v[48:49], v[214:215]
	v_pk_mul_f32 v[224:225], v[50:51], v[216:217]
	v_cvt_pk_f32_fp8_e32 v[214:215], v178
	v_cvt_pk_f32_fp8_sdwa v[216:217], v178 src0_sel:WORD_1
	v_pk_fma_f32 v[222:223], v[52:53], v[218:219], v[222:223]
	v_pk_fma_f32 v[224:225], v[54:55], v[220:221], v[224:225]
	v_cvt_pk_f32_fp8_e32 v[218:219], v179
	v_cvt_pk_f32_fp8_sdwa v[220:221], v179 src0_sel:WORD_1
	v_pk_fma_f32 v[222:223], v[56:57], v[214:215], v[222:223]
	v_pk_fma_f32 v[224:225], v[58:59], v[216:217], v[224:225]
	v_pk_fma_f32 v[222:223], v[60:61], v[218:219], v[222:223]
	v_pk_fma_f32 v[224:225], v[62:63], v[220:221], v[224:225]
	v_pk_add_f32 v[222:223], v[222:223], v[224:225]
	s_nop 0
	v_add_f32_e32 v226, v222, v223
	v_cvt_pk_f32_fp8_e32 v[214:215], v180
	v_cvt_pk_f32_fp8_sdwa v[216:217], v180 src0_sel:WORD_1
	v_cvt_pk_f32_fp8_e32 v[218:219], v181
	v_cvt_pk_f32_fp8_sdwa v[220:221], v181 src0_sel:WORD_1
	v_pk_mul_f32 v[222:223], v[48:49], v[214:215]
	v_pk_mul_f32 v[224:225], v[50:51], v[216:217]
	v_cvt_pk_f32_fp8_e32 v[214:215], v182
	v_cvt_pk_f32_fp8_sdwa v[216:217], v182 src0_sel:WORD_1
	v_pk_fma_f32 v[222:223], v[52:53], v[218:219], v[222:223]
	v_pk_fma_f32 v[224:225], v[54:55], v[220:221], v[224:225]
	v_cvt_pk_f32_fp8_e32 v[218:219], v183
	v_cvt_pk_f32_fp8_sdwa v[220:221], v183 src0_sel:WORD_1
	v_pk_fma_f32 v[222:223], v[56:57], v[214:215], v[222:223]
	v_pk_fma_f32 v[224:225], v[58:59], v[216:217], v[224:225]
	v_pk_fma_f32 v[222:223], v[60:61], v[218:219], v[222:223]
	v_pk_fma_f32 v[224:225], v[62:63], v[220:221], v[224:225]
	v_pk_add_f32 v[222:223], v[222:223], v[224:225]
	s_nop 0
	v_add_f32_e32 v227, v222, v223
	v_cvt_pk_f32_fp8_e32 v[214:215], v184
	v_cvt_pk_f32_fp8_sdwa v[216:217], v184 src0_sel:WORD_1
	v_cvt_pk_f32_fp8_e32 v[218:219], v185
	v_cvt_pk_f32_fp8_sdwa v[220:221], v185 src0_sel:WORD_1
	v_pk_mul_f32 v[222:223], v[48:49], v[214:215]
	v_pk_mul_f32 v[224:225], v[50:51], v[216:217]
	v_cvt_pk_f32_fp8_e32 v[214:215], v186
	v_cvt_pk_f32_fp8_sdwa v[216:217], v186 src0_sel:WORD_1
	v_pk_fma_f32 v[222:223], v[52:53], v[218:219], v[222:223]
	v_pk_fma_f32 v[224:225], v[54:55], v[220:221], v[224:225]
	v_cvt_pk_f32_fp8_e32 v[218:219], v187
	v_cvt_pk_f32_fp8_sdwa v[220:221], v187 src0_sel:WORD_1
	v_pk_fma_f32 v[222:223], v[56:57], v[214:215], v[222:223]
	v_pk_fma_f32 v[224:225], v[58:59], v[216:217], v[224:225]
	v_pk_fma_f32 v[222:223], v[60:61], v[218:219], v[222:223]
	v_pk_fma_f32 v[224:225], v[62:63], v[220:221], v[224:225]
	v_pk_add_f32 v[222:223], v[222:223], v[224:225]
	s_nop 0
	v_add_f32_e32 v228, v222, v223
	v_cvt_pk_f32_fp8_e32 v[214:215], v188
	v_cvt_pk_f32_fp8_sdwa v[216:217], v188 src0_sel:WORD_1
	v_cvt_pk_f32_fp8_e32 v[218:219], v189
	v_cvt_pk_f32_fp8_sdwa v[220:221], v189 src0_sel:WORD_1
	v_pk_mul_f32 v[222:223], v[48:49], v[214:215]
	v_pk_mul_f32 v[224:225], v[50:51], v[216:217]
	v_cvt_pk_f32_fp8_e32 v[214:215], v190
	v_cvt_pk_f32_fp8_sdwa v[216:217], v190 src0_sel:WORD_1
	v_pk_fma_f32 v[222:223], v[52:53], v[218:219], v[222:223]
	v_pk_fma_f32 v[224:225], v[54:55], v[220:221], v[224:225]
	v_cvt_pk_f32_fp8_e32 v[218:219], v191
	v_cvt_pk_f32_fp8_sdwa v[220:221], v191 src0_sel:WORD_1
	v_pk_fma_f32 v[222:223], v[56:57], v[214:215], v[222:223]
	v_pk_fma_f32 v[224:225], v[58:59], v[216:217], v[224:225]
	v_pk_fma_f32 v[222:223], v[60:61], v[218:219], v[222:223]
	v_pk_fma_f32 v[224:225], v[62:63], v[220:221], v[224:225]
	v_pk_add_f32 v[222:223], v[222:223], v[224:225]
	s_nop 0
	v_add_f32_e32 v229, v222, v223
	v_cvt_pk_f32_fp8_e32 v[214:215], v192
	v_cvt_pk_f32_fp8_sdwa v[216:217], v192 src0_sel:WORD_1
	v_cvt_pk_f32_fp8_e32 v[218:219], v193
	v_cvt_pk_f32_fp8_sdwa v[220:221], v193 src0_sel:WORD_1
	v_pk_mul_f32 v[222:223], v[48:49], v[214:215]
	v_pk_mul_f32 v[224:225], v[50:51], v[216:217]
	v_cvt_pk_f32_fp8_e32 v[214:215], v194
	v_cvt_pk_f32_fp8_sdwa v[216:217], v194 src0_sel:WORD_1
; template <bool STORE>
; DI void peer_item(const Params& p, int item, char* smem) {
;     ...
;       float part[8];
; #pragma unroll
;       for (int u = 0; u < 8; ++u) {
;         float d = 0.f;
; #pragma unroll
;         for (int i = 0; i < 4; ++i) {
;           f32x2_t lo = __builtin_amdgcn_cvt_pk_f32_fp8((int)uq[u][i], false);
;           f32x2_t hi = __builtin_amdgcn_cvt_pk_f32_fp8((int)uq[u][i], true);
;           d += xf[4 * i] * lo.x + xf[4 * i + 1] * lo.y + xf[4 * i + 2] * hi.x + xf[4 * i + 3] * hi.y;
;         }
;         part[u] = d;
;       }
;       float q4[4], r2[2], h;
; #pragma unroll
;       for (int j = 0; j < 4; ++j) {
;         float mine = b5 ? part[j + 4] : part[j];
;         float other = b5 ? part[j] : part[j + 4];
;         q4[j] = mine + __shfl_xor(other, 32);
;       }
; #pragma unroll
;       for (int j = 0; j < 2; ++j) {
;         float mine = b4 ? q4[j + 2] : q4[j];
;         float other = b4 ? q4[j] : q4[j + 2];
;         r2[j] = mine + __shfl_xor(other, 16);
;       }
;       {
;         float mine = b3 ? r2[1] : r2[0];
;         float other = b3 ? r2[0] : r2[1];
;         h = mine + __shfl_xor(other, 8);
;       }
;       h += __shfl_xor(h, 4);
;       h += __shfl_xor(h, 2);
;       h += __shfl_xor(h, 1);
	v_pk_fma_f32 v[222:223], v[52:53], v[218:219], v[222:223]
	v_pk_fma_f32 v[224:225], v[54:55], v[220:221], v[224:225]
	v_cvt_pk_f32_fp8_e32 v[218:219], v195
	v_cvt_pk_f32_fp8_sdwa v[220:221], v195 src0_sel:WORD_1
	v_pk_fma_f32 v[222:223], v[56:57], v[214:215], v[222:223]
	v_pk_fma_f32 v[224:225], v[58:59], v[216:217], v[224:225]
	v_pk_fma_f32 v[222:223], v[60:61], v[218:219], v[222:223]
	v_pk_fma_f32 v[224:225], v[62:63], v[220:221], v[224:225]
	v_pk_add_f32 v[222:223], v[222:223], v[224:225]
	s_nop 0
	v_add_f32_e32 v230, v222, v223
	v_cvt_pk_f32_fp8_e32 v[214:215], v196
	v_cvt_pk_f32_fp8_sdwa v[216:217], v196 src0_sel:WORD_1
	v_cvt_pk_f32_fp8_e32 v[218:219], v197
	v_cvt_pk_f32_fp8_sdwa v[220:221], v197 src0_sel:WORD_1
	v_pk_mul_f32 v[222:223], v[48:49], v[214:215]
	v_pk_mul_f32 v[224:225], v[50:51], v[216:217]
	v_cvt_pk_f32_fp8_e32 v[214:215], v198
	v_cvt_pk_f32_fp8_sdwa v[216:217], v198 src0_sel:WORD_1
	v_pk_fma_f32 v[222:223], v[52:53], v[218:219], v[222:223]
	v_pk_fma_f32 v[224:225], v[54:55], v[220:221], v[224:225]
	v_cvt_pk_f32_fp8_e32 v[218:219], v199
	v_cvt_pk_f32_fp8_sdwa v[220:221], v199 src0_sel:WORD_1
	v_pk_fma_f32 v[222:223], v[56:57], v[214:215], v[222:223]
	v_pk_fma_f32 v[224:225], v[58:59], v[216:217], v[224:225]
	v_pk_fma_f32 v[222:223], v[60:61], v[218:219], v[222:223]
	v_pk_fma_f32 v[224:225], v[62:63], v[220:221], v[224:225]
	v_pk_add_f32 v[222:223], v[222:223], v[224:225]
	s_nop 0
	v_add_f32_e32 v231, v222, v223
	v_cvt_pk_f32_fp8_e32 v[214:215], v200
	v_cvt_pk_f32_fp8_sdwa v[216:217], v200 src0_sel:WORD_1
	v_cvt_pk_f32_fp8_e32 v[218:219], v201
	v_cvt_pk_f32_fp8_sdwa v[220:221], v201 src0_sel:WORD_1
	v_pk_mul_f32 v[222:223], v[48:49], v[214:215]
	v_pk_mul_f32 v[224:225], v[50:51], v[216:217]
	v_cvt_pk_f32_fp8_e32 v[214:215], v202
	v_cvt_pk_f32_fp8_sdwa v[216:217], v202 src0_sel:WORD_1
	v_pk_fma_f32 v[222:223], v[52:53], v[218:219], v[222:223]
	v_pk_fma_f32 v[224:225], v[54:55], v[220:221], v[224:225]
	v_cvt_pk_f32_fp8_e32 v[218:219], v203
	v_cvt_pk_f32_fp8_sdwa v[220:221], v203 src0_sel:WORD_1
	v_pk_fma_f32 v[222:223], v[56:57], v[214:215], v[222:223]
	v_pk_fma_f32 v[224:225], v[58:59], v[216:217], v[224:225]
	v_pk_fma_f32 v[222:223], v[60:61], v[218:219], v[222:223]
	v_pk_fma_f32 v[224:225], v[62:63], v[220:221], v[224:225]
	v_pk_add_f32 v[222:223], v[222:223], v[224:225]
	s_nop 0
	v_add_f32_e32 v232, v222, v223
	v_cvt_pk_f32_fp8_e32 v[214:215], v204
	v_cvt_pk_f32_fp8_sdwa v[216:217], v204 src0_sel:WORD_1
	v_cvt_pk_f32_fp8_e32 v[218:219], v205
	v_cvt_pk_f32_fp8_sdwa v[220:221], v205 src0_sel:WORD_1
	v_pk_mul_f32 v[222:223], v[48:49], v[214:215]
	v_pk_mul_f32 v[224:225], v[50:51], v[216:217]
	v_cvt_pk_f32_fp8_e32 v[214:215], v206
	v_cvt_pk_f32_fp8_sdwa v[216:217], v206 src0_sel:WORD_1
	v_pk_fma_f32 v[222:223], v[52:53], v[218:219], v[222:223]
	v_pk_fma_f32 v[224:225], v[54:55], v[220:221], v[224:225]
	v_cvt_pk_f32_fp8_e32 v[218:219], v207
	v_cvt_pk_f32_fp8_sdwa v[220:221], v207 src0_sel:WORD_1
	v_pk_fma_f32 v[222:223], v[56:57], v[214:215], v[222:223]
	v_pk_fma_f32 v[224:225], v[58:59], v[216:217], v[224:225]
	v_pk_fma_f32 v[222:223], v[60:61], v[218:219], v[222:223]
	v_pk_fma_f32 v[224:225], v[62:63], v[220:221], v[224:225]
	v_pk_add_f32 v[222:223], v[222:223], v[224:225]
	s_nop 0
	v_add_f32_e32 v233, v222, v223
	v_permlane32_swap_b32_e32 v226, v230
	v_permlane32_swap_b32_e32 v227, v231
	v_permlane32_swap_b32_e32 v228, v232
	v_permlane32_swap_b32_e32 v229, v233
	v_add_f32_e32 v226, v226, v230
	v_add_f32_e32 v228, v228, v232
	v_add_f32_e32 v227, v227, v231
	v_add_f32_e32 v229, v229, v233
	s_nop 1
	v_permlane16_swap_b32_e32 v226, v228
	v_permlane16_swap_b32_e32 v227, v229
	v_add_f32_e32 v226, v226, v228
	v_add_f32_e32 v227, v227, v229
	s_nop 0
	v_cndmask_b32_e64 v230, v226, v227, s[24:25]
	v_cndmask_b32_e64 v231, v227, v226, s[24:25]
	s_nop 1
	v_add_f32_dpp v232, v231, v230 row_ror:8 row_mask:0xf bank_mask:0xf
	s_nop 1
	v_add_f32_dpp v233, v232, v232 quad_perm:[1,0,3,2] row_mask:0xf bank_mask:0xf
	s_nop 1
	v_add_f32_dpp v232, v233, v233 quad_perm:[2,3,0,1] row_mask:0xf bank_mask:0xf
	s_nop 1
	v_add_f32_dpp v233, v232, v232 row_half_mirror row_mask:0xf bank_mask:0xf
	ds_write_b32 v235, v233 offset:34304
	v_readlane_b32 s48, v138, s72
	v_readlane_b32 s49, v138, s73
	v_readlane_b32 s50, v138, s74
	v_readlane_b32 s51, v138, s75
	v_readlane_b32 s52, v138, s76
	v_readlane_b32 s53, v138, s77
	v_readlane_b32 s54, v138, s78
	v_readlane_b32 s55, v138, s79
	s_add_u32 s32, s0, s48
	s_addc_u32 s33, s1, 0
	s_add_u32 s34, s0, s49
	s_addc_u32 s35, s1, 0
	s_add_u32 s36, s0, s50
	s_addc_u32 s37, s1, 0
	s_add_u32 s38, s0, s51
	s_addc_u32 s39, s1, 0
	s_add_u32 s40, s0, s52
	s_addc_u32 s41, s1, 0
	s_add_u32 s42, s0, s53
	s_addc_u32 s43, s1, 0
	s_add_u32 s44, s0, s54
	s_addc_u32 s45, s1, 0
	s_add_u32 s46, s0, s55
	s_addc_u32 s47, s1, 0
	global_load_dwordx4 v[176:179], v234, s[32:33]
	global_load_dwordx4 v[180:183], v234, s[34:35]
	global_load_dwordx4 v[184:187], v234, s[36:37]
	global_load_dwordx4 v[188:191], v234, s[38:39]
	global_load_dwordx4 v[192:195], v234, s[40:41]
	global_load_dwordx4 v[196:199], v234, s[42:43]
	global_load_dwordx4 v[200:203], v234, s[44:45]
	global_load_dwordx4 v[204:207], v234, s[46:47]
	s_waitcnt vmcnt(8)
; template <bool STORE>
; DI void peer_item(const Params& p, int item, char* smem) {
;     ...
;       float part[8];
; #pragma unroll
;       for (int u = 0; u < 8; ++u) {
;         float d = 0.f;
; #pragma unroll
;         for (int i = 0; i < 4; ++i) {
;           f32x2_t lo = __builtin_amdgcn_cvt_pk_f32_fp8((int)uq[u][i], false);
;           f32x2_t hi = __builtin_amdgcn_cvt_pk_f32_fp8((int)uq[u][i], true);
;           d += xf[4 * i] * lo.x + xf[4 * i + 1] * lo.y + xf[4 * i + 2] * hi.x + xf[4 * i + 3] * hi.y;
;         }
;         part[u] = d;
;       }
	v_cvt_pk_f32_fp8_e32 v[214:215], v144
	v_cvt_pk_f32_fp8_sdwa v[216:217], v144 src0_sel:WORD_1
	v_cvt_pk_f32_fp8_e32 v[218:219], v145
	v_cvt_pk_f32_fp8_sdwa v[220:221], v145 src0_sel:WORD_1
	v_pk_mul_f32 v[222:223], v[64:65], v[214:215]
	v_pk_mul_f32 v[224:225], v[66:67], v[216:217]
	v_cvt_pk_f32_fp8_e32 v[214:215], v146
	v_cvt_pk_f32_fp8_sdwa v[216:217], v146 src0_sel:WORD_1
	v_pk_fma_f32 v[222:223], v[68:69], v[218:219], v[222:223]
	v_pk_fma_f32 v[224:225], v[70:71], v[220:221], v[224:225]
	v_cvt_pk_f32_fp8_e32 v[218:219], v147
	v_cvt_pk_f32_fp8_sdwa v[220:221], v147 src0_sel:WORD_1
	v_pk_fma_f32 v[222:223], v[72:73], v[214:215], v[222:223]
	v_pk_fma_f32 v[224:225], v[74:75], v[216:217], v[224:225]
	v_pk_fma_f32 v[222:223], v[76:77], v[218:219], v[222:223]
	v_pk_fma_f32 v[224:225], v[78:79], v[220:221], v[224:225]
	v_pk_add_f32 v[222:223], v[222:223], v[224:225]
	s_nop 0
	v_add_f32_e32 v226, v222, v223
	v_cvt_pk_f32_fp8_e32 v[214:215], v148
	v_cvt_pk_f32_fp8_sdwa v[216:217], v148 src0_sel:WORD_1
	v_cvt_pk_f32_fp8_e32 v[218:219], v149
	v_cvt_pk_f32_fp8_sdwa v[220:221], v149 src0_sel:WORD_1
	v_pk_mul_f32 v[222:223], v[64:65], v[214:215]
	v_pk_mul_f32 v[224:225], v[66:67], v[216:217]
	v_cvt_pk_f32_fp8_e32 v[214:215], v150
	v_cvt_pk_f32_fp8_sdwa v[216:217], v150 src0_sel:WORD_1
	v_pk_fma_f32 v[222:223], v[68:69], v[218:219], v[222:223]
	v_pk_fma_f32 v[224:225], v[70:71], v[220:221], v[224:225]
	v_cvt_pk_f32_fp8_e32 v[218:219], v151
	v_cvt_pk_f32_fp8_sdwa v[220:221], v151 src0_sel:WORD_1
	v_pk_fma_f32 v[222:223], v[72:73], v[214:215], v[222:223]
	v_pk_fma_f32 v[224:225], v[74:75], v[216:217], v[224:225]
	v_pk_fma_f32 v[222:223], v[76:77], v[218:219], v[222:223]
	v_pk_fma_f32 v[224:225], v[78:79], v[220:221], v[224:225]
	v_pk_add_f32 v[222:223], v[222:223], v[224:225]
	s_nop 0
	v_add_f32_e32 v227, v222, v223
	v_cvt_pk_f32_fp8_e32 v[214:215], v152
	v_cvt_pk_f32_fp8_sdwa v[216:217], v152 src0_sel:WORD_1
	v_cvt_pk_f32_fp8_e32 v[218:219], v153
	v_cvt_pk_f32_fp8_sdwa v[220:221], v153 src0_sel:WORD_1
	v_pk_mul_f32 v[222:223], v[64:65], v[214:215]
	v_pk_mul_f32 v[224:225], v[66:67], v[216:217]
	v_cvt_pk_f32_fp8_e32 v[214:215], v154
	v_cvt_pk_f32_fp8_sdwa v[216:217], v154 src0_sel:WORD_1
	v_pk_fma_f32 v[222:223], v[68:69], v[218:219], v[222:223]
	v_pk_fma_f32 v[224:225], v[70:71], v[220:221], v[224:225]
	v_cvt_pk_f32_fp8_e32 v[218:219], v155
	v_cvt_pk_f32_fp8_sdwa v[220:221], v155 src0_sel:WORD_1
	v_pk_fma_f32 v[222:223], v[72:73], v[214:215], v[222:223]
	v_pk_fma_f32 v[224:225], v[74:75], v[216:217], v[224:225]
	v_pk_fma_f32 v[222:223], v[76:77], v[218:219], v[222:223]
	v_pk_fma_f32 v[224:225], v[78:79], v[220:221], v[224:225]
	v_pk_add_f32 v[222:223], v[222:223], v[224:225]
	s_nop 0
	v_add_f32_e32 v228, v222, v223
	v_cvt_pk_f32_fp8_e32 v[214:215], v156
	v_cvt_pk_f32_fp8_sdwa v[216:217], v156 src0_sel:WORD_1
	v_cvt_pk_f32_fp8_e32 v[218:219], v157
	v_cvt_pk_f32_fp8_sdwa v[220:221], v157 src0_sel:WORD_1
	v_pk_mul_f32 v[222:223], v[64:65], v[214:215]
	v_pk_mul_f32 v[224:225], v[66:67], v[216:217]
	v_cvt_pk_f32_fp8_e32 v[214:215], v158
	v_cvt_pk_f32_fp8_sdwa v[216:217], v158 src0_sel:WORD_1
	v_pk_fma_f32 v[222:223], v[68:69], v[218:219], v[222:223]
	v_pk_fma_f32 v[224:225], v[70:71], v[220:221], v[224:225]
	v_cvt_pk_f32_fp8_e32 v[218:219], v159
	v_cvt_pk_f32_fp8_sdwa v[220:221], v159 src0_sel:WORD_1
	v_pk_fma_f32 v[222:223], v[72:73], v[214:215], v[222:223]
	v_pk_fma_f32 v[224:225], v[74:75], v[216:217], v[224:225]
	v_pk_fma_f32 v[222:223], v[76:77], v[218:219], v[222:223]
	v_pk_fma_f32 v[224:225], v[78:79], v[220:221], v[224:225]
	v_pk_add_f32 v[222:223], v[222:223], v[224:225]
	s_nop 0
	v_add_f32_e32 v229, v222, v223
	v_cvt_pk_f32_fp8_e32 v[214:215], v160
	v_cvt_pk_f32_fp8_sdwa v[216:217], v160 src0_sel:WORD_1
	v_cvt_pk_f32_fp8_e32 v[218:219], v161
	v_cvt_pk_f32_fp8_sdwa v[220:221], v161 src0_sel:WORD_1
	v_pk_mul_f32 v[222:223], v[64:65], v[214:215]
	v_pk_mul_f32 v[224:225], v[66:67], v[216:217]
	v_cvt_pk_f32_fp8_e32 v[214:215], v162
	v_cvt_pk_f32_fp8_sdwa v[216:217], v162 src0_sel:WORD_1
	v_pk_fma_f32 v[222:223], v[68:69], v[218:219], v[222:223]
	v_pk_fma_f32 v[224:225], v[70:71], v[220:221], v[224:225]
	v_cvt_pk_f32_fp8_e32 v[218:219], v163
	v_cvt_pk_f32_fp8_sdwa v[220:221], v163 src0_sel:WORD_1
	v_pk_fma_f32 v[222:223], v[72:73], v[214:215], v[222:223]
	v_pk_fma_f32 v[224:225], v[74:75], v[216:217], v[224:225]
	v_pk_fma_f32 v[222:223], v[76:77], v[218:219], v[222:223]
	v_pk_fma_f32 v[224:225], v[78:79], v[220:221], v[224:225]
	v_pk_add_f32 v[222:223], v[222:223], v[224:225]
	s_nop 0
	v_add_f32_e32 v230, v222, v223
	v_cvt_pk_f32_fp8_e32 v[214:215], v164
	v_cvt_pk_f32_fp8_sdwa v[216:217], v164 src0_sel:WORD_1
	v_cvt_pk_f32_fp8_e32 v[218:219], v165
	v_cvt_pk_f32_fp8_sdwa v[220:221], v165 src0_sel:WORD_1
	v_pk_mul_f32 v[222:223], v[64:65], v[214:215]
	v_pk_mul_f32 v[224:225], v[66:67], v[216:217]
	v_cvt_pk_f32_fp8_e32 v[214:215], v166
	v_cvt_pk_f32_fp8_sdwa v[216:217], v166 src0_sel:WORD_1
	v_pk_fma_f32 v[222:223], v[68:69], v[218:219], v[222:223]
	v_pk_fma_f32 v[224:225], v[70:71], v[220:221], v[224:225]
	v_cvt_pk_f32_fp8_e32 v[218:219], v167
	v_cvt_pk_f32_fp8_sdwa v[220:221], v167 src0_sel:WORD_1
	v_pk_fma_f32 v[222:223], v[72:73], v[214:215], v[222:223]
	v_pk_fma_f32 v[224:225], v[74:75], v[216:217], v[224:225]
	v_pk_fma_f32 v[222:223], v[76:77], v[218:219], v[222:223]
	v_pk_fma_f32 v[224:225], v[78:79], v[220:221], v[224:225]
	v_pk_add_f32 v[222:223], v[222:223], v[224:225]
	s_nop 0
	v_add_f32_e32 v231, v222, v223
	v_cvt_pk_f32_fp8_e32 v[214:215], v168
	v_cvt_pk_f32_fp8_sdwa v[216:217], v168 src0_sel:WORD_1
	v_cvt_pk_f32_fp8_e32 v[218:219], v169
; template <bool STORE>
; DI void peer_item(const Params& p, int item, char* smem) {
;     ...
;       float part[8];
; #pragma unroll
;       for (int u = 0; u < 8; ++u) {
;         float d = 0.f;
; #pragma unroll
;         for (int i = 0; i < 4; ++i) {
;           f32x2_t lo = __builtin_amdgcn_cvt_pk_f32_fp8((int)uq[u][i], false);
;           f32x2_t hi = __builtin_amdgcn_cvt_pk_f32_fp8((int)uq[u][i], true);
;           d += xf[4 * i] * lo.x + xf[4 * i + 1] * lo.y + xf[4 * i + 2] * hi.x + xf[4 * i + 3] * hi.y;
;         }
;         part[u] = d;
;       }
;       float q4[4], r2[2], h;
; #pragma unroll
;       for (int j = 0; j < 4; ++j) {
;         float mine = b5 ? part[j + 4] : part[j];
;         float other = b5 ? part[j] : part[j + 4];
;         q4[j] = mine + __shfl_xor(other, 32);
;       }
; #pragma unroll
;       for (int j = 0; j < 2; ++j) {
;         float mine = b4 ? q4[j + 2] : q4[j];
;         float other = b4 ? q4[j] : q4[j + 2];
;         r2[j] = mine + __shfl_xor(other, 16);
;       }
;       {
;         float mine = b3 ? r2[1] : r2[0];
;         float other = b3 ? r2[0] : r2[1];
;         h = mine + __shfl_xor(other, 8);
;       }
;       h += __shfl_xor(h, 4);
;       h += __shfl_xor(h, 2);
;       h += __shfl_xor(h, 1);
	v_cvt_pk_f32_fp8_sdwa v[220:221], v169 src0_sel:WORD_1
	v_pk_mul_f32 v[222:223], v[64:65], v[214:215]
	v_pk_mul_f32 v[224:225], v[66:67], v[216:217]
	v_cvt_pk_f32_fp8_e32 v[214:215], v170
	v_cvt_pk_f32_fp8_sdwa v[216:217], v170 src0_sel:WORD_1
	v_pk_fma_f32 v[222:223], v[68:69], v[218:219], v[222:223]
	v_pk_fma_f32 v[224:225], v[70:71], v[220:221], v[224:225]
	v_cvt_pk_f32_fp8_e32 v[218:219], v171
	v_cvt_pk_f32_fp8_sdwa v[220:221], v171 src0_sel:WORD_1
	v_pk_fma_f32 v[222:223], v[72:73], v[214:215], v[222:223]
	v_pk_fma_f32 v[224:225], v[74:75], v[216:217], v[224:225]
	v_pk_fma_f32 v[222:223], v[76:77], v[218:219], v[222:223]
	v_pk_fma_f32 v[224:225], v[78:79], v[220:221], v[224:225]
	v_pk_add_f32 v[222:223], v[222:223], v[224:225]
	s_nop 0
	v_add_f32_e32 v232, v222, v223
	v_cvt_pk_f32_fp8_e32 v[214:215], v172
	v_cvt_pk_f32_fp8_sdwa v[216:217], v172 src0_sel:WORD_1
	v_cvt_pk_f32_fp8_e32 v[218:219], v173
	v_cvt_pk_f32_fp8_sdwa v[220:221], v173 src0_sel:WORD_1
	v_pk_mul_f32 v[222:223], v[64:65], v[214:215]
	v_pk_mul_f32 v[224:225], v[66:67], v[216:217]
	v_cvt_pk_f32_fp8_e32 v[214:215], v174
	v_cvt_pk_f32_fp8_sdwa v[216:217], v174 src0_sel:WORD_1
	v_pk_fma_f32 v[222:223], v[68:69], v[218:219], v[222:223]
	v_pk_fma_f32 v[224:225], v[70:71], v[220:221], v[224:225]
	v_cvt_pk_f32_fp8_e32 v[218:219], v175
	v_cvt_pk_f32_fp8_sdwa v[220:221], v175 src0_sel:WORD_1
	v_pk_fma_f32 v[222:223], v[72:73], v[214:215], v[222:223]
	v_pk_fma_f32 v[224:225], v[74:75], v[216:217], v[224:225]
	v_pk_fma_f32 v[222:223], v[76:77], v[218:219], v[222:223]
	v_pk_fma_f32 v[224:225], v[78:79], v[220:221], v[224:225]
	v_pk_add_f32 v[222:223], v[222:223], v[224:225]
	s_nop 0
	v_add_f32_e32 v233, v222, v223
	v_permlane32_swap_b32_e32 v226, v230
	v_permlane32_swap_b32_e32 v227, v231
	v_permlane32_swap_b32_e32 v228, v232
	v_permlane32_swap_b32_e32 v229, v233
	v_add_f32_e32 v226, v226, v230
	v_add_f32_e32 v228, v228, v232
	v_add_f32_e32 v227, v227, v231
	v_add_f32_e32 v229, v229, v233
	s_nop 1
	v_permlane16_swap_b32_e32 v226, v228
	v_permlane16_swap_b32_e32 v227, v229
	v_add_f32_e32 v226, v226, v228
	v_add_f32_e32 v227, v227, v229
	s_nop 0
	v_cndmask_b32_e64 v230, v226, v227, s[24:25]
	v_cndmask_b32_e64 v231, v227, v226, s[24:25]
	s_nop 1
	v_add_f32_dpp v232, v231, v230 row_ror:8 row_mask:0xf bank_mask:0xf
	s_nop 1
	v_add_f32_dpp v233, v232, v232 quad_perm:[1,0,3,2] row_mask:0xf bank_mask:0xf
	s_nop 1
	v_add_f32_dpp v232, v233, v233 quad_perm:[2,3,0,1] row_mask:0xf bank_mask:0xf
	s_nop 1
	v_add_f32_dpp v233, v232, v232 row_half_mirror row_mask:0xf bank_mask:0xf
	ds_write_b32 v235, v233 offset:34816
	v_readlane_b32 s48, v140, s72
	v_readlane_b32 s49, v140, s73
	v_readlane_b32 s50, v140, s74
	v_readlane_b32 s51, v140, s75
	v_readlane_b32 s52, v140, s76
	v_readlane_b32 s53, v140, s77
	v_readlane_b32 s54, v140, s78
	v_readlane_b32 s55, v140, s79
	s_add_u32 s32, s0, s48
	s_addc_u32 s33, s1, 0
	s_add_u32 s34, s0, s49
	s_addc_u32 s35, s1, 0
	s_add_u32 s36, s0, s50
	s_addc_u32 s37, s1, 0
	s_add_u32 s38, s0, s51
	s_addc_u32 s39, s1, 0
	s_add_u32 s40, s0, s52
	s_addc_u32 s41, s1, 0
	s_add_u32 s42, s0, s53
	s_addc_u32 s43, s1, 0
	s_add_u32 s44, s0, s54
	s_addc_u32 s45, s1, 0
	s_add_u32 s46, s0, s55
	s_addc_u32 s47, s1, 0
	global_load_dwordx4 v[144:147], v234, s[32:33]
	global_load_dwordx4 v[148:151], v234, s[34:35]
	global_load_dwordx4 v[152:155], v234, s[36:37]
	global_load_dwordx4 v[156:159], v234, s[38:39]
	global_load_dwordx4 v[160:163], v234, s[40:41]
	global_load_dwordx4 v[164:167], v234, s[42:43]
	global_load_dwordx4 v[168:171], v234, s[44:45]
	global_load_dwordx4 v[172:175], v234, s[46:47]
	s_waitcnt vmcnt(8)
	v_cvt_pk_f32_fp8_e32 v[214:215], v176
	v_cvt_pk_f32_fp8_sdwa v[216:217], v176 src0_sel:WORD_1
	v_cvt_pk_f32_fp8_e32 v[218:219], v177
	v_cvt_pk_f32_fp8_sdwa v[220:221], v177 src0_sel:WORD_1
	v_pk_mul_f32 v[222:223], v[80:81], v[214:215]
	v_pk_mul_f32 v[224:225], v[82:83], v[216:217]
	v_cvt_pk_f32_fp8_e32 v[214:215], v178
	v_cvt_pk_f32_fp8_sdwa v[216:217], v178 src0_sel:WORD_1
	v_pk_fma_f32 v[222:223], v[84:85], v[218:219], v[222:223]
	v_pk_fma_f32 v[224:225], v[86:87], v[220:221], v[224:225]
	v_cvt_pk_f32_fp8_e32 v[218:219], v179
	v_cvt_pk_f32_fp8_sdwa v[220:221], v179 src0_sel:WORD_1
	v_pk_fma_f32 v[222:223], v[88:89], v[214:215], v[222:223]
	v_pk_fma_f32 v[224:225], v[90:91], v[216:217], v[224:225]
	v_pk_fma_f32 v[222:223], v[92:93], v[218:219], v[222:223]
	v_pk_fma_f32 v[224:225], v[94:95], v[220:221], v[224:225]
	v_pk_add_f32 v[222:223], v[222:223], v[224:225]
	s_nop 0
	v_add_f32_e32 v226, v222, v223
	v_cvt_pk_f32_fp8_e32 v[214:215], v180
	v_cvt_pk_f32_fp8_sdwa v[216:217], v180 src0_sel:WORD_1
	v_cvt_pk_f32_fp8_e32 v[218:219], v181
	v_cvt_pk_f32_fp8_sdwa v[220:221], v181 src0_sel:WORD_1
	v_pk_mul_f32 v[222:223], v[80:81], v[214:215]
	v_pk_mul_f32 v[224:225], v[82:83], v[216:217]
	v_cvt_pk_f32_fp8_e32 v[214:215], v182
	v_cvt_pk_f32_fp8_sdwa v[216:217], v182 src0_sel:WORD_1
	v_pk_fma_f32 v[222:223], v[84:85], v[218:219], v[222:223]
	v_pk_fma_f32 v[224:225], v[86:87], v[220:221], v[224:225]
	v_cvt_pk_f32_fp8_e32 v[218:219], v183
	v_cvt_pk_f32_fp8_sdwa v[220:221], v183 src0_sel:WORD_1
	v_pk_fma_f32 v[222:223], v[88:89], v[214:215], v[222:223]
	v_pk_fma_f32 v[224:225], v[90:91], v[216:217], v[224:225]
	v_pk_fma_f32 v[222:223], v[92:93], v[218:219], v[222:223]
	v_pk_fma_f32 v[224:225], v[94:95], v[220:221], v[224:225]
	v_pk_add_f32 v[222:223], v[222:223], v[224:225]
	s_nop 0
	v_add_f32_e32 v227, v222, v223
	v_cvt_pk_f32_fp8_e32 v[214:215], v184
	v_cvt_pk_f32_fp8_sdwa v[216:217], v184 src0_sel:WORD_1
	v_cvt_pk_f32_fp8_e32 v[218:219], v185
	v_cvt_pk_f32_fp8_sdwa v[220:221], v185 src0_sel:WORD_1
; template <bool STORE>
; DI void peer_item(const Params& p, int item, char* smem) {
;     ...
;       float part[8];
; #pragma unroll
;       for (int u = 0; u < 8; ++u) {
;         float d = 0.f;
; #pragma unroll
;         for (int i = 0; i < 4; ++i) {
;           f32x2_t lo = __builtin_amdgcn_cvt_pk_f32_fp8((int)uq[u][i], false);
;           f32x2_t hi = __builtin_amdgcn_cvt_pk_f32_fp8((int)uq[u][i], true);
;           d += xf[4 * i] * lo.x + xf[4 * i + 1] * lo.y + xf[4 * i + 2] * hi.x + xf[4 * i + 3] * hi.y;
;         }
;         part[u] = d;
;       }
;       float q4[4], r2[2], h;
; #pragma unroll
;       for (int j = 0; j < 4; ++j) {
;         float mine = b5 ? part[j + 4] : part[j];
;         float other = b5 ? part[j] : part[j + 4];
;         q4[j] = mine + __shfl_xor(other, 32);
;       }
; #pragma unroll
;       for (int j = 0; j < 2; ++j) {
;         float mine = b4 ? q4[j + 2] : q4[j];
;         float other = b4 ? q4[j] : q4[j + 2];
;         r2[j] = mine + __shfl_xor(other, 16);
;       }
;       {
;         float mine = b3 ? r2[1] : r2[0];
;         float other = b3 ? r2[0] : r2[1];
;         h = mine + __shfl_xor(other, 8);
;       }
;       h += __shfl_xor(h, 4);
;       h += __shfl_xor(h, 2);
;       h += __shfl_xor(h, 1);
	v_pk_mul_f32 v[222:223], v[80:81], v[214:215]
	v_pk_mul_f32 v[224:225], v[82:83], v[216:217]
	v_cvt_pk_f32_fp8_e32 v[214:215], v186
	v_cvt_pk_f32_fp8_sdwa v[216:217], v186 src0_sel:WORD_1
	v_pk_fma_f32 v[222:223], v[84:85], v[218:219], v[222:223]
	v_pk_fma_f32 v[224:225], v[86:87], v[220:221], v[224:225]
	v_cvt_pk_f32_fp8_e32 v[218:219], v187
	v_cvt_pk_f32_fp8_sdwa v[220:221], v187 src0_sel:WORD_1
	v_pk_fma_f32 v[222:223], v[88:89], v[214:215], v[222:223]
	v_pk_fma_f32 v[224:225], v[90:91], v[216:217], v[224:225]
	v_pk_fma_f32 v[222:223], v[92:93], v[218:219], v[222:223]
	v_pk_fma_f32 v[224:225], v[94:95], v[220:221], v[224:225]
	v_pk_add_f32 v[222:223], v[222:223], v[224:225]
	s_nop 0
	v_add_f32_e32 v228, v222, v223
	v_cvt_pk_f32_fp8_e32 v[214:215], v188
	v_cvt_pk_f32_fp8_sdwa v[216:217], v188 src0_sel:WORD_1
	v_cvt_pk_f32_fp8_e32 v[218:219], v189
	v_cvt_pk_f32_fp8_sdwa v[220:221], v189 src0_sel:WORD_1
	v_pk_mul_f32 v[222:223], v[80:81], v[214:215]
	v_pk_mul_f32 v[224:225], v[82:83], v[216:217]
	v_cvt_pk_f32_fp8_e32 v[214:215], v190
	v_cvt_pk_f32_fp8_sdwa v[216:217], v190 src0_sel:WORD_1
	v_pk_fma_f32 v[222:223], v[84:85], v[218:219], v[222:223]
	v_pk_fma_f32 v[224:225], v[86:87], v[220:221], v[224:225]
	v_cvt_pk_f32_fp8_e32 v[218:219], v191
	v_cvt_pk_f32_fp8_sdwa v[220:221], v191 src0_sel:WORD_1
	v_pk_fma_f32 v[222:223], v[88:89], v[214:215], v[222:223]
	v_pk_fma_f32 v[224:225], v[90:91], v[216:217], v[224:225]
	v_pk_fma_f32 v[222:223], v[92:93], v[218:219], v[222:223]
	v_pk_fma_f32 v[224:225], v[94:95], v[220:221], v[224:225]
	v_pk_add_f32 v[222:223], v[222:223], v[224:225]
	s_nop 0
	v_add_f32_e32 v229, v222, v223
	v_cvt_pk_f32_fp8_e32 v[214:215], v192
	v_cvt_pk_f32_fp8_sdwa v[216:217], v192 src0_sel:WORD_1
	v_cvt_pk_f32_fp8_e32 v[218:219], v193
	v_cvt_pk_f32_fp8_sdwa v[220:221], v193 src0_sel:WORD_1
	v_pk_mul_f32 v[222:223], v[80:81], v[214:215]
	v_pk_mul_f32 v[224:225], v[82:83], v[216:217]
	v_cvt_pk_f32_fp8_e32 v[214:215], v194
	v_cvt_pk_f32_fp8_sdwa v[216:217], v194 src0_sel:WORD_1
	v_pk_fma_f32 v[222:223], v[84:85], v[218:219], v[222:223]
	v_pk_fma_f32 v[224:225], v[86:87], v[220:221], v[224:225]
	v_cvt_pk_f32_fp8_e32 v[218:219], v195
	v_cvt_pk_f32_fp8_sdwa v[220:221], v195 src0_sel:WORD_1
	v_pk_fma_f32 v[222:223], v[88:89], v[214:215], v[222:223]
	v_pk_fma_f32 v[224:225], v[90:91], v[216:217], v[224:225]
	v_pk_fma_f32 v[222:223], v[92:93], v[218:219], v[222:223]
	v_pk_fma_f32 v[224:225], v[94:95], v[220:221], v[224:225]
	v_pk_add_f32 v[222:223], v[222:223], v[224:225]
	s_nop 0
	v_add_f32_e32 v230, v222, v223
	v_cvt_pk_f32_fp8_e32 v[214:215], v196
	v_cvt_pk_f32_fp8_sdwa v[216:217], v196 src0_sel:WORD_1
	v_cvt_pk_f32_fp8_e32 v[218:219], v197
	v_cvt_pk_f32_fp8_sdwa v[220:221], v197 src0_sel:WORD_1
	v_pk_mul_f32 v[222:223], v[80:81], v[214:215]
	v_pk_mul_f32 v[224:225], v[82:83], v[216:217]
	v_cvt_pk_f32_fp8_e32 v[214:215], v198
	v_cvt_pk_f32_fp8_sdwa v[216:217], v198 src0_sel:WORD_1
	v_pk_fma_f32 v[222:223], v[84:85], v[218:219], v[222:223]
	v_pk_fma_f32 v[224:225], v[86:87], v[220:221], v[224:225]
	v_cvt_pk_f32_fp8_e32 v[218:219], v199
	v_cvt_pk_f32_fp8_sdwa v[220:221], v199 src0_sel:WORD_1
	v_pk_fma_f32 v[222:223], v[88:89], v[214:215], v[222:223]
	v_pk_fma_f32 v[224:225], v[90:91], v[216:217], v[224:225]
	v_pk_fma_f32 v[222:223], v[92:93], v[218:219], v[222:223]
	v_pk_fma_f32 v[224:225], v[94:95], v[220:221], v[224:225]
	v_pk_add_f32 v[222:223], v[222:223], v[224:225]
	s_nop 0
	v_add_f32_e32 v231, v222, v223
	v_cvt_pk_f32_fp8_e32 v[214:215], v200
	v_cvt_pk_f32_fp8_sdwa v[216:217], v200 src0_sel:WORD_1
	v_cvt_pk_f32_fp8_e32 v[218:219], v201
	v_cvt_pk_f32_fp8_sdwa v[220:221], v201 src0_sel:WORD_1
	v_pk_mul_f32 v[222:223], v[80:81], v[214:215]
	v_pk_mul_f32 v[224:225], v[82:83], v[216:217]
	v_cvt_pk_f32_fp8_e32 v[214:215], v202
	v_cvt_pk_f32_fp8_sdwa v[216:217], v202 src0_sel:WORD_1
	v_pk_fma_f32 v[222:223], v[84:85], v[218:219], v[222:223]
	v_pk_fma_f32 v[224:225], v[86:87], v[220:221], v[224:225]
	v_cvt_pk_f32_fp8_e32 v[218:219], v203
	v_cvt_pk_f32_fp8_sdwa v[220:221], v203 src0_sel:WORD_1
	v_pk_fma_f32 v[222:223], v[88:89], v[214:215], v[222:223]
	v_pk_fma_f32 v[224:225], v[90:91], v[216:217], v[224:225]
	v_pk_fma_f32 v[222:223], v[92:93], v[218:219], v[222:223]
	v_pk_fma_f32 v[224:225], v[94:95], v[220:221], v[224:225]
	v_pk_add_f32 v[222:223], v[222:223], v[224:225]
	s_nop 0
	v_add_f32_e32 v232, v222, v223
	v_cvt_pk_f32_fp8_e32 v[214:215], v204
	v_cvt_pk_f32_fp8_sdwa v[216:217], v204 src0_sel:WORD_1
	v_cvt_pk_f32_fp8_e32 v[218:219], v205
	v_cvt_pk_f32_fp8_sdwa v[220:221], v205 src0_sel:WORD_1
	v_pk_mul_f32 v[222:223], v[80:81], v[214:215]
	v_pk_mul_f32 v[224:225], v[82:83], v[216:217]
	v_cvt_pk_f32_fp8_e32 v[214:215], v206
	v_cvt_pk_f32_fp8_sdwa v[216:217], v206 src0_sel:WORD_1
	v_pk_fma_f32 v[222:223], v[84:85], v[218:219], v[222:223]
	v_pk_fma_f32 v[224:225], v[86:87], v[220:221], v[224:225]
	v_cvt_pk_f32_fp8_e32 v[218:219], v207
	v_cvt_pk_f32_fp8_sdwa v[220:221], v207 src0_sel:WORD_1
	v_pk_fma_f32 v[222:223], v[88:89], v[214:215], v[222:223]
	v_pk_fma_f32 v[224:225], v[90:91], v[216:217], v[224:225]
	v_pk_fma_f32 v[222:223], v[92:93], v[218:219], v[222:223]
	v_pk_fma_f32 v[224:225], v[94:95], v[220:221], v[224:225]
	v_pk_add_f32 v[222:223], v[222:223], v[224:225]
	s_nop 0
	v_add_f32_e32 v233, v222, v223
	v_permlane32_swap_b32_e32 v226, v230
	v_permlane32_swap_b32_e32 v227, v231
	v_permlane32_swap_b32_e32 v228, v232
	v_permlane32_swap_b32_e32 v229, v233
	v_add_f32_e32 v226, v226, v230
	v_add_f32_e32 v228, v228, v232
	v_add_f32_e32 v227, v227, v231
	v_add_f32_e32 v229, v229, v233
	s_nop 1
	v_permlane16_swap_b32_e32 v226, v228
; template <bool STORE>
; DI void peer_item(const Params& p, int item, char* smem) {
;     ...
;       float part[8];
; #pragma unroll
;       for (int u = 0; u < 8; ++u) {
;         float d = 0.f;
; #pragma unroll
;         for (int i = 0; i < 4; ++i) {
;           f32x2_t lo = __builtin_amdgcn_cvt_pk_f32_fp8((int)uq[u][i], false);
;           f32x2_t hi = __builtin_amdgcn_cvt_pk_f32_fp8((int)uq[u][i], true);
;           d += xf[4 * i] * lo.x + xf[4 * i + 1] * lo.y + xf[4 * i + 2] * hi.x + xf[4 * i + 3] * hi.y;
;         }
;         part[u] = d;
;       }
;       float q4[4], r2[2], h;
; #pragma unroll
;       for (int j = 0; j < 4; ++j) {
;         float mine = b5 ? part[j + 4] : part[j];
;         float other = b5 ? part[j] : part[j + 4];
;         q4[j] = mine + __shfl_xor(other, 32);
;       }
; #pragma unroll
;       for (int j = 0; j < 2; ++j) {
;         float mine = b4 ? q4[j + 2] : q4[j];
;         float other = b4 ? q4[j] : q4[j + 2];
;         r2[j] = mine + __shfl_xor(other, 16);
;       }
;       {
;         float mine = b3 ? r2[1] : r2[0];
;         float other = b3 ? r2[0] : r2[1];
;         h = mine + __shfl_xor(other, 8);
;       }
;       h += __shfl_xor(h, 4);
;       h += __shfl_xor(h, 2);
;       h += __shfl_xor(h, 1);
	v_permlane16_swap_b32_e32 v227, v229
	v_add_f32_e32 v226, v226, v228
	v_add_f32_e32 v227, v227, v229
	s_nop 0
	v_cndmask_b32_e64 v230, v226, v227, s[24:25]
	v_cndmask_b32_e64 v231, v227, v226, s[24:25]
	s_nop 1
	v_add_f32_dpp v232, v231, v230 row_ror:8 row_mask:0xf bank_mask:0xf
	s_nop 1
	v_add_f32_dpp v233, v232, v232 quad_perm:[1,0,3,2] row_mask:0xf bank_mask:0xf
	s_nop 1
	v_add_f32_dpp v232, v233, v233 quad_perm:[2,3,0,1] row_mask:0xf bank_mask:0xf
	s_nop 1
	v_add_f32_dpp v233, v232, v232 row_half_mirror row_mask:0xf bank_mask:0xf
	ds_write_b32 v235, v233 offset:35328
	v_readlane_b32 s48, v142, s72
	v_readlane_b32 s49, v142, s73
	v_readlane_b32 s50, v142, s74
	v_readlane_b32 s51, v142, s75
	v_readlane_b32 s52, v142, s76
	v_readlane_b32 s53, v142, s77
	v_readlane_b32 s54, v142, s78
	v_readlane_b32 s55, v142, s79
	s_add_u32 s32, s0, s48
	s_addc_u32 s33, s1, 0
	s_add_u32 s34, s0, s49
	s_addc_u32 s35, s1, 0
	s_add_u32 s36, s0, s50
	s_addc_u32 s37, s1, 0
	s_add_u32 s38, s0, s51
	s_addc_u32 s39, s1, 0
	s_add_u32 s40, s0, s52
	s_addc_u32 s41, s1, 0
	s_add_u32 s42, s0, s53
	s_addc_u32 s43, s1, 0
	s_add_u32 s44, s0, s54
	s_addc_u32 s45, s1, 0
	s_add_u32 s46, s0, s55
	s_addc_u32 s47, s1, 0
	global_load_dwordx4 v[176:179], v234, s[32:33]
	global_load_dwordx4 v[180:183], v234, s[34:35]
	global_load_dwordx4 v[184:187], v234, s[36:37]
	global_load_dwordx4 v[188:191], v234, s[38:39]
	global_load_dwordx4 v[192:195], v234, s[40:41]
	global_load_dwordx4 v[196:199], v234, s[42:43]
	global_load_dwordx4 v[200:203], v234, s[44:45]
	global_load_dwordx4 v[204:207], v234, s[46:47]
	s_waitcnt vmcnt(8)
	v_cvt_pk_f32_fp8_e32 v[214:215], v144
	v_cvt_pk_f32_fp8_sdwa v[216:217], v144 src0_sel:WORD_1
	v_cvt_pk_f32_fp8_e32 v[218:219], v145
	v_cvt_pk_f32_fp8_sdwa v[220:221], v145 src0_sel:WORD_1
	v_pk_mul_f32 v[222:223], v[96:97], v[214:215]
	v_pk_mul_f32 v[224:225], v[98:99], v[216:217]
	v_cvt_pk_f32_fp8_e32 v[214:215], v146
	v_cvt_pk_f32_fp8_sdwa v[216:217], v146 src0_sel:WORD_1
	v_pk_fma_f32 v[222:223], v[100:101], v[218:219], v[222:223]
	v_pk_fma_f32 v[224:225], v[102:103], v[220:221], v[224:225]
	v_cvt_pk_f32_fp8_e32 v[218:219], v147
	v_cvt_pk_f32_fp8_sdwa v[220:221], v147 src0_sel:WORD_1
	v_pk_fma_f32 v[222:223], v[104:105], v[214:215], v[222:223]
	v_pk_fma_f32 v[224:225], v[106:107], v[216:217], v[224:225]
	v_pk_fma_f32 v[222:223], v[108:109], v[218:219], v[222:223]
	v_pk_fma_f32 v[224:225], v[110:111], v[220:221], v[224:225]
	v_pk_add_f32 v[222:223], v[222:223], v[224:225]
	s_nop 0
	v_add_f32_e32 v226, v222, v223
	v_cvt_pk_f32_fp8_e32 v[214:215], v148
	v_cvt_pk_f32_fp8_sdwa v[216:217], v148 src0_sel:WORD_1
	v_cvt_pk_f32_fp8_e32 v[218:219], v149
	v_cvt_pk_f32_fp8_sdwa v[220:221], v149 src0_sel:WORD_1
	v_pk_mul_f32 v[222:223], v[96:97], v[214:215]
	v_pk_mul_f32 v[224:225], v[98:99], v[216:217]
	v_cvt_pk_f32_fp8_e32 v[214:215], v150
	v_cvt_pk_f32_fp8_sdwa v[216:217], v150 src0_sel:WORD_1
	v_pk_fma_f32 v[222:223], v[100:101], v[218:219], v[222:223]
	v_pk_fma_f32 v[224:225], v[102:103], v[220:221], v[224:225]
	v_cvt_pk_f32_fp8_e32 v[218:219], v151
	v_cvt_pk_f32_fp8_sdwa v[220:221], v151 src0_sel:WORD_1
	v_pk_fma_f32 v[222:223], v[104:105], v[214:215], v[222:223]
	v_pk_fma_f32 v[224:225], v[106:107], v[216:217], v[224:225]
	v_pk_fma_f32 v[222:223], v[108:109], v[218:219], v[222:223]
	v_pk_fma_f32 v[224:225], v[110:111], v[220:221], v[224:225]
	v_pk_add_f32 v[222:223], v[222:223], v[224:225]
	s_nop 0
	v_add_f32_e32 v227, v222, v223
	v_cvt_pk_f32_fp8_e32 v[214:215], v152
	v_cvt_pk_f32_fp8_sdwa v[216:217], v152 src0_sel:WORD_1
	v_cvt_pk_f32_fp8_e32 v[218:219], v153
	v_cvt_pk_f32_fp8_sdwa v[220:221], v153 src0_sel:WORD_1
	v_pk_mul_f32 v[222:223], v[96:97], v[214:215]
	v_pk_mul_f32 v[224:225], v[98:99], v[216:217]
	v_cvt_pk_f32_fp8_e32 v[214:215], v154
	v_cvt_pk_f32_fp8_sdwa v[216:217], v154 src0_sel:WORD_1
	v_pk_fma_f32 v[222:223], v[100:101], v[218:219], v[222:223]
	v_pk_fma_f32 v[224:225], v[102:103], v[220:221], v[224:225]
	v_cvt_pk_f32_fp8_e32 v[218:219], v155
	v_cvt_pk_f32_fp8_sdwa v[220:221], v155 src0_sel:WORD_1
	v_pk_fma_f32 v[222:223], v[104:105], v[214:215], v[222:223]
	v_pk_fma_f32 v[224:225], v[106:107], v[216:217], v[224:225]
	v_pk_fma_f32 v[222:223], v[108:109], v[218:219], v[222:223]
	v_pk_fma_f32 v[224:225], v[110:111], v[220:221], v[224:225]
	v_pk_add_f32 v[222:223], v[222:223], v[224:225]
	s_nop 0
	v_add_f32_e32 v228, v222, v223
	v_cvt_pk_f32_fp8_e32 v[214:215], v156
	v_cvt_pk_f32_fp8_sdwa v[216:217], v156 src0_sel:WORD_1
	v_cvt_pk_f32_fp8_e32 v[218:219], v157
	v_cvt_pk_f32_fp8_sdwa v[220:221], v157 src0_sel:WORD_1
	v_pk_mul_f32 v[222:223], v[96:97], v[214:215]
	v_pk_mul_f32 v[224:225], v[98:99], v[216:217]
	v_cvt_pk_f32_fp8_e32 v[214:215], v158
	v_cvt_pk_f32_fp8_sdwa v[216:217], v158 src0_sel:WORD_1
	v_pk_fma_f32 v[222:223], v[100:101], v[218:219], v[222:223]
	v_pk_fma_f32 v[224:225], v[102:103], v[220:221], v[224:225]
	v_cvt_pk_f32_fp8_e32 v[218:219], v159
	v_cvt_pk_f32_fp8_sdwa v[220:221], v159 src0_sel:WORD_1
	v_pk_fma_f32 v[222:223], v[104:105], v[214:215], v[222:223]
	v_pk_fma_f32 v[224:225], v[106:107], v[216:217], v[224:225]
	v_pk_fma_f32 v[222:223], v[108:109], v[218:219], v[222:223]
	v_pk_fma_f32 v[224:225], v[110:111], v[220:221], v[224:225]
	v_pk_add_f32 v[222:223], v[222:223], v[224:225]
	s_nop 0
	v_add_f32_e32 v229, v222, v223
	v_cvt_pk_f32_fp8_e32 v[214:215], v160
	v_cvt_pk_f32_fp8_sdwa v[216:217], v160 src0_sel:WORD_1
	v_cvt_pk_f32_fp8_e32 v[218:219], v161
	v_cvt_pk_f32_fp8_sdwa v[220:221], v161 src0_sel:WORD_1
	v_pk_mul_f32 v[222:223], v[96:97], v[214:215]
	v_pk_mul_f32 v[224:225], v[98:99], v[216:217]
	v_cvt_pk_f32_fp8_e32 v[214:215], v162
; template <bool STORE>
; DI void peer_item(const Params& p, int item, char* smem) {
;     ...
;       for (int u = 0; u < 8; ++u) {
;         int e = e_s[tl * 128 + k + u];
;         uq[u] = *(const u32x4*)(U8 + (size_t)e * 1024 + lane * 16);
;       }
;       float part[8];
; #pragma unroll
;       for (int u = 0; u < 8; ++u) {
;         float d = 0.f;
; #pragma unroll
;         for (int i = 0; i < 4; ++i) {
;           f32x2_t lo = __builtin_amdgcn_cvt_pk_f32_fp8((int)uq[u][i], false);
;           f32x2_t hi = __builtin_amdgcn_cvt_pk_f32_fp8((int)uq[u][i], true);
;           d += xf[4 * i] * lo.x + xf[4 * i + 1] * lo.y + xf[4 * i + 2] * hi.x + xf[4 * i + 3] * hi.y;
;         }
;         part[u] = d;
;       }
;       float q4[4], r2[2], h;
; #pragma unroll
;       for (int j = 0; j < 4; ++j) {
;         float mine = b5 ? part[j + 4] : part[j];
;         float other = b5 ? part[j] : part[j + 4];
;         q4[j] = mine + __shfl_xor(other, 32);
;       }
; #pragma unroll
;       for (int j = 0; j < 2; ++j) {
;         float mine = b4 ? q4[j + 2] : q4[j];
;         float other = b4 ? q4[j] : q4[j + 2];
;         r2[j] = mine + __shfl_xor(other, 16);
;       }
;       {
;         float mine = b3 ? r2[1] : r2[0];
;         float other = b3 ? r2[0] : r2[1];
;         h = mine + __shfl_xor(other, 8);
;       }
;       h += __shfl_xor(h, 4);
;       h += __shfl_xor(h, 2);
;       h += __shfl_xor(h, 1);
	v_cvt_pk_f32_fp8_sdwa v[216:217], v162 src0_sel:WORD_1
	v_pk_fma_f32 v[222:223], v[100:101], v[218:219], v[222:223]
	v_pk_fma_f32 v[224:225], v[102:103], v[220:221], v[224:225]
	v_cvt_pk_f32_fp8_e32 v[218:219], v163
	v_cvt_pk_f32_fp8_sdwa v[220:221], v163 src0_sel:WORD_1
	v_pk_fma_f32 v[222:223], v[104:105], v[214:215], v[222:223]
	v_pk_fma_f32 v[224:225], v[106:107], v[216:217], v[224:225]
	v_pk_fma_f32 v[222:223], v[108:109], v[218:219], v[222:223]
	v_pk_fma_f32 v[224:225], v[110:111], v[220:221], v[224:225]
	v_pk_add_f32 v[222:223], v[222:223], v[224:225]
	s_nop 0
	v_add_f32_e32 v230, v222, v223
	v_cvt_pk_f32_fp8_e32 v[214:215], v164
	v_cvt_pk_f32_fp8_sdwa v[216:217], v164 src0_sel:WORD_1
	v_cvt_pk_f32_fp8_e32 v[218:219], v165
	v_cvt_pk_f32_fp8_sdwa v[220:221], v165 src0_sel:WORD_1
	v_pk_mul_f32 v[222:223], v[96:97], v[214:215]
	v_pk_mul_f32 v[224:225], v[98:99], v[216:217]
	v_cvt_pk_f32_fp8_e32 v[214:215], v166
	v_cvt_pk_f32_fp8_sdwa v[216:217], v166 src0_sel:WORD_1
	v_pk_fma_f32 v[222:223], v[100:101], v[218:219], v[222:223]
	v_pk_fma_f32 v[224:225], v[102:103], v[220:221], v[224:225]
	v_cvt_pk_f32_fp8_e32 v[218:219], v167
	v_cvt_pk_f32_fp8_sdwa v[220:221], v167 src0_sel:WORD_1
	v_pk_fma_f32 v[222:223], v[104:105], v[214:215], v[222:223]
	v_pk_fma_f32 v[224:225], v[106:107], v[216:217], v[224:225]
	v_pk_fma_f32 v[222:223], v[108:109], v[218:219], v[222:223]
	v_pk_fma_f32 v[224:225], v[110:111], v[220:221], v[224:225]
	v_pk_add_f32 v[222:223], v[222:223], v[224:225]
	s_nop 0
	v_add_f32_e32 v231, v222, v223
	v_cvt_pk_f32_fp8_e32 v[214:215], v168
	v_cvt_pk_f32_fp8_sdwa v[216:217], v168 src0_sel:WORD_1
	v_cvt_pk_f32_fp8_e32 v[218:219], v169
	v_cvt_pk_f32_fp8_sdwa v[220:221], v169 src0_sel:WORD_1
	v_pk_mul_f32 v[222:223], v[96:97], v[214:215]
	v_pk_mul_f32 v[224:225], v[98:99], v[216:217]
	v_cvt_pk_f32_fp8_e32 v[214:215], v170
	v_cvt_pk_f32_fp8_sdwa v[216:217], v170 src0_sel:WORD_1
	v_pk_fma_f32 v[222:223], v[100:101], v[218:219], v[222:223]
	v_pk_fma_f32 v[224:225], v[102:103], v[220:221], v[224:225]
	v_cvt_pk_f32_fp8_e32 v[218:219], v171
	v_cvt_pk_f32_fp8_sdwa v[220:221], v171 src0_sel:WORD_1
	v_pk_fma_f32 v[222:223], v[104:105], v[214:215], v[222:223]
	v_pk_fma_f32 v[224:225], v[106:107], v[216:217], v[224:225]
	v_pk_fma_f32 v[222:223], v[108:109], v[218:219], v[222:223]
	v_pk_fma_f32 v[224:225], v[110:111], v[220:221], v[224:225]
	v_pk_add_f32 v[222:223], v[222:223], v[224:225]
	s_nop 0
	v_add_f32_e32 v232, v222, v223
	v_cvt_pk_f32_fp8_e32 v[214:215], v172
	v_cvt_pk_f32_fp8_sdwa v[216:217], v172 src0_sel:WORD_1
	v_cvt_pk_f32_fp8_e32 v[218:219], v173
	v_cvt_pk_f32_fp8_sdwa v[220:221], v173 src0_sel:WORD_1
	v_pk_mul_f32 v[222:223], v[96:97], v[214:215]
	v_pk_mul_f32 v[224:225], v[98:99], v[216:217]
	v_cvt_pk_f32_fp8_e32 v[214:215], v174
	v_cvt_pk_f32_fp8_sdwa v[216:217], v174 src0_sel:WORD_1
	v_pk_fma_f32 v[222:223], v[100:101], v[218:219], v[222:223]
	v_pk_fma_f32 v[224:225], v[102:103], v[220:221], v[224:225]
	v_cvt_pk_f32_fp8_e32 v[218:219], v175
	v_cvt_pk_f32_fp8_sdwa v[220:221], v175 src0_sel:WORD_1
	v_pk_fma_f32 v[222:223], v[104:105], v[214:215], v[222:223]
	v_pk_fma_f32 v[224:225], v[106:107], v[216:217], v[224:225]
	v_pk_fma_f32 v[222:223], v[108:109], v[218:219], v[222:223]
	v_pk_fma_f32 v[224:225], v[110:111], v[220:221], v[224:225]
	v_pk_add_f32 v[222:223], v[222:223], v[224:225]
	s_nop 0
	v_add_f32_e32 v233, v222, v223
	v_permlane32_swap_b32_e32 v226, v230
	v_permlane32_swap_b32_e32 v227, v231
	v_permlane32_swap_b32_e32 v228, v232
	v_permlane32_swap_b32_e32 v229, v233
	v_add_f32_e32 v226, v226, v230
	v_add_f32_e32 v228, v228, v232
	v_add_f32_e32 v227, v227, v231
	v_add_f32_e32 v229, v229, v233
	s_nop 1
	v_permlane16_swap_b32_e32 v226, v228
	v_permlane16_swap_b32_e32 v227, v229
	v_add_f32_e32 v226, v226, v228
	v_add_f32_e32 v227, v227, v229
	s_nop 0
	v_cndmask_b32_e64 v230, v226, v227, s[24:25]
	v_cndmask_b32_e64 v231, v227, v226, s[24:25]
	s_nop 1
	v_add_f32_dpp v232, v231, v230 row_ror:8 row_mask:0xf bank_mask:0xf
	s_nop 1
	v_add_f32_dpp v233, v232, v232 quad_perm:[1,0,3,2] row_mask:0xf bank_mask:0xf
	s_nop 1
	v_add_f32_dpp v232, v233, v233 quad_perm:[2,3,0,1] row_mask:0xf bank_mask:0xf
	s_nop 1
	v_add_f32_dpp v233, v232, v232 row_half_mirror row_mask:0xf bank_mask:0xf
	ds_write_b32 v235, v233 offset:35840
	v_readlane_b32 s48, v129, s72
	v_readlane_b32 s49, v129, s73
	v_readlane_b32 s50, v129, s74
	v_readlane_b32 s51, v129, s75
	v_readlane_b32 s52, v129, s76
	v_readlane_b32 s53, v129, s77
	v_readlane_b32 s54, v129, s78
	v_readlane_b32 s55, v129, s79
	s_add_u32 s32, s0, s48
	s_addc_u32 s33, s1, 0
	s_add_u32 s34, s0, s49
	s_addc_u32 s35, s1, 0
	s_add_u32 s36, s0, s50
	s_addc_u32 s37, s1, 0
	s_add_u32 s38, s0, s51
	s_addc_u32 s39, s1, 0
	s_add_u32 s40, s0, s52
	s_addc_u32 s41, s1, 0
	s_add_u32 s42, s0, s53
	s_addc_u32 s43, s1, 0
	s_add_u32 s44, s0, s54
	s_addc_u32 s45, s1, 0
	s_add_u32 s46, s0, s55
	s_addc_u32 s47, s1, 0
	global_load_dwordx4 v[144:147], v234, s[32:33]
	global_load_dwordx4 v[148:151], v234, s[34:35]
	global_load_dwordx4 v[152:155], v234, s[36:37]
	global_load_dwordx4 v[156:159], v234, s[38:39]
	global_load_dwordx4 v[160:163], v234, s[40:41]
	global_load_dwordx4 v[164:167], v234, s[42:43]
	global_load_dwordx4 v[168:171], v234, s[44:45]
	global_load_dwordx4 v[172:175], v234, s[46:47]
	s_waitcnt vmcnt(8)
; template <bool STORE>
; DI void peer_item(const Params& p, int item, char* smem) {
;     ...
;       for (int u = 0; u < 8; ++u) {
;         int e = e_s[tl * 128 + k + u];
;         uq[u] = *(const u32x4*)(U8 + (size_t)e * 1024 + lane * 16);
;       }
;       float part[8];
; #pragma unroll
;       for (int u = 0; u < 8; ++u) {
;         float d = 0.f;
; #pragma unroll
;         for (int i = 0; i < 4; ++i) {
;           f32x2_t lo = __builtin_amdgcn_cvt_pk_f32_fp8((int)uq[u][i], false);
;           f32x2_t hi = __builtin_amdgcn_cvt_pk_f32_fp8((int)uq[u][i], true);
;           d += xf[4 * i] * lo.x + xf[4 * i + 1] * lo.y + xf[4 * i + 2] * hi.x + xf[4 * i + 3] * hi.y;
;         }
;         part[u] = d;
	v_cvt_pk_f32_fp8_e32 v[214:215], v176
	v_cvt_pk_f32_fp8_sdwa v[216:217], v176 src0_sel:WORD_1
	v_cvt_pk_f32_fp8_e32 v[218:219], v177
	v_cvt_pk_f32_fp8_sdwa v[220:221], v177 src0_sel:WORD_1
	v_pk_mul_f32 v[222:223], v[112:113], v[214:215]
	v_pk_mul_f32 v[224:225], v[114:115], v[216:217]
	v_cvt_pk_f32_fp8_e32 v[214:215], v178
	v_cvt_pk_f32_fp8_sdwa v[216:217], v178 src0_sel:WORD_1
	v_pk_fma_f32 v[222:223], v[116:117], v[218:219], v[222:223]
	v_pk_fma_f32 v[224:225], v[118:119], v[220:221], v[224:225]
	v_cvt_pk_f32_fp8_e32 v[218:219], v179
	v_cvt_pk_f32_fp8_sdwa v[220:221], v179 src0_sel:WORD_1
	v_pk_fma_f32 v[222:223], v[120:121], v[214:215], v[222:223]
	v_pk_fma_f32 v[224:225], v[122:123], v[216:217], v[224:225]
	v_pk_fma_f32 v[222:223], v[124:125], v[218:219], v[222:223]
	v_pk_fma_f32 v[224:225], v[126:127], v[220:221], v[224:225]
	v_pk_add_f32 v[222:223], v[222:223], v[224:225]
	s_nop 0
	v_add_f32_e32 v226, v222, v223
	v_cvt_pk_f32_fp8_e32 v[214:215], v180
	v_cvt_pk_f32_fp8_sdwa v[216:217], v180 src0_sel:WORD_1
	v_cvt_pk_f32_fp8_e32 v[218:219], v181
	v_cvt_pk_f32_fp8_sdwa v[220:221], v181 src0_sel:WORD_1
	v_pk_mul_f32 v[222:223], v[112:113], v[214:215]
	v_pk_mul_f32 v[224:225], v[114:115], v[216:217]
	v_cvt_pk_f32_fp8_e32 v[214:215], v182
	v_cvt_pk_f32_fp8_sdwa v[216:217], v182 src0_sel:WORD_1
	v_pk_fma_f32 v[222:223], v[116:117], v[218:219], v[222:223]
	v_pk_fma_f32 v[224:225], v[118:119], v[220:221], v[224:225]
	v_cvt_pk_f32_fp8_e32 v[218:219], v183
	v_cvt_pk_f32_fp8_sdwa v[220:221], v183 src0_sel:WORD_1
	v_pk_fma_f32 v[222:223], v[120:121], v[214:215], v[222:223]
	v_pk_fma_f32 v[224:225], v[122:123], v[216:217], v[224:225]
	v_pk_fma_f32 v[222:223], v[124:125], v[218:219], v[222:223]
	v_pk_fma_f32 v[224:225], v[126:127], v[220:221], v[224:225]
	v_pk_add_f32 v[222:223], v[222:223], v[224:225]
	s_nop 0
	v_add_f32_e32 v227, v222, v223
	v_cvt_pk_f32_fp8_e32 v[214:215], v184
	v_cvt_pk_f32_fp8_sdwa v[216:217], v184 src0_sel:WORD_1
	v_cvt_pk_f32_fp8_e32 v[218:219], v185
	v_cvt_pk_f32_fp8_sdwa v[220:221], v185 src0_sel:WORD_1
	v_pk_mul_f32 v[222:223], v[112:113], v[214:215]
	v_pk_mul_f32 v[224:225], v[114:115], v[216:217]
	v_cvt_pk_f32_fp8_e32 v[214:215], v186
	v_cvt_pk_f32_fp8_sdwa v[216:217], v186 src0_sel:WORD_1
	v_pk_fma_f32 v[222:223], v[116:117], v[218:219], v[222:223]
	v_pk_fma_f32 v[224:225], v[118:119], v[220:221], v[224:225]
	v_cvt_pk_f32_fp8_e32 v[218:219], v187
	v_cvt_pk_f32_fp8_sdwa v[220:221], v187 src0_sel:WORD_1
	v_pk_fma_f32 v[222:223], v[120:121], v[214:215], v[222:223]
	v_pk_fma_f32 v[224:225], v[122:123], v[216:217], v[224:225]
	v_pk_fma_f32 v[222:223], v[124:125], v[218:219], v[222:223]
	v_pk_fma_f32 v[224:225], v[126:127], v[220:221], v[224:225]
	v_pk_add_f32 v[222:223], v[222:223], v[224:225]
	s_nop 0
	v_add_f32_e32 v228, v222, v223
	v_cvt_pk_f32_fp8_e32 v[214:215], v188
	v_cvt_pk_f32_fp8_sdwa v[216:217], v188 src0_sel:WORD_1
	v_cvt_pk_f32_fp8_e32 v[218:219], v189
	v_cvt_pk_f32_fp8_sdwa v[220:221], v189 src0_sel:WORD_1
	v_pk_mul_f32 v[222:223], v[112:113], v[214:215]
	v_pk_mul_f32 v[224:225], v[114:115], v[216:217]
	v_cvt_pk_f32_fp8_e32 v[214:215], v190
	v_cvt_pk_f32_fp8_sdwa v[216:217], v190 src0_sel:WORD_1
	v_pk_fma_f32 v[222:223], v[116:117], v[218:219], v[222:223]
	v_pk_fma_f32 v[224:225], v[118:119], v[220:221], v[224:225]
	v_cvt_pk_f32_fp8_e32 v[218:219], v191
	v_cvt_pk_f32_fp8_sdwa v[220:221], v191 src0_sel:WORD_1
	v_pk_fma_f32 v[222:223], v[120:121], v[214:215], v[222:223]
	v_pk_fma_f32 v[224:225], v[122:123], v[216:217], v[224:225]
	v_pk_fma_f32 v[222:223], v[124:125], v[218:219], v[222:223]
	v_pk_fma_f32 v[224:225], v[126:127], v[220:221], v[224:225]
	v_pk_add_f32 v[222:223], v[222:223], v[224:225]
	s_nop 0
	v_add_f32_e32 v229, v222, v223
	v_cvt_pk_f32_fp8_e32 v[214:215], v192
	v_cvt_pk_f32_fp8_sdwa v[216:217], v192 src0_sel:WORD_1
	v_cvt_pk_f32_fp8_e32 v[218:219], v193
	v_cvt_pk_f32_fp8_sdwa v[220:221], v193 src0_sel:WORD_1
	v_pk_mul_f32 v[222:223], v[112:113], v[214:215]
	v_pk_mul_f32 v[224:225], v[114:115], v[216:217]
	v_cvt_pk_f32_fp8_e32 v[214:215], v194
	v_cvt_pk_f32_fp8_sdwa v[216:217], v194 src0_sel:WORD_1
	v_pk_fma_f32 v[222:223], v[116:117], v[218:219], v[222:223]
	v_pk_fma_f32 v[224:225], v[118:119], v[220:221], v[224:225]
	v_cvt_pk_f32_fp8_e32 v[218:219], v195
	v_cvt_pk_f32_fp8_sdwa v[220:221], v195 src0_sel:WORD_1
	v_pk_fma_f32 v[222:223], v[120:121], v[214:215], v[222:223]
	v_pk_fma_f32 v[224:225], v[122:123], v[216:217], v[224:225]
	v_pk_fma_f32 v[222:223], v[124:125], v[218:219], v[222:223]
	v_pk_fma_f32 v[224:225], v[126:127], v[220:221], v[224:225]
	v_pk_add_f32 v[222:223], v[222:223], v[224:225]
	s_nop 0
	v_add_f32_e32 v230, v222, v223
	v_cvt_pk_f32_fp8_e32 v[214:215], v196
	v_cvt_pk_f32_fp8_sdwa v[216:217], v196 src0_sel:WORD_1
	v_cvt_pk_f32_fp8_e32 v[218:219], v197
	v_cvt_pk_f32_fp8_sdwa v[220:221], v197 src0_sel:WORD_1
	v_pk_mul_f32 v[222:223], v[112:113], v[214:215]
	v_pk_mul_f32 v[224:225], v[114:115], v[216:217]
	v_cvt_pk_f32_fp8_e32 v[214:215], v198
	v_cvt_pk_f32_fp8_sdwa v[216:217], v198 src0_sel:WORD_1
	v_pk_fma_f32 v[222:223], v[116:117], v[218:219], v[222:223]
	v_pk_fma_f32 v[224:225], v[118:119], v[220:221], v[224:225]
	v_cvt_pk_f32_fp8_e32 v[218:219], v199
	v_cvt_pk_f32_fp8_sdwa v[220:221], v199 src0_sel:WORD_1
	v_pk_fma_f32 v[222:223], v[120:121], v[214:215], v[222:223]
	v_pk_fma_f32 v[224:225], v[122:123], v[216:217], v[224:225]
	v_pk_fma_f32 v[222:223], v[124:125], v[218:219], v[222:223]
	v_pk_fma_f32 v[224:225], v[126:127], v[220:221], v[224:225]
	v_pk_add_f32 v[222:223], v[222:223], v[224:225]
	s_nop 0
	v_add_f32_e32 v231, v222, v223
	v_cvt_pk_f32_fp8_e32 v[214:215], v200
; template <bool STORE>
; DI void peer_item(const Params& p, int item, char* smem) {
;     ...
;       for (int u = 0; u < 8; ++u) {
;         int e = e_s[tl * 128 + k + u];
;         uq[u] = *(const u32x4*)(U8 + (size_t)e * 1024 + lane * 16);
;       }
;       float part[8];
; #pragma unroll
;       for (int u = 0; u < 8; ++u) {
;         float d = 0.f;
; #pragma unroll
;         for (int i = 0; i < 4; ++i) {
;           f32x2_t lo = __builtin_amdgcn_cvt_pk_f32_fp8((int)uq[u][i], false);
;           f32x2_t hi = __builtin_amdgcn_cvt_pk_f32_fp8((int)uq[u][i], true);
;           d += xf[4 * i] * lo.x + xf[4 * i + 1] * lo.y + xf[4 * i + 2] * hi.x + xf[4 * i + 3] * hi.y;
;         }
;         part[u] = d;
;       }
;       float q4[4], r2[2], h;
; #pragma unroll
;       for (int j = 0; j < 4; ++j) {
;         float mine = b5 ? part[j + 4] : part[j];
;         float other = b5 ? part[j] : part[j + 4];
;         q4[j] = mine + __shfl_xor(other, 32);
;       }
; #pragma unroll
;       for (int j = 0; j < 2; ++j) {
;         float mine = b4 ? q4[j + 2] : q4[j];
;         float other = b4 ? q4[j] : q4[j + 2];
;         r2[j] = mine + __shfl_xor(other, 16);
;       }
;       {
;         float mine = b3 ? r2[1] : r2[0];
;         float other = b3 ? r2[0] : r2[1];
;         h = mine + __shfl_xor(other, 8);
;       }
;       h += __shfl_xor(h, 4);
;       h += __shfl_xor(h, 2);
;       h += __shfl_xor(h, 1);
	v_cvt_pk_f32_fp8_sdwa v[216:217], v200 src0_sel:WORD_1
	v_cvt_pk_f32_fp8_e32 v[218:219], v201
	v_cvt_pk_f32_fp8_sdwa v[220:221], v201 src0_sel:WORD_1
	v_pk_mul_f32 v[222:223], v[112:113], v[214:215]
	v_pk_mul_f32 v[224:225], v[114:115], v[216:217]
	v_cvt_pk_f32_fp8_e32 v[214:215], v202
	v_cvt_pk_f32_fp8_sdwa v[216:217], v202 src0_sel:WORD_1
	v_pk_fma_f32 v[222:223], v[116:117], v[218:219], v[222:223]
	v_pk_fma_f32 v[224:225], v[118:119], v[220:221], v[224:225]
	v_cvt_pk_f32_fp8_e32 v[218:219], v203
	v_cvt_pk_f32_fp8_sdwa v[220:221], v203 src0_sel:WORD_1
	v_pk_fma_f32 v[222:223], v[120:121], v[214:215], v[222:223]
	v_pk_fma_f32 v[224:225], v[122:123], v[216:217], v[224:225]
	v_pk_fma_f32 v[222:223], v[124:125], v[218:219], v[222:223]
	v_pk_fma_f32 v[224:225], v[126:127], v[220:221], v[224:225]
	v_pk_add_f32 v[222:223], v[222:223], v[224:225]
	s_nop 0
	v_add_f32_e32 v232, v222, v223
	v_cvt_pk_f32_fp8_e32 v[214:215], v204
	v_cvt_pk_f32_fp8_sdwa v[216:217], v204 src0_sel:WORD_1
	v_cvt_pk_f32_fp8_e32 v[218:219], v205
	v_cvt_pk_f32_fp8_sdwa v[220:221], v205 src0_sel:WORD_1
	v_pk_mul_f32 v[222:223], v[112:113], v[214:215]
	v_pk_mul_f32 v[224:225], v[114:115], v[216:217]
	v_cvt_pk_f32_fp8_e32 v[214:215], v206
	v_cvt_pk_f32_fp8_sdwa v[216:217], v206 src0_sel:WORD_1
	v_pk_fma_f32 v[222:223], v[116:117], v[218:219], v[222:223]
	v_pk_fma_f32 v[224:225], v[118:119], v[220:221], v[224:225]
	v_cvt_pk_f32_fp8_e32 v[218:219], v207
	v_cvt_pk_f32_fp8_sdwa v[220:221], v207 src0_sel:WORD_1
	v_pk_fma_f32 v[222:223], v[120:121], v[214:215], v[222:223]
	v_pk_fma_f32 v[224:225], v[122:123], v[216:217], v[224:225]
	v_pk_fma_f32 v[222:223], v[124:125], v[218:219], v[222:223]
	v_pk_fma_f32 v[224:225], v[126:127], v[220:221], v[224:225]
	v_pk_add_f32 v[222:223], v[222:223], v[224:225]
	s_nop 0
	v_add_f32_e32 v233, v222, v223
	v_permlane32_swap_b32_e32 v226, v230
	v_permlane32_swap_b32_e32 v227, v231
	v_permlane32_swap_b32_e32 v228, v232
	v_permlane32_swap_b32_e32 v229, v233
	v_add_f32_e32 v226, v226, v230
	v_add_f32_e32 v228, v228, v232
	v_add_f32_e32 v227, v227, v231
	v_add_f32_e32 v229, v229, v233
	s_nop 1
	v_permlane16_swap_b32_e32 v226, v228
	v_permlane16_swap_b32_e32 v227, v229
	v_add_f32_e32 v226, v226, v228
	v_add_f32_e32 v227, v227, v229
	s_nop 0
	v_cndmask_b32_e64 v230, v226, v227, s[24:25]
	v_cndmask_b32_e64 v231, v227, v226, s[24:25]
	s_nop 1
	v_add_f32_dpp v232, v231, v230 row_ror:8 row_mask:0xf bank_mask:0xf
	s_nop 1
	v_add_f32_dpp v233, v232, v232 quad_perm:[1,0,3,2] row_mask:0xf bank_mask:0xf
	s_nop 1
	v_add_f32_dpp v232, v233, v233 quad_perm:[2,3,0,1] row_mask:0xf bank_mask:0xf
	s_nop 1
	v_add_f32_dpp v233, v232, v232 row_half_mirror row_mask:0xf bank_mask:0xf
	ds_write_b32 v235, v233 offset:36352
	v_readlane_b32 s48, v131, s72
	v_readlane_b32 s49, v131, s73
	v_readlane_b32 s50, v131, s74
	v_readlane_b32 s51, v131, s75
	v_readlane_b32 s52, v131, s76
	v_readlane_b32 s53, v131, s77
	v_readlane_b32 s54, v131, s78
	v_readlane_b32 s55, v131, s79
	s_add_u32 s32, s0, s48
	s_addc_u32 s33, s1, 0
	s_add_u32 s34, s0, s49
	s_addc_u32 s35, s1, 0
	s_add_u32 s36, s0, s50
	s_addc_u32 s37, s1, 0
	s_add_u32 s38, s0, s51
	s_addc_u32 s39, s1, 0
	s_add_u32 s40, s0, s52
	s_addc_u32 s41, s1, 0
	s_add_u32 s42, s0, s53
	s_addc_u32 s43, s1, 0
	s_add_u32 s44, s0, s54
	s_addc_u32 s45, s1, 0
	s_add_u32 s46, s0, s55
	s_addc_u32 s47, s1, 0
	global_load_dwordx4 v[176:179], v234, s[32:33]
	global_load_dwordx4 v[180:183], v234, s[34:35]
	global_load_dwordx4 v[184:187], v234, s[36:37]
	global_load_dwordx4 v[188:191], v234, s[38:39]
	global_load_dwordx4 v[192:195], v234, s[40:41]
	global_load_dwordx4 v[196:199], v234, s[42:43]
	global_load_dwordx4 v[200:203], v234, s[44:45]
	global_load_dwordx4 v[204:207], v234, s[46:47]
	s_waitcnt vmcnt(8)
	v_cvt_pk_f32_fp8_e32 v[214:215], v144
	v_cvt_pk_f32_fp8_sdwa v[216:217], v144 src0_sel:WORD_1
	v_cvt_pk_f32_fp8_e32 v[218:219], v145
	v_cvt_pk_f32_fp8_sdwa v[220:221], v145 src0_sel:WORD_1
	v_pk_mul_f32 v[222:223], v[0:1], v[214:215]
	v_pk_mul_f32 v[224:225], v[2:3], v[216:217]
	v_cvt_pk_f32_fp8_e32 v[214:215], v146
	v_cvt_pk_f32_fp8_sdwa v[216:217], v146 src0_sel:WORD_1
	v_pk_fma_f32 v[222:223], v[4:5], v[218:219], v[222:223]
	v_pk_fma_f32 v[224:225], v[6:7], v[220:221], v[224:225]
	v_cvt_pk_f32_fp8_e32 v[218:219], v147
	v_cvt_pk_f32_fp8_sdwa v[220:221], v147 src0_sel:WORD_1
	v_pk_fma_f32 v[222:223], v[8:9], v[214:215], v[222:223]
	v_pk_fma_f32 v[224:225], v[10:11], v[216:217], v[224:225]
	v_pk_fma_f32 v[222:223], v[12:13], v[218:219], v[222:223]
	v_pk_fma_f32 v[224:225], v[14:15], v[220:221], v[224:225]
	v_pk_add_f32 v[222:223], v[222:223], v[224:225]
	s_nop 0
	v_add_f32_e32 v226, v222, v223
	v_cvt_pk_f32_fp8_e32 v[214:215], v148
	v_cvt_pk_f32_fp8_sdwa v[216:217], v148 src0_sel:WORD_1
	v_cvt_pk_f32_fp8_e32 v[218:219], v149
	v_cvt_pk_f32_fp8_sdwa v[220:221], v149 src0_sel:WORD_1
	v_pk_mul_f32 v[222:223], v[0:1], v[214:215]
	v_pk_mul_f32 v[224:225], v[2:3], v[216:217]
	v_cvt_pk_f32_fp8_e32 v[214:215], v150
	v_cvt_pk_f32_fp8_sdwa v[216:217], v150 src0_sel:WORD_1
	v_pk_fma_f32 v[222:223], v[4:5], v[218:219], v[222:223]
	v_pk_fma_f32 v[224:225], v[6:7], v[220:221], v[224:225]
	v_cvt_pk_f32_fp8_e32 v[218:219], v151
	v_cvt_pk_f32_fp8_sdwa v[220:221], v151 src0_sel:WORD_1
	v_pk_fma_f32 v[222:223], v[8:9], v[214:215], v[222:223]
	v_pk_fma_f32 v[224:225], v[10:11], v[216:217], v[224:225]
	v_pk_fma_f32 v[222:223], v[12:13], v[218:219], v[222:223]
	v_pk_fma_f32 v[224:225], v[14:15], v[220:221], v[224:225]
	v_pk_add_f32 v[222:223], v[222:223], v[224:225]
	s_nop 0
	v_add_f32_e32 v227, v222, v223
	v_cvt_pk_f32_fp8_e32 v[214:215], v152
; template <bool STORE>
; DI void peer_item(const Params& p, int item, char* smem) {
;     ...
;       for (int u = 0; u < 8; ++u) {
;         int e = e_s[tl * 128 + k + u];
;         uq[u] = *(const u32x4*)(U8 + (size_t)e * 1024 + lane * 16);
;       }
;       float part[8];
; #pragma unroll
;       for (int u = 0; u < 8; ++u) {
;         float d = 0.f;
; #pragma unroll
;         for (int i = 0; i < 4; ++i) {
;           f32x2_t lo = __builtin_amdgcn_cvt_pk_f32_fp8((int)uq[u][i], false);
;           f32x2_t hi = __builtin_amdgcn_cvt_pk_f32_fp8((int)uq[u][i], true);
;           d += xf[4 * i] * lo.x + xf[4 * i + 1] * lo.y + xf[4 * i + 2] * hi.x + xf[4 * i + 3] * hi.y;
;         }
;         part[u] = d;
;       }
;       float q4[4], r2[2], h;
; #pragma unroll
;       for (int j = 0; j < 4; ++j) {
;         float mine = b5 ? part[j + 4] : part[j];
;         float other = b5 ? part[j] : part[j + 4];
;         q4[j] = mine + __shfl_xor(other, 32);
;       }
; #pragma unroll
;       for (int j = 0; j < 2; ++j) {
;         float mine = b4 ? q4[j + 2] : q4[j];
;         float other = b4 ? q4[j] : q4[j + 2];
;         r2[j] = mine + __shfl_xor(other, 16);
;       }
;       {
;         float mine = b3 ? r2[1] : r2[0];
;         float other = b3 ? r2[0] : r2[1];
;         h = mine + __shfl_xor(other, 8);
;       }
;       h += __shfl_xor(h, 4);
;       h += __shfl_xor(h, 2);
;       h += __shfl_xor(h, 1);
	v_cvt_pk_f32_fp8_sdwa v[216:217], v152 src0_sel:WORD_1
	v_cvt_pk_f32_fp8_e32 v[218:219], v153
	v_cvt_pk_f32_fp8_sdwa v[220:221], v153 src0_sel:WORD_1
	v_pk_mul_f32 v[222:223], v[0:1], v[214:215]
	v_pk_mul_f32 v[224:225], v[2:3], v[216:217]
	v_cvt_pk_f32_fp8_e32 v[214:215], v154
	v_cvt_pk_f32_fp8_sdwa v[216:217], v154 src0_sel:WORD_1
	v_pk_fma_f32 v[222:223], v[4:5], v[218:219], v[222:223]
	v_pk_fma_f32 v[224:225], v[6:7], v[220:221], v[224:225]
	v_cvt_pk_f32_fp8_e32 v[218:219], v155
	v_cvt_pk_f32_fp8_sdwa v[220:221], v155 src0_sel:WORD_1
	v_pk_fma_f32 v[222:223], v[8:9], v[214:215], v[222:223]
	v_pk_fma_f32 v[224:225], v[10:11], v[216:217], v[224:225]
	v_pk_fma_f32 v[222:223], v[12:13], v[218:219], v[222:223]
	v_pk_fma_f32 v[224:225], v[14:15], v[220:221], v[224:225]
	v_pk_add_f32 v[222:223], v[222:223], v[224:225]
	s_nop 0
	v_add_f32_e32 v228, v222, v223
	v_cvt_pk_f32_fp8_e32 v[214:215], v156
	v_cvt_pk_f32_fp8_sdwa v[216:217], v156 src0_sel:WORD_1
	v_cvt_pk_f32_fp8_e32 v[218:219], v157
	v_cvt_pk_f32_fp8_sdwa v[220:221], v157 src0_sel:WORD_1
	v_pk_mul_f32 v[222:223], v[0:1], v[214:215]
	v_pk_mul_f32 v[224:225], v[2:3], v[216:217]
	v_cvt_pk_f32_fp8_e32 v[214:215], v158
	v_cvt_pk_f32_fp8_sdwa v[216:217], v158 src0_sel:WORD_1
	v_pk_fma_f32 v[222:223], v[4:5], v[218:219], v[222:223]
	v_pk_fma_f32 v[224:225], v[6:7], v[220:221], v[224:225]
	v_cvt_pk_f32_fp8_e32 v[218:219], v159
	v_cvt_pk_f32_fp8_sdwa v[220:221], v159 src0_sel:WORD_1
	v_pk_fma_f32 v[222:223], v[8:9], v[214:215], v[222:223]
	v_pk_fma_f32 v[224:225], v[10:11], v[216:217], v[224:225]
	v_pk_fma_f32 v[222:223], v[12:13], v[218:219], v[222:223]
	v_pk_fma_f32 v[224:225], v[14:15], v[220:221], v[224:225]
	v_pk_add_f32 v[222:223], v[222:223], v[224:225]
	s_nop 0
	v_add_f32_e32 v229, v222, v223
	v_cvt_pk_f32_fp8_e32 v[214:215], v160
	v_cvt_pk_f32_fp8_sdwa v[216:217], v160 src0_sel:WORD_1
	v_cvt_pk_f32_fp8_e32 v[218:219], v161
	v_cvt_pk_f32_fp8_sdwa v[220:221], v161 src0_sel:WORD_1
	v_pk_mul_f32 v[222:223], v[0:1], v[214:215]
	v_pk_mul_f32 v[224:225], v[2:3], v[216:217]
	v_cvt_pk_f32_fp8_e32 v[214:215], v162
	v_cvt_pk_f32_fp8_sdwa v[216:217], v162 src0_sel:WORD_1
	v_pk_fma_f32 v[222:223], v[4:5], v[218:219], v[222:223]
	v_pk_fma_f32 v[224:225], v[6:7], v[220:221], v[224:225]
	v_cvt_pk_f32_fp8_e32 v[218:219], v163
	v_cvt_pk_f32_fp8_sdwa v[220:221], v163 src0_sel:WORD_1
	v_pk_fma_f32 v[222:223], v[8:9], v[214:215], v[222:223]
	v_pk_fma_f32 v[224:225], v[10:11], v[216:217], v[224:225]
	v_pk_fma_f32 v[222:223], v[12:13], v[218:219], v[222:223]
	v_pk_fma_f32 v[224:225], v[14:15], v[220:221], v[224:225]
	v_pk_add_f32 v[222:223], v[222:223], v[224:225]
	s_nop 0
	v_add_f32_e32 v230, v222, v223
	v_cvt_pk_f32_fp8_e32 v[214:215], v164
	v_cvt_pk_f32_fp8_sdwa v[216:217], v164 src0_sel:WORD_1
	v_cvt_pk_f32_fp8_e32 v[218:219], v165
	v_cvt_pk_f32_fp8_sdwa v[220:221], v165 src0_sel:WORD_1
	v_pk_mul_f32 v[222:223], v[0:1], v[214:215]
	v_pk_mul_f32 v[224:225], v[2:3], v[216:217]
	v_cvt_pk_f32_fp8_e32 v[214:215], v166
	v_cvt_pk_f32_fp8_sdwa v[216:217], v166 src0_sel:WORD_1
	v_pk_fma_f32 v[222:223], v[4:5], v[218:219], v[222:223]
	v_pk_fma_f32 v[224:225], v[6:7], v[220:221], v[224:225]
	v_cvt_pk_f32_fp8_e32 v[218:219], v167
	v_cvt_pk_f32_fp8_sdwa v[220:221], v167 src0_sel:WORD_1
	v_pk_fma_f32 v[222:223], v[8:9], v[214:215], v[222:223]
	v_pk_fma_f32 v[224:225], v[10:11], v[216:217], v[224:225]
	v_pk_fma_f32 v[222:223], v[12:13], v[218:219], v[222:223]
	v_pk_fma_f32 v[224:225], v[14:15], v[220:221], v[224:225]
	v_pk_add_f32 v[222:223], v[222:223], v[224:225]
	s_nop 0
	v_add_f32_e32 v231, v222, v223
	v_cvt_pk_f32_fp8_e32 v[214:215], v168
	v_cvt_pk_f32_fp8_sdwa v[216:217], v168 src0_sel:WORD_1
	v_cvt_pk_f32_fp8_e32 v[218:219], v169
	v_cvt_pk_f32_fp8_sdwa v[220:221], v169 src0_sel:WORD_1
	v_pk_mul_f32 v[222:223], v[0:1], v[214:215]
	v_pk_mul_f32 v[224:225], v[2:3], v[216:217]
	v_cvt_pk_f32_fp8_e32 v[214:215], v170
	v_cvt_pk_f32_fp8_sdwa v[216:217], v170 src0_sel:WORD_1
	v_pk_fma_f32 v[222:223], v[4:5], v[218:219], v[222:223]
	v_pk_fma_f32 v[224:225], v[6:7], v[220:221], v[224:225]
	v_cvt_pk_f32_fp8_e32 v[218:219], v171
	v_cvt_pk_f32_fp8_sdwa v[220:221], v171 src0_sel:WORD_1
	v_pk_fma_f32 v[222:223], v[8:9], v[214:215], v[222:223]
	v_pk_fma_f32 v[224:225], v[10:11], v[216:217], v[224:225]
	v_pk_fma_f32 v[222:223], v[12:13], v[218:219], v[222:223]
	v_pk_fma_f32 v[224:225], v[14:15], v[220:221], v[224:225]
	v_pk_add_f32 v[222:223], v[222:223], v[224:225]
	s_nop 0
	v_add_f32_e32 v232, v222, v223
	v_cvt_pk_f32_fp8_e32 v[214:215], v172
	v_cvt_pk_f32_fp8_sdwa v[216:217], v172 src0_sel:WORD_1
	v_cvt_pk_f32_fp8_e32 v[218:219], v173
	v_cvt_pk_f32_fp8_sdwa v[220:221], v173 src0_sel:WORD_1
	v_pk_mul_f32 v[222:223], v[0:1], v[214:215]
	v_pk_mul_f32 v[224:225], v[2:3], v[216:217]
	v_cvt_pk_f32_fp8_e32 v[214:215], v174
	v_cvt_pk_f32_fp8_sdwa v[216:217], v174 src0_sel:WORD_1
	v_pk_fma_f32 v[222:223], v[4:5], v[218:219], v[222:223]
	v_pk_fma_f32 v[224:225], v[6:7], v[220:221], v[224:225]
	v_cvt_pk_f32_fp8_e32 v[218:219], v175
	v_cvt_pk_f32_fp8_sdwa v[220:221], v175 src0_sel:WORD_1
	v_pk_fma_f32 v[222:223], v[8:9], v[214:215], v[222:223]
	v_pk_fma_f32 v[224:225], v[10:11], v[216:217], v[224:225]
	v_pk_fma_f32 v[222:223], v[12:13], v[218:219], v[222:223]
	v_pk_fma_f32 v[224:225], v[14:15], v[220:221], v[224:225]
	v_pk_add_f32 v[222:223], v[222:223], v[224:225]
	s_nop 0
	v_add_f32_e32 v233, v222, v223
	v_permlane32_swap_b32_e32 v226, v230
	v_permlane32_swap_b32_e32 v227, v231
	v_permlane32_swap_b32_e32 v228, v232
	v_permlane32_swap_b32_e32 v229, v233
	v_add_f32_e32 v226, v226, v230
	v_add_f32_e32 v228, v228, v232
; template <bool STORE>
; DI void peer_item(const Params& p, int item, char* smem) {
;     ...
;       for (int u = 0; u < 8; ++u) {
;         int e = e_s[tl * 128 + k + u];
;         uq[u] = *(const u32x4*)(U8 + (size_t)e * 1024 + lane * 16);
;       }
;       float part[8];
; #pragma unroll
;       for (int u = 0; u < 8; ++u) {
;         float d = 0.f;
; #pragma unroll
;         for (int i = 0; i < 4; ++i) {
;           f32x2_t lo = __builtin_amdgcn_cvt_pk_f32_fp8((int)uq[u][i], false);
;           f32x2_t hi = __builtin_amdgcn_cvt_pk_f32_fp8((int)uq[u][i], true);
;           d += xf[4 * i] * lo.x + xf[4 * i + 1] * lo.y + xf[4 * i + 2] * hi.x + xf[4 * i + 3] * hi.y;
;         }
;         part[u] = d;
;       }
;       float q4[4], r2[2], h;
; #pragma unroll
;       for (int j = 0; j < 4; ++j) {
;         float mine = b5 ? part[j + 4] : part[j];
;         float other = b5 ? part[j] : part[j + 4];
;         q4[j] = mine + __shfl_xor(other, 32);
;       }
; #pragma unroll
;       for (int j = 0; j < 2; ++j) {
;         float mine = b4 ? q4[j + 2] : q4[j];
;         float other = b4 ? q4[j] : q4[j + 2];
;         r2[j] = mine + __shfl_xor(other, 16);
;       }
;       {
;         float mine = b3 ? r2[1] : r2[0];
;         float other = b3 ? r2[0] : r2[1];
;         h = mine + __shfl_xor(other, 8);
;       }
;       h += __shfl_xor(h, 4);
;       h += __shfl_xor(h, 2);
;       h += __shfl_xor(h, 1);
	v_add_f32_e32 v227, v227, v231
	v_add_f32_e32 v229, v229, v233
	s_nop 1
	v_permlane16_swap_b32_e32 v226, v228
	v_permlane16_swap_b32_e32 v227, v229
	v_add_f32_e32 v226, v226, v228
	v_add_f32_e32 v227, v227, v229
	s_nop 0
	v_cndmask_b32_e64 v230, v226, v227, s[24:25]
	v_cndmask_b32_e64 v231, v227, v226, s[24:25]
	s_nop 1
	v_add_f32_dpp v232, v231, v230 row_ror:8 row_mask:0xf bank_mask:0xf
	s_nop 1
	v_add_f32_dpp v233, v232, v232 quad_perm:[1,0,3,2] row_mask:0xf bank_mask:0xf
	s_nop 1
	v_add_f32_dpp v232, v233, v233 quad_perm:[2,3,0,1] row_mask:0xf bank_mask:0xf
	s_nop 1
	v_add_f32_dpp v233, v232, v232 row_half_mirror row_mask:0xf bank_mask:0xf
	ds_write_b32 v235, v233 offset:32800
	v_readlane_b32 s48, v133, s72
	v_readlane_b32 s49, v133, s73
	v_readlane_b32 s50, v133, s74
	v_readlane_b32 s51, v133, s75
	v_readlane_b32 s52, v133, s76
	v_readlane_b32 s53, v133, s77
	v_readlane_b32 s54, v133, s78
	v_readlane_b32 s55, v133, s79
	s_add_u32 s32, s0, s48
	s_addc_u32 s33, s1, 0
	s_add_u32 s34, s0, s49
	s_addc_u32 s35, s1, 0
	s_add_u32 s36, s0, s50
	s_addc_u32 s37, s1, 0
	s_add_u32 s38, s0, s51
	s_addc_u32 s39, s1, 0
	s_add_u32 s40, s0, s52
	s_addc_u32 s41, s1, 0
	s_add_u32 s42, s0, s53
	s_addc_u32 s43, s1, 0
	s_add_u32 s44, s0, s54
	s_addc_u32 s45, s1, 0
	s_add_u32 s46, s0, s55
	s_addc_u32 s47, s1, 0
	global_load_dwordx4 v[144:147], v234, s[32:33]
	global_load_dwordx4 v[148:151], v234, s[34:35]
	global_load_dwordx4 v[152:155], v234, s[36:37]
	global_load_dwordx4 v[156:159], v234, s[38:39]
	global_load_dwordx4 v[160:163], v234, s[40:41]
	global_load_dwordx4 v[164:167], v234, s[42:43]
	global_load_dwordx4 v[168:171], v234, s[44:45]
	global_load_dwordx4 v[172:175], v234, s[46:47]
	s_waitcnt vmcnt(8)
	v_cvt_pk_f32_fp8_e32 v[214:215], v176
	v_cvt_pk_f32_fp8_sdwa v[216:217], v176 src0_sel:WORD_1
	v_cvt_pk_f32_fp8_e32 v[218:219], v177
	v_cvt_pk_f32_fp8_sdwa v[220:221], v177 src0_sel:WORD_1
	v_pk_mul_f32 v[222:223], v[16:17], v[214:215]
	v_pk_mul_f32 v[224:225], v[18:19], v[216:217]
	v_cvt_pk_f32_fp8_e32 v[214:215], v178
	v_cvt_pk_f32_fp8_sdwa v[216:217], v178 src0_sel:WORD_1
	v_pk_fma_f32 v[222:223], v[20:21], v[218:219], v[222:223]
	v_pk_fma_f32 v[224:225], v[22:23], v[220:221], v[224:225]
	v_cvt_pk_f32_fp8_e32 v[218:219], v179
	v_cvt_pk_f32_fp8_sdwa v[220:221], v179 src0_sel:WORD_1
	v_pk_fma_f32 v[222:223], v[24:25], v[214:215], v[222:223]
	v_pk_fma_f32 v[224:225], v[26:27], v[216:217], v[224:225]
	v_pk_fma_f32 v[222:223], v[28:29], v[218:219], v[222:223]
	v_pk_fma_f32 v[224:225], v[30:31], v[220:221], v[224:225]
	v_pk_add_f32 v[222:223], v[222:223], v[224:225]
	s_nop 0
	v_add_f32_e32 v226, v222, v223
	v_cvt_pk_f32_fp8_e32 v[214:215], v180
	v_cvt_pk_f32_fp8_sdwa v[216:217], v180 src0_sel:WORD_1
	v_cvt_pk_f32_fp8_e32 v[218:219], v181
	v_cvt_pk_f32_fp8_sdwa v[220:221], v181 src0_sel:WORD_1
	v_pk_mul_f32 v[222:223], v[16:17], v[214:215]
	v_pk_mul_f32 v[224:225], v[18:19], v[216:217]
	v_cvt_pk_f32_fp8_e32 v[214:215], v182
	v_cvt_pk_f32_fp8_sdwa v[216:217], v182 src0_sel:WORD_1
	v_pk_fma_f32 v[222:223], v[20:21], v[218:219], v[222:223]
	v_pk_fma_f32 v[224:225], v[22:23], v[220:221], v[224:225]
	v_cvt_pk_f32_fp8_e32 v[218:219], v183
	v_cvt_pk_f32_fp8_sdwa v[220:221], v183 src0_sel:WORD_1
	v_pk_fma_f32 v[222:223], v[24:25], v[214:215], v[222:223]
	v_pk_fma_f32 v[224:225], v[26:27], v[216:217], v[224:225]
	v_pk_fma_f32 v[222:223], v[28:29], v[218:219], v[222:223]
	v_pk_fma_f32 v[224:225], v[30:31], v[220:221], v[224:225]
	v_pk_add_f32 v[222:223], v[222:223], v[224:225]
	s_nop 0
	v_add_f32_e32 v227, v222, v223
	v_cvt_pk_f32_fp8_e32 v[214:215], v184
	v_cvt_pk_f32_fp8_sdwa v[216:217], v184 src0_sel:WORD_1
	v_cvt_pk_f32_fp8_e32 v[218:219], v185
	v_cvt_pk_f32_fp8_sdwa v[220:221], v185 src0_sel:WORD_1
	v_pk_mul_f32 v[222:223], v[16:17], v[214:215]
	v_pk_mul_f32 v[224:225], v[18:19], v[216:217]
	v_cvt_pk_f32_fp8_e32 v[214:215], v186
	v_cvt_pk_f32_fp8_sdwa v[216:217], v186 src0_sel:WORD_1
	v_pk_fma_f32 v[222:223], v[20:21], v[218:219], v[222:223]
	v_pk_fma_f32 v[224:225], v[22:23], v[220:221], v[224:225]
	v_cvt_pk_f32_fp8_e32 v[218:219], v187
	v_cvt_pk_f32_fp8_sdwa v[220:221], v187 src0_sel:WORD_1
	v_pk_fma_f32 v[222:223], v[24:25], v[214:215], v[222:223]
	v_pk_fma_f32 v[224:225], v[26:27], v[216:217], v[224:225]
	v_pk_fma_f32 v[222:223], v[28:29], v[218:219], v[222:223]
	v_pk_fma_f32 v[224:225], v[30:31], v[220:221], v[224:225]
	v_pk_add_f32 v[222:223], v[222:223], v[224:225]
	s_nop 0
	v_add_f32_e32 v228, v222, v223
	v_cvt_pk_f32_fp8_e32 v[214:215], v188
	v_cvt_pk_f32_fp8_sdwa v[216:217], v188 src0_sel:WORD_1
	v_cvt_pk_f32_fp8_e32 v[218:219], v189
	v_cvt_pk_f32_fp8_sdwa v[220:221], v189 src0_sel:WORD_1
	v_pk_mul_f32 v[222:223], v[16:17], v[214:215]
	v_pk_mul_f32 v[224:225], v[18:19], v[216:217]
	v_cvt_pk_f32_fp8_e32 v[214:215], v190
	v_cvt_pk_f32_fp8_sdwa v[216:217], v190 src0_sel:WORD_1
	v_pk_fma_f32 v[222:223], v[20:21], v[218:219], v[222:223]
	v_pk_fma_f32 v[224:225], v[22:23], v[220:221], v[224:225]
	v_cvt_pk_f32_fp8_e32 v[218:219], v191
	v_cvt_pk_f32_fp8_sdwa v[220:221], v191 src0_sel:WORD_1
	v_pk_fma_f32 v[222:223], v[24:25], v[214:215], v[222:223]
	v_pk_fma_f32 v[224:225], v[26:27], v[216:217], v[224:225]
	v_pk_fma_f32 v[222:223], v[28:29], v[218:219], v[222:223]
	v_pk_fma_f32 v[224:225], v[30:31], v[220:221], v[224:225]
	v_pk_add_f32 v[222:223], v[222:223], v[224:225]
	s_nop 0
	v_add_f32_e32 v229, v222, v223
	v_cvt_pk_f32_fp8_e32 v[214:215], v192
	v_cvt_pk_f32_fp8_sdwa v[216:217], v192 src0_sel:WORD_1
	v_cvt_pk_f32_fp8_e32 v[218:219], v193
	v_cvt_pk_f32_fp8_sdwa v[220:221], v193 src0_sel:WORD_1
	v_pk_mul_f32 v[222:223], v[16:17], v[214:215]
; template <bool STORE>
; DI void peer_item(const Params& p, int item, char* smem) {
;     ...
;       for (int u = 0; u < 8; ++u) {
;         int e = e_s[tl * 128 + k + u];
;         uq[u] = *(const u32x4*)(U8 + (size_t)e * 1024 + lane * 16);
;       }
;       float part[8];
; #pragma unroll
;       for (int u = 0; u < 8; ++u) {
;         float d = 0.f;
; #pragma unroll
;         for (int i = 0; i < 4; ++i) {
;           f32x2_t lo = __builtin_amdgcn_cvt_pk_f32_fp8((int)uq[u][i], false);
;           f32x2_t hi = __builtin_amdgcn_cvt_pk_f32_fp8((int)uq[u][i], true);
;           d += xf[4 * i] * lo.x + xf[4 * i + 1] * lo.y + xf[4 * i + 2] * hi.x + xf[4 * i + 3] * hi.y;
;         }
;         part[u] = d;
;       }
;       float q4[4], r2[2], h;
; #pragma unroll
;       for (int j = 0; j < 4; ++j) {
;         float mine = b5 ? part[j + 4] : part[j];
;         float other = b5 ? part[j] : part[j + 4];
;         q4[j] = mine + __shfl_xor(other, 32);
;       }
; #pragma unroll
;       for (int j = 0; j < 2; ++j) {
;         float mine = b4 ? q4[j + 2] : q4[j];
;         float other = b4 ? q4[j] : q4[j + 2];
;         r2[j] = mine + __shfl_xor(other, 16);
;       }
;       {
;         float mine = b3 ? r2[1] : r2[0];
;         float other = b3 ? r2[0] : r2[1];
;         h = mine + __shfl_xor(other, 8);
;       }
;       h += __shfl_xor(h, 4);
;       h += __shfl_xor(h, 2);
;       h += __shfl_xor(h, 1);
	v_pk_mul_f32 v[224:225], v[18:19], v[216:217]
	v_cvt_pk_f32_fp8_e32 v[214:215], v194
	v_cvt_pk_f32_fp8_sdwa v[216:217], v194 src0_sel:WORD_1
	v_pk_fma_f32 v[222:223], v[20:21], v[218:219], v[222:223]
	v_pk_fma_f32 v[224:225], v[22:23], v[220:221], v[224:225]
	v_cvt_pk_f32_fp8_e32 v[218:219], v195
	v_cvt_pk_f32_fp8_sdwa v[220:221], v195 src0_sel:WORD_1
	v_pk_fma_f32 v[222:223], v[24:25], v[214:215], v[222:223]
	v_pk_fma_f32 v[224:225], v[26:27], v[216:217], v[224:225]
	v_pk_fma_f32 v[222:223], v[28:29], v[218:219], v[222:223]
	v_pk_fma_f32 v[224:225], v[30:31], v[220:221], v[224:225]
	v_pk_add_f32 v[222:223], v[222:223], v[224:225]
	s_nop 0
	v_add_f32_e32 v230, v222, v223
	v_cvt_pk_f32_fp8_e32 v[214:215], v196
	v_cvt_pk_f32_fp8_sdwa v[216:217], v196 src0_sel:WORD_1
	v_cvt_pk_f32_fp8_e32 v[218:219], v197
	v_cvt_pk_f32_fp8_sdwa v[220:221], v197 src0_sel:WORD_1
	v_pk_mul_f32 v[222:223], v[16:17], v[214:215]
	v_pk_mul_f32 v[224:225], v[18:19], v[216:217]
	v_cvt_pk_f32_fp8_e32 v[214:215], v198
	v_cvt_pk_f32_fp8_sdwa v[216:217], v198 src0_sel:WORD_1
	v_pk_fma_f32 v[222:223], v[20:21], v[218:219], v[222:223]
	v_pk_fma_f32 v[224:225], v[22:23], v[220:221], v[224:225]
	v_cvt_pk_f32_fp8_e32 v[218:219], v199
	v_cvt_pk_f32_fp8_sdwa v[220:221], v199 src0_sel:WORD_1
	v_pk_fma_f32 v[222:223], v[24:25], v[214:215], v[222:223]
	v_pk_fma_f32 v[224:225], v[26:27], v[216:217], v[224:225]
	v_pk_fma_f32 v[222:223], v[28:29], v[218:219], v[222:223]
	v_pk_fma_f32 v[224:225], v[30:31], v[220:221], v[224:225]
	v_pk_add_f32 v[222:223], v[222:223], v[224:225]
	s_nop 0
	v_add_f32_e32 v231, v222, v223
	v_cvt_pk_f32_fp8_e32 v[214:215], v200
	v_cvt_pk_f32_fp8_sdwa v[216:217], v200 src0_sel:WORD_1
	v_cvt_pk_f32_fp8_e32 v[218:219], v201
	v_cvt_pk_f32_fp8_sdwa v[220:221], v201 src0_sel:WORD_1
	v_pk_mul_f32 v[222:223], v[16:17], v[214:215]
	v_pk_mul_f32 v[224:225], v[18:19], v[216:217]
	v_cvt_pk_f32_fp8_e32 v[214:215], v202
	v_cvt_pk_f32_fp8_sdwa v[216:217], v202 src0_sel:WORD_1
	v_pk_fma_f32 v[222:223], v[20:21], v[218:219], v[222:223]
	v_pk_fma_f32 v[224:225], v[22:23], v[220:221], v[224:225]
	v_cvt_pk_f32_fp8_e32 v[218:219], v203
	v_cvt_pk_f32_fp8_sdwa v[220:221], v203 src0_sel:WORD_1
	v_pk_fma_f32 v[222:223], v[24:25], v[214:215], v[222:223]
	v_pk_fma_f32 v[224:225], v[26:27], v[216:217], v[224:225]
	v_pk_fma_f32 v[222:223], v[28:29], v[218:219], v[222:223]
	v_pk_fma_f32 v[224:225], v[30:31], v[220:221], v[224:225]
	v_pk_add_f32 v[222:223], v[222:223], v[224:225]
	s_nop 0
	v_add_f32_e32 v232, v222, v223
	v_cvt_pk_f32_fp8_e32 v[214:215], v204
	v_cvt_pk_f32_fp8_sdwa v[216:217], v204 src0_sel:WORD_1
	v_cvt_pk_f32_fp8_e32 v[218:219], v205
	v_cvt_pk_f32_fp8_sdwa v[220:221], v205 src0_sel:WORD_1
	v_pk_mul_f32 v[222:223], v[16:17], v[214:215]
	v_pk_mul_f32 v[224:225], v[18:19], v[216:217]
	v_cvt_pk_f32_fp8_e32 v[214:215], v206
	v_cvt_pk_f32_fp8_sdwa v[216:217], v206 src0_sel:WORD_1
	v_pk_fma_f32 v[222:223], v[20:21], v[218:219], v[222:223]
	v_pk_fma_f32 v[224:225], v[22:23], v[220:221], v[224:225]
	v_cvt_pk_f32_fp8_e32 v[218:219], v207
	v_cvt_pk_f32_fp8_sdwa v[220:221], v207 src0_sel:WORD_1
	v_pk_fma_f32 v[222:223], v[24:25], v[214:215], v[222:223]
	v_pk_fma_f32 v[224:225], v[26:27], v[216:217], v[224:225]
	v_pk_fma_f32 v[222:223], v[28:29], v[218:219], v[222:223]
	v_pk_fma_f32 v[224:225], v[30:31], v[220:221], v[224:225]
	v_pk_add_f32 v[222:223], v[222:223], v[224:225]
	s_nop 0
	v_add_f32_e32 v233, v222, v223
	v_permlane32_swap_b32_e32 v226, v230
	v_permlane32_swap_b32_e32 v227, v231
	v_permlane32_swap_b32_e32 v228, v232
	v_permlane32_swap_b32_e32 v229, v233
	v_add_f32_e32 v226, v226, v230
	v_add_f32_e32 v228, v228, v232
	v_add_f32_e32 v227, v227, v231
	v_add_f32_e32 v229, v229, v233
	s_nop 1
	v_permlane16_swap_b32_e32 v226, v228
	v_permlane16_swap_b32_e32 v227, v229
	v_add_f32_e32 v226, v226, v228
	v_add_f32_e32 v227, v227, v229
	s_nop 0
	v_cndmask_b32_e64 v230, v226, v227, s[24:25]
	v_cndmask_b32_e64 v231, v227, v226, s[24:25]
	s_nop 1
	v_add_f32_dpp v232, v231, v230 row_ror:8 row_mask:0xf bank_mask:0xf
	s_nop 1
	v_add_f32_dpp v233, v232, v232 quad_perm:[1,0,3,2] row_mask:0xf bank_mask:0xf
	s_nop 1
	v_add_f32_dpp v232, v233, v233 quad_perm:[2,3,0,1] row_mask:0xf bank_mask:0xf
	s_nop 1
	v_add_f32_dpp v233, v232, v232 row_half_mirror row_mask:0xf bank_mask:0xf
	ds_write_b32 v235, v233 offset:33312
	v_readlane_b32 s48, v135, s72
	v_readlane_b32 s49, v135, s73
	v_readlane_b32 s50, v135, s74
	v_readlane_b32 s51, v135, s75
	v_readlane_b32 s52, v135, s76
	v_readlane_b32 s53, v135, s77
	v_readlane_b32 s54, v135, s78
	v_readlane_b32 s55, v135, s79
	s_add_u32 s32, s0, s48
	s_addc_u32 s33, s1, 0
	s_add_u32 s34, s0, s49
	s_addc_u32 s35, s1, 0
	s_add_u32 s36, s0, s50
	s_addc_u32 s37, s1, 0
	s_add_u32 s38, s0, s51
	s_addc_u32 s39, s1, 0
	s_add_u32 s40, s0, s52
	s_addc_u32 s41, s1, 0
	s_add_u32 s42, s0, s53
	s_addc_u32 s43, s1, 0
	s_add_u32 s44, s0, s54
	s_addc_u32 s45, s1, 0
	s_add_u32 s46, s0, s55
	s_addc_u32 s47, s1, 0
	global_load_dwordx4 v[176:179], v234, s[32:33]
	global_load_dwordx4 v[180:183], v234, s[34:35]
	global_load_dwordx4 v[184:187], v234, s[36:37]
	global_load_dwordx4 v[188:191], v234, s[38:39]
	global_load_dwordx4 v[192:195], v234, s[40:41]
	global_load_dwordx4 v[196:199], v234, s[42:43]
	global_load_dwordx4 v[200:203], v234, s[44:45]
	global_load_dwordx4 v[204:207], v234, s[46:47]
	s_waitcnt vmcnt(8)
; template <bool STORE>
; DI void peer_item(const Params& p, int item, char* smem) {
;     ...
;       for (int u = 0; u < 8; ++u) {
;         int e = e_s[tl * 128 + k + u];
;         uq[u] = *(const u32x4*)(U8 + (size_t)e * 1024 + lane * 16);
;       }
;       float part[8];
; #pragma unroll
;       for (int u = 0; u < 8; ++u) {
;         float d = 0.f;
; #pragma unroll
;         for (int i = 0; i < 4; ++i) {
;           f32x2_t lo = __builtin_amdgcn_cvt_pk_f32_fp8((int)uq[u][i], false);
;           f32x2_t hi = __builtin_amdgcn_cvt_pk_f32_fp8((int)uq[u][i], true);
;           d += xf[4 * i] * lo.x + xf[4 * i + 1] * lo.y + xf[4 * i + 2] * hi.x + xf[4 * i + 3] * hi.y;
;         }
;         part[u] = d;
	v_cvt_pk_f32_fp8_e32 v[214:215], v144
	v_cvt_pk_f32_fp8_sdwa v[216:217], v144 src0_sel:WORD_1
	v_cvt_pk_f32_fp8_e32 v[218:219], v145
	v_cvt_pk_f32_fp8_sdwa v[220:221], v145 src0_sel:WORD_1
	v_pk_mul_f32 v[222:223], v[32:33], v[214:215]
	v_pk_mul_f32 v[224:225], v[34:35], v[216:217]
	v_cvt_pk_f32_fp8_e32 v[214:215], v146
	v_cvt_pk_f32_fp8_sdwa v[216:217], v146 src0_sel:WORD_1
	v_pk_fma_f32 v[222:223], v[36:37], v[218:219], v[222:223]
	v_pk_fma_f32 v[224:225], v[38:39], v[220:221], v[224:225]
	v_cvt_pk_f32_fp8_e32 v[218:219], v147
	v_cvt_pk_f32_fp8_sdwa v[220:221], v147 src0_sel:WORD_1
	v_pk_fma_f32 v[222:223], v[40:41], v[214:215], v[222:223]
	v_pk_fma_f32 v[224:225], v[42:43], v[216:217], v[224:225]
	v_pk_fma_f32 v[222:223], v[44:45], v[218:219], v[222:223]
	v_pk_fma_f32 v[224:225], v[46:47], v[220:221], v[224:225]
	v_pk_add_f32 v[222:223], v[222:223], v[224:225]
	s_nop 0
	v_add_f32_e32 v226, v222, v223
	v_cvt_pk_f32_fp8_e32 v[214:215], v148
	v_cvt_pk_f32_fp8_sdwa v[216:217], v148 src0_sel:WORD_1
	v_cvt_pk_f32_fp8_e32 v[218:219], v149
	v_cvt_pk_f32_fp8_sdwa v[220:221], v149 src0_sel:WORD_1
	v_pk_mul_f32 v[222:223], v[32:33], v[214:215]
	v_pk_mul_f32 v[224:225], v[34:35], v[216:217]
	v_cvt_pk_f32_fp8_e32 v[214:215], v150
	v_cvt_pk_f32_fp8_sdwa v[216:217], v150 src0_sel:WORD_1
	v_pk_fma_f32 v[222:223], v[36:37], v[218:219], v[222:223]
	v_pk_fma_f32 v[224:225], v[38:39], v[220:221], v[224:225]
	v_cvt_pk_f32_fp8_e32 v[218:219], v151
	v_cvt_pk_f32_fp8_sdwa v[220:221], v151 src0_sel:WORD_1
	v_pk_fma_f32 v[222:223], v[40:41], v[214:215], v[222:223]
	v_pk_fma_f32 v[224:225], v[42:43], v[216:217], v[224:225]
	v_pk_fma_f32 v[222:223], v[44:45], v[218:219], v[222:223]
	v_pk_fma_f32 v[224:225], v[46:47], v[220:221], v[224:225]
	v_pk_add_f32 v[222:223], v[222:223], v[224:225]
	s_nop 0
	v_add_f32_e32 v227, v222, v223
	v_cvt_pk_f32_fp8_e32 v[214:215], v152
	v_cvt_pk_f32_fp8_sdwa v[216:217], v152 src0_sel:WORD_1
	v_cvt_pk_f32_fp8_e32 v[218:219], v153
	v_cvt_pk_f32_fp8_sdwa v[220:221], v153 src0_sel:WORD_1
	v_pk_mul_f32 v[222:223], v[32:33], v[214:215]
	v_pk_mul_f32 v[224:225], v[34:35], v[216:217]
	v_cvt_pk_f32_fp8_e32 v[214:215], v154
	v_cvt_pk_f32_fp8_sdwa v[216:217], v154 src0_sel:WORD_1
	v_pk_fma_f32 v[222:223], v[36:37], v[218:219], v[222:223]
	v_pk_fma_f32 v[224:225], v[38:39], v[220:221], v[224:225]
	v_cvt_pk_f32_fp8_e32 v[218:219], v155
	v_cvt_pk_f32_fp8_sdwa v[220:221], v155 src0_sel:WORD_1
	v_pk_fma_f32 v[222:223], v[40:41], v[214:215], v[222:223]
	v_pk_fma_f32 v[224:225], v[42:43], v[216:217], v[224:225]
	v_pk_fma_f32 v[222:223], v[44:45], v[218:219], v[222:223]
	v_pk_fma_f32 v[224:225], v[46:47], v[220:221], v[224:225]
	v_pk_add_f32 v[222:223], v[222:223], v[224:225]
	s_nop 0
	v_add_f32_e32 v228, v222, v223
	v_cvt_pk_f32_fp8_e32 v[214:215], v156
	v_cvt_pk_f32_fp8_sdwa v[216:217], v156 src0_sel:WORD_1
	v_cvt_pk_f32_fp8_e32 v[218:219], v157
	v_cvt_pk_f32_fp8_sdwa v[220:221], v157 src0_sel:WORD_1
	v_pk_mul_f32 v[222:223], v[32:33], v[214:215]
	v_pk_mul_f32 v[224:225], v[34:35], v[216:217]
	v_cvt_pk_f32_fp8_e32 v[214:215], v158
	v_cvt_pk_f32_fp8_sdwa v[216:217], v158 src0_sel:WORD_1
	v_pk_fma_f32 v[222:223], v[36:37], v[218:219], v[222:223]
	v_pk_fma_f32 v[224:225], v[38:39], v[220:221], v[224:225]
	v_cvt_pk_f32_fp8_e32 v[218:219], v159
	v_cvt_pk_f32_fp8_sdwa v[220:221], v159 src0_sel:WORD_1
	v_pk_fma_f32 v[222:223], v[40:41], v[214:215], v[222:223]
	v_pk_fma_f32 v[224:225], v[42:43], v[216:217], v[224:225]
	v_pk_fma_f32 v[222:223], v[44:45], v[218:219], v[222:223]
	v_pk_fma_f32 v[224:225], v[46:47], v[220:221], v[224:225]
	v_pk_add_f32 v[222:223], v[222:223], v[224:225]
	s_nop 0
	v_add_f32_e32 v229, v222, v223
	v_cvt_pk_f32_fp8_e32 v[214:215], v160
	v_cvt_pk_f32_fp8_sdwa v[216:217], v160 src0_sel:WORD_1
	v_cvt_pk_f32_fp8_e32 v[218:219], v161
	v_cvt_pk_f32_fp8_sdwa v[220:221], v161 src0_sel:WORD_1
	v_pk_mul_f32 v[222:223], v[32:33], v[214:215]
	v_pk_mul_f32 v[224:225], v[34:35], v[216:217]
	v_cvt_pk_f32_fp8_e32 v[214:215], v162
	v_cvt_pk_f32_fp8_sdwa v[216:217], v162 src0_sel:WORD_1
	v_pk_fma_f32 v[222:223], v[36:37], v[218:219], v[222:223]
	v_pk_fma_f32 v[224:225], v[38:39], v[220:221], v[224:225]
	v_cvt_pk_f32_fp8_e32 v[218:219], v163
	v_cvt_pk_f32_fp8_sdwa v[220:221], v163 src0_sel:WORD_1
	v_pk_fma_f32 v[222:223], v[40:41], v[214:215], v[222:223]
	v_pk_fma_f32 v[224:225], v[42:43], v[216:217], v[224:225]
	v_pk_fma_f32 v[222:223], v[44:45], v[218:219], v[222:223]
	v_pk_fma_f32 v[224:225], v[46:47], v[220:221], v[224:225]
	v_pk_add_f32 v[222:223], v[222:223], v[224:225]
	s_nop 0
	v_add_f32_e32 v230, v222, v223
	v_cvt_pk_f32_fp8_e32 v[214:215], v164
	v_cvt_pk_f32_fp8_sdwa v[216:217], v164 src0_sel:WORD_1
	v_cvt_pk_f32_fp8_e32 v[218:219], v165
	v_cvt_pk_f32_fp8_sdwa v[220:221], v165 src0_sel:WORD_1
	v_pk_mul_f32 v[222:223], v[32:33], v[214:215]
	v_pk_mul_f32 v[224:225], v[34:35], v[216:217]
	v_cvt_pk_f32_fp8_e32 v[214:215], v166
	v_cvt_pk_f32_fp8_sdwa v[216:217], v166 src0_sel:WORD_1
	v_pk_fma_f32 v[222:223], v[36:37], v[218:219], v[222:223]
	v_pk_fma_f32 v[224:225], v[38:39], v[220:221], v[224:225]
	v_cvt_pk_f32_fp8_e32 v[218:219], v167
	v_cvt_pk_f32_fp8_sdwa v[220:221], v167 src0_sel:WORD_1
	v_pk_fma_f32 v[222:223], v[40:41], v[214:215], v[222:223]
	v_pk_fma_f32 v[224:225], v[42:43], v[216:217], v[224:225]
	v_pk_fma_f32 v[222:223], v[44:45], v[218:219], v[222:223]
	v_pk_fma_f32 v[224:225], v[46:47], v[220:221], v[224:225]
	v_pk_add_f32 v[222:223], v[222:223], v[224:225]
	s_nop 0
	v_add_f32_e32 v231, v222, v223
	v_cvt_pk_f32_fp8_e32 v[214:215], v168
	v_cvt_pk_f32_fp8_sdwa v[216:217], v168 src0_sel:WORD_1
	v_cvt_pk_f32_fp8_e32 v[218:219], v169
; template <bool STORE>
; DI void peer_item(const Params& p, int item, char* smem) {
;     ...
;       for (int u = 0; u < 8; ++u) {
;         int e = e_s[tl * 128 + k + u];
;         uq[u] = *(const u32x4*)(U8 + (size_t)e * 1024 + lane * 16);
;       }
;       float part[8];
; #pragma unroll
;       for (int u = 0; u < 8; ++u) {
;         float d = 0.f;
; #pragma unroll
;         for (int i = 0; i < 4; ++i) {
;           f32x2_t lo = __builtin_amdgcn_cvt_pk_f32_fp8((int)uq[u][i], false);
;           f32x2_t hi = __builtin_amdgcn_cvt_pk_f32_fp8((int)uq[u][i], true);
;           d += xf[4 * i] * lo.x + xf[4 * i + 1] * lo.y + xf[4 * i + 2] * hi.x + xf[4 * i + 3] * hi.y;
;         }
;         part[u] = d;
;       }
;       float q4[4], r2[2], h;
; #pragma unroll
;       for (int j = 0; j < 4; ++j) {
;         float mine = b5 ? part[j + 4] : part[j];
;         float other = b5 ? part[j] : part[j + 4];
;         q4[j] = mine + __shfl_xor(other, 32);
;       }
; #pragma unroll
;       for (int j = 0; j < 2; ++j) {
;         float mine = b4 ? q4[j + 2] : q4[j];
;         float other = b4 ? q4[j] : q4[j + 2];
;         r2[j] = mine + __shfl_xor(other, 16);
;       }
;       {
;         float mine = b3 ? r2[1] : r2[0];
;         float other = b3 ? r2[0] : r2[1];
;         h = mine + __shfl_xor(other, 8);
;       }
;       h += __shfl_xor(h, 4);
;       h += __shfl_xor(h, 2);
;       h += __shfl_xor(h, 1);
	v_cvt_pk_f32_fp8_sdwa v[220:221], v169 src0_sel:WORD_1
	v_pk_mul_f32 v[222:223], v[32:33], v[214:215]
	v_pk_mul_f32 v[224:225], v[34:35], v[216:217]
	v_cvt_pk_f32_fp8_e32 v[214:215], v170
	v_cvt_pk_f32_fp8_sdwa v[216:217], v170 src0_sel:WORD_1
	v_pk_fma_f32 v[222:223], v[36:37], v[218:219], v[222:223]
	v_pk_fma_f32 v[224:225], v[38:39], v[220:221], v[224:225]
	v_cvt_pk_f32_fp8_e32 v[218:219], v171
	v_cvt_pk_f32_fp8_sdwa v[220:221], v171 src0_sel:WORD_1
	v_pk_fma_f32 v[222:223], v[40:41], v[214:215], v[222:223]
	v_pk_fma_f32 v[224:225], v[42:43], v[216:217], v[224:225]
	v_pk_fma_f32 v[222:223], v[44:45], v[218:219], v[222:223]
	v_pk_fma_f32 v[224:225], v[46:47], v[220:221], v[224:225]
	v_pk_add_f32 v[222:223], v[222:223], v[224:225]
	s_nop 0
	v_add_f32_e32 v232, v222, v223
	v_cvt_pk_f32_fp8_e32 v[214:215], v172
	v_cvt_pk_f32_fp8_sdwa v[216:217], v172 src0_sel:WORD_1
	v_cvt_pk_f32_fp8_e32 v[218:219], v173
	v_cvt_pk_f32_fp8_sdwa v[220:221], v173 src0_sel:WORD_1
	v_pk_mul_f32 v[222:223], v[32:33], v[214:215]
	v_pk_mul_f32 v[224:225], v[34:35], v[216:217]
	v_cvt_pk_f32_fp8_e32 v[214:215], v174
	v_cvt_pk_f32_fp8_sdwa v[216:217], v174 src0_sel:WORD_1
	v_pk_fma_f32 v[222:223], v[36:37], v[218:219], v[222:223]
	v_pk_fma_f32 v[224:225], v[38:39], v[220:221], v[224:225]
	v_cvt_pk_f32_fp8_e32 v[218:219], v175
	v_cvt_pk_f32_fp8_sdwa v[220:221], v175 src0_sel:WORD_1
	v_pk_fma_f32 v[222:223], v[40:41], v[214:215], v[222:223]
	v_pk_fma_f32 v[224:225], v[42:43], v[216:217], v[224:225]
	v_pk_fma_f32 v[222:223], v[44:45], v[218:219], v[222:223]
	v_pk_fma_f32 v[224:225], v[46:47], v[220:221], v[224:225]
	v_pk_add_f32 v[222:223], v[222:223], v[224:225]
	s_nop 0
	v_add_f32_e32 v233, v222, v223
	v_permlane32_swap_b32_e32 v226, v230
	v_permlane32_swap_b32_e32 v227, v231
	v_permlane32_swap_b32_e32 v228, v232
	v_permlane32_swap_b32_e32 v229, v233
	v_add_f32_e32 v226, v226, v230
	v_add_f32_e32 v228, v228, v232
	v_add_f32_e32 v227, v227, v231
	v_add_f32_e32 v229, v229, v233
	s_nop 1
	v_permlane16_swap_b32_e32 v226, v228
	v_permlane16_swap_b32_e32 v227, v229
	v_add_f32_e32 v226, v226, v228
	v_add_f32_e32 v227, v227, v229
	s_nop 0
	v_cndmask_b32_e64 v230, v226, v227, s[24:25]
	v_cndmask_b32_e64 v231, v227, v226, s[24:25]
	s_nop 1
	v_add_f32_dpp v232, v231, v230 row_ror:8 row_mask:0xf bank_mask:0xf
	s_nop 1
	v_add_f32_dpp v233, v232, v232 quad_perm:[1,0,3,2] row_mask:0xf bank_mask:0xf
	s_nop 1
	v_add_f32_dpp v232, v233, v233 quad_perm:[2,3,0,1] row_mask:0xf bank_mask:0xf
	s_nop 1
	v_add_f32_dpp v233, v232, v232 row_half_mirror row_mask:0xf bank_mask:0xf
	ds_write_b32 v235, v233 offset:33824
	v_readlane_b32 s48, v137, s72
	v_readlane_b32 s49, v137, s73
	v_readlane_b32 s50, v137, s74
	v_readlane_b32 s51, v137, s75
	v_readlane_b32 s52, v137, s76
	v_readlane_b32 s53, v137, s77
	v_readlane_b32 s54, v137, s78
	v_readlane_b32 s55, v137, s79
	s_add_u32 s32, s0, s48
	s_addc_u32 s33, s1, 0
	s_add_u32 s34, s0, s49
	s_addc_u32 s35, s1, 0
	s_add_u32 s36, s0, s50
	s_addc_u32 s37, s1, 0
	s_add_u32 s38, s0, s51
	s_addc_u32 s39, s1, 0
	s_add_u32 s40, s0, s52
	s_addc_u32 s41, s1, 0
	s_add_u32 s42, s0, s53
	s_addc_u32 s43, s1, 0
	s_add_u32 s44, s0, s54
	s_addc_u32 s45, s1, 0
	s_add_u32 s46, s0, s55
	s_addc_u32 s47, s1, 0
	global_load_dwordx4 v[144:147], v234, s[32:33]
	global_load_dwordx4 v[148:151], v234, s[34:35]
	global_load_dwordx4 v[152:155], v234, s[36:37]
	global_load_dwordx4 v[156:159], v234, s[38:39]
	global_load_dwordx4 v[160:163], v234, s[40:41]
	global_load_dwordx4 v[164:167], v234, s[42:43]
	global_load_dwordx4 v[168:171], v234, s[44:45]
	global_load_dwordx4 v[172:175], v234, s[46:47]
	s_waitcnt vmcnt(8)
	v_cvt_pk_f32_fp8_e32 v[214:215], v176
	v_cvt_pk_f32_fp8_sdwa v[216:217], v176 src0_sel:WORD_1
	v_cvt_pk_f32_fp8_e32 v[218:219], v177
	v_cvt_pk_f32_fp8_sdwa v[220:221], v177 src0_sel:WORD_1
	v_pk_mul_f32 v[222:223], v[48:49], v[214:215]
	v_pk_mul_f32 v[224:225], v[50:51], v[216:217]
	v_cvt_pk_f32_fp8_e32 v[214:215], v178
	v_cvt_pk_f32_fp8_sdwa v[216:217], v178 src0_sel:WORD_1
	v_pk_fma_f32 v[222:223], v[52:53], v[218:219], v[222:223]
	v_pk_fma_f32 v[224:225], v[54:55], v[220:221], v[224:225]
	v_cvt_pk_f32_fp8_e32 v[218:219], v179
	v_cvt_pk_f32_fp8_sdwa v[220:221], v179 src0_sel:WORD_1
	v_pk_fma_f32 v[222:223], v[56:57], v[214:215], v[222:223]
	v_pk_fma_f32 v[224:225], v[58:59], v[216:217], v[224:225]
	v_pk_fma_f32 v[222:223], v[60:61], v[218:219], v[222:223]
	v_pk_fma_f32 v[224:225], v[62:63], v[220:221], v[224:225]
	v_pk_add_f32 v[222:223], v[222:223], v[224:225]
	s_nop 0
	v_add_f32_e32 v226, v222, v223
	v_cvt_pk_f32_fp8_e32 v[214:215], v180
	v_cvt_pk_f32_fp8_sdwa v[216:217], v180 src0_sel:WORD_1
	v_cvt_pk_f32_fp8_e32 v[218:219], v181
	v_cvt_pk_f32_fp8_sdwa v[220:221], v181 src0_sel:WORD_1
	v_pk_mul_f32 v[222:223], v[48:49], v[214:215]
	v_pk_mul_f32 v[224:225], v[50:51], v[216:217]
	v_cvt_pk_f32_fp8_e32 v[214:215], v182
	v_cvt_pk_f32_fp8_sdwa v[216:217], v182 src0_sel:WORD_1
	v_pk_fma_f32 v[222:223], v[52:53], v[218:219], v[222:223]
	v_pk_fma_f32 v[224:225], v[54:55], v[220:221], v[224:225]
	v_cvt_pk_f32_fp8_e32 v[218:219], v183
	v_cvt_pk_f32_fp8_sdwa v[220:221], v183 src0_sel:WORD_1
	v_pk_fma_f32 v[222:223], v[56:57], v[214:215], v[222:223]
	v_pk_fma_f32 v[224:225], v[58:59], v[216:217], v[224:225]
	v_pk_fma_f32 v[222:223], v[60:61], v[218:219], v[222:223]
	v_pk_fma_f32 v[224:225], v[62:63], v[220:221], v[224:225]
	v_pk_add_f32 v[222:223], v[222:223], v[224:225]
	s_nop 0
	v_add_f32_e32 v227, v222, v223
	v_cvt_pk_f32_fp8_e32 v[214:215], v184
	v_cvt_pk_f32_fp8_sdwa v[216:217], v184 src0_sel:WORD_1
	v_cvt_pk_f32_fp8_e32 v[218:219], v185
	v_cvt_pk_f32_fp8_sdwa v[220:221], v185 src0_sel:WORD_1
; template <bool STORE>
; DI void peer_item(const Params& p, int item, char* smem) {
;     ...
;       for (int u = 0; u < 8; ++u) {
;         int e = e_s[tl * 128 + k + u];
;         uq[u] = *(const u32x4*)(U8 + (size_t)e * 1024 + lane * 16);
;       }
;       float part[8];
; #pragma unroll
;       for (int u = 0; u < 8; ++u) {
;         float d = 0.f;
; #pragma unroll
;         for (int i = 0; i < 4; ++i) {
;           f32x2_t lo = __builtin_amdgcn_cvt_pk_f32_fp8((int)uq[u][i], false);
;           f32x2_t hi = __builtin_amdgcn_cvt_pk_f32_fp8((int)uq[u][i], true);
;           d += xf[4 * i] * lo.x + xf[4 * i + 1] * lo.y + xf[4 * i + 2] * hi.x + xf[4 * i + 3] * hi.y;
;         }
;         part[u] = d;
;       }
;       float q4[4], r2[2], h;
; #pragma unroll
;       for (int j = 0; j < 4; ++j) {
;         float mine = b5 ? part[j + 4] : part[j];
;         float other = b5 ? part[j] : part[j + 4];
;         q4[j] = mine + __shfl_xor(other, 32);
;       }
; #pragma unroll
;       for (int j = 0; j < 2; ++j) {
;         float mine = b4 ? q4[j + 2] : q4[j];
;         float other = b4 ? q4[j] : q4[j + 2];
;         r2[j] = mine + __shfl_xor(other, 16);
;       }
;       {
;         float mine = b3 ? r2[1] : r2[0];
;         float other = b3 ? r2[0] : r2[1];
;         h = mine + __shfl_xor(other, 8);
;       }
;       h += __shfl_xor(h, 4);
;       h += __shfl_xor(h, 2);
;       h += __shfl_xor(h, 1);
	v_pk_mul_f32 v[222:223], v[48:49], v[214:215]
	v_pk_mul_f32 v[224:225], v[50:51], v[216:217]
	v_cvt_pk_f32_fp8_e32 v[214:215], v186
	v_cvt_pk_f32_fp8_sdwa v[216:217], v186 src0_sel:WORD_1
	v_pk_fma_f32 v[222:223], v[52:53], v[218:219], v[222:223]
	v_pk_fma_f32 v[224:225], v[54:55], v[220:221], v[224:225]
	v_cvt_pk_f32_fp8_e32 v[218:219], v187
	v_cvt_pk_f32_fp8_sdwa v[220:221], v187 src0_sel:WORD_1
	v_pk_fma_f32 v[222:223], v[56:57], v[214:215], v[222:223]
	v_pk_fma_f32 v[224:225], v[58:59], v[216:217], v[224:225]
	v_pk_fma_f32 v[222:223], v[60:61], v[218:219], v[222:223]
	v_pk_fma_f32 v[224:225], v[62:63], v[220:221], v[224:225]
	v_pk_add_f32 v[222:223], v[222:223], v[224:225]
	s_nop 0
	v_add_f32_e32 v228, v222, v223
	v_cvt_pk_f32_fp8_e32 v[214:215], v188
	v_cvt_pk_f32_fp8_sdwa v[216:217], v188 src0_sel:WORD_1
	v_cvt_pk_f32_fp8_e32 v[218:219], v189
	v_cvt_pk_f32_fp8_sdwa v[220:221], v189 src0_sel:WORD_1
	v_pk_mul_f32 v[222:223], v[48:49], v[214:215]
	v_pk_mul_f32 v[224:225], v[50:51], v[216:217]
	v_cvt_pk_f32_fp8_e32 v[214:215], v190
	v_cvt_pk_f32_fp8_sdwa v[216:217], v190 src0_sel:WORD_1
	v_pk_fma_f32 v[222:223], v[52:53], v[218:219], v[222:223]
	v_pk_fma_f32 v[224:225], v[54:55], v[220:221], v[224:225]
	v_cvt_pk_f32_fp8_e32 v[218:219], v191
	v_cvt_pk_f32_fp8_sdwa v[220:221], v191 src0_sel:WORD_1
	v_pk_fma_f32 v[222:223], v[56:57], v[214:215], v[222:223]
	v_pk_fma_f32 v[224:225], v[58:59], v[216:217], v[224:225]
	v_pk_fma_f32 v[222:223], v[60:61], v[218:219], v[222:223]
	v_pk_fma_f32 v[224:225], v[62:63], v[220:221], v[224:225]
	v_pk_add_f32 v[222:223], v[222:223], v[224:225]
	s_nop 0
	v_add_f32_e32 v229, v222, v223
	v_cvt_pk_f32_fp8_e32 v[214:215], v192
	v_cvt_pk_f32_fp8_sdwa v[216:217], v192 src0_sel:WORD_1
	v_cvt_pk_f32_fp8_e32 v[218:219], v193
	v_cvt_pk_f32_fp8_sdwa v[220:221], v193 src0_sel:WORD_1
	v_pk_mul_f32 v[222:223], v[48:49], v[214:215]
	v_pk_mul_f32 v[224:225], v[50:51], v[216:217]
	v_cvt_pk_f32_fp8_e32 v[214:215], v194
	v_cvt_pk_f32_fp8_sdwa v[216:217], v194 src0_sel:WORD_1
	v_pk_fma_f32 v[222:223], v[52:53], v[218:219], v[222:223]
	v_pk_fma_f32 v[224:225], v[54:55], v[220:221], v[224:225]
	v_cvt_pk_f32_fp8_e32 v[218:219], v195
	v_cvt_pk_f32_fp8_sdwa v[220:221], v195 src0_sel:WORD_1
	v_pk_fma_f32 v[222:223], v[56:57], v[214:215], v[222:223]
	v_pk_fma_f32 v[224:225], v[58:59], v[216:217], v[224:225]
	v_pk_fma_f32 v[222:223], v[60:61], v[218:219], v[222:223]
	v_pk_fma_f32 v[224:225], v[62:63], v[220:221], v[224:225]
	v_pk_add_f32 v[222:223], v[222:223], v[224:225]
	s_nop 0
	v_add_f32_e32 v230, v222, v223
	v_cvt_pk_f32_fp8_e32 v[214:215], v196
	v_cvt_pk_f32_fp8_sdwa v[216:217], v196 src0_sel:WORD_1
	v_cvt_pk_f32_fp8_e32 v[218:219], v197
	v_cvt_pk_f32_fp8_sdwa v[220:221], v197 src0_sel:WORD_1
	v_pk_mul_f32 v[222:223], v[48:49], v[214:215]
	v_pk_mul_f32 v[224:225], v[50:51], v[216:217]
	v_cvt_pk_f32_fp8_e32 v[214:215], v198
	v_cvt_pk_f32_fp8_sdwa v[216:217], v198 src0_sel:WORD_1
	v_pk_fma_f32 v[222:223], v[52:53], v[218:219], v[222:223]
	v_pk_fma_f32 v[224:225], v[54:55], v[220:221], v[224:225]
	v_cvt_pk_f32_fp8_e32 v[218:219], v199
	v_cvt_pk_f32_fp8_sdwa v[220:221], v199 src0_sel:WORD_1
	v_pk_fma_f32 v[222:223], v[56:57], v[214:215], v[222:223]
	v_pk_fma_f32 v[224:225], v[58:59], v[216:217], v[224:225]
	v_pk_fma_f32 v[222:223], v[60:61], v[218:219], v[222:223]
	v_pk_fma_f32 v[224:225], v[62:63], v[220:221], v[224:225]
	v_pk_add_f32 v[222:223], v[222:223], v[224:225]
	s_nop 0
	v_add_f32_e32 v231, v222, v223
	v_cvt_pk_f32_fp8_e32 v[214:215], v200
	v_cvt_pk_f32_fp8_sdwa v[216:217], v200 src0_sel:WORD_1
	v_cvt_pk_f32_fp8_e32 v[218:219], v201
	v_cvt_pk_f32_fp8_sdwa v[220:221], v201 src0_sel:WORD_1
	v_pk_mul_f32 v[222:223], v[48:49], v[214:215]
	v_pk_mul_f32 v[224:225], v[50:51], v[216:217]
	v_cvt_pk_f32_fp8_e32 v[214:215], v202
	v_cvt_pk_f32_fp8_sdwa v[216:217], v202 src0_sel:WORD_1
	v_pk_fma_f32 v[222:223], v[52:53], v[218:219], v[222:223]
	v_pk_fma_f32 v[224:225], v[54:55], v[220:221], v[224:225]
	v_cvt_pk_f32_fp8_e32 v[218:219], v203
	v_cvt_pk_f32_fp8_sdwa v[220:221], v203 src0_sel:WORD_1
	v_pk_fma_f32 v[222:223], v[56:57], v[214:215], v[222:223]
	v_pk_fma_f32 v[224:225], v[58:59], v[216:217], v[224:225]
	v_pk_fma_f32 v[222:223], v[60:61], v[218:219], v[222:223]
	v_pk_fma_f32 v[224:225], v[62:63], v[220:221], v[224:225]
	v_pk_add_f32 v[222:223], v[222:223], v[224:225]
	s_nop 0
	v_add_f32_e32 v232, v222, v223
	v_cvt_pk_f32_fp8_e32 v[214:215], v204
	v_cvt_pk_f32_fp8_sdwa v[216:217], v204 src0_sel:WORD_1
	v_cvt_pk_f32_fp8_e32 v[218:219], v205
	v_cvt_pk_f32_fp8_sdwa v[220:221], v205 src0_sel:WORD_1
	v_pk_mul_f32 v[222:223], v[48:49], v[214:215]
	v_pk_mul_f32 v[224:225], v[50:51], v[216:217]
	v_cvt_pk_f32_fp8_e32 v[214:215], v206
	v_cvt_pk_f32_fp8_sdwa v[216:217], v206 src0_sel:WORD_1
	v_pk_fma_f32 v[222:223], v[52:53], v[218:219], v[222:223]
	v_pk_fma_f32 v[224:225], v[54:55], v[220:221], v[224:225]
	v_cvt_pk_f32_fp8_e32 v[218:219], v207
	v_cvt_pk_f32_fp8_sdwa v[220:221], v207 src0_sel:WORD_1
	v_pk_fma_f32 v[222:223], v[56:57], v[214:215], v[222:223]
	v_pk_fma_f32 v[224:225], v[58:59], v[216:217], v[224:225]
	v_pk_fma_f32 v[222:223], v[60:61], v[218:219], v[222:223]
	v_pk_fma_f32 v[224:225], v[62:63], v[220:221], v[224:225]
	v_pk_add_f32 v[222:223], v[222:223], v[224:225]
	s_nop 0
	v_add_f32_e32 v233, v222, v223
	v_permlane32_swap_b32_e32 v226, v230
	v_permlane32_swap_b32_e32 v227, v231
	v_permlane32_swap_b32_e32 v228, v232
	v_permlane32_swap_b32_e32 v229, v233
	v_add_f32_e32 v226, v226, v230
	v_add_f32_e32 v228, v228, v232
	v_add_f32_e32 v227, v227, v231
	v_add_f32_e32 v229, v229, v233
	s_nop 1
	v_permlane16_swap_b32_e32 v226, v228
; template <bool STORE>
; DI void peer_item(const Params& p, int item, char* smem) {
;     ...
;       for (int u = 0; u < 8; ++u) {
;         int e = e_s[tl * 128 + k + u];
;         uq[u] = *(const u32x4*)(U8 + (size_t)e * 1024 + lane * 16);
;       }
;       float part[8];
; #pragma unroll
;       for (int u = 0; u < 8; ++u) {
;         float d = 0.f;
; #pragma unroll
;         for (int i = 0; i < 4; ++i) {
;           f32x2_t lo = __builtin_amdgcn_cvt_pk_f32_fp8((int)uq[u][i], false);
;           f32x2_t hi = __builtin_amdgcn_cvt_pk_f32_fp8((int)uq[u][i], true);
;           d += xf[4 * i] * lo.x + xf[4 * i + 1] * lo.y + xf[4 * i + 2] * hi.x + xf[4 * i + 3] * hi.y;
;         }
;         part[u] = d;
;       }
;       float q4[4], r2[2], h;
; #pragma unroll
;       for (int j = 0; j < 4; ++j) {
;         float mine = b5 ? part[j + 4] : part[j];
;         float other = b5 ? part[j] : part[j + 4];
;         q4[j] = mine + __shfl_xor(other, 32);
;       }
; #pragma unroll
;       for (int j = 0; j < 2; ++j) {
;         float mine = b4 ? q4[j + 2] : q4[j];
;         float other = b4 ? q4[j] : q4[j + 2];
;         r2[j] = mine + __shfl_xor(other, 16);
;       }
;       {
;         float mine = b3 ? r2[1] : r2[0];
;         float other = b3 ? r2[0] : r2[1];
;         h = mine + __shfl_xor(other, 8);
;       }
;       h += __shfl_xor(h, 4);
;       h += __shfl_xor(h, 2);
;       h += __shfl_xor(h, 1);
	v_permlane16_swap_b32_e32 v227, v229
	v_add_f32_e32 v226, v226, v228
	v_add_f32_e32 v227, v227, v229
	s_nop 0
	v_cndmask_b32_e64 v230, v226, v227, s[24:25]
	v_cndmask_b32_e64 v231, v227, v226, s[24:25]
	s_nop 1
	v_add_f32_dpp v232, v231, v230 row_ror:8 row_mask:0xf bank_mask:0xf
	s_nop 1
	v_add_f32_dpp v233, v232, v232 quad_perm:[1,0,3,2] row_mask:0xf bank_mask:0xf
	s_nop 1
	v_add_f32_dpp v232, v233, v233 quad_perm:[2,3,0,1] row_mask:0xf bank_mask:0xf
	s_nop 1
	v_add_f32_dpp v233, v232, v232 row_half_mirror row_mask:0xf bank_mask:0xf
	ds_write_b32 v235, v233 offset:34336
	v_readlane_b32 s48, v139, s72
	v_readlane_b32 s49, v139, s73
	v_readlane_b32 s50, v139, s74
	v_readlane_b32 s51, v139, s75
	v_readlane_b32 s52, v139, s76
	v_readlane_b32 s53, v139, s77
	v_readlane_b32 s54, v139, s78
	v_readlane_b32 s55, v139, s79
	s_add_u32 s32, s0, s48
	s_addc_u32 s33, s1, 0
	s_add_u32 s34, s0, s49
	s_addc_u32 s35, s1, 0
	s_add_u32 s36, s0, s50
	s_addc_u32 s37, s1, 0
	s_add_u32 s38, s0, s51
	s_addc_u32 s39, s1, 0
	s_add_u32 s40, s0, s52
	s_addc_u32 s41, s1, 0
	s_add_u32 s42, s0, s53
	s_addc_u32 s43, s1, 0
	s_add_u32 s44, s0, s54
	s_addc_u32 s45, s1, 0
	s_add_u32 s46, s0, s55
	s_addc_u32 s47, s1, 0
	global_load_dwordx4 v[176:179], v234, s[32:33]
	global_load_dwordx4 v[180:183], v234, s[34:35]
	global_load_dwordx4 v[184:187], v234, s[36:37]
	global_load_dwordx4 v[188:191], v234, s[38:39]
	global_load_dwordx4 v[192:195], v234, s[40:41]
	global_load_dwordx4 v[196:199], v234, s[42:43]
	global_load_dwordx4 v[200:203], v234, s[44:45]
	global_load_dwordx4 v[204:207], v234, s[46:47]
	s_waitcnt vmcnt(8)
	v_cvt_pk_f32_fp8_e32 v[214:215], v144
	v_cvt_pk_f32_fp8_sdwa v[216:217], v144 src0_sel:WORD_1
	v_cvt_pk_f32_fp8_e32 v[218:219], v145
	v_cvt_pk_f32_fp8_sdwa v[220:221], v145 src0_sel:WORD_1
	v_pk_mul_f32 v[222:223], v[64:65], v[214:215]
	v_pk_mul_f32 v[224:225], v[66:67], v[216:217]
	v_cvt_pk_f32_fp8_e32 v[214:215], v146
	v_cvt_pk_f32_fp8_sdwa v[216:217], v146 src0_sel:WORD_1
	v_pk_fma_f32 v[222:223], v[68:69], v[218:219], v[222:223]
	v_pk_fma_f32 v[224:225], v[70:71], v[220:221], v[224:225]
	v_cvt_pk_f32_fp8_e32 v[218:219], v147
	v_cvt_pk_f32_fp8_sdwa v[220:221], v147 src0_sel:WORD_1
	v_pk_fma_f32 v[222:223], v[72:73], v[214:215], v[222:223]
	v_pk_fma_f32 v[224:225], v[74:75], v[216:217], v[224:225]
	v_pk_fma_f32 v[222:223], v[76:77], v[218:219], v[222:223]
	v_pk_fma_f32 v[224:225], v[78:79], v[220:221], v[224:225]
	v_pk_add_f32 v[222:223], v[222:223], v[224:225]
	s_nop 0
	v_add_f32_e32 v226, v222, v223
	v_cvt_pk_f32_fp8_e32 v[214:215], v148
	v_cvt_pk_f32_fp8_sdwa v[216:217], v148 src0_sel:WORD_1
	v_cvt_pk_f32_fp8_e32 v[218:219], v149
	v_cvt_pk_f32_fp8_sdwa v[220:221], v149 src0_sel:WORD_1
	v_pk_mul_f32 v[222:223], v[64:65], v[214:215]
	v_pk_mul_f32 v[224:225], v[66:67], v[216:217]
	v_cvt_pk_f32_fp8_e32 v[214:215], v150
	v_cvt_pk_f32_fp8_sdwa v[216:217], v150 src0_sel:WORD_1
	v_pk_fma_f32 v[222:223], v[68:69], v[218:219], v[222:223]
	v_pk_fma_f32 v[224:225], v[70:71], v[220:221], v[224:225]
	v_cvt_pk_f32_fp8_e32 v[218:219], v151
	v_cvt_pk_f32_fp8_sdwa v[220:221], v151 src0_sel:WORD_1
	v_pk_fma_f32 v[222:223], v[72:73], v[214:215], v[222:223]
	v_pk_fma_f32 v[224:225], v[74:75], v[216:217], v[224:225]
	v_pk_fma_f32 v[222:223], v[76:77], v[218:219], v[222:223]
	v_pk_fma_f32 v[224:225], v[78:79], v[220:221], v[224:225]
	v_pk_add_f32 v[222:223], v[222:223], v[224:225]
	s_nop 0
	v_add_f32_e32 v227, v222, v223
	v_cvt_pk_f32_fp8_e32 v[214:215], v152
	v_cvt_pk_f32_fp8_sdwa v[216:217], v152 src0_sel:WORD_1
	v_cvt_pk_f32_fp8_e32 v[218:219], v153
	v_cvt_pk_f32_fp8_sdwa v[220:221], v153 src0_sel:WORD_1
	v_pk_mul_f32 v[222:223], v[64:65], v[214:215]
	v_pk_mul_f32 v[224:225], v[66:67], v[216:217]
	v_cvt_pk_f32_fp8_e32 v[214:215], v154
	v_cvt_pk_f32_fp8_sdwa v[216:217], v154 src0_sel:WORD_1
	v_pk_fma_f32 v[222:223], v[68:69], v[218:219], v[222:223]
	v_pk_fma_f32 v[224:225], v[70:71], v[220:221], v[224:225]
	v_cvt_pk_f32_fp8_e32 v[218:219], v155
	v_cvt_pk_f32_fp8_sdwa v[220:221], v155 src0_sel:WORD_1
	v_pk_fma_f32 v[222:223], v[72:73], v[214:215], v[222:223]
	v_pk_fma_f32 v[224:225], v[74:75], v[216:217], v[224:225]
	v_pk_fma_f32 v[222:223], v[76:77], v[218:219], v[222:223]
	v_pk_fma_f32 v[224:225], v[78:79], v[220:221], v[224:225]
	v_pk_add_f32 v[222:223], v[222:223], v[224:225]
	s_nop 0
	v_add_f32_e32 v228, v222, v223
	v_cvt_pk_f32_fp8_e32 v[214:215], v156
	v_cvt_pk_f32_fp8_sdwa v[216:217], v156 src0_sel:WORD_1
	v_cvt_pk_f32_fp8_e32 v[218:219], v157
	v_cvt_pk_f32_fp8_sdwa v[220:221], v157 src0_sel:WORD_1
	v_pk_mul_f32 v[222:223], v[64:65], v[214:215]
	v_pk_mul_f32 v[224:225], v[66:67], v[216:217]
	v_cvt_pk_f32_fp8_e32 v[214:215], v158
	v_cvt_pk_f32_fp8_sdwa v[216:217], v158 src0_sel:WORD_1
	v_pk_fma_f32 v[222:223], v[68:69], v[218:219], v[222:223]
	v_pk_fma_f32 v[224:225], v[70:71], v[220:221], v[224:225]
	v_cvt_pk_f32_fp8_e32 v[218:219], v159
	v_cvt_pk_f32_fp8_sdwa v[220:221], v159 src0_sel:WORD_1
	v_pk_fma_f32 v[222:223], v[72:73], v[214:215], v[222:223]
	v_pk_fma_f32 v[224:225], v[74:75], v[216:217], v[224:225]
	v_pk_fma_f32 v[222:223], v[76:77], v[218:219], v[222:223]
	v_pk_fma_f32 v[224:225], v[78:79], v[220:221], v[224:225]
	v_pk_add_f32 v[222:223], v[222:223], v[224:225]
	s_nop 0
	v_add_f32_e32 v229, v222, v223
	v_cvt_pk_f32_fp8_e32 v[214:215], v160
	v_cvt_pk_f32_fp8_sdwa v[216:217], v160 src0_sel:WORD_1
	v_cvt_pk_f32_fp8_e32 v[218:219], v161
	v_cvt_pk_f32_fp8_sdwa v[220:221], v161 src0_sel:WORD_1
	v_pk_mul_f32 v[222:223], v[64:65], v[214:215]
	v_pk_mul_f32 v[224:225], v[66:67], v[216:217]
	v_cvt_pk_f32_fp8_e32 v[214:215], v162
	v_cvt_pk_f32_fp8_sdwa v[216:217], v162 src0_sel:WORD_1
; template <bool STORE>
; DI void peer_item(const Params& p, int item, char* smem) {
;     ...
;       for (int u = 0; u < 8; ++u) {
;         int e = e_s[tl * 128 + k + u];
;         uq[u] = *(const u32x4*)(U8 + (size_t)e * 1024 + lane * 16);
;       }
;       float part[8];
; #pragma unroll
;       for (int u = 0; u < 8; ++u) {
;         float d = 0.f;
; #pragma unroll
;         for (int i = 0; i < 4; ++i) {
;           f32x2_t lo = __builtin_amdgcn_cvt_pk_f32_fp8((int)uq[u][i], false);
;           f32x2_t hi = __builtin_amdgcn_cvt_pk_f32_fp8((int)uq[u][i], true);
;           d += xf[4 * i] * lo.x + xf[4 * i + 1] * lo.y + xf[4 * i + 2] * hi.x + xf[4 * i + 3] * hi.y;
;         }
;         part[u] = d;
;       }
;       float q4[4], r2[2], h;
; #pragma unroll
;       for (int j = 0; j < 4; ++j) {
;         float mine = b5 ? part[j + 4] : part[j];
;         float other = b5 ? part[j] : part[j + 4];
;         q4[j] = mine + __shfl_xor(other, 32);
;       }
; #pragma unroll
;       for (int j = 0; j < 2; ++j) {
;         float mine = b4 ? q4[j + 2] : q4[j];
;         float other = b4 ? q4[j] : q4[j + 2];
;         r2[j] = mine + __shfl_xor(other, 16);
;       }
;       {
;         float mine = b3 ? r2[1] : r2[0];
;         float other = b3 ? r2[0] : r2[1];
;         h = mine + __shfl_xor(other, 8);
;       }
;       h += __shfl_xor(h, 4);
;       h += __shfl_xor(h, 2);
;       h += __shfl_xor(h, 1);
	v_pk_fma_f32 v[222:223], v[68:69], v[218:219], v[222:223]
	v_pk_fma_f32 v[224:225], v[70:71], v[220:221], v[224:225]
	v_cvt_pk_f32_fp8_e32 v[218:219], v163
	v_cvt_pk_f32_fp8_sdwa v[220:221], v163 src0_sel:WORD_1
	v_pk_fma_f32 v[222:223], v[72:73], v[214:215], v[222:223]
	v_pk_fma_f32 v[224:225], v[74:75], v[216:217], v[224:225]
	v_pk_fma_f32 v[222:223], v[76:77], v[218:219], v[222:223]
	v_pk_fma_f32 v[224:225], v[78:79], v[220:221], v[224:225]
	v_pk_add_f32 v[222:223], v[222:223], v[224:225]
	s_nop 0
	v_add_f32_e32 v230, v222, v223
	v_cvt_pk_f32_fp8_e32 v[214:215], v164
	v_cvt_pk_f32_fp8_sdwa v[216:217], v164 src0_sel:WORD_1
	v_cvt_pk_f32_fp8_e32 v[218:219], v165
	v_cvt_pk_f32_fp8_sdwa v[220:221], v165 src0_sel:WORD_1
	v_pk_mul_f32 v[222:223], v[64:65], v[214:215]
	v_pk_mul_f32 v[224:225], v[66:67], v[216:217]
	v_cvt_pk_f32_fp8_e32 v[214:215], v166
	v_cvt_pk_f32_fp8_sdwa v[216:217], v166 src0_sel:WORD_1
	v_pk_fma_f32 v[222:223], v[68:69], v[218:219], v[222:223]
	v_pk_fma_f32 v[224:225], v[70:71], v[220:221], v[224:225]
	v_cvt_pk_f32_fp8_e32 v[218:219], v167
	v_cvt_pk_f32_fp8_sdwa v[220:221], v167 src0_sel:WORD_1
	v_pk_fma_f32 v[222:223], v[72:73], v[214:215], v[222:223]
	v_pk_fma_f32 v[224:225], v[74:75], v[216:217], v[224:225]
	v_pk_fma_f32 v[222:223], v[76:77], v[218:219], v[222:223]
	v_pk_fma_f32 v[224:225], v[78:79], v[220:221], v[224:225]
	v_pk_add_f32 v[222:223], v[222:223], v[224:225]
	s_nop 0
	v_add_f32_e32 v231, v222, v223
	v_cvt_pk_f32_fp8_e32 v[214:215], v168
	v_cvt_pk_f32_fp8_sdwa v[216:217], v168 src0_sel:WORD_1
	v_cvt_pk_f32_fp8_e32 v[218:219], v169
	v_cvt_pk_f32_fp8_sdwa v[220:221], v169 src0_sel:WORD_1
	v_pk_mul_f32 v[222:223], v[64:65], v[214:215]
	v_pk_mul_f32 v[224:225], v[66:67], v[216:217]
	v_cvt_pk_f32_fp8_e32 v[214:215], v170
	v_cvt_pk_f32_fp8_sdwa v[216:217], v170 src0_sel:WORD_1
	v_pk_fma_f32 v[222:223], v[68:69], v[218:219], v[222:223]
	v_pk_fma_f32 v[224:225], v[70:71], v[220:221], v[224:225]
	v_cvt_pk_f32_fp8_e32 v[218:219], v171
	v_cvt_pk_f32_fp8_sdwa v[220:221], v171 src0_sel:WORD_1
	v_pk_fma_f32 v[222:223], v[72:73], v[214:215], v[222:223]
	v_pk_fma_f32 v[224:225], v[74:75], v[216:217], v[224:225]
	v_pk_fma_f32 v[222:223], v[76:77], v[218:219], v[222:223]
	v_pk_fma_f32 v[224:225], v[78:79], v[220:221], v[224:225]
	v_pk_add_f32 v[222:223], v[222:223], v[224:225]
	s_nop 0
	v_add_f32_e32 v232, v222, v223
	v_cvt_pk_f32_fp8_e32 v[214:215], v172
	v_cvt_pk_f32_fp8_sdwa v[216:217], v172 src0_sel:WORD_1
	v_cvt_pk_f32_fp8_e32 v[218:219], v173
	v_cvt_pk_f32_fp8_sdwa v[220:221], v173 src0_sel:WORD_1
	v_pk_mul_f32 v[222:223], v[64:65], v[214:215]
	v_pk_mul_f32 v[224:225], v[66:67], v[216:217]
	v_cvt_pk_f32_fp8_e32 v[214:215], v174
	v_cvt_pk_f32_fp8_sdwa v[216:217], v174 src0_sel:WORD_1
	v_pk_fma_f32 v[222:223], v[68:69], v[218:219], v[222:223]
	v_pk_fma_f32 v[224:225], v[70:71], v[220:221], v[224:225]
	v_cvt_pk_f32_fp8_e32 v[218:219], v175
	v_cvt_pk_f32_fp8_sdwa v[220:221], v175 src0_sel:WORD_1
	v_pk_fma_f32 v[222:223], v[72:73], v[214:215], v[222:223]
	v_pk_fma_f32 v[224:225], v[74:75], v[216:217], v[224:225]
	v_pk_fma_f32 v[222:223], v[76:77], v[218:219], v[222:223]
	v_pk_fma_f32 v[224:225], v[78:79], v[220:221], v[224:225]
	v_pk_add_f32 v[222:223], v[222:223], v[224:225]
	s_nop 0
	v_add_f32_e32 v233, v222, v223
	v_permlane32_swap_b32_e32 v226, v230
	v_permlane32_swap_b32_e32 v227, v231
	v_permlane32_swap_b32_e32 v228, v232
	v_permlane32_swap_b32_e32 v229, v233
	v_add_f32_e32 v226, v226, v230
	v_add_f32_e32 v228, v228, v232
	v_add_f32_e32 v227, v227, v231
	v_add_f32_e32 v229, v229, v233
	s_nop 1
	v_permlane16_swap_b32_e32 v226, v228
	v_permlane16_swap_b32_e32 v227, v229
	v_add_f32_e32 v226, v226, v228
	v_add_f32_e32 v227, v227, v229
	s_nop 0
	v_cndmask_b32_e64 v230, v226, v227, s[24:25]
	v_cndmask_b32_e64 v231, v227, v226, s[24:25]
	s_nop 1
	v_add_f32_dpp v232, v231, v230 row_ror:8 row_mask:0xf bank_mask:0xf
	s_nop 1
	v_add_f32_dpp v233, v232, v232 quad_perm:[1,0,3,2] row_mask:0xf bank_mask:0xf
	s_nop 1
	v_add_f32_dpp v232, v233, v233 quad_perm:[2,3,0,1] row_mask:0xf bank_mask:0xf
	s_nop 1
	v_add_f32_dpp v233, v232, v232 row_half_mirror row_mask:0xf bank_mask:0xf
	ds_write_b32 v235, v233 offset:34848
	v_readlane_b32 s48, v141, s72
	v_readlane_b32 s49, v141, s73
	v_readlane_b32 s50, v141, s74
	v_readlane_b32 s51, v141, s75
	v_readlane_b32 s52, v141, s76
	v_readlane_b32 s53, v141, s77
	v_readlane_b32 s54, v141, s78
	v_readlane_b32 s55, v141, s79
	s_add_u32 s32, s0, s48
	s_addc_u32 s33, s1, 0
	s_add_u32 s34, s0, s49
	s_addc_u32 s35, s1, 0
	s_add_u32 s36, s0, s50
	s_addc_u32 s37, s1, 0
	s_add_u32 s38, s0, s51
	s_addc_u32 s39, s1, 0
	s_add_u32 s40, s0, s52
	s_addc_u32 s41, s1, 0
	s_add_u32 s42, s0, s53
	s_addc_u32 s43, s1, 0
	s_add_u32 s44, s0, s54
	s_addc_u32 s45, s1, 0
	s_add_u32 s46, s0, s55
	s_addc_u32 s47, s1, 0
	global_load_dwordx4 v[144:147], v234, s[32:33]
	global_load_dwordx4 v[148:151], v234, s[34:35]
	global_load_dwordx4 v[152:155], v234, s[36:37]
	global_load_dwordx4 v[156:159], v234, s[38:39]
	global_load_dwordx4 v[160:163], v234, s[40:41]
	global_load_dwordx4 v[164:167], v234, s[42:43]
	global_load_dwordx4 v[168:171], v234, s[44:45]
	global_load_dwordx4 v[172:175], v234, s[46:47]
	s_waitcnt vmcnt(8)
; template <bool STORE>
; DI void peer_item(const Params& p, int item, char* smem) {
;     ...
;       for (int u = 0; u < 8; ++u) {
;         int e = e_s[tl * 128 + k + u];
;         uq[u] = *(const u32x4*)(U8 + (size_t)e * 1024 + lane * 16);
;       }
;       float part[8];
; #pragma unroll
;       for (int u = 0; u < 8; ++u) {
;         float d = 0.f;
; #pragma unroll
;         for (int i = 0; i < 4; ++i) {
;           f32x2_t lo = __builtin_amdgcn_cvt_pk_f32_fp8((int)uq[u][i], false);
;           f32x2_t hi = __builtin_amdgcn_cvt_pk_f32_fp8((int)uq[u][i], true);
;           d += xf[4 * i] * lo.x + xf[4 * i + 1] * lo.y + xf[4 * i + 2] * hi.x + xf[4 * i + 3] * hi.y;
;         }
;         part[u] = d;
	v_cvt_pk_f32_fp8_e32 v[214:215], v176
	v_cvt_pk_f32_fp8_sdwa v[216:217], v176 src0_sel:WORD_1
	v_cvt_pk_f32_fp8_e32 v[218:219], v177
	v_cvt_pk_f32_fp8_sdwa v[220:221], v177 src0_sel:WORD_1
	v_pk_mul_f32 v[222:223], v[80:81], v[214:215]
	v_pk_mul_f32 v[224:225], v[82:83], v[216:217]
	v_cvt_pk_f32_fp8_e32 v[214:215], v178
	v_cvt_pk_f32_fp8_sdwa v[216:217], v178 src0_sel:WORD_1
	v_pk_fma_f32 v[222:223], v[84:85], v[218:219], v[222:223]
	v_pk_fma_f32 v[224:225], v[86:87], v[220:221], v[224:225]
	v_cvt_pk_f32_fp8_e32 v[218:219], v179
	v_cvt_pk_f32_fp8_sdwa v[220:221], v179 src0_sel:WORD_1
	v_pk_fma_f32 v[222:223], v[88:89], v[214:215], v[222:223]
	v_pk_fma_f32 v[224:225], v[90:91], v[216:217], v[224:225]
	v_pk_fma_f32 v[222:223], v[92:93], v[218:219], v[222:223]
	v_pk_fma_f32 v[224:225], v[94:95], v[220:221], v[224:225]
	v_pk_add_f32 v[222:223], v[222:223], v[224:225]
	s_nop 0
	v_add_f32_e32 v226, v222, v223
	v_cvt_pk_f32_fp8_e32 v[214:215], v180
	v_cvt_pk_f32_fp8_sdwa v[216:217], v180 src0_sel:WORD_1
	v_cvt_pk_f32_fp8_e32 v[218:219], v181
	v_cvt_pk_f32_fp8_sdwa v[220:221], v181 src0_sel:WORD_1
	v_pk_mul_f32 v[222:223], v[80:81], v[214:215]
	v_pk_mul_f32 v[224:225], v[82:83], v[216:217]
	v_cvt_pk_f32_fp8_e32 v[214:215], v182
	v_cvt_pk_f32_fp8_sdwa v[216:217], v182 src0_sel:WORD_1
	v_pk_fma_f32 v[222:223], v[84:85], v[218:219], v[222:223]
	v_pk_fma_f32 v[224:225], v[86:87], v[220:221], v[224:225]
	v_cvt_pk_f32_fp8_e32 v[218:219], v183
	v_cvt_pk_f32_fp8_sdwa v[220:221], v183 src0_sel:WORD_1
	v_pk_fma_f32 v[222:223], v[88:89], v[214:215], v[222:223]
	v_pk_fma_f32 v[224:225], v[90:91], v[216:217], v[224:225]
	v_pk_fma_f32 v[222:223], v[92:93], v[218:219], v[222:223]
	v_pk_fma_f32 v[224:225], v[94:95], v[220:221], v[224:225]
	v_pk_add_f32 v[222:223], v[222:223], v[224:225]
	s_nop 0
	v_add_f32_e32 v227, v222, v223
	v_cvt_pk_f32_fp8_e32 v[214:215], v184
	v_cvt_pk_f32_fp8_sdwa v[216:217], v184 src0_sel:WORD_1
	v_cvt_pk_f32_fp8_e32 v[218:219], v185
	v_cvt_pk_f32_fp8_sdwa v[220:221], v185 src0_sel:WORD_1
	v_pk_mul_f32 v[222:223], v[80:81], v[214:215]
	v_pk_mul_f32 v[224:225], v[82:83], v[216:217]
	v_cvt_pk_f32_fp8_e32 v[214:215], v186
	v_cvt_pk_f32_fp8_sdwa v[216:217], v186 src0_sel:WORD_1
	v_pk_fma_f32 v[222:223], v[84:85], v[218:219], v[222:223]
	v_pk_fma_f32 v[224:225], v[86:87], v[220:221], v[224:225]
	v_cvt_pk_f32_fp8_e32 v[218:219], v187
	v_cvt_pk_f32_fp8_sdwa v[220:221], v187 src0_sel:WORD_1
	v_pk_fma_f32 v[222:223], v[88:89], v[214:215], v[222:223]
	v_pk_fma_f32 v[224:225], v[90:91], v[216:217], v[224:225]
	v_pk_fma_f32 v[222:223], v[92:93], v[218:219], v[222:223]
	v_pk_fma_f32 v[224:225], v[94:95], v[220:221], v[224:225]
	v_pk_add_f32 v[222:223], v[222:223], v[224:225]
	s_nop 0
	v_add_f32_e32 v228, v222, v223
	v_cvt_pk_f32_fp8_e32 v[214:215], v188
	v_cvt_pk_f32_fp8_sdwa v[216:217], v188 src0_sel:WORD_1
	v_cvt_pk_f32_fp8_e32 v[218:219], v189
	v_cvt_pk_f32_fp8_sdwa v[220:221], v189 src0_sel:WORD_1
	v_pk_mul_f32 v[222:223], v[80:81], v[214:215]
	v_pk_mul_f32 v[224:225], v[82:83], v[216:217]
	v_cvt_pk_f32_fp8_e32 v[214:215], v190
	v_cvt_pk_f32_fp8_sdwa v[216:217], v190 src0_sel:WORD_1
	v_pk_fma_f32 v[222:223], v[84:85], v[218:219], v[222:223]
	v_pk_fma_f32 v[224:225], v[86:87], v[220:221], v[224:225]
	v_cvt_pk_f32_fp8_e32 v[218:219], v191
	v_cvt_pk_f32_fp8_sdwa v[220:221], v191 src0_sel:WORD_1
	v_pk_fma_f32 v[222:223], v[88:89], v[214:215], v[222:223]
	v_pk_fma_f32 v[224:225], v[90:91], v[216:217], v[224:225]
	v_pk_fma_f32 v[222:223], v[92:93], v[218:219], v[222:223]
	v_pk_fma_f32 v[224:225], v[94:95], v[220:221], v[224:225]
	v_pk_add_f32 v[222:223], v[222:223], v[224:225]
	s_nop 0
	v_add_f32_e32 v229, v222, v223
	v_cvt_pk_f32_fp8_e32 v[214:215], v192
	v_cvt_pk_f32_fp8_sdwa v[216:217], v192 src0_sel:WORD_1
	v_cvt_pk_f32_fp8_e32 v[218:219], v193
	v_cvt_pk_f32_fp8_sdwa v[220:221], v193 src0_sel:WORD_1
	v_pk_mul_f32 v[222:223], v[80:81], v[214:215]
	v_pk_mul_f32 v[224:225], v[82:83], v[216:217]
	v_cvt_pk_f32_fp8_e32 v[214:215], v194
	v_cvt_pk_f32_fp8_sdwa v[216:217], v194 src0_sel:WORD_1
	v_pk_fma_f32 v[222:223], v[84:85], v[218:219], v[222:223]
	v_pk_fma_f32 v[224:225], v[86:87], v[220:221], v[224:225]
	v_cvt_pk_f32_fp8_e32 v[218:219], v195
	v_cvt_pk_f32_fp8_sdwa v[220:221], v195 src0_sel:WORD_1
	v_pk_fma_f32 v[222:223], v[88:89], v[214:215], v[222:223]
	v_pk_fma_f32 v[224:225], v[90:91], v[216:217], v[224:225]
	v_pk_fma_f32 v[222:223], v[92:93], v[218:219], v[222:223]
	v_pk_fma_f32 v[224:225], v[94:95], v[220:221], v[224:225]
	v_pk_add_f32 v[222:223], v[222:223], v[224:225]
	s_nop 0
	v_add_f32_e32 v230, v222, v223
	v_cvt_pk_f32_fp8_e32 v[214:215], v196
	v_cvt_pk_f32_fp8_sdwa v[216:217], v196 src0_sel:WORD_1
	v_cvt_pk_f32_fp8_e32 v[218:219], v197
	v_cvt_pk_f32_fp8_sdwa v[220:221], v197 src0_sel:WORD_1
	v_pk_mul_f32 v[222:223], v[80:81], v[214:215]
	v_pk_mul_f32 v[224:225], v[82:83], v[216:217]
	v_cvt_pk_f32_fp8_e32 v[214:215], v198
	v_cvt_pk_f32_fp8_sdwa v[216:217], v198 src0_sel:WORD_1
	v_pk_fma_f32 v[222:223], v[84:85], v[218:219], v[222:223]
	v_pk_fma_f32 v[224:225], v[86:87], v[220:221], v[224:225]
	v_cvt_pk_f32_fp8_e32 v[218:219], v199
	v_cvt_pk_f32_fp8_sdwa v[220:221], v199 src0_sel:WORD_1
	v_pk_fma_f32 v[222:223], v[88:89], v[214:215], v[222:223]
	v_pk_fma_f32 v[224:225], v[90:91], v[216:217], v[224:225]
	v_pk_fma_f32 v[222:223], v[92:93], v[218:219], v[222:223]
	v_pk_fma_f32 v[224:225], v[94:95], v[220:221], v[224:225]
	v_pk_add_f32 v[222:223], v[222:223], v[224:225]
	s_nop 0
	v_add_f32_e32 v231, v222, v223
	v_cvt_pk_f32_fp8_e32 v[214:215], v200
	v_cvt_pk_f32_fp8_sdwa v[216:217], v200 src0_sel:WORD_1
	v_cvt_pk_f32_fp8_e32 v[218:219], v201
; template <bool STORE>
; DI void peer_item(const Params& p, int item, char* smem) {
;     ...
;       for (int u = 0; u < 8; ++u) {
;         int e = e_s[tl * 128 + k + u];
;         uq[u] = *(const u32x4*)(U8 + (size_t)e * 1024 + lane * 16);
;       }
;       float part[8];
; #pragma unroll
;       for (int u = 0; u < 8; ++u) {
;         float d = 0.f;
; #pragma unroll
;         for (int i = 0; i < 4; ++i) {
;           f32x2_t lo = __builtin_amdgcn_cvt_pk_f32_fp8((int)uq[u][i], false);
;           f32x2_t hi = __builtin_amdgcn_cvt_pk_f32_fp8((int)uq[u][i], true);
;           d += xf[4 * i] * lo.x + xf[4 * i + 1] * lo.y + xf[4 * i + 2] * hi.x + xf[4 * i + 3] * hi.y;
;         }
;         part[u] = d;
;       }
;       float q4[4], r2[2], h;
; #pragma unroll
;       for (int j = 0; j < 4; ++j) {
;         float mine = b5 ? part[j + 4] : part[j];
;         float other = b5 ? part[j] : part[j + 4];
;         q4[j] = mine + __shfl_xor(other, 32);
;       }
; #pragma unroll
;       for (int j = 0; j < 2; ++j) {
;         float mine = b4 ? q4[j + 2] : q4[j];
;         float other = b4 ? q4[j] : q4[j + 2];
;         r2[j] = mine + __shfl_xor(other, 16);
;       }
;       {
;         float mine = b3 ? r2[1] : r2[0];
;         float other = b3 ? r2[0] : r2[1];
;         h = mine + __shfl_xor(other, 8);
;       }
;       h += __shfl_xor(h, 4);
;       h += __shfl_xor(h, 2);
;       h += __shfl_xor(h, 1);
	v_cvt_pk_f32_fp8_sdwa v[220:221], v201 src0_sel:WORD_1
	v_pk_mul_f32 v[222:223], v[80:81], v[214:215]
	v_pk_mul_f32 v[224:225], v[82:83], v[216:217]
	v_cvt_pk_f32_fp8_e32 v[214:215], v202
	v_cvt_pk_f32_fp8_sdwa v[216:217], v202 src0_sel:WORD_1
	v_pk_fma_f32 v[222:223], v[84:85], v[218:219], v[222:223]
	v_pk_fma_f32 v[224:225], v[86:87], v[220:221], v[224:225]
	v_cvt_pk_f32_fp8_e32 v[218:219], v203
	v_cvt_pk_f32_fp8_sdwa v[220:221], v203 src0_sel:WORD_1
	v_pk_fma_f32 v[222:223], v[88:89], v[214:215], v[222:223]
	v_pk_fma_f32 v[224:225], v[90:91], v[216:217], v[224:225]
	v_pk_fma_f32 v[222:223], v[92:93], v[218:219], v[222:223]
	v_pk_fma_f32 v[224:225], v[94:95], v[220:221], v[224:225]
	v_pk_add_f32 v[222:223], v[222:223], v[224:225]
	s_nop 0
	v_add_f32_e32 v232, v222, v223
	v_cvt_pk_f32_fp8_e32 v[214:215], v204
	v_cvt_pk_f32_fp8_sdwa v[216:217], v204 src0_sel:WORD_1
	v_cvt_pk_f32_fp8_e32 v[218:219], v205
	v_cvt_pk_f32_fp8_sdwa v[220:221], v205 src0_sel:WORD_1
	v_pk_mul_f32 v[222:223], v[80:81], v[214:215]
	v_pk_mul_f32 v[224:225], v[82:83], v[216:217]
	v_cvt_pk_f32_fp8_e32 v[214:215], v206
	v_cvt_pk_f32_fp8_sdwa v[216:217], v206 src0_sel:WORD_1
	v_pk_fma_f32 v[222:223], v[84:85], v[218:219], v[222:223]
	v_pk_fma_f32 v[224:225], v[86:87], v[220:221], v[224:225]
	v_cvt_pk_f32_fp8_e32 v[218:219], v207
	v_cvt_pk_f32_fp8_sdwa v[220:221], v207 src0_sel:WORD_1
	v_pk_fma_f32 v[222:223], v[88:89], v[214:215], v[222:223]
	v_pk_fma_f32 v[224:225], v[90:91], v[216:217], v[224:225]
	v_pk_fma_f32 v[222:223], v[92:93], v[218:219], v[222:223]
	v_pk_fma_f32 v[224:225], v[94:95], v[220:221], v[224:225]
	v_pk_add_f32 v[222:223], v[222:223], v[224:225]
	s_nop 0
	v_add_f32_e32 v233, v222, v223
	v_permlane32_swap_b32_e32 v226, v230
	v_permlane32_swap_b32_e32 v227, v231
	v_permlane32_swap_b32_e32 v228, v232
	v_permlane32_swap_b32_e32 v229, v233
	v_add_f32_e32 v226, v226, v230
	v_add_f32_e32 v228, v228, v232
	v_add_f32_e32 v227, v227, v231
	v_add_f32_e32 v229, v229, v233
	s_nop 1
	v_permlane16_swap_b32_e32 v226, v228
	v_permlane16_swap_b32_e32 v227, v229
	v_add_f32_e32 v226, v226, v228
	v_add_f32_e32 v227, v227, v229
	s_nop 0
	v_cndmask_b32_e64 v230, v226, v227, s[24:25]
	v_cndmask_b32_e64 v231, v227, v226, s[24:25]
	s_nop 1
	v_add_f32_dpp v232, v231, v230 row_ror:8 row_mask:0xf bank_mask:0xf
	s_nop 1
	v_add_f32_dpp v233, v232, v232 quad_perm:[1,0,3,2] row_mask:0xf bank_mask:0xf
	s_nop 1
	v_add_f32_dpp v232, v233, v233 quad_perm:[2,3,0,1] row_mask:0xf bank_mask:0xf
	s_nop 1
	v_add_f32_dpp v233, v232, v232 row_half_mirror row_mask:0xf bank_mask:0xf
	ds_write_b32 v235, v233 offset:35360
	v_readlane_b32 s48, v143, s72
	v_readlane_b32 s49, v143, s73
	v_readlane_b32 s50, v143, s74
	v_readlane_b32 s51, v143, s75
	v_readlane_b32 s52, v143, s76
	v_readlane_b32 s53, v143, s77
	v_readlane_b32 s54, v143, s78
	v_readlane_b32 s55, v143, s79
	s_add_u32 s32, s0, s48
	s_addc_u32 s33, s1, 0
	s_add_u32 s34, s0, s49
	s_addc_u32 s35, s1, 0
	s_add_u32 s36, s0, s50
	s_addc_u32 s37, s1, 0
	s_add_u32 s38, s0, s51
	s_addc_u32 s39, s1, 0
	s_add_u32 s40, s0, s52
	s_addc_u32 s41, s1, 0
	s_add_u32 s42, s0, s53
	s_addc_u32 s43, s1, 0
	s_add_u32 s44, s0, s54
	s_addc_u32 s45, s1, 0
	s_add_u32 s46, s0, s55
	s_addc_u32 s47, s1, 0
	global_load_dwordx4 v[176:179], v234, s[32:33]
	global_load_dwordx4 v[180:183], v234, s[34:35]
	global_load_dwordx4 v[184:187], v234, s[36:37]
	global_load_dwordx4 v[188:191], v234, s[38:39]
	global_load_dwordx4 v[192:195], v234, s[40:41]
	global_load_dwordx4 v[196:199], v234, s[42:43]
	global_load_dwordx4 v[200:203], v234, s[44:45]
	global_load_dwordx4 v[204:207], v234, s[46:47]
	s_waitcnt vmcnt(8)
	v_cvt_pk_f32_fp8_e32 v[214:215], v144
	v_cvt_pk_f32_fp8_sdwa v[216:217], v144 src0_sel:WORD_1
	v_cvt_pk_f32_fp8_e32 v[218:219], v145
	v_cvt_pk_f32_fp8_sdwa v[220:221], v145 src0_sel:WORD_1
	v_pk_mul_f32 v[222:223], v[96:97], v[214:215]
	v_pk_mul_f32 v[224:225], v[98:99], v[216:217]
	v_cvt_pk_f32_fp8_e32 v[214:215], v146
	v_cvt_pk_f32_fp8_sdwa v[216:217], v146 src0_sel:WORD_1
	v_pk_fma_f32 v[222:223], v[100:101], v[218:219], v[222:223]
	v_pk_fma_f32 v[224:225], v[102:103], v[220:221], v[224:225]
	v_cvt_pk_f32_fp8_e32 v[218:219], v147
	v_cvt_pk_f32_fp8_sdwa v[220:221], v147 src0_sel:WORD_1
	v_pk_fma_f32 v[222:223], v[104:105], v[214:215], v[222:223]
	v_pk_fma_f32 v[224:225], v[106:107], v[216:217], v[224:225]
	v_pk_fma_f32 v[222:223], v[108:109], v[218:219], v[222:223]
	v_pk_fma_f32 v[224:225], v[110:111], v[220:221], v[224:225]
	v_pk_add_f32 v[222:223], v[222:223], v[224:225]
	s_nop 0
	v_add_f32_e32 v226, v222, v223
	v_cvt_pk_f32_fp8_e32 v[214:215], v148
	v_cvt_pk_f32_fp8_sdwa v[216:217], v148 src0_sel:WORD_1
	v_cvt_pk_f32_fp8_e32 v[218:219], v149
	v_cvt_pk_f32_fp8_sdwa v[220:221], v149 src0_sel:WORD_1
	v_pk_mul_f32 v[222:223], v[96:97], v[214:215]
	v_pk_mul_f32 v[224:225], v[98:99], v[216:217]
	v_cvt_pk_f32_fp8_e32 v[214:215], v150
	v_cvt_pk_f32_fp8_sdwa v[216:217], v150 src0_sel:WORD_1
	v_pk_fma_f32 v[222:223], v[100:101], v[218:219], v[222:223]
	v_pk_fma_f32 v[224:225], v[102:103], v[220:221], v[224:225]
	v_cvt_pk_f32_fp8_e32 v[218:219], v151
	v_cvt_pk_f32_fp8_sdwa v[220:221], v151 src0_sel:WORD_1
	v_pk_fma_f32 v[222:223], v[104:105], v[214:215], v[222:223]
	v_pk_fma_f32 v[224:225], v[106:107], v[216:217], v[224:225]
	v_pk_fma_f32 v[222:223], v[108:109], v[218:219], v[222:223]
	v_pk_fma_f32 v[224:225], v[110:111], v[220:221], v[224:225]
	v_pk_add_f32 v[222:223], v[222:223], v[224:225]
	s_nop 0
	v_add_f32_e32 v227, v222, v223
	v_cvt_pk_f32_fp8_e32 v[214:215], v152
	v_cvt_pk_f32_fp8_sdwa v[216:217], v152 src0_sel:WORD_1
	v_cvt_pk_f32_fp8_e32 v[218:219], v153
; template <bool STORE>
; DI void peer_item(const Params& p, int item, char* smem) {
;     ...
;       for (int u = 0; u < 8; ++u) {
;         int e = e_s[tl * 128 + k + u];
;         uq[u] = *(const u32x4*)(U8 + (size_t)e * 1024 + lane * 16);
;       }
;       float part[8];
; #pragma unroll
;       for (int u = 0; u < 8; ++u) {
;         float d = 0.f;
; #pragma unroll
;         for (int i = 0; i < 4; ++i) {
;           f32x2_t lo = __builtin_amdgcn_cvt_pk_f32_fp8((int)uq[u][i], false);
;           f32x2_t hi = __builtin_amdgcn_cvt_pk_f32_fp8((int)uq[u][i], true);
;           d += xf[4 * i] * lo.x + xf[4 * i + 1] * lo.y + xf[4 * i + 2] * hi.x + xf[4 * i + 3] * hi.y;
;         }
;         part[u] = d;
;       }
;       float q4[4], r2[2], h;
; #pragma unroll
;       for (int j = 0; j < 4; ++j) {
;         float mine = b5 ? part[j + 4] : part[j];
;         float other = b5 ? part[j] : part[j + 4];
;         q4[j] = mine + __shfl_xor(other, 32);
;       }
; #pragma unroll
;       for (int j = 0; j < 2; ++j) {
;         float mine = b4 ? q4[j + 2] : q4[j];
;         float other = b4 ? q4[j] : q4[j + 2];
;         r2[j] = mine + __shfl_xor(other, 16);
;       }
;       {
;         float mine = b3 ? r2[1] : r2[0];
;         float other = b3 ? r2[0] : r2[1];
;         h = mine + __shfl_xor(other, 8);
;       }
;       h += __shfl_xor(h, 4);
;       h += __shfl_xor(h, 2);
;       h += __shfl_xor(h, 1);
	v_cvt_pk_f32_fp8_sdwa v[220:221], v153 src0_sel:WORD_1
	v_pk_mul_f32 v[222:223], v[96:97], v[214:215]
	v_pk_mul_f32 v[224:225], v[98:99], v[216:217]
	v_cvt_pk_f32_fp8_e32 v[214:215], v154
	v_cvt_pk_f32_fp8_sdwa v[216:217], v154 src0_sel:WORD_1
	v_pk_fma_f32 v[222:223], v[100:101], v[218:219], v[222:223]
	v_pk_fma_f32 v[224:225], v[102:103], v[220:221], v[224:225]
	v_cvt_pk_f32_fp8_e32 v[218:219], v155
	v_cvt_pk_f32_fp8_sdwa v[220:221], v155 src0_sel:WORD_1
	v_pk_fma_f32 v[222:223], v[104:105], v[214:215], v[222:223]
	v_pk_fma_f32 v[224:225], v[106:107], v[216:217], v[224:225]
	v_pk_fma_f32 v[222:223], v[108:109], v[218:219], v[222:223]
	v_pk_fma_f32 v[224:225], v[110:111], v[220:221], v[224:225]
	v_pk_add_f32 v[222:223], v[222:223], v[224:225]
	s_nop 0
	v_add_f32_e32 v228, v222, v223
	v_cvt_pk_f32_fp8_e32 v[214:215], v156
	v_cvt_pk_f32_fp8_sdwa v[216:217], v156 src0_sel:WORD_1
	v_cvt_pk_f32_fp8_e32 v[218:219], v157
	v_cvt_pk_f32_fp8_sdwa v[220:221], v157 src0_sel:WORD_1
	v_pk_mul_f32 v[222:223], v[96:97], v[214:215]
	v_pk_mul_f32 v[224:225], v[98:99], v[216:217]
	v_cvt_pk_f32_fp8_e32 v[214:215], v158
	v_cvt_pk_f32_fp8_sdwa v[216:217], v158 src0_sel:WORD_1
	v_pk_fma_f32 v[222:223], v[100:101], v[218:219], v[222:223]
	v_pk_fma_f32 v[224:225], v[102:103], v[220:221], v[224:225]
	v_cvt_pk_f32_fp8_e32 v[218:219], v159
	v_cvt_pk_f32_fp8_sdwa v[220:221], v159 src0_sel:WORD_1
	v_pk_fma_f32 v[222:223], v[104:105], v[214:215], v[222:223]
	v_pk_fma_f32 v[224:225], v[106:107], v[216:217], v[224:225]
	v_pk_fma_f32 v[222:223], v[108:109], v[218:219], v[222:223]
	v_pk_fma_f32 v[224:225], v[110:111], v[220:221], v[224:225]
	v_pk_add_f32 v[222:223], v[222:223], v[224:225]
	s_nop 0
	v_add_f32_e32 v229, v222, v223
	v_cvt_pk_f32_fp8_e32 v[214:215], v160
	v_cvt_pk_f32_fp8_sdwa v[216:217], v160 src0_sel:WORD_1
	v_cvt_pk_f32_fp8_e32 v[218:219], v161
	v_cvt_pk_f32_fp8_sdwa v[220:221], v161 src0_sel:WORD_1
	v_pk_mul_f32 v[222:223], v[96:97], v[214:215]
	v_pk_mul_f32 v[224:225], v[98:99], v[216:217]
	v_cvt_pk_f32_fp8_e32 v[214:215], v162
	v_cvt_pk_f32_fp8_sdwa v[216:217], v162 src0_sel:WORD_1
	v_pk_fma_f32 v[222:223], v[100:101], v[218:219], v[222:223]
	v_pk_fma_f32 v[224:225], v[102:103], v[220:221], v[224:225]
	v_cvt_pk_f32_fp8_e32 v[218:219], v163
	v_cvt_pk_f32_fp8_sdwa v[220:221], v163 src0_sel:WORD_1
	v_pk_fma_f32 v[222:223], v[104:105], v[214:215], v[222:223]
	v_pk_fma_f32 v[224:225], v[106:107], v[216:217], v[224:225]
	v_pk_fma_f32 v[222:223], v[108:109], v[218:219], v[222:223]
	v_pk_fma_f32 v[224:225], v[110:111], v[220:221], v[224:225]
	v_pk_add_f32 v[222:223], v[222:223], v[224:225]
	s_nop 0
	v_add_f32_e32 v230, v222, v223
	v_cvt_pk_f32_fp8_e32 v[214:215], v164
	v_cvt_pk_f32_fp8_sdwa v[216:217], v164 src0_sel:WORD_1
	v_cvt_pk_f32_fp8_e32 v[218:219], v165
	v_cvt_pk_f32_fp8_sdwa v[220:221], v165 src0_sel:WORD_1
	v_pk_mul_f32 v[222:223], v[96:97], v[214:215]
	v_pk_mul_f32 v[224:225], v[98:99], v[216:217]
	v_cvt_pk_f32_fp8_e32 v[214:215], v166
	v_cvt_pk_f32_fp8_sdwa v[216:217], v166 src0_sel:WORD_1
	v_pk_fma_f32 v[222:223], v[100:101], v[218:219], v[222:223]
	v_pk_fma_f32 v[224:225], v[102:103], v[220:221], v[224:225]
	v_cvt_pk_f32_fp8_e32 v[218:219], v167
	v_cvt_pk_f32_fp8_sdwa v[220:221], v167 src0_sel:WORD_1
	v_pk_fma_f32 v[222:223], v[104:105], v[214:215], v[222:223]
	v_pk_fma_f32 v[224:225], v[106:107], v[216:217], v[224:225]
	v_pk_fma_f32 v[222:223], v[108:109], v[218:219], v[222:223]
	v_pk_fma_f32 v[224:225], v[110:111], v[220:221], v[224:225]
	v_pk_add_f32 v[222:223], v[222:223], v[224:225]
	s_nop 0
	v_add_f32_e32 v231, v222, v223
	v_cvt_pk_f32_fp8_e32 v[214:215], v168
	v_cvt_pk_f32_fp8_sdwa v[216:217], v168 src0_sel:WORD_1
	v_cvt_pk_f32_fp8_e32 v[218:219], v169
	v_cvt_pk_f32_fp8_sdwa v[220:221], v169 src0_sel:WORD_1
	v_pk_mul_f32 v[222:223], v[96:97], v[214:215]
	v_pk_mul_f32 v[224:225], v[98:99], v[216:217]
	v_cvt_pk_f32_fp8_e32 v[214:215], v170
	v_cvt_pk_f32_fp8_sdwa v[216:217], v170 src0_sel:WORD_1
	v_pk_fma_f32 v[222:223], v[100:101], v[218:219], v[222:223]
	v_pk_fma_f32 v[224:225], v[102:103], v[220:221], v[224:225]
	v_cvt_pk_f32_fp8_e32 v[218:219], v171
	v_cvt_pk_f32_fp8_sdwa v[220:221], v171 src0_sel:WORD_1
	v_pk_fma_f32 v[222:223], v[104:105], v[214:215], v[222:223]
	v_pk_fma_f32 v[224:225], v[106:107], v[216:217], v[224:225]
	v_pk_fma_f32 v[222:223], v[108:109], v[218:219], v[222:223]
	v_pk_fma_f32 v[224:225], v[110:111], v[220:221], v[224:225]
	v_pk_add_f32 v[222:223], v[222:223], v[224:225]
	s_nop 0
	v_add_f32_e32 v232, v222, v223
	v_cvt_pk_f32_fp8_e32 v[214:215], v172
	v_cvt_pk_f32_fp8_sdwa v[216:217], v172 src0_sel:WORD_1
	v_cvt_pk_f32_fp8_e32 v[218:219], v173
	v_cvt_pk_f32_fp8_sdwa v[220:221], v173 src0_sel:WORD_1
	v_pk_mul_f32 v[222:223], v[96:97], v[214:215]
	v_pk_mul_f32 v[224:225], v[98:99], v[216:217]
	v_cvt_pk_f32_fp8_e32 v[214:215], v174
	v_cvt_pk_f32_fp8_sdwa v[216:217], v174 src0_sel:WORD_1
	v_pk_fma_f32 v[222:223], v[100:101], v[218:219], v[222:223]
	v_pk_fma_f32 v[224:225], v[102:103], v[220:221], v[224:225]
	v_cvt_pk_f32_fp8_e32 v[218:219], v175
	v_cvt_pk_f32_fp8_sdwa v[220:221], v175 src0_sel:WORD_1
	v_pk_fma_f32 v[222:223], v[104:105], v[214:215], v[222:223]
	v_pk_fma_f32 v[224:225], v[106:107], v[216:217], v[224:225]
	v_pk_fma_f32 v[222:223], v[108:109], v[218:219], v[222:223]
	v_pk_fma_f32 v[224:225], v[110:111], v[220:221], v[224:225]
	v_pk_add_f32 v[222:223], v[222:223], v[224:225]
	s_nop 0
	v_add_f32_e32 v233, v222, v223
	v_permlane32_swap_b32_e32 v226, v230
	v_permlane32_swap_b32_e32 v227, v231
	v_permlane32_swap_b32_e32 v228, v232
	v_permlane32_swap_b32_e32 v229, v233
	v_add_f32_e32 v226, v226, v230
; template <bool STORE>
; DI void peer_item(const Params& p, int item, char* smem) {
;     ...
;     for (int k = 0; k < 128; k += 8) {
;       u32x4 uq[8];
;       const int emine = e_s[tl * 128 + k + (lane >> 3)];
;       const float gmine = g_s[tl * 128 + k + (lane >> 3)];
;       const float su = SU[emine], sv = SV[emine];
; #pragma unroll
;       for (int u = 0; u < 8; ++u) {
;         int e = e_s[tl * 128 + k + u];
;         uq[u] = *(const u32x4*)(U8 + (size_t)e * 1024 + lane * 16);
;     ...
;       for (int j = 0; j < 4; ++j) {
;         float mine = b5 ? part[j + 4] : part[j];
;         float other = b5 ? part[j] : part[j + 4];
;         q4[j] = mine + __shfl_xor(other, 32);
;       }
; #pragma unroll
;       for (int j = 0; j < 2; ++j) {
;         float mine = b4 ? q4[j + 2] : q4[j];
;         float other = b4 ? q4[j] : q4[j + 2];
;         r2[j] = mine + __shfl_xor(other, 16);
;       }
;       {
;         float mine = b3 ? r2[1] : r2[0];
;         float other = b3 ? r2[0] : r2[1];
;         h = mine + __shfl_xor(other, 8);
;       }
;       h += __shfl_xor(h, 4);
;       h += __shfl_xor(h, 2);
;       h += __shfl_xor(h, 1);
	v_add_f32_e32 v228, v228, v232
	v_add_f32_e32 v227, v227, v231
	v_add_f32_e32 v229, v229, v233
	s_nop 1
	v_permlane16_swap_b32_e32 v226, v228
	v_permlane16_swap_b32_e32 v227, v229
	v_add_f32_e32 v226, v226, v228
	v_add_f32_e32 v227, v227, v229
	s_nop 0
	v_cndmask_b32_e64 v230, v226, v227, s[24:25]
	v_cndmask_b32_e64 v231, v227, v226, s[24:25]
	s_nop 1
	v_add_f32_dpp v232, v231, v230 row_ror:8 row_mask:0xf bank_mask:0xf
	s_nop 1
	v_add_f32_dpp v233, v232, v232 quad_perm:[1,0,3,2] row_mask:0xf bank_mask:0xf
	s_nop 1
	v_add_f32_dpp v232, v233, v233 quad_perm:[2,3,0,1] row_mask:0xf bank_mask:0xf
	s_nop 1
	v_add_f32_dpp v233, v232, v232 row_half_mirror row_mask:0xf bank_mask:0xf
	ds_write_b32 v235, v233 offset:35872
	s_add_u32 s72, s72, 8
	s_add_u32 s73, s73, 8
	s_add_u32 s74, s74, 8
	s_add_u32 s75, s75, 8
	s_add_u32 s76, s76, 8
	s_add_u32 s77, s77, 8
	s_add_u32 s78, s78, 8
	s_add_u32 s79, s79, 8
	s_and_b32 s72, s72, 63
	s_and_b32 s73, s73, 63
	s_and_b32 s74, s74, 63
	s_and_b32 s75, s75, 63
	s_and_b32 s76, s76, 63
	s_and_b32 s77, s77, 63
	s_and_b32 s78, s78, 63
	s_and_b32 s79, s79, 63
	v_readlane_b32 s48, v128, s72
	v_readlane_b32 s49, v128, s73
	v_readlane_b32 s50, v128, s74
	v_readlane_b32 s51, v128, s75
	v_readlane_b32 s52, v128, s76
	v_readlane_b32 s53, v128, s77
	v_readlane_b32 s54, v128, s78
	v_readlane_b32 s55, v128, s79
	s_add_u32 s32, s0, s48
	s_addc_u32 s33, s1, 0
	s_add_u32 s34, s0, s49
	s_addc_u32 s35, s1, 0
	s_add_u32 s36, s0, s50
	s_addc_u32 s37, s1, 0
	s_add_u32 s38, s0, s51
	s_addc_u32 s39, s1, 0
	s_add_u32 s40, s0, s52
	s_addc_u32 s41, s1, 0
	s_add_u32 s42, s0, s53
	s_addc_u32 s43, s1, 0
	s_add_u32 s44, s0, s54
	s_addc_u32 s45, s1, 0
	s_add_u32 s46, s0, s55
	s_addc_u32 s47, s1, 0
	global_load_dwordx4 v[144:147], v234, s[32:33]
	global_load_dwordx4 v[148:151], v234, s[34:35]
	global_load_dwordx4 v[152:155], v234, s[36:37]
	global_load_dwordx4 v[156:159], v234, s[38:39]
	global_load_dwordx4 v[160:163], v234, s[40:41]
	global_load_dwordx4 v[164:167], v234, s[42:43]
	global_load_dwordx4 v[168:171], v234, s[44:45]
	global_load_dwordx4 v[172:175], v234, s[46:47]
	s_waitcnt vmcnt(8)
	v_cvt_pk_f32_fp8_e32 v[214:215], v176
	v_cvt_pk_f32_fp8_sdwa v[216:217], v176 src0_sel:WORD_1
	v_cvt_pk_f32_fp8_e32 v[218:219], v177
	v_cvt_pk_f32_fp8_sdwa v[220:221], v177 src0_sel:WORD_1
	v_pk_mul_f32 v[222:223], v[112:113], v[214:215]
	v_pk_mul_f32 v[224:225], v[114:115], v[216:217]
	v_cvt_pk_f32_fp8_e32 v[214:215], v178
	v_cvt_pk_f32_fp8_sdwa v[216:217], v178 src0_sel:WORD_1
	v_pk_fma_f32 v[222:223], v[116:117], v[218:219], v[222:223]
	v_pk_fma_f32 v[224:225], v[118:119], v[220:221], v[224:225]
	v_cvt_pk_f32_fp8_e32 v[218:219], v179
	v_cvt_pk_f32_fp8_sdwa v[220:221], v179 src0_sel:WORD_1
	v_pk_fma_f32 v[222:223], v[120:121], v[214:215], v[222:223]
	v_pk_fma_f32 v[224:225], v[122:123], v[216:217], v[224:225]
	v_pk_fma_f32 v[222:223], v[124:125], v[218:219], v[222:223]
	v_pk_fma_f32 v[224:225], v[126:127], v[220:221], v[224:225]
	v_pk_add_f32 v[222:223], v[222:223], v[224:225]
	s_nop 0
	v_add_f32_e32 v226, v222, v223
	v_cvt_pk_f32_fp8_e32 v[214:215], v180
	v_cvt_pk_f32_fp8_sdwa v[216:217], v180 src0_sel:WORD_1
	v_cvt_pk_f32_fp8_e32 v[218:219], v181
	v_cvt_pk_f32_fp8_sdwa v[220:221], v181 src0_sel:WORD_1
	v_pk_mul_f32 v[222:223], v[112:113], v[214:215]
	v_pk_mul_f32 v[224:225], v[114:115], v[216:217]
	v_cvt_pk_f32_fp8_e32 v[214:215], v182
	v_cvt_pk_f32_fp8_sdwa v[216:217], v182 src0_sel:WORD_1
	v_pk_fma_f32 v[222:223], v[116:117], v[218:219], v[222:223]
	v_pk_fma_f32 v[224:225], v[118:119], v[220:221], v[224:225]
	v_cvt_pk_f32_fp8_e32 v[218:219], v183
	v_cvt_pk_f32_fp8_sdwa v[220:221], v183 src0_sel:WORD_1
	v_pk_fma_f32 v[222:223], v[120:121], v[214:215], v[222:223]
	v_pk_fma_f32 v[224:225], v[122:123], v[216:217], v[224:225]
	v_pk_fma_f32 v[222:223], v[124:125], v[218:219], v[222:223]
	v_pk_fma_f32 v[224:225], v[126:127], v[220:221], v[224:225]
	v_pk_add_f32 v[222:223], v[222:223], v[224:225]
	s_nop 0
	v_add_f32_e32 v227, v222, v223
	v_cvt_pk_f32_fp8_e32 v[214:215], v184
	v_cvt_pk_f32_fp8_sdwa v[216:217], v184 src0_sel:WORD_1
	v_cvt_pk_f32_fp8_e32 v[218:219], v185
	v_cvt_pk_f32_fp8_sdwa v[220:221], v185 src0_sel:WORD_1
	v_pk_mul_f32 v[222:223], v[112:113], v[214:215]
	v_pk_mul_f32 v[224:225], v[114:115], v[216:217]
	v_cvt_pk_f32_fp8_e32 v[214:215], v186
	v_cvt_pk_f32_fp8_sdwa v[216:217], v186 src0_sel:WORD_1
	v_pk_fma_f32 v[222:223], v[116:117], v[218:219], v[222:223]
	v_pk_fma_f32 v[224:225], v[118:119], v[220:221], v[224:225]
	v_cvt_pk_f32_fp8_e32 v[218:219], v187
	v_cvt_pk_f32_fp8_sdwa v[220:221], v187 src0_sel:WORD_1
	v_pk_fma_f32 v[222:223], v[120:121], v[214:215], v[222:223]
	v_pk_fma_f32 v[224:225], v[122:123], v[216:217], v[224:225]
	v_pk_fma_f32 v[222:223], v[124:125], v[218:219], v[222:223]
	v_pk_fma_f32 v[224:225], v[126:127], v[220:221], v[224:225]
	v_pk_add_f32 v[222:223], v[222:223], v[224:225]
	s_nop 0
	v_add_f32_e32 v228, v222, v223
	v_cvt_pk_f32_fp8_e32 v[214:215], v188
	v_cvt_pk_f32_fp8_sdwa v[216:217], v188 src0_sel:WORD_1
	v_cvt_pk_f32_fp8_e32 v[218:219], v189
	v_cvt_pk_f32_fp8_sdwa v[220:221], v189 src0_sel:WORD_1
	v_pk_mul_f32 v[222:223], v[112:113], v[214:215]
	v_pk_mul_f32 v[224:225], v[114:115], v[216:217]
	v_cvt_pk_f32_fp8_e32 v[214:215], v190
	v_cvt_pk_f32_fp8_sdwa v[216:217], v190 src0_sel:WORD_1
	v_pk_fma_f32 v[222:223], v[116:117], v[218:219], v[222:223]
	v_pk_fma_f32 v[224:225], v[118:119], v[220:221], v[224:225]
	v_cvt_pk_f32_fp8_e32 v[218:219], v191
	v_cvt_pk_f32_fp8_sdwa v[220:221], v191 src0_sel:WORD_1
	v_pk_fma_f32 v[222:223], v[120:121], v[214:215], v[222:223]
	v_pk_fma_f32 v[224:225], v[122:123], v[216:217], v[224:225]
; template <bool STORE>
; DI void peer_item(const Params& p, int item, char* smem) {
;     ...
; #pragma unroll 2
;     for (int k = 0; k < 128; k += 8) {
;       u32x4 uq[8];
;       const int emine = e_s[tl * 128 + k + (lane >> 3)];
;       const float gmine = g_s[tl * 128 + k + (lane >> 3)];
;       const float su = SU[emine], sv = SV[emine];
; #pragma unroll
;       for (int u = 0; u < 8; ++u) {
;         int e = e_s[tl * 128 + k + u];
;         uq[u] = *(const u32x4*)(U8 + (size_t)e * 1024 + lane * 16);
;       }
;       float part[8];
; #pragma unroll
;       for (int u = 0; u < 8; ++u) {
;         float d = 0.f;
; #pragma unroll
;         for (int i = 0; i < 4; ++i) {
;           f32x2_t lo = __builtin_amdgcn_cvt_pk_f32_fp8((int)uq[u][i], false);
;           f32x2_t hi = __builtin_amdgcn_cvt_pk_f32_fp8((int)uq[u][i], true);
;           d += xf[4 * i] * lo.x + xf[4 * i + 1] * lo.y + xf[4 * i + 2] * hi.x + xf[4 * i + 3] * hi.y;
;         }
;         part[u] = d;
;       }
;       float q4[4], r2[2], h;
; #pragma unroll
;       for (int j = 0; j < 4; ++j) {
;         float mine = b5 ? part[j + 4] : part[j];
;         float other = b5 ? part[j] : part[j + 4];
;         q4[j] = mine + __shfl_xor(other, 32);
;       }
; #pragma unroll
;       for (int j = 0; j < 2; ++j) {
;         float mine = b4 ? q4[j + 2] : q4[j];
;         float other = b4 ? q4[j] : q4[j + 2];
;         r2[j] = mine + __shfl_xor(other, 16);
;       }
;       {
;         float mine = b3 ? r2[1] : r2[0];
;         float other = b3 ? r2[0] : r2[1];
;         h = mine + __shfl_xor(other, 8);
;       }
;       h += __shfl_xor(h, 4);
;       h += __shfl_xor(h, 2);
;       h += __shfl_xor(h, 1);
	v_pk_fma_f32 v[222:223], v[124:125], v[218:219], v[222:223]
	v_pk_fma_f32 v[224:225], v[126:127], v[220:221], v[224:225]
	v_pk_add_f32 v[222:223], v[222:223], v[224:225]
	s_nop 0
	v_add_f32_e32 v229, v222, v223
	v_cvt_pk_f32_fp8_e32 v[214:215], v192
	v_cvt_pk_f32_fp8_sdwa v[216:217], v192 src0_sel:WORD_1
	v_cvt_pk_f32_fp8_e32 v[218:219], v193
	v_cvt_pk_f32_fp8_sdwa v[220:221], v193 src0_sel:WORD_1
	v_pk_mul_f32 v[222:223], v[112:113], v[214:215]
	v_pk_mul_f32 v[224:225], v[114:115], v[216:217]
	v_cvt_pk_f32_fp8_e32 v[214:215], v194
	v_cvt_pk_f32_fp8_sdwa v[216:217], v194 src0_sel:WORD_1
	v_pk_fma_f32 v[222:223], v[116:117], v[218:219], v[222:223]
	v_pk_fma_f32 v[224:225], v[118:119], v[220:221], v[224:225]
	v_cvt_pk_f32_fp8_e32 v[218:219], v195
	v_cvt_pk_f32_fp8_sdwa v[220:221], v195 src0_sel:WORD_1
	v_pk_fma_f32 v[222:223], v[120:121], v[214:215], v[222:223]
	v_pk_fma_f32 v[224:225], v[122:123], v[216:217], v[224:225]
	v_pk_fma_f32 v[222:223], v[124:125], v[218:219], v[222:223]
	v_pk_fma_f32 v[224:225], v[126:127], v[220:221], v[224:225]
	v_pk_add_f32 v[222:223], v[222:223], v[224:225]
	s_nop 0
	v_add_f32_e32 v230, v222, v223
	v_cvt_pk_f32_fp8_e32 v[214:215], v196
	v_cvt_pk_f32_fp8_sdwa v[216:217], v196 src0_sel:WORD_1
	v_cvt_pk_f32_fp8_e32 v[218:219], v197
	v_cvt_pk_f32_fp8_sdwa v[220:221], v197 src0_sel:WORD_1
	v_pk_mul_f32 v[222:223], v[112:113], v[214:215]
	v_pk_mul_f32 v[224:225], v[114:115], v[216:217]
	v_cvt_pk_f32_fp8_e32 v[214:215], v198
	v_cvt_pk_f32_fp8_sdwa v[216:217], v198 src0_sel:WORD_1
	v_pk_fma_f32 v[222:223], v[116:117], v[218:219], v[222:223]
	v_pk_fma_f32 v[224:225], v[118:119], v[220:221], v[224:225]
	v_cvt_pk_f32_fp8_e32 v[218:219], v199
	v_cvt_pk_f32_fp8_sdwa v[220:221], v199 src0_sel:WORD_1
	v_pk_fma_f32 v[222:223], v[120:121], v[214:215], v[222:223]
	v_pk_fma_f32 v[224:225], v[122:123], v[216:217], v[224:225]
	v_pk_fma_f32 v[222:223], v[124:125], v[218:219], v[222:223]
	v_pk_fma_f32 v[224:225], v[126:127], v[220:221], v[224:225]
	v_pk_add_f32 v[222:223], v[222:223], v[224:225]
	s_nop 0
	v_add_f32_e32 v231, v222, v223
	v_cvt_pk_f32_fp8_e32 v[214:215], v200
	v_cvt_pk_f32_fp8_sdwa v[216:217], v200 src0_sel:WORD_1
	v_cvt_pk_f32_fp8_e32 v[218:219], v201
	v_cvt_pk_f32_fp8_sdwa v[220:221], v201 src0_sel:WORD_1
	v_pk_mul_f32 v[222:223], v[112:113], v[214:215]
	v_pk_mul_f32 v[224:225], v[114:115], v[216:217]
	v_cvt_pk_f32_fp8_e32 v[214:215], v202
	v_cvt_pk_f32_fp8_sdwa v[216:217], v202 src0_sel:WORD_1
	v_pk_fma_f32 v[222:223], v[116:117], v[218:219], v[222:223]
	v_pk_fma_f32 v[224:225], v[118:119], v[220:221], v[224:225]
	v_cvt_pk_f32_fp8_e32 v[218:219], v203
	v_cvt_pk_f32_fp8_sdwa v[220:221], v203 src0_sel:WORD_1
	v_pk_fma_f32 v[222:223], v[120:121], v[214:215], v[222:223]
	v_pk_fma_f32 v[224:225], v[122:123], v[216:217], v[224:225]
	v_pk_fma_f32 v[222:223], v[124:125], v[218:219], v[222:223]
	v_pk_fma_f32 v[224:225], v[126:127], v[220:221], v[224:225]
	v_pk_add_f32 v[222:223], v[222:223], v[224:225]
	s_nop 0
	v_add_f32_e32 v232, v222, v223
	v_cvt_pk_f32_fp8_e32 v[214:215], v204
	v_cvt_pk_f32_fp8_sdwa v[216:217], v204 src0_sel:WORD_1
	v_cvt_pk_f32_fp8_e32 v[218:219], v205
	v_cvt_pk_f32_fp8_sdwa v[220:221], v205 src0_sel:WORD_1
	v_pk_mul_f32 v[222:223], v[112:113], v[214:215]
	v_pk_mul_f32 v[224:225], v[114:115], v[216:217]
	v_cvt_pk_f32_fp8_e32 v[214:215], v206
	v_cvt_pk_f32_fp8_sdwa v[216:217], v206 src0_sel:WORD_1
	v_pk_fma_f32 v[222:223], v[116:117], v[218:219], v[222:223]
	v_pk_fma_f32 v[224:225], v[118:119], v[220:221], v[224:225]
	v_cvt_pk_f32_fp8_e32 v[218:219], v207
	v_cvt_pk_f32_fp8_sdwa v[220:221], v207 src0_sel:WORD_1
	v_pk_fma_f32 v[222:223], v[120:121], v[214:215], v[222:223]
	v_pk_fma_f32 v[224:225], v[122:123], v[216:217], v[224:225]
	v_pk_fma_f32 v[222:223], v[124:125], v[218:219], v[222:223]
	v_pk_fma_f32 v[224:225], v[126:127], v[220:221], v[224:225]
	v_pk_add_f32 v[222:223], v[222:223], v[224:225]
	s_nop 0
	v_add_f32_e32 v233, v222, v223
	v_permlane32_swap_b32_e32 v226, v230
	v_permlane32_swap_b32_e32 v227, v231
	v_permlane32_swap_b32_e32 v228, v232
	v_permlane32_swap_b32_e32 v229, v233
	v_add_f32_e32 v226, v226, v230
	v_add_f32_e32 v228, v228, v232
	v_add_f32_e32 v227, v227, v231
	v_add_f32_e32 v229, v229, v233
	s_nop 1
	v_permlane16_swap_b32_e32 v226, v228
	v_permlane16_swap_b32_e32 v227, v229
	v_add_f32_e32 v226, v226, v228
	v_add_f32_e32 v227, v227, v229
	s_nop 0
	v_cndmask_b32_e64 v230, v226, v227, s[24:25]
	v_cndmask_b32_e64 v231, v227, v226, s[24:25]
	s_nop 1
	v_add_f32_dpp v232, v231, v230 row_ror:8 row_mask:0xf bank_mask:0xf
	s_nop 1
	v_add_f32_dpp v233, v232, v232 quad_perm:[1,0,3,2] row_mask:0xf bank_mask:0xf
	s_nop 1
	v_add_f32_dpp v232, v233, v233 quad_perm:[2,3,0,1] row_mask:0xf bank_mask:0xf
	s_nop 1
	v_add_f32_dpp v233, v232, v232 row_half_mirror row_mask:0xf bank_mask:0xf
	ds_write_b32 v235, v233 offset:36384
	v_add_u32_e32 v235, 64, v235
	s_add_u32 s12, s12, 1
	s_cmp_lt_u32 s12, 8
	s_cbranch_scc1 .Lup_k
; DI float gelu_exact(float x) { return 0.5f * x * (1.f + erff(x * 0.7071067811865476f)); }
; template <bool STORE>
; DI void peer_item(const Params& p, int item, char* smem) {
;     ...
;       const int emine = e_s[tl * 128 + k + (lane >> 3)];
;       const float gmine = g_s[tl * 128 + k + (lane >> 3)];
;       const float su = SU[emine], sv = SV[emine];
;     ...
;       const float amine = gelu_exact(h * su) * gmine * sv;
;       if ((lane & 7) == 0) {
;         EG[tok * 128 + k + (lane >> 3)] = emine;
;         AG[tok * 128 + k + (lane >> 3)] = amine;
;       }
	s_waitcnt vmcnt(0) lgkmcnt(0)
	s_lshl_b32 s13, s14, 9
	s_add_u32 s26, s4, s13
	s_addc_u32 s27, s5, 0
	s_add_u32 s28, s6, s13
	s_addc_u32 s29, s7, 0
	ds_read_b32 v0, v237 offset:32768
	ds_read_b32 v1, v237 offset:33024
	ds_read_b32 v2, v237 offset:0
	ds_read_b32 v3, v237 offset:256
	ds_read_b32 v4, v237 offset:16384
	ds_read_b32 v5, v237 offset:16640
	ds_read_b32 v16, v237 offset:33280
	ds_read_b32 v17, v237 offset:33536
	ds_read_b32 v18, v237 offset:512
	ds_read_b32 v19, v237 offset:768
	ds_read_b32 v20, v237 offset:16896
	ds_read_b32 v21, v237 offset:17152
	ds_read_b32 v32, v237 offset:33792
	ds_read_b32 v33, v237 offset:34048
	ds_read_b32 v34, v237 offset:1024
	ds_read_b32 v35, v237 offset:1280
	ds_read_b32 v36, v237 offset:17408
	ds_read_b32 v37, v237 offset:17664
	ds_read_b32 v48, v237 offset:34304
	ds_read_b32 v49, v237 offset:34560
	ds_read_b32 v50, v237 offset:1536
	ds_read_b32 v51, v237 offset:1792
	ds_read_b32 v52, v237 offset:17920
	ds_read_b32 v53, v237 offset:18176
	ds_read_b32 v64, v237 offset:34816
	ds_read_b32 v65, v237 offset:35072
	ds_read_b32 v66, v237 offset:2048
	ds_read_b32 v67, v237 offset:2304
	ds_read_b32 v68, v237 offset:18432
	ds_read_b32 v69, v237 offset:18688
	ds_read_b32 v80, v237 offset:35328
	ds_read_b32 v81, v237 offset:35584
	ds_read_b32 v82, v237 offset:2560
	ds_read_b32 v83, v237 offset:2816
	ds_read_b32 v84, v237 offset:18944
	ds_read_b32 v85, v237 offset:19200
	ds_read_b32 v96, v237 offset:35840
	ds_read_b32 v97, v237 offset:36096
	ds_read_b32 v98, v237 offset:3072
	ds_read_b32 v99, v237 offset:3328
	ds_read_b32 v100, v237 offset:19456
	ds_read_b32 v101, v237 offset:19712
	ds_read_b32 v112, v237 offset:36352
	ds_read_b32 v113, v237 offset:36608
	ds_read_b32 v114, v237 offset:3584
	ds_read_b32 v115, v237 offset:3840
	ds_read_b32 v116, v237 offset:19968
	ds_read_b32 v117, v237 offset:20224
	s_waitcnt lgkmcnt(15)
	v_lshlrev_b32_e32 v10, 2, v2
	v_lshlrev_b32_e32 v11, 2, v3
	global_load_dword v6, v10, s[8:9]
	global_load_dword v7, v11, s[8:9]
	global_load_dword v8, v10, s[10:11]
	global_load_dword v9, v11, s[10:11]
	s_waitcnt lgkmcnt(15)
	v_lshlrev_b32_e32 v26, 2, v18
	v_lshlrev_b32_e32 v27, 2, v19
	global_load_dword v22, v26, s[8:9]
	global_load_dword v23, v27, s[8:9]
	global_load_dword v24, v26, s[10:11]
	global_load_dword v25, v27, s[10:11]
	s_waitcnt lgkmcnt(15)
	v_lshlrev_b32_e32 v42, 2, v34
	v_lshlrev_b32_e32 v43, 2, v35
	global_load_dword v38, v42, s[8:9]
	global_load_dword v39, v43, s[8:9]
	global_load_dword v40, v42, s[10:11]
	global_load_dword v41, v43, s[10:11]
	s_waitcnt lgkmcnt(15)
	v_lshlrev_b32_e32 v58, 2, v50
	v_lshlrev_b32_e32 v59, 2, v51
	global_load_dword v54, v58, s[8:9]
	global_load_dword v55, v59, s[8:9]
	global_load_dword v56, v58, s[10:11]
	global_load_dword v57, v59, s[10:11]
	s_waitcnt lgkmcnt(15)
	v_lshlrev_b32_e32 v74, 2, v66
	v_lshlrev_b32_e32 v75, 2, v67
	global_load_dword v70, v74, s[8:9]
	global_load_dword v71, v75, s[8:9]
	global_load_dword v72, v74, s[10:11]
	global_load_dword v73, v75, s[10:11]
	s_waitcnt lgkmcnt(12)
	v_lshlrev_b32_e32 v90, 2, v82
	v_lshlrev_b32_e32 v91, 2, v83
	global_load_dword v86, v90, s[8:9]
	global_load_dword v87, v91, s[8:9]
	global_load_dword v88, v90, s[10:11]
	global_load_dword v89, v91, s[10:11]
	s_waitcnt lgkmcnt(6)
	v_lshlrev_b32_e32 v106, 2, v98
	v_lshlrev_b32_e32 v107, 2, v99
	global_load_dword v102, v106, s[8:9]
	global_load_dword v103, v107, s[8:9]
	global_load_dword v104, v106, s[10:11]
	global_load_dword v105, v107, s[10:11]
	s_waitcnt lgkmcnt(0)
	v_lshlrev_b32_e32 v122, 2, v114
	v_lshlrev_b32_e32 v123, 2, v115
	global_load_dword v118, v122, s[8:9]
	global_load_dword v119, v123, s[8:9]
	global_load_dword v120, v122, s[10:11]
	global_load_dword v121, v123, s[10:11]
	s_waitcnt vmcnt(28)
	v_mul_f32_e32 v144, v6, v0
	v_mul_f32_e32 v145, 0x3f3504f3, v144
	v_mov_b32_e32 v146, 0xb9c68948
	v_fma_f32 v146, |v145|, s80, v146
	v_fma_f32 v146, |v145|, v146, s81
	v_fma_f32 v146, |v145|, v146, s82
	v_fma_f32 v146, |v145|, v146, s83
	v_fma_f32 v146, |v145|, v146, s84
	v_fma_f32 v146, |v145|, v146, s85
	v_fma_f32 v146, |v145|, v146, |v145|
	v_mul_f32_e32 v147, 0xbfb8aa3b, v146
	v_fma_f32 v148, v146, s86, -v147
	v_rndne_f32_e32 v149, v147
	v_fmac_f32_e32 v148, 0xb2a5705f, v146
	v_sub_f32_e32 v147, v147, v149
	v_add_f32_e32 v147, v147, v148
	v_cvt_i32_f32_e32 v148, v149
	v_exp_f32_e32 v147, v147
	v_cmp_nlt_f32_e32 vcc, s87, v146
	v_ldexp_f32 v147, v147, v148
	s_nop 0
	v_cndmask_b32_e32 v147, 0, v147, vcc
	v_cmp_ngt_f32_e32 vcc, s88, v146
	v_mov_b32_e32 v148, 0x7f800000
	s_nop 0
	v_cndmask_b32_e32 v147, v148, v147, vcc
	v_sub_f32_e32 v147, 1.0, v147
	v_mul_f32_e32 v148, v145, v145
	v_mov_b32_e32 v149, 0x3ba10414
	v_fmamk_f32 v149, v148, 0xba1345e1, v149
	v_fmaak_f32 v149, v148, v149, 0xbcdac9b8
	v_fmaak_f32 v149, v148, v149, 0x3de703be
	v_fmaak_f32 v149, v148, v149, 0xbec09330
	v_fmaak_f32 v149, v148, v149, 0x3e0375d0
	v_fma_f32 v149, |v145|, v149, |v145|
	v_cmp_nlt_f32_e64 vcc, |v145|, 1.0
	s_nop 1
	v_cndmask_b32_e32 v147, v149, v147, vcc
	v_bfi_b32 v147, s89, v147, v145
	v_mul_f32_e32 v144, 0.5, v144
	v_add_f32_e32 v147, 1.0, v147
	v_mul_f32_e32 v144, v144, v147
	v_mul_f32_e32 v144, v4, v144
	v_mul_f32_e32 v0, v8, v144
	v_mul_f32_e32 v144, v7, v1
	v_mul_f32_e32 v145, 0x3f3504f3, v144
	v_mov_b32_e32 v146, 0xb9c68948
	v_fma_f32 v146, |v145|, s80, v146
	v_fma_f32 v146, |v145|, v146, s81
	v_fma_f32 v146, |v145|, v146, s82
	v_fma_f32 v146, |v145|, v146, s83
	v_fma_f32 v146, |v145|, v146, s84
	v_fma_f32 v146, |v145|, v146, s85
	v_fma_f32 v146, |v145|, v146, |v145|
	v_mul_f32_e32 v147, 0xbfb8aa3b, v146
	v_fma_f32 v148, v146, s86, -v147
	v_rndne_f32_e32 v149, v147
	v_fmac_f32_e32 v148, 0xb2a5705f, v146
	v_sub_f32_e32 v147, v147, v149
	v_add_f32_e32 v147, v147, v148
	v_cvt_i32_f32_e32 v148, v149
	v_exp_f32_e32 v147, v147
	v_cmp_nlt_f32_e32 vcc, s87, v146
	v_ldexp_f32 v147, v147, v148
	s_nop 0
	v_cndmask_b32_e32 v147, 0, v147, vcc
	v_cmp_ngt_f32_e32 vcc, s88, v146
	v_mov_b32_e32 v148, 0x7f800000
	s_nop 0
	v_cndmask_b32_e32 v147, v148, v147, vcc
	v_sub_f32_e32 v147, 1.0, v147
	v_mul_f32_e32 v148, v145, v145
	v_mov_b32_e32 v149, 0x3ba10414
	v_fmamk_f32 v149, v148, 0xba1345e1, v149
	v_fmaak_f32 v149, v148, v149, 0xbcdac9b8
	v_fmaak_f32 v149, v148, v149, 0x3de703be
	v_fmaak_f32 v149, v148, v149, 0xbec09330
	v_fmaak_f32 v149, v148, v149, 0x3e0375d0
	v_fma_f32 v149, |v145|, v149, |v145|
	v_cmp_nlt_f32_e64 vcc, |v145|, 1.0
	s_nop 1
	v_cndmask_b32_e32 v147, v149, v147, vcc
	v_bfi_b32 v147, s89, v147, v145
	v_mul_f32_e32 v144, 0.5, v144
	v_add_f32_e32 v147, 1.0, v147
	v_mul_f32_e32 v144, v144, v147
	v_mul_f32_e32 v144, v5, v144
	v_mul_f32_e32 v1, v9, v144
	ds_write_b32 v237, v0 offset:32768
	ds_write_b32 v237, v1 offset:33024
	s_waitcnt vmcnt(24)
; DI float gelu_exact(float x) { return 0.5f * x * (1.f + erff(x * 0.7071067811865476f)); }
; template <bool STORE>
; DI void peer_item(const Params& p, int item, char* smem) {
;     ...
;       const float amine = gelu_exact(h * su) * gmine * sv;
;       if ((lane & 7) == 0) {
;         EG[tok * 128 + k + (lane >> 3)] = emine;
;         AG[tok * 128 + k + (lane >> 3)] = amine;
;       }
	v_mul_f32_e32 v144, v22, v16
	v_mul_f32_e32 v145, 0x3f3504f3, v144
	v_mov_b32_e32 v146, 0xb9c68948
	v_fma_f32 v146, |v145|, s80, v146
	v_fma_f32 v146, |v145|, v146, s81
	v_fma_f32 v146, |v145|, v146, s82
	v_fma_f32 v146, |v145|, v146, s83
	v_fma_f32 v146, |v145|, v146, s84
	v_fma_f32 v146, |v145|, v146, s85
	v_fma_f32 v146, |v145|, v146, |v145|
	v_mul_f32_e32 v147, 0xbfb8aa3b, v146
	v_fma_f32 v148, v146, s86, -v147
	v_rndne_f32_e32 v149, v147
	v_fmac_f32_e32 v148, 0xb2a5705f, v146
	v_sub_f32_e32 v147, v147, v149
	v_add_f32_e32 v147, v147, v148
	v_cvt_i32_f32_e32 v148, v149
	v_exp_f32_e32 v147, v147
	v_cmp_nlt_f32_e32 vcc, s87, v146
	v_ldexp_f32 v147, v147, v148
	s_nop 0
	v_cndmask_b32_e32 v147, 0, v147, vcc
	v_cmp_ngt_f32_e32 vcc, s88, v146
	v_mov_b32_e32 v148, 0x7f800000
	s_nop 0
	v_cndmask_b32_e32 v147, v148, v147, vcc
	v_sub_f32_e32 v147, 1.0, v147
	v_mul_f32_e32 v148, v145, v145
	v_mov_b32_e32 v149, 0x3ba10414
	v_fmamk_f32 v149, v148, 0xba1345e1, v149
	v_fmaak_f32 v149, v148, v149, 0xbcdac9b8
	v_fmaak_f32 v149, v148, v149, 0x3de703be
	v_fmaak_f32 v149, v148, v149, 0xbec09330
	v_fmaak_f32 v149, v148, v149, 0x3e0375d0
	v_fma_f32 v149, |v145|, v149, |v145|
	v_cmp_nlt_f32_e64 vcc, |v145|, 1.0
	s_nop 1
	v_cndmask_b32_e32 v147, v149, v147, vcc
	v_bfi_b32 v147, s89, v147, v145
	v_mul_f32_e32 v144, 0.5, v144
	v_add_f32_e32 v147, 1.0, v147
	v_mul_f32_e32 v144, v144, v147
	v_mul_f32_e32 v144, v20, v144
	v_mul_f32_e32 v16, v24, v144
	v_mul_f32_e32 v144, v23, v17
	v_mul_f32_e32 v145, 0x3f3504f3, v144
	v_mov_b32_e32 v146, 0xb9c68948
	v_fma_f32 v146, |v145|, s80, v146
	v_fma_f32 v146, |v145|, v146, s81
	v_fma_f32 v146, |v145|, v146, s82
	v_fma_f32 v146, |v145|, v146, s83
	v_fma_f32 v146, |v145|, v146, s84
	v_fma_f32 v146, |v145|, v146, s85
	v_fma_f32 v146, |v145|, v146, |v145|
	v_mul_f32_e32 v147, 0xbfb8aa3b, v146
	v_fma_f32 v148, v146, s86, -v147
	v_rndne_f32_e32 v149, v147
	v_fmac_f32_e32 v148, 0xb2a5705f, v146
	v_sub_f32_e32 v147, v147, v149
	v_add_f32_e32 v147, v147, v148
	v_cvt_i32_f32_e32 v148, v149
	v_exp_f32_e32 v147, v147
	v_cmp_nlt_f32_e32 vcc, s87, v146
	v_ldexp_f32 v147, v147, v148
	s_nop 0
	v_cndmask_b32_e32 v147, 0, v147, vcc
	v_cmp_ngt_f32_e32 vcc, s88, v146
	v_mov_b32_e32 v148, 0x7f800000
	s_nop 0
	v_cndmask_b32_e32 v147, v148, v147, vcc
	v_sub_f32_e32 v147, 1.0, v147
	v_mul_f32_e32 v148, v145, v145
	v_mov_b32_e32 v149, 0x3ba10414
	v_fmamk_f32 v149, v148, 0xba1345e1, v149
	v_fmaak_f32 v149, v148, v149, 0xbcdac9b8
	v_fmaak_f32 v149, v148, v149, 0x3de703be
	v_fmaak_f32 v149, v148, v149, 0xbec09330
	v_fmaak_f32 v149, v148, v149, 0x3e0375d0
	v_fma_f32 v149, |v145|, v149, |v145|
	v_cmp_nlt_f32_e64 vcc, |v145|, 1.0
	s_nop 1
	v_cndmask_b32_e32 v147, v149, v147, vcc
	v_bfi_b32 v147, s89, v147, v145
	v_mul_f32_e32 v144, 0.5, v144
	v_add_f32_e32 v147, 1.0, v147
	v_mul_f32_e32 v144, v144, v147
	v_mul_f32_e32 v144, v21, v144
	v_mul_f32_e32 v17, v25, v144
	ds_write_b32 v237, v16 offset:33280
	ds_write_b32 v237, v17 offset:33536
	s_waitcnt vmcnt(20)
	v_mul_f32_e32 v144, v38, v32
	v_mul_f32_e32 v145, 0x3f3504f3, v144
	v_mov_b32_e32 v146, 0xb9c68948
	v_fma_f32 v146, |v145|, s80, v146
	v_fma_f32 v146, |v145|, v146, s81
	v_fma_f32 v146, |v145|, v146, s82
	v_fma_f32 v146, |v145|, v146, s83
	v_fma_f32 v146, |v145|, v146, s84
	v_fma_f32 v146, |v145|, v146, s85
	v_fma_f32 v146, |v145|, v146, |v145|
	v_mul_f32_e32 v147, 0xbfb8aa3b, v146
	v_fma_f32 v148, v146, s86, -v147
	v_rndne_f32_e32 v149, v147
	v_fmac_f32_e32 v148, 0xb2a5705f, v146
	v_sub_f32_e32 v147, v147, v149
	v_add_f32_e32 v147, v147, v148
	v_cvt_i32_f32_e32 v148, v149
	v_exp_f32_e32 v147, v147
	v_cmp_nlt_f32_e32 vcc, s87, v146
	v_ldexp_f32 v147, v147, v148
	s_nop 0
	v_cndmask_b32_e32 v147, 0, v147, vcc
	v_cmp_ngt_f32_e32 vcc, s88, v146
	v_mov_b32_e32 v148, 0x7f800000
	s_nop 0
	v_cndmask_b32_e32 v147, v148, v147, vcc
	v_sub_f32_e32 v147, 1.0, v147
	v_mul_f32_e32 v148, v145, v145
	v_mov_b32_e32 v149, 0x3ba10414
	v_fmamk_f32 v149, v148, 0xba1345e1, v149
	v_fmaak_f32 v149, v148, v149, 0xbcdac9b8
	v_fmaak_f32 v149, v148, v149, 0x3de703be
	v_fmaak_f32 v149, v148, v149, 0xbec09330
	v_fmaak_f32 v149, v148, v149, 0x3e0375d0
	v_fma_f32 v149, |v145|, v149, |v145|
	v_cmp_nlt_f32_e64 vcc, |v145|, 1.0
	s_nop 1
	v_cndmask_b32_e32 v147, v149, v147, vcc
	v_bfi_b32 v147, s89, v147, v145
	v_mul_f32_e32 v144, 0.5, v144
	v_add_f32_e32 v147, 1.0, v147
	v_mul_f32_e32 v144, v144, v147
	v_mul_f32_e32 v144, v36, v144
	v_mul_f32_e32 v32, v40, v144
	v_mul_f32_e32 v144, v39, v33
	v_mul_f32_e32 v145, 0x3f3504f3, v144
	v_mov_b32_e32 v146, 0xb9c68948
	v_fma_f32 v146, |v145|, s80, v146
	v_fma_f32 v146, |v145|, v146, s81
	v_fma_f32 v146, |v145|, v146, s82
	v_fma_f32 v146, |v145|, v146, s83
	v_fma_f32 v146, |v145|, v146, s84
	v_fma_f32 v146, |v145|, v146, s85
	v_fma_f32 v146, |v145|, v146, |v145|
	v_mul_f32_e32 v147, 0xbfb8aa3b, v146
	v_fma_f32 v148, v146, s86, -v147
	v_rndne_f32_e32 v149, v147
	v_fmac_f32_e32 v148, 0xb2a5705f, v146
	v_sub_f32_e32 v147, v147, v149
	v_add_f32_e32 v147, v147, v148
	v_cvt_i32_f32_e32 v148, v149
	v_exp_f32_e32 v147, v147
	v_cmp_nlt_f32_e32 vcc, s87, v146
	v_ldexp_f32 v147, v147, v148
	s_nop 0
	v_cndmask_b32_e32 v147, 0, v147, vcc
	v_cmp_ngt_f32_e32 vcc, s88, v146
	v_mov_b32_e32 v148, 0x7f800000
	s_nop 0
	v_cndmask_b32_e32 v147, v148, v147, vcc
	v_sub_f32_e32 v147, 1.0, v147
	v_mul_f32_e32 v148, v145, v145
	v_mov_b32_e32 v149, 0x3ba10414
	v_fmamk_f32 v149, v148, 0xba1345e1, v149
	v_fmaak_f32 v149, v148, v149, 0xbcdac9b8
	v_fmaak_f32 v149, v148, v149, 0x3de703be
	v_fmaak_f32 v149, v148, v149, 0xbec09330
	v_fmaak_f32 v149, v148, v149, 0x3e0375d0
	v_fma_f32 v149, |v145|, v149, |v145|
	v_cmp_nlt_f32_e64 vcc, |v145|, 1.0
	s_nop 1
	v_cndmask_b32_e32 v147, v149, v147, vcc
	v_bfi_b32 v147, s89, v147, v145
	v_mul_f32_e32 v144, 0.5, v144
	v_add_f32_e32 v147, 1.0, v147
	v_mul_f32_e32 v144, v144, v147
	v_mul_f32_e32 v144, v37, v144
	v_mul_f32_e32 v33, v41, v144
	ds_write_b32 v237, v32 offset:33792
	ds_write_b32 v237, v33 offset:34048
	s_waitcnt vmcnt(16)
; DI float gelu_exact(float x) { return 0.5f * x * (1.f + erff(x * 0.7071067811865476f)); }
; template <bool STORE>
; DI void peer_item(const Params& p, int item, char* smem) {
;     ...
;       const float amine = gelu_exact(h * su) * gmine * sv;
;       if ((lane & 7) == 0) {
;         EG[tok * 128 + k + (lane >> 3)] = emine;
;         AG[tok * 128 + k + (lane >> 3)] = amine;
;       }
	v_mul_f32_e32 v144, v54, v48
	v_mul_f32_e32 v145, 0x3f3504f3, v144
	v_mov_b32_e32 v146, 0xb9c68948
	v_fma_f32 v146, |v145|, s80, v146
	v_fma_f32 v146, |v145|, v146, s81
	v_fma_f32 v146, |v145|, v146, s82
	v_fma_f32 v146, |v145|, v146, s83
	v_fma_f32 v146, |v145|, v146, s84
	v_fma_f32 v146, |v145|, v146, s85
	v_fma_f32 v146, |v145|, v146, |v145|
	v_mul_f32_e32 v147, 0xbfb8aa3b, v146
	v_fma_f32 v148, v146, s86, -v147
	v_rndne_f32_e32 v149, v147
	v_fmac_f32_e32 v148, 0xb2a5705f, v146
	v_sub_f32_e32 v147, v147, v149
	v_add_f32_e32 v147, v147, v148
	v_cvt_i32_f32_e32 v148, v149
	v_exp_f32_e32 v147, v147
	v_cmp_nlt_f32_e32 vcc, s87, v146
	v_ldexp_f32 v147, v147, v148
	s_nop 0
	v_cndmask_b32_e32 v147, 0, v147, vcc
	v_cmp_ngt_f32_e32 vcc, s88, v146
	v_mov_b32_e32 v148, 0x7f800000
	s_nop 0
	v_cndmask_b32_e32 v147, v148, v147, vcc
	v_sub_f32_e32 v147, 1.0, v147
	v_mul_f32_e32 v148, v145, v145
	v_mov_b32_e32 v149, 0x3ba10414
	v_fmamk_f32 v149, v148, 0xba1345e1, v149
	v_fmaak_f32 v149, v148, v149, 0xbcdac9b8
	v_fmaak_f32 v149, v148, v149, 0x3de703be
	v_fmaak_f32 v149, v148, v149, 0xbec09330
	v_fmaak_f32 v149, v148, v149, 0x3e0375d0
	v_fma_f32 v149, |v145|, v149, |v145|
	v_cmp_nlt_f32_e64 vcc, |v145|, 1.0
	s_nop 1
	v_cndmask_b32_e32 v147, v149, v147, vcc
	v_bfi_b32 v147, s89, v147, v145
	v_mul_f32_e32 v144, 0.5, v144
	v_add_f32_e32 v147, 1.0, v147
	v_mul_f32_e32 v144, v144, v147
	v_mul_f32_e32 v144, v52, v144
	v_mul_f32_e32 v48, v56, v144
	v_mul_f32_e32 v144, v55, v49
	v_mul_f32_e32 v145, 0x3f3504f3, v144
	v_mov_b32_e32 v146, 0xb9c68948
	v_fma_f32 v146, |v145|, s80, v146
	v_fma_f32 v146, |v145|, v146, s81
	v_fma_f32 v146, |v145|, v146, s82
	v_fma_f32 v146, |v145|, v146, s83
	v_fma_f32 v146, |v145|, v146, s84
	v_fma_f32 v146, |v145|, v146, s85
	v_fma_f32 v146, |v145|, v146, |v145|
	v_mul_f32_e32 v147, 0xbfb8aa3b, v146
	v_fma_f32 v148, v146, s86, -v147
	v_rndne_f32_e32 v149, v147
	v_fmac_f32_e32 v148, 0xb2a5705f, v146
	v_sub_f32_e32 v147, v147, v149
	v_add_f32_e32 v147, v147, v148
	v_cvt_i32_f32_e32 v148, v149
	v_exp_f32_e32 v147, v147
	v_cmp_nlt_f32_e32 vcc, s87, v146
	v_ldexp_f32 v147, v147, v148
	s_nop 0
	v_cndmask_b32_e32 v147, 0, v147, vcc
	v_cmp_ngt_f32_e32 vcc, s88, v146
	v_mov_b32_e32 v148, 0x7f800000
	s_nop 0
	v_cndmask_b32_e32 v147, v148, v147, vcc
	v_sub_f32_e32 v147, 1.0, v147
	v_mul_f32_e32 v148, v145, v145
	v_mov_b32_e32 v149, 0x3ba10414
	v_fmamk_f32 v149, v148, 0xba1345e1, v149
	v_fmaak_f32 v149, v148, v149, 0xbcdac9b8
	v_fmaak_f32 v149, v148, v149, 0x3de703be
	v_fmaak_f32 v149, v148, v149, 0xbec09330
	v_fmaak_f32 v149, v148, v149, 0x3e0375d0
	v_fma_f32 v149, |v145|, v149, |v145|
	v_cmp_nlt_f32_e64 vcc, |v145|, 1.0
	s_nop 1
	v_cndmask_b32_e32 v147, v149, v147, vcc
	v_bfi_b32 v147, s89, v147, v145
	v_mul_f32_e32 v144, 0.5, v144
	v_add_f32_e32 v147, 1.0, v147
	v_mul_f32_e32 v144, v144, v147
	v_mul_f32_e32 v144, v53, v144
	v_mul_f32_e32 v49, v57, v144
	ds_write_b32 v237, v48 offset:34304
	ds_write_b32 v237, v49 offset:34560
	s_waitcnt vmcnt(12)
	v_mul_f32_e32 v144, v70, v64
	v_mul_f32_e32 v145, 0x3f3504f3, v144
	v_mov_b32_e32 v146, 0xb9c68948
	v_fma_f32 v146, |v145|, s80, v146
	v_fma_f32 v146, |v145|, v146, s81
	v_fma_f32 v146, |v145|, v146, s82
	v_fma_f32 v146, |v145|, v146, s83
	v_fma_f32 v146, |v145|, v146, s84
	v_fma_f32 v146, |v145|, v146, s85
	v_fma_f32 v146, |v145|, v146, |v145|
	v_mul_f32_e32 v147, 0xbfb8aa3b, v146
	v_fma_f32 v148, v146, s86, -v147
	v_rndne_f32_e32 v149, v147
	v_fmac_f32_e32 v148, 0xb2a5705f, v146
	v_sub_f32_e32 v147, v147, v149
	v_add_f32_e32 v147, v147, v148
	v_cvt_i32_f32_e32 v148, v149
	v_exp_f32_e32 v147, v147
	v_cmp_nlt_f32_e32 vcc, s87, v146
	v_ldexp_f32 v147, v147, v148
	s_nop 0
	v_cndmask_b32_e32 v147, 0, v147, vcc
	v_cmp_ngt_f32_e32 vcc, s88, v146
	v_mov_b32_e32 v148, 0x7f800000
	s_nop 0
	v_cndmask_b32_e32 v147, v148, v147, vcc
	v_sub_f32_e32 v147, 1.0, v147
	v_mul_f32_e32 v148, v145, v145
	v_mov_b32_e32 v149, 0x3ba10414
	v_fmamk_f32 v149, v148, 0xba1345e1, v149
	v_fmaak_f32 v149, v148, v149, 0xbcdac9b8
	v_fmaak_f32 v149, v148, v149, 0x3de703be
	v_fmaak_f32 v149, v148, v149, 0xbec09330
	v_fmaak_f32 v149, v148, v149, 0x3e0375d0
	v_fma_f32 v149, |v145|, v149, |v145|
	v_cmp_nlt_f32_e64 vcc, |v145|, 1.0
	s_nop 1
	v_cndmask_b32_e32 v147, v149, v147, vcc
	v_bfi_b32 v147, s89, v147, v145
	v_mul_f32_e32 v144, 0.5, v144
	v_add_f32_e32 v147, 1.0, v147
	v_mul_f32_e32 v144, v144, v147
	v_mul_f32_e32 v144, v68, v144
	v_mul_f32_e32 v64, v72, v144
	v_mul_f32_e32 v144, v71, v65
	v_mul_f32_e32 v145, 0x3f3504f3, v144
	v_mov_b32_e32 v146, 0xb9c68948
	v_fma_f32 v146, |v145|, s80, v146
	v_fma_f32 v146, |v145|, v146, s81
	v_fma_f32 v146, |v145|, v146, s82
	v_fma_f32 v146, |v145|, v146, s83
	v_fma_f32 v146, |v145|, v146, s84
	v_fma_f32 v146, |v145|, v146, s85
	v_fma_f32 v146, |v145|, v146, |v145|
	v_mul_f32_e32 v147, 0xbfb8aa3b, v146
	v_fma_f32 v148, v146, s86, -v147
	v_rndne_f32_e32 v149, v147
	v_fmac_f32_e32 v148, 0xb2a5705f, v146
	v_sub_f32_e32 v147, v147, v149
	v_add_f32_e32 v147, v147, v148
	v_cvt_i32_f32_e32 v148, v149
	v_exp_f32_e32 v147, v147
	v_cmp_nlt_f32_e32 vcc, s87, v146
	v_ldexp_f32 v147, v147, v148
	s_nop 0
	v_cndmask_b32_e32 v147, 0, v147, vcc
	v_cmp_ngt_f32_e32 vcc, s88, v146
	v_mov_b32_e32 v148, 0x7f800000
	s_nop 0
	v_cndmask_b32_e32 v147, v148, v147, vcc
	v_sub_f32_e32 v147, 1.0, v147
	v_mul_f32_e32 v148, v145, v145
	v_mov_b32_e32 v149, 0x3ba10414
	v_fmamk_f32 v149, v148, 0xba1345e1, v149
	v_fmaak_f32 v149, v148, v149, 0xbcdac9b8
	v_fmaak_f32 v149, v148, v149, 0x3de703be
	v_fmaak_f32 v149, v148, v149, 0xbec09330
	v_fmaak_f32 v149, v148, v149, 0x3e0375d0
	v_fma_f32 v149, |v145|, v149, |v145|
	v_cmp_nlt_f32_e64 vcc, |v145|, 1.0
	s_nop 1
	v_cndmask_b32_e32 v147, v149, v147, vcc
	v_bfi_b32 v147, s89, v147, v145
	v_mul_f32_e32 v144, 0.5, v144
	v_add_f32_e32 v147, 1.0, v147
	v_mul_f32_e32 v144, v144, v147
	v_mul_f32_e32 v144, v69, v144
	v_mul_f32_e32 v65, v73, v144
	ds_write_b32 v237, v64 offset:34816
	ds_write_b32 v237, v65 offset:35072
	s_waitcnt vmcnt(8)
; DI float gelu_exact(float x) { return 0.5f * x * (1.f + erff(x * 0.7071067811865476f)); }
; template <bool STORE>
; DI void peer_item(const Params& p, int item, char* smem) {
;     ...
;       const float amine = gelu_exact(h * su) * gmine * sv;
;       if ((lane & 7) == 0) {
;         EG[tok * 128 + k + (lane >> 3)] = emine;
;         AG[tok * 128 + k + (lane >> 3)] = amine;
;       }
	v_mul_f32_e32 v144, v86, v80
	v_mul_f32_e32 v145, 0x3f3504f3, v144
	v_mov_b32_e32 v146, 0xb9c68948
	v_fma_f32 v146, |v145|, s80, v146
	v_fma_f32 v146, |v145|, v146, s81
	v_fma_f32 v146, |v145|, v146, s82
	v_fma_f32 v146, |v145|, v146, s83
	v_fma_f32 v146, |v145|, v146, s84
	v_fma_f32 v146, |v145|, v146, s85
	v_fma_f32 v146, |v145|, v146, |v145|
	v_mul_f32_e32 v147, 0xbfb8aa3b, v146
	v_fma_f32 v148, v146, s86, -v147
	v_rndne_f32_e32 v149, v147
	v_fmac_f32_e32 v148, 0xb2a5705f, v146
	v_sub_f32_e32 v147, v147, v149
	v_add_f32_e32 v147, v147, v148
	v_cvt_i32_f32_e32 v148, v149
	v_exp_f32_e32 v147, v147
	v_cmp_nlt_f32_e32 vcc, s87, v146
	v_ldexp_f32 v147, v147, v148
	s_nop 0
	v_cndmask_b32_e32 v147, 0, v147, vcc
	v_cmp_ngt_f32_e32 vcc, s88, v146
	v_mov_b32_e32 v148, 0x7f800000
	s_nop 0
	v_cndmask_b32_e32 v147, v148, v147, vcc
	v_sub_f32_e32 v147, 1.0, v147
	v_mul_f32_e32 v148, v145, v145
	v_mov_b32_e32 v149, 0x3ba10414
	v_fmamk_f32 v149, v148, 0xba1345e1, v149
	v_fmaak_f32 v149, v148, v149, 0xbcdac9b8
	v_fmaak_f32 v149, v148, v149, 0x3de703be
	v_fmaak_f32 v149, v148, v149, 0xbec09330
	v_fmaak_f32 v149, v148, v149, 0x3e0375d0
	v_fma_f32 v149, |v145|, v149, |v145|
	v_cmp_nlt_f32_e64 vcc, |v145|, 1.0
	s_nop 1
	v_cndmask_b32_e32 v147, v149, v147, vcc
	v_bfi_b32 v147, s89, v147, v145
	v_mul_f32_e32 v144, 0.5, v144
	v_add_f32_e32 v147, 1.0, v147
	v_mul_f32_e32 v144, v144, v147
	v_mul_f32_e32 v144, v84, v144
	v_mul_f32_e32 v80, v88, v144
	v_mul_f32_e32 v144, v87, v81
	v_mul_f32_e32 v145, 0x3f3504f3, v144
	v_mov_b32_e32 v146, 0xb9c68948
	v_fma_f32 v146, |v145|, s80, v146
	v_fma_f32 v146, |v145|, v146, s81
	v_fma_f32 v146, |v145|, v146, s82
	v_fma_f32 v146, |v145|, v146, s83
	v_fma_f32 v146, |v145|, v146, s84
	v_fma_f32 v146, |v145|, v146, s85
	v_fma_f32 v146, |v145|, v146, |v145|
	v_mul_f32_e32 v147, 0xbfb8aa3b, v146
	v_fma_f32 v148, v146, s86, -v147
	v_rndne_f32_e32 v149, v147
	v_fmac_f32_e32 v148, 0xb2a5705f, v146
	v_sub_f32_e32 v147, v147, v149
	v_add_f32_e32 v147, v147, v148
	v_cvt_i32_f32_e32 v148, v149
	v_exp_f32_e32 v147, v147
	v_cmp_nlt_f32_e32 vcc, s87, v146
	v_ldexp_f32 v147, v147, v148
	s_nop 0
	v_cndmask_b32_e32 v147, 0, v147, vcc
	v_cmp_ngt_f32_e32 vcc, s88, v146
	v_mov_b32_e32 v148, 0x7f800000
	s_nop 0
	v_cndmask_b32_e32 v147, v148, v147, vcc
	v_sub_f32_e32 v147, 1.0, v147
	v_mul_f32_e32 v148, v145, v145
	v_mov_b32_e32 v149, 0x3ba10414
	v_fmamk_f32 v149, v148, 0xba1345e1, v149
	v_fmaak_f32 v149, v148, v149, 0xbcdac9b8
	v_fmaak_f32 v149, v148, v149, 0x3de703be
	v_fmaak_f32 v149, v148, v149, 0xbec09330
	v_fmaak_f32 v149, v148, v149, 0x3e0375d0
	v_fma_f32 v149, |v145|, v149, |v145|
	v_cmp_nlt_f32_e64 vcc, |v145|, 1.0
	s_nop 1
	v_cndmask_b32_e32 v147, v149, v147, vcc
	v_bfi_b32 v147, s89, v147, v145
	v_mul_f32_e32 v144, 0.5, v144
	v_add_f32_e32 v147, 1.0, v147
	v_mul_f32_e32 v144, v144, v147
	v_mul_f32_e32 v144, v85, v144
	v_mul_f32_e32 v81, v89, v144
	ds_write_b32 v237, v80 offset:35328
	ds_write_b32 v237, v81 offset:35584
	s_waitcnt vmcnt(4)
	v_mul_f32_e32 v144, v102, v96
	v_mul_f32_e32 v145, 0x3f3504f3, v144
	v_mov_b32_e32 v146, 0xb9c68948
	v_fma_f32 v146, |v145|, s80, v146
	v_fma_f32 v146, |v145|, v146, s81
	v_fma_f32 v146, |v145|, v146, s82
	v_fma_f32 v146, |v145|, v146, s83
	v_fma_f32 v146, |v145|, v146, s84
	v_fma_f32 v146, |v145|, v146, s85
	v_fma_f32 v146, |v145|, v146, |v145|
	v_mul_f32_e32 v147, 0xbfb8aa3b, v146
	v_fma_f32 v148, v146, s86, -v147
	v_rndne_f32_e32 v149, v147
	v_fmac_f32_e32 v148, 0xb2a5705f, v146
	v_sub_f32_e32 v147, v147, v149
	v_add_f32_e32 v147, v147, v148
	v_cvt_i32_f32_e32 v148, v149
	v_exp_f32_e32 v147, v147
	v_cmp_nlt_f32_e32 vcc, s87, v146
	v_ldexp_f32 v147, v147, v148
	s_nop 0
	v_cndmask_b32_e32 v147, 0, v147, vcc
	v_cmp_ngt_f32_e32 vcc, s88, v146
	v_mov_b32_e32 v148, 0x7f800000
	s_nop 0
	v_cndmask_b32_e32 v147, v148, v147, vcc
	v_sub_f32_e32 v147, 1.0, v147
	v_mul_f32_e32 v148, v145, v145
	v_mov_b32_e32 v149, 0x3ba10414
	v_fmamk_f32 v149, v148, 0xba1345e1, v149
	v_fmaak_f32 v149, v148, v149, 0xbcdac9b8
	v_fmaak_f32 v149, v148, v149, 0x3de703be
	v_fmaak_f32 v149, v148, v149, 0xbec09330
	v_fmaak_f32 v149, v148, v149, 0x3e0375d0
	v_fma_f32 v149, |v145|, v149, |v145|
	v_cmp_nlt_f32_e64 vcc, |v145|, 1.0
	s_nop 1
	v_cndmask_b32_e32 v147, v149, v147, vcc
	v_bfi_b32 v147, s89, v147, v145
	v_mul_f32_e32 v144, 0.5, v144
	v_add_f32_e32 v147, 1.0, v147
	v_mul_f32_e32 v144, v144, v147
	v_mul_f32_e32 v144, v100, v144
	v_mul_f32_e32 v96, v104, v144
	v_mul_f32_e32 v144, v103, v97
	v_mul_f32_e32 v145, 0x3f3504f3, v144
	v_mov_b32_e32 v146, 0xb9c68948
	v_fma_f32 v146, |v145|, s80, v146
	v_fma_f32 v146, |v145|, v146, s81
	v_fma_f32 v146, |v145|, v146, s82
	v_fma_f32 v146, |v145|, v146, s83
	v_fma_f32 v146, |v145|, v146, s84
	v_fma_f32 v146, |v145|, v146, s85
	v_fma_f32 v146, |v145|, v146, |v145|
	v_mul_f32_e32 v147, 0xbfb8aa3b, v146
	v_fma_f32 v148, v146, s86, -v147
	v_rndne_f32_e32 v149, v147
	v_fmac_f32_e32 v148, 0xb2a5705f, v146
	v_sub_f32_e32 v147, v147, v149
	v_add_f32_e32 v147, v147, v148
	v_cvt_i32_f32_e32 v148, v149
	v_exp_f32_e32 v147, v147
	v_cmp_nlt_f32_e32 vcc, s87, v146
	v_ldexp_f32 v147, v147, v148
	s_nop 0
	v_cndmask_b32_e32 v147, 0, v147, vcc
	v_cmp_ngt_f32_e32 vcc, s88, v146
	v_mov_b32_e32 v148, 0x7f800000
	s_nop 0
	v_cndmask_b32_e32 v147, v148, v147, vcc
	v_sub_f32_e32 v147, 1.0, v147
	v_mul_f32_e32 v148, v145, v145
	v_mov_b32_e32 v149, 0x3ba10414
	v_fmamk_f32 v149, v148, 0xba1345e1, v149
	v_fmaak_f32 v149, v148, v149, 0xbcdac9b8
	v_fmaak_f32 v149, v148, v149, 0x3de703be
	v_fmaak_f32 v149, v148, v149, 0xbec09330
	v_fmaak_f32 v149, v148, v149, 0x3e0375d0
	v_fma_f32 v149, |v145|, v149, |v145|
	v_cmp_nlt_f32_e64 vcc, |v145|, 1.0
	s_nop 1
	v_cndmask_b32_e32 v147, v149, v147, vcc
	v_bfi_b32 v147, s89, v147, v145
	v_mul_f32_e32 v144, 0.5, v144
	v_add_f32_e32 v147, 1.0, v147
	v_mul_f32_e32 v144, v144, v147
	v_mul_f32_e32 v144, v101, v144
	v_mul_f32_e32 v97, v105, v144
	ds_write_b32 v237, v96 offset:35840
	ds_write_b32 v237, v97 offset:36096
	s_waitcnt vmcnt(0)
; DI float gelu_exact(float x) { return 0.5f * x * (1.f + erff(x * 0.7071067811865476f)); }
; template <bool STORE>
; DI void peer_item(const Params& p, int item, char* smem) {
;     ...
;       const float amine = gelu_exact(h * su) * gmine * sv;
;       if ((lane & 7) == 0) {
;         EG[tok * 128 + k + (lane >> 3)] = emine;
;         AG[tok * 128 + k + (lane >> 3)] = amine;
;       }
; DI void peer_item_v(const Params& p, int item) {
;     ...
;   for (int ti = 0; ti < 8; ++ti) {
;     const size_t tok = (size_t)item * 32 + wave * 8 + ti;
;     const int e_lo = EG[tok * 128 + lane], e_hi = EG[tok * 128 + 64 + lane];
;     const int a_lo = __float_as_int(AG[tok * 128 + lane]), a_hi = __float_as_int(AG[tok * 128 + 64 + lane]);
;     float out[16];
; #pragma unroll
;     for (int i = 0; i < 16; ++i) out[i] = 0.f;
;     u32x4 vqa[8], vqb[8];
	v_mul_f32_e32 v144, v118, v112
	v_mul_f32_e32 v145, 0x3f3504f3, v144
	v_mov_b32_e32 v146, 0xb9c68948
	v_fma_f32 v146, |v145|, s80, v146
	v_fma_f32 v146, |v145|, v146, s81
	v_fma_f32 v146, |v145|, v146, s82
	v_fma_f32 v146, |v145|, v146, s83
	v_fma_f32 v146, |v145|, v146, s84
	v_fma_f32 v146, |v145|, v146, s85
	v_fma_f32 v146, |v145|, v146, |v145|
	v_mul_f32_e32 v147, 0xbfb8aa3b, v146
	v_fma_f32 v148, v146, s86, -v147
	v_rndne_f32_e32 v149, v147
	v_fmac_f32_e32 v148, 0xb2a5705f, v146
	v_sub_f32_e32 v147, v147, v149
	v_add_f32_e32 v147, v147, v148
	v_cvt_i32_f32_e32 v148, v149
	v_exp_f32_e32 v147, v147
	v_cmp_nlt_f32_e32 vcc, s87, v146
	v_ldexp_f32 v147, v147, v148
	s_nop 0
	v_cndmask_b32_e32 v147, 0, v147, vcc
	v_cmp_ngt_f32_e32 vcc, s88, v146
	v_mov_b32_e32 v148, 0x7f800000
	s_nop 0
	v_cndmask_b32_e32 v147, v148, v147, vcc
	v_sub_f32_e32 v147, 1.0, v147
	v_mul_f32_e32 v148, v145, v145
	v_mov_b32_e32 v149, 0x3ba10414
	v_fmamk_f32 v149, v148, 0xba1345e1, v149
	v_fmaak_f32 v149, v148, v149, 0xbcdac9b8
	v_fmaak_f32 v149, v148, v149, 0x3de703be
	v_fmaak_f32 v149, v148, v149, 0xbec09330
	v_fmaak_f32 v149, v148, v149, 0x3e0375d0
	v_fma_f32 v149, |v145|, v149, |v145|
	v_cmp_nlt_f32_e64 vcc, |v145|, 1.0
	s_nop 1
	v_cndmask_b32_e32 v147, v149, v147, vcc
	v_bfi_b32 v147, s89, v147, v145
	v_mul_f32_e32 v144, 0.5, v144
	v_add_f32_e32 v147, 1.0, v147
	v_mul_f32_e32 v144, v144, v147
	v_mul_f32_e32 v144, v116, v144
	v_mul_f32_e32 v112, v120, v144
	v_mul_f32_e32 v144, v119, v113
	v_mul_f32_e32 v145, 0x3f3504f3, v144
	v_mov_b32_e32 v146, 0xb9c68948
	v_fma_f32 v146, |v145|, s80, v146
	v_fma_f32 v146, |v145|, v146, s81
	v_fma_f32 v146, |v145|, v146, s82
	v_fma_f32 v146, |v145|, v146, s83
	v_fma_f32 v146, |v145|, v146, s84
	v_fma_f32 v146, |v145|, v146, s85
	v_fma_f32 v146, |v145|, v146, |v145|
	v_mul_f32_e32 v147, 0xbfb8aa3b, v146
	v_fma_f32 v148, v146, s86, -v147
	v_rndne_f32_e32 v149, v147
	v_fmac_f32_e32 v148, 0xb2a5705f, v146
	v_sub_f32_e32 v147, v147, v149
	v_add_f32_e32 v147, v147, v148
	v_cvt_i32_f32_e32 v148, v149
	v_exp_f32_e32 v147, v147
	v_cmp_nlt_f32_e32 vcc, s87, v146
	v_ldexp_f32 v147, v147, v148
	s_nop 0
	v_cndmask_b32_e32 v147, 0, v147, vcc
	v_cmp_ngt_f32_e32 vcc, s88, v146
	v_mov_b32_e32 v148, 0x7f800000
	s_nop 0
	v_cndmask_b32_e32 v147, v148, v147, vcc
	v_sub_f32_e32 v147, 1.0, v147
	v_mul_f32_e32 v148, v145, v145
	v_mov_b32_e32 v149, 0x3ba10414
	v_fmamk_f32 v149, v148, 0xba1345e1, v149
	v_fmaak_f32 v149, v148, v149, 0xbcdac9b8
	v_fmaak_f32 v149, v148, v149, 0x3de703be
	v_fmaak_f32 v149, v148, v149, 0xbec09330
	v_fmaak_f32 v149, v148, v149, 0x3e0375d0
	v_fma_f32 v149, |v145|, v149, |v145|
	v_cmp_nlt_f32_e64 vcc, |v145|, 1.0
	s_nop 1
	v_cndmask_b32_e32 v147, v149, v147, vcc
	v_bfi_b32 v147, s89, v147, v145
	v_mul_f32_e32 v144, 0.5, v144
	v_add_f32_e32 v147, 1.0, v147
	v_mul_f32_e32 v144, v144, v147
	v_mul_f32_e32 v144, v117, v144
	v_mul_f32_e32 v113, v121, v144
	ds_write_b32 v237, v112 offset:36352
	ds_write_b32 v237, v113 offset:36608
	s_mov_b32 s90, s19
	v_writelane_b32 v254, s18, 60
	s_waitcnt vmcnt(0) lgkmcnt(0)
	v_readlane_b32 s64, v253, 48
	v_readlane_b32 s65, v253, 49
	v_readlane_b32 s6, v253, 46
	v_readlane_b32 s7, v253, 47
	v_readlane_b32 s8, v253, 44
	v_readlane_b32 s9, v253, 45
	v_mbcnt_lo_u32_b32 v249, -1, 0
	v_mbcnt_hi_u32_b32 v249, -1, v249
	s_nop 3
	s_add_u32 s0, s64, 0x3200200
	s_addc_u32 s1, s65, 0
	v_lshlrev_b32_e32 v240, 4, v249
	v_lshlrev_b32_e32 v241, 2, v249
	v_xor_b32_e32 v242, 32, v249
	v_xor_b32_e32 v243, 16, v249
	v_xor_b32_e32 v244, 8, v249
	v_xor_b32_e32 v245, 4, v249
	v_xor_b32_e32 v246, 2, v249
	v_xor_b32_e32 v247, 1, v249
	v_lshlrev_b32_e32 v242, 2, v242
	v_lshlrev_b32_e32 v243, 2, v243
	v_lshlrev_b32_e32 v244, 2, v244
	v_lshlrev_b32_e32 v245, 2, v245
	v_lshlrev_b32_e32 v246, 2, v246
	v_lshlrev_b32_e32 v247, 2, v247
	v_mov_b32_e32 v248, 0x358637bd
	v_lshrrev_b32_e32 v250, 3, v249
	v_and_b32_e32 v251, 7, v249
	v_lshlrev_b32_e32 v250, 6, v250
	v_lshl_add_u32 v250, v251, 2, v250
	v_add_u32_e32 v250, s90, v250
	ds_read_b32 v128, v250 offset:0
	ds_read_b32 v129, v250 offset:32
	ds_read_b32 v130, v250 offset:32768
	ds_read_b32 v131, v250 offset:32800
	ds_read_b32 v132, v250 offset:512
	ds_read_b32 v133, v250 offset:544
	ds_read_b32 v134, v250 offset:33280
	ds_read_b32 v135, v250 offset:33312
	ds_read_b32 v136, v250 offset:1024
	ds_read_b32 v137, v250 offset:1056
	ds_read_b32 v138, v250 offset:33792
	ds_read_b32 v139, v250 offset:33824
	ds_read_b32 v140, v250 offset:1536
	ds_read_b32 v141, v250 offset:1568
	ds_read_b32 v142, v250 offset:34304
	ds_read_b32 v143, v250 offset:34336
	ds_read_b32 v144, v250 offset:2048
	ds_read_b32 v145, v250 offset:2080
	ds_read_b32 v146, v250 offset:34816
	ds_read_b32 v147, v250 offset:34848
	ds_read_b32 v148, v250 offset:2560
	ds_read_b32 v149, v250 offset:2592
	ds_read_b32 v150, v250 offset:35328
	ds_read_b32 v151, v250 offset:35360
	ds_read_b32 v152, v250 offset:3072
	ds_read_b32 v153, v250 offset:3104
	ds_read_b32 v154, v250 offset:35840
	ds_read_b32 v155, v250 offset:35872
	ds_read_b32 v156, v250 offset:3584
	ds_read_b32 v157, v250 offset:3616
	ds_read_b32 v158, v250 offset:36352
	ds_read_b32 v159, v250 offset:36384
	v_mov_b32_e32 v0, 0
	v_mov_b32_e32 v1, 0
	v_mov_b32_e32 v2, 0
	v_mov_b32_e32 v3, 0
	v_mov_b32_e32 v4, 0
	v_mov_b32_e32 v5, 0
	v_mov_b32_e32 v6, 0
	v_mov_b32_e32 v7, 0
	v_mov_b32_e32 v8, 0
	v_mov_b32_e32 v9, 0
	v_mov_b32_e32 v10, 0
	v_mov_b32_e32 v11, 0
	v_mov_b32_e32 v12, 0
	v_mov_b32_e32 v13, 0
	v_mov_b32_e32 v14, 0
	v_mov_b32_e32 v15, 0
	v_mov_b32_e32 v16, 0
	v_mov_b32_e32 v17, 0
	v_mov_b32_e32 v18, 0
	v_mov_b32_e32 v19, 0
	v_mov_b32_e32 v20, 0
	v_mov_b32_e32 v21, 0
; DI void peer_item_v(const Params& p, int item) {
;     ...
;     float out[16];
; #pragma unroll
;     for (int i = 0; i < 16; ++i) out[i] = 0.f;
;     u32x4 vqa[8], vqb[8];
	v_mov_b32_e32 v22, 0
	v_mov_b32_e32 v23, 0
	v_mov_b32_e32 v24, 0
	v_mov_b32_e32 v25, 0
	v_mov_b32_e32 v26, 0
	v_mov_b32_e32 v27, 0
	v_mov_b32_e32 v28, 0
	v_mov_b32_e32 v29, 0
	v_mov_b32_e32 v30, 0
	v_mov_b32_e32 v31, 0
	v_mov_b32_e32 v32, 0
	v_mov_b32_e32 v33, 0
	v_mov_b32_e32 v34, 0
	v_mov_b32_e32 v35, 0
	v_mov_b32_e32 v36, 0
	v_mov_b32_e32 v37, 0
	v_mov_b32_e32 v38, 0
	v_mov_b32_e32 v39, 0
	v_mov_b32_e32 v40, 0
	v_mov_b32_e32 v41, 0
	v_mov_b32_e32 v42, 0
	v_mov_b32_e32 v43, 0
	v_mov_b32_e32 v44, 0
	v_mov_b32_e32 v45, 0
	v_mov_b32_e32 v46, 0
	v_mov_b32_e32 v47, 0
	v_mov_b32_e32 v48, 0
	v_mov_b32_e32 v49, 0
	v_mov_b32_e32 v50, 0
	v_mov_b32_e32 v51, 0
	v_mov_b32_e32 v52, 0
	v_mov_b32_e32 v53, 0
	v_mov_b32_e32 v54, 0
	v_mov_b32_e32 v55, 0
	v_mov_b32_e32 v56, 0
	v_mov_b32_e32 v57, 0
	v_mov_b32_e32 v58, 0
	v_mov_b32_e32 v59, 0
	v_mov_b32_e32 v60, 0
	v_mov_b32_e32 v61, 0
	v_mov_b32_e32 v62, 0
	v_mov_b32_e32 v63, 0
	v_mov_b32_e32 v64, 0
	v_mov_b32_e32 v65, 0
	v_mov_b32_e32 v66, 0
	v_mov_b32_e32 v67, 0
	v_mov_b32_e32 v68, 0
	v_mov_b32_e32 v69, 0
	v_mov_b32_e32 v70, 0
	v_mov_b32_e32 v71, 0
	v_mov_b32_e32 v72, 0
	v_mov_b32_e32 v73, 0
	v_mov_b32_e32 v74, 0
	v_mov_b32_e32 v75, 0
	v_mov_b32_e32 v76, 0
	v_mov_b32_e32 v77, 0
	v_mov_b32_e32 v78, 0
	v_mov_b32_e32 v79, 0
	v_mov_b32_e32 v80, 0
	v_mov_b32_e32 v81, 0
	v_mov_b32_e32 v82, 0
	v_mov_b32_e32 v83, 0
	v_mov_b32_e32 v84, 0
	v_mov_b32_e32 v85, 0
	v_mov_b32_e32 v86, 0
	v_mov_b32_e32 v87, 0
	v_mov_b32_e32 v88, 0
	v_mov_b32_e32 v89, 0
	v_mov_b32_e32 v90, 0
	v_mov_b32_e32 v91, 0
	v_mov_b32_e32 v92, 0
	v_mov_b32_e32 v93, 0
	v_mov_b32_e32 v94, 0
	v_mov_b32_e32 v95, 0
	v_mov_b32_e32 v96, 0
	v_mov_b32_e32 v97, 0
	v_mov_b32_e32 v98, 0
	v_mov_b32_e32 v99, 0
	v_mov_b32_e32 v100, 0
	v_mov_b32_e32 v101, 0
	v_mov_b32_e32 v102, 0
	v_mov_b32_e32 v103, 0
	v_mov_b32_e32 v104, 0
	v_mov_b32_e32 v105, 0
	v_mov_b32_e32 v106, 0
	v_mov_b32_e32 v107, 0
	v_mov_b32_e32 v108, 0
	v_mov_b32_e32 v109, 0
	v_mov_b32_e32 v110, 0
	v_mov_b32_e32 v111, 0
	v_mov_b32_e32 v112, 0
	v_mov_b32_e32 v113, 0
	v_mov_b32_e32 v114, 0
	v_mov_b32_e32 v115, 0
	v_mov_b32_e32 v116, 0
	v_mov_b32_e32 v117, 0
	v_mov_b32_e32 v118, 0
	v_mov_b32_e32 v119, 0
	v_mov_b32_e32 v120, 0
	v_mov_b32_e32 v121, 0
	v_mov_b32_e32 v122, 0
	v_mov_b32_e32 v123, 0
	v_mov_b32_e32 v124, 0
	v_mov_b32_e32 v125, 0
	v_mov_b32_e32 v126, 0
	v_mov_b32_e32 v127, 0
	s_waitcnt lgkmcnt(0)
	v_lshlrev_b32_e32 v128, 10, v128
	v_lshlrev_b32_e32 v129, 10, v129
	v_lshlrev_b32_e32 v132, 10, v132
	v_lshlrev_b32_e32 v133, 10, v133
	v_lshlrev_b32_e32 v136, 10, v136
	v_lshlrev_b32_e32 v137, 10, v137
	v_lshlrev_b32_e32 v140, 10, v140
	v_lshlrev_b32_e32 v141, 10, v141
	v_lshlrev_b32_e32 v144, 10, v144
	v_lshlrev_b32_e32 v145, 10, v145
	v_lshlrev_b32_e32 v148, 10, v148
	v_lshlrev_b32_e32 v149, 10, v149
	v_lshlrev_b32_e32 v152, 10, v152
	v_lshlrev_b32_e32 v153, 10, v153
	v_lshlrev_b32_e32 v156, 10, v156
	v_lshlrev_b32_e32 v157, 10, v157
	s_mov_b32 s72, 0
	s_mov_b32 s73, 1
	s_mov_b32 s74, 2
	s_mov_b32 s75, 3
	s_mov_b32 s76, 4
	s_mov_b32 s77, 5
	s_mov_b32 s78, 6
	s_mov_b32 s79, 7
	s_nop 0
	v_readlane_b32 s48, v128, s72
	v_readlane_b32 s49, v128, s73
	v_readlane_b32 s50, v128, s74
	v_readlane_b32 s51, v128, s75
	v_readlane_b32 s52, v128, s76
	v_readlane_b32 s53, v128, s77
	v_readlane_b32 s54, v128, s78
	v_readlane_b32 s55, v128, s79
	s_add_u32 s32, s0, s48
	s_addc_u32 s33, s1, 0
	s_add_u32 s34, s0, s49
	s_addc_u32 s35, s1, 0
	s_add_u32 s36, s0, s50
	s_addc_u32 s37, s1, 0
	s_add_u32 s38, s0, s51
	s_addc_u32 s39, s1, 0
	s_add_u32 s40, s0, s52
	s_addc_u32 s41, s1, 0
	s_add_u32 s42, s0, s53
	s_addc_u32 s43, s1, 0
	s_add_u32 s44, s0, s54
	s_addc_u32 s45, s1, 0
	s_add_u32 s46, s0, s55
	s_addc_u32 s47, s1, 0
	global_load_dwordx4 v[160:163], v240, s[32:33]
	global_load_dwordx4 v[164:167], v240, s[34:35]
	global_load_dwordx4 v[168:171], v240, s[36:37]
	global_load_dwordx4 v[172:175], v240, s[38:39]
	global_load_dwordx4 v[176:179], v240, s[40:41]
	global_load_dwordx4 v[180:183], v240, s[42:43]
	global_load_dwordx4 v[184:187], v240, s[44:45]
	global_load_dwordx4 v[188:191], v240, s[46:47]
	s_mov_b32 s12, 0
.Lvf_k:
	v_readlane_b32 s16, v130, s72
	v_readlane_b32 s18, v130, s73
	v_readlane_b32 s20, v130, s74
	v_readlane_b32 s22, v130, s75
	v_readlane_b32 s24, v130, s76
	v_readlane_b32 s26, v130, s77
	v_readlane_b32 s28, v130, s78
	v_readlane_b32 s30, v130, s79
	v_readlane_b32 s48, v132, s72
	v_readlane_b32 s49, v132, s73
	v_readlane_b32 s50, v132, s74
	v_readlane_b32 s51, v132, s75
	v_readlane_b32 s52, v132, s76
	v_readlane_b32 s53, v132, s77
	v_readlane_b32 s54, v132, s78
	v_readlane_b32 s55, v132, s79
	s_add_u32 s32, s0, s48
	s_addc_u32 s33, s1, 0
	s_add_u32 s34, s0, s49
	s_addc_u32 s35, s1, 0
	s_add_u32 s36, s0, s50
	s_addc_u32 s37, s1, 0
	s_add_u32 s38, s0, s51
	s_addc_u32 s39, s1, 0
	s_add_u32 s40, s0, s52
	s_addc_u32 s41, s1, 0
	s_add_u32 s42, s0, s53
	s_addc_u32 s43, s1, 0
	s_add_u32 s44, s0, s54
	s_addc_u32 s45, s1, 0
	s_add_u32 s46, s0, s55
	s_addc_u32 s47, s1, 0
	global_load_dwordx4 v[192:195], v240, s[32:33]
	global_load_dwordx4 v[196:199], v240, s[34:35]
	global_load_dwordx4 v[200:203], v240, s[36:37]
	global_load_dwordx4 v[204:207], v240, s[38:39]
	global_load_dwordx4 v[208:211], v240, s[40:41]
	global_load_dwordx4 v[212:215], v240, s[42:43]
	global_load_dwordx4 v[216:219], v240, s[44:45]
	global_load_dwordx4 v[220:223], v240, s[46:47]
	s_waitcnt vmcnt(8)
	v_cvt_pk_f32_fp8_e32 v[224:225], v160
	v_cvt_pk_f32_fp8_sdwa v[226:227], v160 src0_sel:WORD_1
	v_cvt_pk_f32_fp8_e32 v[228:229], v161
	v_cvt_pk_f32_fp8_sdwa v[230:231], v161 src0_sel:WORD_1
	v_cvt_pk_f32_fp8_e32 v[232:233], v162
	v_cvt_pk_f32_fp8_sdwa v[234:235], v162 src0_sel:WORD_1
	v_cvt_pk_f32_fp8_e32 v[236:237], v163
	v_cvt_pk_f32_fp8_sdwa v[238:239], v163 src0_sel:WORD_1
	v_pk_fma_f32 v[0:1], v[224:225], s[16:17], v[0:1] op_sel_hi:[1,0,1]
	v_pk_fma_f32 v[2:3], v[226:227], s[16:17], v[2:3] op_sel_hi:[1,0,1]
	v_pk_fma_f32 v[4:5], v[228:229], s[16:17], v[4:5] op_sel_hi:[1,0,1]
	v_pk_fma_f32 v[6:7], v[230:231], s[16:17], v[6:7] op_sel_hi:[1,0,1]
	v_pk_fma_f32 v[8:9], v[232:233], s[16:17], v[8:9] op_sel_hi:[1,0,1]
	v_pk_fma_f32 v[10:11], v[234:235], s[16:17], v[10:11] op_sel_hi:[1,0,1]
	v_pk_fma_f32 v[12:13], v[236:237], s[16:17], v[12:13] op_sel_hi:[1,0,1]
	v_pk_fma_f32 v[14:15], v[238:239], s[16:17], v[14:15] op_sel_hi:[1,0,1]
	v_cvt_pk_f32_fp8_e32 v[224:225], v164
	v_cvt_pk_f32_fp8_sdwa v[226:227], v164 src0_sel:WORD_1
	v_cvt_pk_f32_fp8_e32 v[228:229], v165
	v_cvt_pk_f32_fp8_sdwa v[230:231], v165 src0_sel:WORD_1
	v_cvt_pk_f32_fp8_e32 v[232:233], v166
	v_cvt_pk_f32_fp8_sdwa v[234:235], v166 src0_sel:WORD_1
	v_cvt_pk_f32_fp8_e32 v[236:237], v167
	v_cvt_pk_f32_fp8_sdwa v[238:239], v167 src0_sel:WORD_1
	v_pk_fma_f32 v[0:1], v[224:225], s[18:19], v[0:1] op_sel_hi:[1,0,1]
	v_pk_fma_f32 v[2:3], v[226:227], s[18:19], v[2:3] op_sel_hi:[1,0,1]
	v_pk_fma_f32 v[4:5], v[228:229], s[18:19], v[4:5] op_sel_hi:[1,0,1]
	v_pk_fma_f32 v[6:7], v[230:231], s[18:19], v[6:7] op_sel_hi:[1,0,1]
	v_pk_fma_f32 v[8:9], v[232:233], s[18:19], v[8:9] op_sel_hi:[1,0,1]
	v_pk_fma_f32 v[10:11], v[234:235], s[18:19], v[10:11] op_sel_hi:[1,0,1]
	v_pk_fma_f32 v[12:13], v[236:237], s[18:19], v[12:13] op_sel_hi:[1,0,1]
	v_pk_fma_f32 v[14:15], v[238:239], s[18:19], v[14:15] op_sel_hi:[1,0,1]
	v_cvt_pk_f32_fp8_e32 v[224:225], v168
	v_cvt_pk_f32_fp8_sdwa v[226:227], v168 src0_sel:WORD_1
	v_cvt_pk_f32_fp8_e32 v[228:229], v169
	v_cvt_pk_f32_fp8_sdwa v[230:231], v169 src0_sel:WORD_1
	v_cvt_pk_f32_fp8_e32 v[232:233], v170
	v_cvt_pk_f32_fp8_sdwa v[234:235], v170 src0_sel:WORD_1
	v_cvt_pk_f32_fp8_e32 v[236:237], v171
	v_cvt_pk_f32_fp8_sdwa v[238:239], v171 src0_sel:WORD_1
	v_pk_fma_f32 v[0:1], v[224:225], s[20:21], v[0:1] op_sel_hi:[1,0,1]
	v_pk_fma_f32 v[2:3], v[226:227], s[20:21], v[2:3] op_sel_hi:[1,0,1]
	v_pk_fma_f32 v[4:5], v[228:229], s[20:21], v[4:5] op_sel_hi:[1,0,1]
	v_pk_fma_f32 v[6:7], v[230:231], s[20:21], v[6:7] op_sel_hi:[1,0,1]
	v_pk_fma_f32 v[8:9], v[232:233], s[20:21], v[8:9] op_sel_hi:[1,0,1]
	v_pk_fma_f32 v[10:11], v[234:235], s[20:21], v[10:11] op_sel_hi:[1,0,1]
	v_pk_fma_f32 v[12:13], v[236:237], s[20:21], v[12:13] op_sel_hi:[1,0,1]
	v_pk_fma_f32 v[14:15], v[238:239], s[20:21], v[14:15] op_sel_hi:[1,0,1]
	v_cvt_pk_f32_fp8_e32 v[224:225], v172
	v_cvt_pk_f32_fp8_sdwa v[226:227], v172 src0_sel:WORD_1
	v_cvt_pk_f32_fp8_e32 v[228:229], v173
	v_cvt_pk_f32_fp8_sdwa v[230:231], v173 src0_sel:WORD_1
	v_cvt_pk_f32_fp8_e32 v[232:233], v174
	v_cvt_pk_f32_fp8_sdwa v[234:235], v174 src0_sel:WORD_1
	v_cvt_pk_f32_fp8_e32 v[236:237], v175
	v_cvt_pk_f32_fp8_sdwa v[238:239], v175 src0_sel:WORD_1
	v_pk_fma_f32 v[0:1], v[224:225], s[22:23], v[0:1] op_sel_hi:[1,0,1]
	v_pk_fma_f32 v[2:3], v[226:227], s[22:23], v[2:3] op_sel_hi:[1,0,1]
	v_pk_fma_f32 v[4:5], v[228:229], s[22:23], v[4:5] op_sel_hi:[1,0,1]
	v_pk_fma_f32 v[6:7], v[230:231], s[22:23], v[6:7] op_sel_hi:[1,0,1]
	v_pk_fma_f32 v[8:9], v[232:233], s[22:23], v[8:9] op_sel_hi:[1,0,1]
	v_pk_fma_f32 v[10:11], v[234:235], s[22:23], v[10:11] op_sel_hi:[1,0,1]
	v_pk_fma_f32 v[12:13], v[236:237], s[22:23], v[12:13] op_sel_hi:[1,0,1]
	v_pk_fma_f32 v[14:15], v[238:239], s[22:23], v[14:15] op_sel_hi:[1,0,1]
	v_cvt_pk_f32_fp8_e32 v[224:225], v176
	v_cvt_pk_f32_fp8_sdwa v[226:227], v176 src0_sel:WORD_1
	v_cvt_pk_f32_fp8_e32 v[228:229], v177
	v_cvt_pk_f32_fp8_sdwa v[230:231], v177 src0_sel:WORD_1
	v_cvt_pk_f32_fp8_e32 v[232:233], v178
	v_cvt_pk_f32_fp8_sdwa v[234:235], v178 src0_sel:WORD_1
	v_cvt_pk_f32_fp8_e32 v[236:237], v179
	v_cvt_pk_f32_fp8_sdwa v[238:239], v179 src0_sel:WORD_1
	v_pk_fma_f32 v[0:1], v[224:225], s[24:25], v[0:1] op_sel_hi:[1,0,1]
	v_pk_fma_f32 v[2:3], v[226:227], s[24:25], v[2:3] op_sel_hi:[1,0,1]
	v_pk_fma_f32 v[4:5], v[228:229], s[24:25], v[4:5] op_sel_hi:[1,0,1]
	v_pk_fma_f32 v[6:7], v[230:231], s[24:25], v[6:7] op_sel_hi:[1,0,1]
	v_pk_fma_f32 v[8:9], v[232:233], s[24:25], v[8:9] op_sel_hi:[1,0,1]
	v_pk_fma_f32 v[10:11], v[234:235], s[24:25], v[10:11] op_sel_hi:[1,0,1]
	v_pk_fma_f32 v[12:13], v[236:237], s[24:25], v[12:13] op_sel_hi:[1,0,1]
	v_pk_fma_f32 v[14:15], v[238:239], s[24:25], v[14:15] op_sel_hi:[1,0,1]
	v_cvt_pk_f32_fp8_e32 v[224:225], v180
	v_cvt_pk_f32_fp8_sdwa v[226:227], v180 src0_sel:WORD_1
	v_cvt_pk_f32_fp8_e32 v[228:229], v181
	v_cvt_pk_f32_fp8_sdwa v[230:231], v181 src0_sel:WORD_1
	v_cvt_pk_f32_fp8_e32 v[232:233], v182
	v_cvt_pk_f32_fp8_sdwa v[234:235], v182 src0_sel:WORD_1
	v_cvt_pk_f32_fp8_e32 v[236:237], v183
	v_cvt_pk_f32_fp8_sdwa v[238:239], v183 src0_sel:WORD_1
	v_pk_fma_f32 v[0:1], v[224:225], s[26:27], v[0:1] op_sel_hi:[1,0,1]
	v_pk_fma_f32 v[2:3], v[226:227], s[26:27], v[2:3] op_sel_hi:[1,0,1]
	v_pk_fma_f32 v[4:5], v[228:229], s[26:27], v[4:5] op_sel_hi:[1,0,1]
	v_pk_fma_f32 v[6:7], v[230:231], s[26:27], v[6:7] op_sel_hi:[1,0,1]
	v_pk_fma_f32 v[8:9], v[232:233], s[26:27], v[8:9] op_sel_hi:[1,0,1]
	v_pk_fma_f32 v[10:11], v[234:235], s[26:27], v[10:11] op_sel_hi:[1,0,1]
	v_pk_fma_f32 v[12:13], v[236:237], s[26:27], v[12:13] op_sel_hi:[1,0,1]
	v_pk_fma_f32 v[14:15], v[238:239], s[26:27], v[14:15] op_sel_hi:[1,0,1]
	v_cvt_pk_f32_fp8_e32 v[224:225], v184
	v_cvt_pk_f32_fp8_sdwa v[226:227], v184 src0_sel:WORD_1
	v_cvt_pk_f32_fp8_e32 v[228:229], v185
	v_cvt_pk_f32_fp8_sdwa v[230:231], v185 src0_sel:WORD_1
	v_cvt_pk_f32_fp8_e32 v[232:233], v186
	v_cvt_pk_f32_fp8_sdwa v[234:235], v186 src0_sel:WORD_1
	v_cvt_pk_f32_fp8_e32 v[236:237], v187
	v_cvt_pk_f32_fp8_sdwa v[238:239], v187 src0_sel:WORD_1
	v_pk_fma_f32 v[0:1], v[224:225], s[28:29], v[0:1] op_sel_hi:[1,0,1]
	v_pk_fma_f32 v[2:3], v[226:227], s[28:29], v[2:3] op_sel_hi:[1,0,1]
	v_pk_fma_f32 v[4:5], v[228:229], s[28:29], v[4:5] op_sel_hi:[1,0,1]
	v_pk_fma_f32 v[6:7], v[230:231], s[28:29], v[6:7] op_sel_hi:[1,0,1]
	v_pk_fma_f32 v[8:9], v[232:233], s[28:29], v[8:9] op_sel_hi:[1,0,1]
	v_pk_fma_f32 v[10:11], v[234:235], s[28:29], v[10:11] op_sel_hi:[1,0,1]
	v_pk_fma_f32 v[12:13], v[236:237], s[28:29], v[12:13] op_sel_hi:[1,0,1]
	v_pk_fma_f32 v[14:15], v[238:239], s[28:29], v[14:15] op_sel_hi:[1,0,1]
	v_cvt_pk_f32_fp8_e32 v[224:225], v188
	v_cvt_pk_f32_fp8_sdwa v[226:227], v188 src0_sel:WORD_1
	v_cvt_pk_f32_fp8_e32 v[228:229], v189
	v_cvt_pk_f32_fp8_sdwa v[230:231], v189 src0_sel:WORD_1
	v_cvt_pk_f32_fp8_e32 v[232:233], v190
	v_cvt_pk_f32_fp8_sdwa v[234:235], v190 src0_sel:WORD_1
	v_cvt_pk_f32_fp8_e32 v[236:237], v191
	v_cvt_pk_f32_fp8_sdwa v[238:239], v191 src0_sel:WORD_1
	v_pk_fma_f32 v[0:1], v[224:225], s[30:31], v[0:1] op_sel_hi:[1,0,1]
	v_pk_fma_f32 v[2:3], v[226:227], s[30:31], v[2:3] op_sel_hi:[1,0,1]
	v_pk_fma_f32 v[4:5], v[228:229], s[30:31], v[4:5] op_sel_hi:[1,0,1]
	v_pk_fma_f32 v[6:7], v[230:231], s[30:31], v[6:7] op_sel_hi:[1,0,1]
	v_pk_fma_f32 v[8:9], v[232:233], s[30:31], v[8:9] op_sel_hi:[1,0,1]
	v_pk_fma_f32 v[10:11], v[234:235], s[30:31], v[10:11] op_sel_hi:[1,0,1]
	v_pk_fma_f32 v[12:13], v[236:237], s[30:31], v[12:13] op_sel_hi:[1,0,1]
	v_pk_fma_f32 v[14:15], v[238:239], s[30:31], v[14:15] op_sel_hi:[1,0,1]
	v_readlane_b32 s16, v134, s72
	v_readlane_b32 s18, v134, s73
	v_readlane_b32 s20, v134, s74
	v_readlane_b32 s22, v134, s75
	v_readlane_b32 s24, v134, s76
	v_readlane_b32 s26, v134, s77
	v_readlane_b32 s28, v134, s78
	v_readlane_b32 s30, v134, s79
	v_readlane_b32 s48, v136, s72
	v_readlane_b32 s49, v136, s73
	v_readlane_b32 s50, v136, s74
	v_readlane_b32 s51, v136, s75
	v_readlane_b32 s52, v136, s76
	v_readlane_b32 s53, v136, s77
	v_readlane_b32 s54, v136, s78
	v_readlane_b32 s55, v136, s79
	s_add_u32 s32, s0, s48
	s_addc_u32 s33, s1, 0
	s_add_u32 s34, s0, s49
	s_addc_u32 s35, s1, 0
	s_add_u32 s36, s0, s50
	s_addc_u32 s37, s1, 0
	s_add_u32 s38, s0, s51
	s_addc_u32 s39, s1, 0
	s_add_u32 s40, s0, s52
	s_addc_u32 s41, s1, 0
	s_add_u32 s42, s0, s53
	s_addc_u32 s43, s1, 0
	s_add_u32 s44, s0, s54
	s_addc_u32 s45, s1, 0
	s_add_u32 s46, s0, s55
	s_addc_u32 s47, s1, 0
	global_load_dwordx4 v[160:163], v240, s[32:33]
	global_load_dwordx4 v[164:167], v240, s[34:35]
	global_load_dwordx4 v[168:171], v240, s[36:37]
	global_load_dwordx4 v[172:175], v240, s[38:39]
	global_load_dwordx4 v[176:179], v240, s[40:41]
	global_load_dwordx4 v[180:183], v240, s[42:43]
	global_load_dwordx4 v[184:187], v240, s[44:45]
	global_load_dwordx4 v[188:191], v240, s[46:47]
	s_waitcnt vmcnt(8)
	v_cvt_pk_f32_fp8_e32 v[224:225], v192
	v_cvt_pk_f32_fp8_sdwa v[226:227], v192 src0_sel:WORD_1
	v_cvt_pk_f32_fp8_e32 v[228:229], v193
	v_cvt_pk_f32_fp8_sdwa v[230:231], v193 src0_sel:WORD_1
	v_cvt_pk_f32_fp8_e32 v[232:233], v194
	v_cvt_pk_f32_fp8_sdwa v[234:235], v194 src0_sel:WORD_1
	v_cvt_pk_f32_fp8_e32 v[236:237], v195
	v_cvt_pk_f32_fp8_sdwa v[238:239], v195 src0_sel:WORD_1
	v_pk_fma_f32 v[16:17], v[224:225], s[16:17], v[16:17] op_sel_hi:[1,0,1]
	v_pk_fma_f32 v[18:19], v[226:227], s[16:17], v[18:19] op_sel_hi:[1,0,1]
	v_pk_fma_f32 v[20:21], v[228:229], s[16:17], v[20:21] op_sel_hi:[1,0,1]
	v_pk_fma_f32 v[22:23], v[230:231], s[16:17], v[22:23] op_sel_hi:[1,0,1]
	v_pk_fma_f32 v[24:25], v[232:233], s[16:17], v[24:25] op_sel_hi:[1,0,1]
	v_pk_fma_f32 v[26:27], v[234:235], s[16:17], v[26:27] op_sel_hi:[1,0,1]
	v_pk_fma_f32 v[28:29], v[236:237], s[16:17], v[28:29] op_sel_hi:[1,0,1]
	v_pk_fma_f32 v[30:31], v[238:239], s[16:17], v[30:31] op_sel_hi:[1,0,1]
	v_cvt_pk_f32_fp8_e32 v[224:225], v196
	v_cvt_pk_f32_fp8_sdwa v[226:227], v196 src0_sel:WORD_1
	v_cvt_pk_f32_fp8_e32 v[228:229], v197
	v_cvt_pk_f32_fp8_sdwa v[230:231], v197 src0_sel:WORD_1
	v_cvt_pk_f32_fp8_e32 v[232:233], v198
	v_cvt_pk_f32_fp8_sdwa v[234:235], v198 src0_sel:WORD_1
	v_cvt_pk_f32_fp8_e32 v[236:237], v199
	v_cvt_pk_f32_fp8_sdwa v[238:239], v199 src0_sel:WORD_1
	v_pk_fma_f32 v[16:17], v[224:225], s[18:19], v[16:17] op_sel_hi:[1,0,1]
	v_pk_fma_f32 v[18:19], v[226:227], s[18:19], v[18:19] op_sel_hi:[1,0,1]
	v_pk_fma_f32 v[20:21], v[228:229], s[18:19], v[20:21] op_sel_hi:[1,0,1]
	v_pk_fma_f32 v[22:23], v[230:231], s[18:19], v[22:23] op_sel_hi:[1,0,1]
	v_pk_fma_f32 v[24:25], v[232:233], s[18:19], v[24:25] op_sel_hi:[1,0,1]
	v_pk_fma_f32 v[26:27], v[234:235], s[18:19], v[26:27] op_sel_hi:[1,0,1]
	v_pk_fma_f32 v[28:29], v[236:237], s[18:19], v[28:29] op_sel_hi:[1,0,1]
	v_pk_fma_f32 v[30:31], v[238:239], s[18:19], v[30:31] op_sel_hi:[1,0,1]
	v_cvt_pk_f32_fp8_e32 v[224:225], v200
	v_cvt_pk_f32_fp8_sdwa v[226:227], v200 src0_sel:WORD_1
	v_cvt_pk_f32_fp8_e32 v[228:229], v201
	v_cvt_pk_f32_fp8_sdwa v[230:231], v201 src0_sel:WORD_1
	v_cvt_pk_f32_fp8_e32 v[232:233], v202
	v_cvt_pk_f32_fp8_sdwa v[234:235], v202 src0_sel:WORD_1
	v_cvt_pk_f32_fp8_e32 v[236:237], v203
	v_cvt_pk_f32_fp8_sdwa v[238:239], v203 src0_sel:WORD_1
	v_pk_fma_f32 v[16:17], v[224:225], s[20:21], v[16:17] op_sel_hi:[1,0,1]
	v_pk_fma_f32 v[18:19], v[226:227], s[20:21], v[18:19] op_sel_hi:[1,0,1]
	v_pk_fma_f32 v[20:21], v[228:229], s[20:21], v[20:21] op_sel_hi:[1,0,1]
	v_pk_fma_f32 v[22:23], v[230:231], s[20:21], v[22:23] op_sel_hi:[1,0,1]
	v_pk_fma_f32 v[24:25], v[232:233], s[20:21], v[24:25] op_sel_hi:[1,0,1]
	v_pk_fma_f32 v[26:27], v[234:235], s[20:21], v[26:27] op_sel_hi:[1,0,1]
	v_pk_fma_f32 v[28:29], v[236:237], s[20:21], v[28:29] op_sel_hi:[1,0,1]
	v_pk_fma_f32 v[30:31], v[238:239], s[20:21], v[30:31] op_sel_hi:[1,0,1]
	v_cvt_pk_f32_fp8_e32 v[224:225], v204
	v_cvt_pk_f32_fp8_sdwa v[226:227], v204 src0_sel:WORD_1
	v_cvt_pk_f32_fp8_e32 v[228:229], v205
	v_cvt_pk_f32_fp8_sdwa v[230:231], v205 src0_sel:WORD_1
	v_cvt_pk_f32_fp8_e32 v[232:233], v206
	v_cvt_pk_f32_fp8_sdwa v[234:235], v206 src0_sel:WORD_1
	v_cvt_pk_f32_fp8_e32 v[236:237], v207
	v_cvt_pk_f32_fp8_sdwa v[238:239], v207 src0_sel:WORD_1
	v_pk_fma_f32 v[16:17], v[224:225], s[22:23], v[16:17] op_sel_hi:[1,0,1]
	v_pk_fma_f32 v[18:19], v[226:227], s[22:23], v[18:19] op_sel_hi:[1,0,1]
	v_pk_fma_f32 v[20:21], v[228:229], s[22:23], v[20:21] op_sel_hi:[1,0,1]
	v_pk_fma_f32 v[22:23], v[230:231], s[22:23], v[22:23] op_sel_hi:[1,0,1]
	v_pk_fma_f32 v[24:25], v[232:233], s[22:23], v[24:25] op_sel_hi:[1,0,1]
	v_pk_fma_f32 v[26:27], v[234:235], s[22:23], v[26:27] op_sel_hi:[1,0,1]
	v_pk_fma_f32 v[28:29], v[236:237], s[22:23], v[28:29] op_sel_hi:[1,0,1]
	v_pk_fma_f32 v[30:31], v[238:239], s[22:23], v[30:31] op_sel_hi:[1,0,1]
	v_cvt_pk_f32_fp8_e32 v[224:225], v208
	v_cvt_pk_f32_fp8_sdwa v[226:227], v208 src0_sel:WORD_1
	v_cvt_pk_f32_fp8_e32 v[228:229], v209
	v_cvt_pk_f32_fp8_sdwa v[230:231], v209 src0_sel:WORD_1
	v_cvt_pk_f32_fp8_e32 v[232:233], v210
	v_cvt_pk_f32_fp8_sdwa v[234:235], v210 src0_sel:WORD_1
	v_cvt_pk_f32_fp8_e32 v[236:237], v211
	v_cvt_pk_f32_fp8_sdwa v[238:239], v211 src0_sel:WORD_1
	v_pk_fma_f32 v[16:17], v[224:225], s[24:25], v[16:17] op_sel_hi:[1,0,1]
	v_pk_fma_f32 v[18:19], v[226:227], s[24:25], v[18:19] op_sel_hi:[1,0,1]
	v_pk_fma_f32 v[20:21], v[228:229], s[24:25], v[20:21] op_sel_hi:[1,0,1]
	v_pk_fma_f32 v[22:23], v[230:231], s[24:25], v[22:23] op_sel_hi:[1,0,1]
	v_pk_fma_f32 v[24:25], v[232:233], s[24:25], v[24:25] op_sel_hi:[1,0,1]
	v_pk_fma_f32 v[26:27], v[234:235], s[24:25], v[26:27] op_sel_hi:[1,0,1]
	v_pk_fma_f32 v[28:29], v[236:237], s[24:25], v[28:29] op_sel_hi:[1,0,1]
	v_pk_fma_f32 v[30:31], v[238:239], s[24:25], v[30:31] op_sel_hi:[1,0,1]
	v_cvt_pk_f32_fp8_e32 v[224:225], v212
	v_cvt_pk_f32_fp8_sdwa v[226:227], v212 src0_sel:WORD_1
	v_cvt_pk_f32_fp8_e32 v[228:229], v213
	v_cvt_pk_f32_fp8_sdwa v[230:231], v213 src0_sel:WORD_1
	v_cvt_pk_f32_fp8_e32 v[232:233], v214
	v_cvt_pk_f32_fp8_sdwa v[234:235], v214 src0_sel:WORD_1
	v_cvt_pk_f32_fp8_e32 v[236:237], v215
	v_cvt_pk_f32_fp8_sdwa v[238:239], v215 src0_sel:WORD_1
	v_pk_fma_f32 v[16:17], v[224:225], s[26:27], v[16:17] op_sel_hi:[1,0,1]
	v_pk_fma_f32 v[18:19], v[226:227], s[26:27], v[18:19] op_sel_hi:[1,0,1]
	v_pk_fma_f32 v[20:21], v[228:229], s[26:27], v[20:21] op_sel_hi:[1,0,1]
	v_pk_fma_f32 v[22:23], v[230:231], s[26:27], v[22:23] op_sel_hi:[1,0,1]
	v_pk_fma_f32 v[24:25], v[232:233], s[26:27], v[24:25] op_sel_hi:[1,0,1]
	v_pk_fma_f32 v[26:27], v[234:235], s[26:27], v[26:27] op_sel_hi:[1,0,1]
	v_pk_fma_f32 v[28:29], v[236:237], s[26:27], v[28:29] op_sel_hi:[1,0,1]
	v_pk_fma_f32 v[30:31], v[238:239], s[26:27], v[30:31] op_sel_hi:[1,0,1]
	v_cvt_pk_f32_fp8_e32 v[224:225], v216
	v_cvt_pk_f32_fp8_sdwa v[226:227], v216 src0_sel:WORD_1
	v_cvt_pk_f32_fp8_e32 v[228:229], v217
	v_cvt_pk_f32_fp8_sdwa v[230:231], v217 src0_sel:WORD_1
	v_cvt_pk_f32_fp8_e32 v[232:233], v218
	v_cvt_pk_f32_fp8_sdwa v[234:235], v218 src0_sel:WORD_1
	v_cvt_pk_f32_fp8_e32 v[236:237], v219
	v_cvt_pk_f32_fp8_sdwa v[238:239], v219 src0_sel:WORD_1
	v_pk_fma_f32 v[16:17], v[224:225], s[28:29], v[16:17] op_sel_hi:[1,0,1]
	v_pk_fma_f32 v[18:19], v[226:227], s[28:29], v[18:19] op_sel_hi:[1,0,1]
	v_pk_fma_f32 v[20:21], v[228:229], s[28:29], v[20:21] op_sel_hi:[1,0,1]
	v_pk_fma_f32 v[22:23], v[230:231], s[28:29], v[22:23] op_sel_hi:[1,0,1]
	v_pk_fma_f32 v[24:25], v[232:233], s[28:29], v[24:25] op_sel_hi:[1,0,1]
	v_pk_fma_f32 v[26:27], v[234:235], s[28:29], v[26:27] op_sel_hi:[1,0,1]
	v_pk_fma_f32 v[28:29], v[236:237], s[28:29], v[28:29] op_sel_hi:[1,0,1]
	v_pk_fma_f32 v[30:31], v[238:239], s[28:29], v[30:31] op_sel_hi:[1,0,1]
	v_cvt_pk_f32_fp8_e32 v[224:225], v220
	v_cvt_pk_f32_fp8_sdwa v[226:227], v220 src0_sel:WORD_1
	v_cvt_pk_f32_fp8_e32 v[228:229], v221
	v_cvt_pk_f32_fp8_sdwa v[230:231], v221 src0_sel:WORD_1
	v_cvt_pk_f32_fp8_e32 v[232:233], v222
	v_cvt_pk_f32_fp8_sdwa v[234:235], v222 src0_sel:WORD_1
	v_cvt_pk_f32_fp8_e32 v[236:237], v223
	v_cvt_pk_f32_fp8_sdwa v[238:239], v223 src0_sel:WORD_1
	v_pk_fma_f32 v[16:17], v[224:225], s[30:31], v[16:17] op_sel_hi:[1,0,1]
	v_pk_fma_f32 v[18:19], v[226:227], s[30:31], v[18:19] op_sel_hi:[1,0,1]
	v_pk_fma_f32 v[20:21], v[228:229], s[30:31], v[20:21] op_sel_hi:[1,0,1]
	v_pk_fma_f32 v[22:23], v[230:231], s[30:31], v[22:23] op_sel_hi:[1,0,1]
	v_pk_fma_f32 v[24:25], v[232:233], s[30:31], v[24:25] op_sel_hi:[1,0,1]
	v_pk_fma_f32 v[26:27], v[234:235], s[30:31], v[26:27] op_sel_hi:[1,0,1]
	v_pk_fma_f32 v[28:29], v[236:237], s[30:31], v[28:29] op_sel_hi:[1,0,1]
	v_pk_fma_f32 v[30:31], v[238:239], s[30:31], v[30:31] op_sel_hi:[1,0,1]
	v_readlane_b32 s16, v138, s72
	v_readlane_b32 s18, v138, s73
	v_readlane_b32 s20, v138, s74
	v_readlane_b32 s22, v138, s75
	v_readlane_b32 s24, v138, s76
	v_readlane_b32 s26, v138, s77
	v_readlane_b32 s28, v138, s78
	v_readlane_b32 s30, v138, s79
	v_readlane_b32 s48, v140, s72
	v_readlane_b32 s49, v140, s73
	v_readlane_b32 s50, v140, s74
	v_readlane_b32 s51, v140, s75
	v_readlane_b32 s52, v140, s76
	v_readlane_b32 s53, v140, s77
	v_readlane_b32 s54, v140, s78
	v_readlane_b32 s55, v140, s79
	s_add_u32 s32, s0, s48
	s_addc_u32 s33, s1, 0
	s_add_u32 s34, s0, s49
	s_addc_u32 s35, s1, 0
	s_add_u32 s36, s0, s50
	s_addc_u32 s37, s1, 0
	s_add_u32 s38, s0, s51
	s_addc_u32 s39, s1, 0
	s_add_u32 s40, s0, s52
	s_addc_u32 s41, s1, 0
	s_add_u32 s42, s0, s53
	s_addc_u32 s43, s1, 0
	s_add_u32 s44, s0, s54
	s_addc_u32 s45, s1, 0
	s_add_u32 s46, s0, s55
	s_addc_u32 s47, s1, 0
	global_load_dwordx4 v[192:195], v240, s[32:33]
	global_load_dwordx4 v[196:199], v240, s[34:35]
	global_load_dwordx4 v[200:203], v240, s[36:37]
	global_load_dwordx4 v[204:207], v240, s[38:39]
	global_load_dwordx4 v[208:211], v240, s[40:41]
	global_load_dwordx4 v[212:215], v240, s[42:43]
	global_load_dwordx4 v[216:219], v240, s[44:45]
	global_load_dwordx4 v[220:223], v240, s[46:47]
	s_waitcnt vmcnt(8)
	v_cvt_pk_f32_fp8_e32 v[224:225], v160
	v_cvt_pk_f32_fp8_sdwa v[226:227], v160 src0_sel:WORD_1
	v_cvt_pk_f32_fp8_e32 v[228:229], v161
	v_cvt_pk_f32_fp8_sdwa v[230:231], v161 src0_sel:WORD_1
	v_cvt_pk_f32_fp8_e32 v[232:233], v162
	v_cvt_pk_f32_fp8_sdwa v[234:235], v162 src0_sel:WORD_1
	v_cvt_pk_f32_fp8_e32 v[236:237], v163
	v_cvt_pk_f32_fp8_sdwa v[238:239], v163 src0_sel:WORD_1
	v_pk_fma_f32 v[32:33], v[224:225], s[16:17], v[32:33] op_sel_hi:[1,0,1]
	v_pk_fma_f32 v[34:35], v[226:227], s[16:17], v[34:35] op_sel_hi:[1,0,1]
	v_pk_fma_f32 v[36:37], v[228:229], s[16:17], v[36:37] op_sel_hi:[1,0,1]
	v_pk_fma_f32 v[38:39], v[230:231], s[16:17], v[38:39] op_sel_hi:[1,0,1]
	v_pk_fma_f32 v[40:41], v[232:233], s[16:17], v[40:41] op_sel_hi:[1,0,1]
	v_pk_fma_f32 v[42:43], v[234:235], s[16:17], v[42:43] op_sel_hi:[1,0,1]
	v_pk_fma_f32 v[44:45], v[236:237], s[16:17], v[44:45] op_sel_hi:[1,0,1]
	v_pk_fma_f32 v[46:47], v[238:239], s[16:17], v[46:47] op_sel_hi:[1,0,1]
	v_cvt_pk_f32_fp8_e32 v[224:225], v164
	v_cvt_pk_f32_fp8_sdwa v[226:227], v164 src0_sel:WORD_1
	v_cvt_pk_f32_fp8_e32 v[228:229], v165
	v_cvt_pk_f32_fp8_sdwa v[230:231], v165 src0_sel:WORD_1
	v_cvt_pk_f32_fp8_e32 v[232:233], v166
	v_cvt_pk_f32_fp8_sdwa v[234:235], v166 src0_sel:WORD_1
	v_cvt_pk_f32_fp8_e32 v[236:237], v167
	v_cvt_pk_f32_fp8_sdwa v[238:239], v167 src0_sel:WORD_1
	v_pk_fma_f32 v[32:33], v[224:225], s[18:19], v[32:33] op_sel_hi:[1,0,1]
	v_pk_fma_f32 v[34:35], v[226:227], s[18:19], v[34:35] op_sel_hi:[1,0,1]
	v_pk_fma_f32 v[36:37], v[228:229], s[18:19], v[36:37] op_sel_hi:[1,0,1]
	v_pk_fma_f32 v[38:39], v[230:231], s[18:19], v[38:39] op_sel_hi:[1,0,1]
	v_pk_fma_f32 v[40:41], v[232:233], s[18:19], v[40:41] op_sel_hi:[1,0,1]
	v_pk_fma_f32 v[42:43], v[234:235], s[18:19], v[42:43] op_sel_hi:[1,0,1]
	v_pk_fma_f32 v[44:45], v[236:237], s[18:19], v[44:45] op_sel_hi:[1,0,1]
	v_pk_fma_f32 v[46:47], v[238:239], s[18:19], v[46:47] op_sel_hi:[1,0,1]
	v_cvt_pk_f32_fp8_e32 v[224:225], v168
	v_cvt_pk_f32_fp8_sdwa v[226:227], v168 src0_sel:WORD_1
	v_cvt_pk_f32_fp8_e32 v[228:229], v169
	v_cvt_pk_f32_fp8_sdwa v[230:231], v169 src0_sel:WORD_1
	v_cvt_pk_f32_fp8_e32 v[232:233], v170
	v_cvt_pk_f32_fp8_sdwa v[234:235], v170 src0_sel:WORD_1
	v_cvt_pk_f32_fp8_e32 v[236:237], v171
	v_cvt_pk_f32_fp8_sdwa v[238:239], v171 src0_sel:WORD_1
	v_pk_fma_f32 v[32:33], v[224:225], s[20:21], v[32:33] op_sel_hi:[1,0,1]
	v_pk_fma_f32 v[34:35], v[226:227], s[20:21], v[34:35] op_sel_hi:[1,0,1]
	v_pk_fma_f32 v[36:37], v[228:229], s[20:21], v[36:37] op_sel_hi:[1,0,1]
	v_pk_fma_f32 v[38:39], v[230:231], s[20:21], v[38:39] op_sel_hi:[1,0,1]
	v_pk_fma_f32 v[40:41], v[232:233], s[20:21], v[40:41] op_sel_hi:[1,0,1]
	v_pk_fma_f32 v[42:43], v[234:235], s[20:21], v[42:43] op_sel_hi:[1,0,1]
	v_pk_fma_f32 v[44:45], v[236:237], s[20:21], v[44:45] op_sel_hi:[1,0,1]
	v_pk_fma_f32 v[46:47], v[238:239], s[20:21], v[46:47] op_sel_hi:[1,0,1]
	v_cvt_pk_f32_fp8_e32 v[224:225], v172
	v_cvt_pk_f32_fp8_sdwa v[226:227], v172 src0_sel:WORD_1
	v_cvt_pk_f32_fp8_e32 v[228:229], v173
	v_cvt_pk_f32_fp8_sdwa v[230:231], v173 src0_sel:WORD_1
	v_cvt_pk_f32_fp8_e32 v[232:233], v174
	v_cvt_pk_f32_fp8_sdwa v[234:235], v174 src0_sel:WORD_1
	v_cvt_pk_f32_fp8_e32 v[236:237], v175
	v_cvt_pk_f32_fp8_sdwa v[238:239], v175 src0_sel:WORD_1
	v_pk_fma_f32 v[32:33], v[224:225], s[22:23], v[32:33] op_sel_hi:[1,0,1]
	v_pk_fma_f32 v[34:35], v[226:227], s[22:23], v[34:35] op_sel_hi:[1,0,1]
	v_pk_fma_f32 v[36:37], v[228:229], s[22:23], v[36:37] op_sel_hi:[1,0,1]
	v_pk_fma_f32 v[38:39], v[230:231], s[22:23], v[38:39] op_sel_hi:[1,0,1]
	v_pk_fma_f32 v[40:41], v[232:233], s[22:23], v[40:41] op_sel_hi:[1,0,1]
	v_pk_fma_f32 v[42:43], v[234:235], s[22:23], v[42:43] op_sel_hi:[1,0,1]
	v_pk_fma_f32 v[44:45], v[236:237], s[22:23], v[44:45] op_sel_hi:[1,0,1]
	v_pk_fma_f32 v[46:47], v[238:239], s[22:23], v[46:47] op_sel_hi:[1,0,1]
	v_cvt_pk_f32_fp8_e32 v[224:225], v176
	v_cvt_pk_f32_fp8_sdwa v[226:227], v176 src0_sel:WORD_1
	v_cvt_pk_f32_fp8_e32 v[228:229], v177
	v_cvt_pk_f32_fp8_sdwa v[230:231], v177 src0_sel:WORD_1
	v_cvt_pk_f32_fp8_e32 v[232:233], v178
	v_cvt_pk_f32_fp8_sdwa v[234:235], v178 src0_sel:WORD_1
	v_cvt_pk_f32_fp8_e32 v[236:237], v179
	v_cvt_pk_f32_fp8_sdwa v[238:239], v179 src0_sel:WORD_1
	v_pk_fma_f32 v[32:33], v[224:225], s[24:25], v[32:33] op_sel_hi:[1,0,1]
	v_pk_fma_f32 v[34:35], v[226:227], s[24:25], v[34:35] op_sel_hi:[1,0,1]
	v_pk_fma_f32 v[36:37], v[228:229], s[24:25], v[36:37] op_sel_hi:[1,0,1]
	v_pk_fma_f32 v[38:39], v[230:231], s[24:25], v[38:39] op_sel_hi:[1,0,1]
	v_pk_fma_f32 v[40:41], v[232:233], s[24:25], v[40:41] op_sel_hi:[1,0,1]
	v_pk_fma_f32 v[42:43], v[234:235], s[24:25], v[42:43] op_sel_hi:[1,0,1]
	v_pk_fma_f32 v[44:45], v[236:237], s[24:25], v[44:45] op_sel_hi:[1,0,1]
	v_pk_fma_f32 v[46:47], v[238:239], s[24:25], v[46:47] op_sel_hi:[1,0,1]
	v_cvt_pk_f32_fp8_e32 v[224:225], v180
	v_cvt_pk_f32_fp8_sdwa v[226:227], v180 src0_sel:WORD_1
	v_cvt_pk_f32_fp8_e32 v[228:229], v181
	v_cvt_pk_f32_fp8_sdwa v[230:231], v181 src0_sel:WORD_1
	v_cvt_pk_f32_fp8_e32 v[232:233], v182
	v_cvt_pk_f32_fp8_sdwa v[234:235], v182 src0_sel:WORD_1
	v_cvt_pk_f32_fp8_e32 v[236:237], v183
	v_cvt_pk_f32_fp8_sdwa v[238:239], v183 src0_sel:WORD_1
	v_pk_fma_f32 v[32:33], v[224:225], s[26:27], v[32:33] op_sel_hi:[1,0,1]
	v_pk_fma_f32 v[34:35], v[226:227], s[26:27], v[34:35] op_sel_hi:[1,0,1]
	v_pk_fma_f32 v[36:37], v[228:229], s[26:27], v[36:37] op_sel_hi:[1,0,1]
	v_pk_fma_f32 v[38:39], v[230:231], s[26:27], v[38:39] op_sel_hi:[1,0,1]
	v_pk_fma_f32 v[40:41], v[232:233], s[26:27], v[40:41] op_sel_hi:[1,0,1]
	v_pk_fma_f32 v[42:43], v[234:235], s[26:27], v[42:43] op_sel_hi:[1,0,1]
	v_pk_fma_f32 v[44:45], v[236:237], s[26:27], v[44:45] op_sel_hi:[1,0,1]
	v_pk_fma_f32 v[46:47], v[238:239], s[26:27], v[46:47] op_sel_hi:[1,0,1]
	v_cvt_pk_f32_fp8_e32 v[224:225], v184
	v_cvt_pk_f32_fp8_sdwa v[226:227], v184 src0_sel:WORD_1
	v_cvt_pk_f32_fp8_e32 v[228:229], v185
	v_cvt_pk_f32_fp8_sdwa v[230:231], v185 src0_sel:WORD_1
	v_cvt_pk_f32_fp8_e32 v[232:233], v186
	v_cvt_pk_f32_fp8_sdwa v[234:235], v186 src0_sel:WORD_1
	v_cvt_pk_f32_fp8_e32 v[236:237], v187
	v_cvt_pk_f32_fp8_sdwa v[238:239], v187 src0_sel:WORD_1
	v_pk_fma_f32 v[32:33], v[224:225], s[28:29], v[32:33] op_sel_hi:[1,0,1]
	v_pk_fma_f32 v[34:35], v[226:227], s[28:29], v[34:35] op_sel_hi:[1,0,1]
	v_pk_fma_f32 v[36:37], v[228:229], s[28:29], v[36:37] op_sel_hi:[1,0,1]
	v_pk_fma_f32 v[38:39], v[230:231], s[28:29], v[38:39] op_sel_hi:[1,0,1]
	v_pk_fma_f32 v[40:41], v[232:233], s[28:29], v[40:41] op_sel_hi:[1,0,1]
	v_pk_fma_f32 v[42:43], v[234:235], s[28:29], v[42:43] op_sel_hi:[1,0,1]
	v_pk_fma_f32 v[44:45], v[236:237], s[28:29], v[44:45] op_sel_hi:[1,0,1]
	v_pk_fma_f32 v[46:47], v[238:239], s[28:29], v[46:47] op_sel_hi:[1,0,1]
	v_cvt_pk_f32_fp8_e32 v[224:225], v188
	v_cvt_pk_f32_fp8_sdwa v[226:227], v188 src0_sel:WORD_1
	v_cvt_pk_f32_fp8_e32 v[228:229], v189
	v_cvt_pk_f32_fp8_sdwa v[230:231], v189 src0_sel:WORD_1
	v_cvt_pk_f32_fp8_e32 v[232:233], v190
	v_cvt_pk_f32_fp8_sdwa v[234:235], v190 src0_sel:WORD_1
	v_cvt_pk_f32_fp8_e32 v[236:237], v191
	v_cvt_pk_f32_fp8_sdwa v[238:239], v191 src0_sel:WORD_1
	v_pk_fma_f32 v[32:33], v[224:225], s[30:31], v[32:33] op_sel_hi:[1,0,1]
	v_pk_fma_f32 v[34:35], v[226:227], s[30:31], v[34:35] op_sel_hi:[1,0,1]
	v_pk_fma_f32 v[36:37], v[228:229], s[30:31], v[36:37] op_sel_hi:[1,0,1]
	v_pk_fma_f32 v[38:39], v[230:231], s[30:31], v[38:39] op_sel_hi:[1,0,1]
	v_pk_fma_f32 v[40:41], v[232:233], s[30:31], v[40:41] op_sel_hi:[1,0,1]
	v_pk_fma_f32 v[42:43], v[234:235], s[30:31], v[42:43] op_sel_hi:[1,0,1]
	v_pk_fma_f32 v[44:45], v[236:237], s[30:31], v[44:45] op_sel_hi:[1,0,1]
	v_pk_fma_f32 v[46:47], v[238:239], s[30:31], v[46:47] op_sel_hi:[1,0,1]
	v_readlane_b32 s16, v142, s72
	v_readlane_b32 s18, v142, s73
	v_readlane_b32 s20, v142, s74
	v_readlane_b32 s22, v142, s75
	v_readlane_b32 s24, v142, s76
	v_readlane_b32 s26, v142, s77
	v_readlane_b32 s28, v142, s78
	v_readlane_b32 s30, v142, s79
	v_readlane_b32 s48, v144, s72
	v_readlane_b32 s49, v144, s73
	v_readlane_b32 s50, v144, s74
	v_readlane_b32 s51, v144, s75
	v_readlane_b32 s52, v144, s76
	v_readlane_b32 s53, v144, s77
	v_readlane_b32 s54, v144, s78
	v_readlane_b32 s55, v144, s79
	s_add_u32 s32, s0, s48
	s_addc_u32 s33, s1, 0
	s_add_u32 s34, s0, s49
	s_addc_u32 s35, s1, 0
	s_add_u32 s36, s0, s50
	s_addc_u32 s37, s1, 0
	s_add_u32 s38, s0, s51
	s_addc_u32 s39, s1, 0
	s_add_u32 s40, s0, s52
	s_addc_u32 s41, s1, 0
	s_add_u32 s42, s0, s53
	s_addc_u32 s43, s1, 0
	s_add_u32 s44, s0, s54
	s_addc_u32 s45, s1, 0
	s_add_u32 s46, s0, s55
	s_addc_u32 s47, s1, 0
	global_load_dwordx4 v[160:163], v240, s[32:33]
	global_load_dwordx4 v[164:167], v240, s[34:35]
	global_load_dwordx4 v[168:171], v240, s[36:37]
	global_load_dwordx4 v[172:175], v240, s[38:39]
	global_load_dwordx4 v[176:179], v240, s[40:41]
	global_load_dwordx4 v[180:183], v240, s[42:43]
	global_load_dwordx4 v[184:187], v240, s[44:45]
	global_load_dwordx4 v[188:191], v240, s[46:47]
	s_waitcnt vmcnt(8)
	v_cvt_pk_f32_fp8_e32 v[224:225], v192
	v_cvt_pk_f32_fp8_sdwa v[226:227], v192 src0_sel:WORD_1
	v_cvt_pk_f32_fp8_e32 v[228:229], v193
	v_cvt_pk_f32_fp8_sdwa v[230:231], v193 src0_sel:WORD_1
	v_cvt_pk_f32_fp8_e32 v[232:233], v194
	v_cvt_pk_f32_fp8_sdwa v[234:235], v194 src0_sel:WORD_1
	v_cvt_pk_f32_fp8_e32 v[236:237], v195
	v_cvt_pk_f32_fp8_sdwa v[238:239], v195 src0_sel:WORD_1
	v_pk_fma_f32 v[48:49], v[224:225], s[16:17], v[48:49] op_sel_hi:[1,0,1]
	v_pk_fma_f32 v[50:51], v[226:227], s[16:17], v[50:51] op_sel_hi:[1,0,1]
	v_pk_fma_f32 v[52:53], v[228:229], s[16:17], v[52:53] op_sel_hi:[1,0,1]
	v_pk_fma_f32 v[54:55], v[230:231], s[16:17], v[54:55] op_sel_hi:[1,0,1]
	v_pk_fma_f32 v[56:57], v[232:233], s[16:17], v[56:57] op_sel_hi:[1,0,1]
	v_pk_fma_f32 v[58:59], v[234:235], s[16:17], v[58:59] op_sel_hi:[1,0,1]
	v_pk_fma_f32 v[60:61], v[236:237], s[16:17], v[60:61] op_sel_hi:[1,0,1]
	v_pk_fma_f32 v[62:63], v[238:239], s[16:17], v[62:63] op_sel_hi:[1,0,1]
	v_cvt_pk_f32_fp8_e32 v[224:225], v196
	v_cvt_pk_f32_fp8_sdwa v[226:227], v196 src0_sel:WORD_1
	v_cvt_pk_f32_fp8_e32 v[228:229], v197
	v_cvt_pk_f32_fp8_sdwa v[230:231], v197 src0_sel:WORD_1
	v_cvt_pk_f32_fp8_e32 v[232:233], v198
	v_cvt_pk_f32_fp8_sdwa v[234:235], v198 src0_sel:WORD_1
	v_cvt_pk_f32_fp8_e32 v[236:237], v199
	v_cvt_pk_f32_fp8_sdwa v[238:239], v199 src0_sel:WORD_1
	v_pk_fma_f32 v[48:49], v[224:225], s[18:19], v[48:49] op_sel_hi:[1,0,1]
	v_pk_fma_f32 v[50:51], v[226:227], s[18:19], v[50:51] op_sel_hi:[1,0,1]
	v_pk_fma_f32 v[52:53], v[228:229], s[18:19], v[52:53] op_sel_hi:[1,0,1]
	v_pk_fma_f32 v[54:55], v[230:231], s[18:19], v[54:55] op_sel_hi:[1,0,1]
	v_pk_fma_f32 v[56:57], v[232:233], s[18:19], v[56:57] op_sel_hi:[1,0,1]
	v_pk_fma_f32 v[58:59], v[234:235], s[18:19], v[58:59] op_sel_hi:[1,0,1]
	v_pk_fma_f32 v[60:61], v[236:237], s[18:19], v[60:61] op_sel_hi:[1,0,1]
	v_pk_fma_f32 v[62:63], v[238:239], s[18:19], v[62:63] op_sel_hi:[1,0,1]
	v_cvt_pk_f32_fp8_e32 v[224:225], v200
	v_cvt_pk_f32_fp8_sdwa v[226:227], v200 src0_sel:WORD_1
	v_cvt_pk_f32_fp8_e32 v[228:229], v201
	v_cvt_pk_f32_fp8_sdwa v[230:231], v201 src0_sel:WORD_1
	v_cvt_pk_f32_fp8_e32 v[232:233], v202
	v_cvt_pk_f32_fp8_sdwa v[234:235], v202 src0_sel:WORD_1
	v_cvt_pk_f32_fp8_e32 v[236:237], v203
	v_cvt_pk_f32_fp8_sdwa v[238:239], v203 src0_sel:WORD_1
	v_pk_fma_f32 v[48:49], v[224:225], s[20:21], v[48:49] op_sel_hi:[1,0,1]
	v_pk_fma_f32 v[50:51], v[226:227], s[20:21], v[50:51] op_sel_hi:[1,0,1]
	v_pk_fma_f32 v[52:53], v[228:229], s[20:21], v[52:53] op_sel_hi:[1,0,1]
	v_pk_fma_f32 v[54:55], v[230:231], s[20:21], v[54:55] op_sel_hi:[1,0,1]
	v_pk_fma_f32 v[56:57], v[232:233], s[20:21], v[56:57] op_sel_hi:[1,0,1]
	v_pk_fma_f32 v[58:59], v[234:235], s[20:21], v[58:59] op_sel_hi:[1,0,1]
	v_pk_fma_f32 v[60:61], v[236:237], s[20:21], v[60:61] op_sel_hi:[1,0,1]
	v_pk_fma_f32 v[62:63], v[238:239], s[20:21], v[62:63] op_sel_hi:[1,0,1]
	v_cvt_pk_f32_fp8_e32 v[224:225], v204
	v_cvt_pk_f32_fp8_sdwa v[226:227], v204 src0_sel:WORD_1
	v_cvt_pk_f32_fp8_e32 v[228:229], v205
	v_cvt_pk_f32_fp8_sdwa v[230:231], v205 src0_sel:WORD_1
	v_cvt_pk_f32_fp8_e32 v[232:233], v206
	v_cvt_pk_f32_fp8_sdwa v[234:235], v206 src0_sel:WORD_1
	v_cvt_pk_f32_fp8_e32 v[236:237], v207
	v_cvt_pk_f32_fp8_sdwa v[238:239], v207 src0_sel:WORD_1
	v_pk_fma_f32 v[48:49], v[224:225], s[22:23], v[48:49] op_sel_hi:[1,0,1]
	v_pk_fma_f32 v[50:51], v[226:227], s[22:23], v[50:51] op_sel_hi:[1,0,1]
	v_pk_fma_f32 v[52:53], v[228:229], s[22:23], v[52:53] op_sel_hi:[1,0,1]
	v_pk_fma_f32 v[54:55], v[230:231], s[22:23], v[54:55] op_sel_hi:[1,0,1]
	v_pk_fma_f32 v[56:57], v[232:233], s[22:23], v[56:57] op_sel_hi:[1,0,1]
	v_pk_fma_f32 v[58:59], v[234:235], s[22:23], v[58:59] op_sel_hi:[1,0,1]
	v_pk_fma_f32 v[60:61], v[236:237], s[22:23], v[60:61] op_sel_hi:[1,0,1]
	v_pk_fma_f32 v[62:63], v[238:239], s[22:23], v[62:63] op_sel_hi:[1,0,1]
	v_cvt_pk_f32_fp8_e32 v[224:225], v208
	v_cvt_pk_f32_fp8_sdwa v[226:227], v208 src0_sel:WORD_1
	v_cvt_pk_f32_fp8_e32 v[228:229], v209
	v_cvt_pk_f32_fp8_sdwa v[230:231], v209 src0_sel:WORD_1
	v_cvt_pk_f32_fp8_e32 v[232:233], v210
	v_cvt_pk_f32_fp8_sdwa v[234:235], v210 src0_sel:WORD_1
	v_cvt_pk_f32_fp8_e32 v[236:237], v211
	v_cvt_pk_f32_fp8_sdwa v[238:239], v211 src0_sel:WORD_1
	v_pk_fma_f32 v[48:49], v[224:225], s[24:25], v[48:49] op_sel_hi:[1,0,1]
	v_pk_fma_f32 v[50:51], v[226:227], s[24:25], v[50:51] op_sel_hi:[1,0,1]
	v_pk_fma_f32 v[52:53], v[228:229], s[24:25], v[52:53] op_sel_hi:[1,0,1]
	v_pk_fma_f32 v[54:55], v[230:231], s[24:25], v[54:55] op_sel_hi:[1,0,1]
	v_pk_fma_f32 v[56:57], v[232:233], s[24:25], v[56:57] op_sel_hi:[1,0,1]
	v_pk_fma_f32 v[58:59], v[234:235], s[24:25], v[58:59] op_sel_hi:[1,0,1]
	v_pk_fma_f32 v[60:61], v[236:237], s[24:25], v[60:61] op_sel_hi:[1,0,1]
	v_pk_fma_f32 v[62:63], v[238:239], s[24:25], v[62:63] op_sel_hi:[1,0,1]
	v_cvt_pk_f32_fp8_e32 v[224:225], v212
	v_cvt_pk_f32_fp8_sdwa v[226:227], v212 src0_sel:WORD_1
	v_cvt_pk_f32_fp8_e32 v[228:229], v213
	v_cvt_pk_f32_fp8_sdwa v[230:231], v213 src0_sel:WORD_1
	v_cvt_pk_f32_fp8_e32 v[232:233], v214
	v_cvt_pk_f32_fp8_sdwa v[234:235], v214 src0_sel:WORD_1
	v_cvt_pk_f32_fp8_e32 v[236:237], v215
	v_cvt_pk_f32_fp8_sdwa v[238:239], v215 src0_sel:WORD_1
	v_pk_fma_f32 v[48:49], v[224:225], s[26:27], v[48:49] op_sel_hi:[1,0,1]
	v_pk_fma_f32 v[50:51], v[226:227], s[26:27], v[50:51] op_sel_hi:[1,0,1]
	v_pk_fma_f32 v[52:53], v[228:229], s[26:27], v[52:53] op_sel_hi:[1,0,1]
	v_pk_fma_f32 v[54:55], v[230:231], s[26:27], v[54:55] op_sel_hi:[1,0,1]
	v_pk_fma_f32 v[56:57], v[232:233], s[26:27], v[56:57] op_sel_hi:[1,0,1]
	v_pk_fma_f32 v[58:59], v[234:235], s[26:27], v[58:59] op_sel_hi:[1,0,1]
	v_pk_fma_f32 v[60:61], v[236:237], s[26:27], v[60:61] op_sel_hi:[1,0,1]
	v_pk_fma_f32 v[62:63], v[238:239], s[26:27], v[62:63] op_sel_hi:[1,0,1]
	v_cvt_pk_f32_fp8_e32 v[224:225], v216
	v_cvt_pk_f32_fp8_sdwa v[226:227], v216 src0_sel:WORD_1
	v_cvt_pk_f32_fp8_e32 v[228:229], v217
	v_cvt_pk_f32_fp8_sdwa v[230:231], v217 src0_sel:WORD_1
	v_cvt_pk_f32_fp8_e32 v[232:233], v218
	v_cvt_pk_f32_fp8_sdwa v[234:235], v218 src0_sel:WORD_1
	v_cvt_pk_f32_fp8_e32 v[236:237], v219
	v_cvt_pk_f32_fp8_sdwa v[238:239], v219 src0_sel:WORD_1
	v_pk_fma_f32 v[48:49], v[224:225], s[28:29], v[48:49] op_sel_hi:[1,0,1]
	v_pk_fma_f32 v[50:51], v[226:227], s[28:29], v[50:51] op_sel_hi:[1,0,1]
	v_pk_fma_f32 v[52:53], v[228:229], s[28:29], v[52:53] op_sel_hi:[1,0,1]
	v_pk_fma_f32 v[54:55], v[230:231], s[28:29], v[54:55] op_sel_hi:[1,0,1]
	v_pk_fma_f32 v[56:57], v[232:233], s[28:29], v[56:57] op_sel_hi:[1,0,1]
	v_pk_fma_f32 v[58:59], v[234:235], s[28:29], v[58:59] op_sel_hi:[1,0,1]
	v_pk_fma_f32 v[60:61], v[236:237], s[28:29], v[60:61] op_sel_hi:[1,0,1]
	v_pk_fma_f32 v[62:63], v[238:239], s[28:29], v[62:63] op_sel_hi:[1,0,1]
	v_cvt_pk_f32_fp8_e32 v[224:225], v220
	v_cvt_pk_f32_fp8_sdwa v[226:227], v220 src0_sel:WORD_1
	v_cvt_pk_f32_fp8_e32 v[228:229], v221
	v_cvt_pk_f32_fp8_sdwa v[230:231], v221 src0_sel:WORD_1
	v_cvt_pk_f32_fp8_e32 v[232:233], v222
	v_cvt_pk_f32_fp8_sdwa v[234:235], v222 src0_sel:WORD_1
	v_cvt_pk_f32_fp8_e32 v[236:237], v223
	v_cvt_pk_f32_fp8_sdwa v[238:239], v223 src0_sel:WORD_1
	v_pk_fma_f32 v[48:49], v[224:225], s[30:31], v[48:49] op_sel_hi:[1,0,1]
	v_pk_fma_f32 v[50:51], v[226:227], s[30:31], v[50:51] op_sel_hi:[1,0,1]
	v_pk_fma_f32 v[52:53], v[228:229], s[30:31], v[52:53] op_sel_hi:[1,0,1]
	v_pk_fma_f32 v[54:55], v[230:231], s[30:31], v[54:55] op_sel_hi:[1,0,1]
	v_pk_fma_f32 v[56:57], v[232:233], s[30:31], v[56:57] op_sel_hi:[1,0,1]
	v_pk_fma_f32 v[58:59], v[234:235], s[30:31], v[58:59] op_sel_hi:[1,0,1]
	v_pk_fma_f32 v[60:61], v[236:237], s[30:31], v[60:61] op_sel_hi:[1,0,1]
	v_pk_fma_f32 v[62:63], v[238:239], s[30:31], v[62:63] op_sel_hi:[1,0,1]
	v_readlane_b32 s16, v146, s72
	v_readlane_b32 s18, v146, s73
	v_readlane_b32 s20, v146, s74
	v_readlane_b32 s22, v146, s75
	v_readlane_b32 s24, v146, s76
	v_readlane_b32 s26, v146, s77
	v_readlane_b32 s28, v146, s78
	v_readlane_b32 s30, v146, s79
	v_readlane_b32 s48, v148, s72
	v_readlane_b32 s49, v148, s73
	v_readlane_b32 s50, v148, s74
	v_readlane_b32 s51, v148, s75
	v_readlane_b32 s52, v148, s76
	v_readlane_b32 s53, v148, s77
	v_readlane_b32 s54, v148, s78
	v_readlane_b32 s55, v148, s79
	s_add_u32 s32, s0, s48
	s_addc_u32 s33, s1, 0
	s_add_u32 s34, s0, s49
	s_addc_u32 s35, s1, 0
	s_add_u32 s36, s0, s50
	s_addc_u32 s37, s1, 0
	s_add_u32 s38, s0, s51
	s_addc_u32 s39, s1, 0
	s_add_u32 s40, s0, s52
	s_addc_u32 s41, s1, 0
	s_add_u32 s42, s0, s53
	s_addc_u32 s43, s1, 0
	s_add_u32 s44, s0, s54
	s_addc_u32 s45, s1, 0
	s_add_u32 s46, s0, s55
	s_addc_u32 s47, s1, 0
	global_load_dwordx4 v[192:195], v240, s[32:33]
	global_load_dwordx4 v[196:199], v240, s[34:35]
	global_load_dwordx4 v[200:203], v240, s[36:37]
	global_load_dwordx4 v[204:207], v240, s[38:39]
	global_load_dwordx4 v[208:211], v240, s[40:41]
	global_load_dwordx4 v[212:215], v240, s[42:43]
	global_load_dwordx4 v[216:219], v240, s[44:45]
	global_load_dwordx4 v[220:223], v240, s[46:47]
	s_waitcnt vmcnt(8)
	v_cvt_pk_f32_fp8_e32 v[224:225], v160
	v_cvt_pk_f32_fp8_sdwa v[226:227], v160 src0_sel:WORD_1
	v_cvt_pk_f32_fp8_e32 v[228:229], v161
	v_cvt_pk_f32_fp8_sdwa v[230:231], v161 src0_sel:WORD_1
	v_cvt_pk_f32_fp8_e32 v[232:233], v162
	v_cvt_pk_f32_fp8_sdwa v[234:235], v162 src0_sel:WORD_1
	v_cvt_pk_f32_fp8_e32 v[236:237], v163
	v_cvt_pk_f32_fp8_sdwa v[238:239], v163 src0_sel:WORD_1
	v_pk_fma_f32 v[64:65], v[224:225], s[16:17], v[64:65] op_sel_hi:[1,0,1]
	v_pk_fma_f32 v[66:67], v[226:227], s[16:17], v[66:67] op_sel_hi:[1,0,1]
	v_pk_fma_f32 v[68:69], v[228:229], s[16:17], v[68:69] op_sel_hi:[1,0,1]
	v_pk_fma_f32 v[70:71], v[230:231], s[16:17], v[70:71] op_sel_hi:[1,0,1]
	v_pk_fma_f32 v[72:73], v[232:233], s[16:17], v[72:73] op_sel_hi:[1,0,1]
	v_pk_fma_f32 v[74:75], v[234:235], s[16:17], v[74:75] op_sel_hi:[1,0,1]
	v_pk_fma_f32 v[76:77], v[236:237], s[16:17], v[76:77] op_sel_hi:[1,0,1]
	v_pk_fma_f32 v[78:79], v[238:239], s[16:17], v[78:79] op_sel_hi:[1,0,1]
	v_cvt_pk_f32_fp8_e32 v[224:225], v164
	v_cvt_pk_f32_fp8_sdwa v[226:227], v164 src0_sel:WORD_1
	v_cvt_pk_f32_fp8_e32 v[228:229], v165
	v_cvt_pk_f32_fp8_sdwa v[230:231], v165 src0_sel:WORD_1
	v_cvt_pk_f32_fp8_e32 v[232:233], v166
	v_cvt_pk_f32_fp8_sdwa v[234:235], v166 src0_sel:WORD_1
	v_cvt_pk_f32_fp8_e32 v[236:237], v167
	v_cvt_pk_f32_fp8_sdwa v[238:239], v167 src0_sel:WORD_1
	v_pk_fma_f32 v[64:65], v[224:225], s[18:19], v[64:65] op_sel_hi:[1,0,1]
	v_pk_fma_f32 v[66:67], v[226:227], s[18:19], v[66:67] op_sel_hi:[1,0,1]
	v_pk_fma_f32 v[68:69], v[228:229], s[18:19], v[68:69] op_sel_hi:[1,0,1]
	v_pk_fma_f32 v[70:71], v[230:231], s[18:19], v[70:71] op_sel_hi:[1,0,1]
	v_pk_fma_f32 v[72:73], v[232:233], s[18:19], v[72:73] op_sel_hi:[1,0,1]
	v_pk_fma_f32 v[74:75], v[234:235], s[18:19], v[74:75] op_sel_hi:[1,0,1]
	v_pk_fma_f32 v[76:77], v[236:237], s[18:19], v[76:77] op_sel_hi:[1,0,1]
	v_pk_fma_f32 v[78:79], v[238:239], s[18:19], v[78:79] op_sel_hi:[1,0,1]
	v_cvt_pk_f32_fp8_e32 v[224:225], v168
	v_cvt_pk_f32_fp8_sdwa v[226:227], v168 src0_sel:WORD_1
	v_cvt_pk_f32_fp8_e32 v[228:229], v169
	v_cvt_pk_f32_fp8_sdwa v[230:231], v169 src0_sel:WORD_1
	v_cvt_pk_f32_fp8_e32 v[232:233], v170
	v_cvt_pk_f32_fp8_sdwa v[234:235], v170 src0_sel:WORD_1
	v_cvt_pk_f32_fp8_e32 v[236:237], v171
	v_cvt_pk_f32_fp8_sdwa v[238:239], v171 src0_sel:WORD_1
	v_pk_fma_f32 v[64:65], v[224:225], s[20:21], v[64:65] op_sel_hi:[1,0,1]
	v_pk_fma_f32 v[66:67], v[226:227], s[20:21], v[66:67] op_sel_hi:[1,0,1]
	v_pk_fma_f32 v[68:69], v[228:229], s[20:21], v[68:69] op_sel_hi:[1,0,1]
	v_pk_fma_f32 v[70:71], v[230:231], s[20:21], v[70:71] op_sel_hi:[1,0,1]
	v_pk_fma_f32 v[72:73], v[232:233], s[20:21], v[72:73] op_sel_hi:[1,0,1]
	v_pk_fma_f32 v[74:75], v[234:235], s[20:21], v[74:75] op_sel_hi:[1,0,1]
	v_pk_fma_f32 v[76:77], v[236:237], s[20:21], v[76:77] op_sel_hi:[1,0,1]
	v_pk_fma_f32 v[78:79], v[238:239], s[20:21], v[78:79] op_sel_hi:[1,0,1]
	v_cvt_pk_f32_fp8_e32 v[224:225], v172
	v_cvt_pk_f32_fp8_sdwa v[226:227], v172 src0_sel:WORD_1
	v_cvt_pk_f32_fp8_e32 v[228:229], v173
	v_cvt_pk_f32_fp8_sdwa v[230:231], v173 src0_sel:WORD_1
	v_cvt_pk_f32_fp8_e32 v[232:233], v174
	v_cvt_pk_f32_fp8_sdwa v[234:235], v174 src0_sel:WORD_1
	v_cvt_pk_f32_fp8_e32 v[236:237], v175
	v_cvt_pk_f32_fp8_sdwa v[238:239], v175 src0_sel:WORD_1
	v_pk_fma_f32 v[64:65], v[224:225], s[22:23], v[64:65] op_sel_hi:[1,0,1]
	v_pk_fma_f32 v[66:67], v[226:227], s[22:23], v[66:67] op_sel_hi:[1,0,1]
	v_pk_fma_f32 v[68:69], v[228:229], s[22:23], v[68:69] op_sel_hi:[1,0,1]
	v_pk_fma_f32 v[70:71], v[230:231], s[22:23], v[70:71] op_sel_hi:[1,0,1]
	v_pk_fma_f32 v[72:73], v[232:233], s[22:23], v[72:73] op_sel_hi:[1,0,1]
	v_pk_fma_f32 v[74:75], v[234:235], s[22:23], v[74:75] op_sel_hi:[1,0,1]
	v_pk_fma_f32 v[76:77], v[236:237], s[22:23], v[76:77] op_sel_hi:[1,0,1]
	v_pk_fma_f32 v[78:79], v[238:239], s[22:23], v[78:79] op_sel_hi:[1,0,1]
	v_cvt_pk_f32_fp8_e32 v[224:225], v176
	v_cvt_pk_f32_fp8_sdwa v[226:227], v176 src0_sel:WORD_1
	v_cvt_pk_f32_fp8_e32 v[228:229], v177
	v_cvt_pk_f32_fp8_sdwa v[230:231], v177 src0_sel:WORD_1
	v_cvt_pk_f32_fp8_e32 v[232:233], v178
	v_cvt_pk_f32_fp8_sdwa v[234:235], v178 src0_sel:WORD_1
	v_cvt_pk_f32_fp8_e32 v[236:237], v179
	v_cvt_pk_f32_fp8_sdwa v[238:239], v179 src0_sel:WORD_1
	v_pk_fma_f32 v[64:65], v[224:225], s[24:25], v[64:65] op_sel_hi:[1,0,1]
	v_pk_fma_f32 v[66:67], v[226:227], s[24:25], v[66:67] op_sel_hi:[1,0,1]
	v_pk_fma_f32 v[68:69], v[228:229], s[24:25], v[68:69] op_sel_hi:[1,0,1]
	v_pk_fma_f32 v[70:71], v[230:231], s[24:25], v[70:71] op_sel_hi:[1,0,1]
	v_pk_fma_f32 v[72:73], v[232:233], s[24:25], v[72:73] op_sel_hi:[1,0,1]
	v_pk_fma_f32 v[74:75], v[234:235], s[24:25], v[74:75] op_sel_hi:[1,0,1]
	v_pk_fma_f32 v[76:77], v[236:237], s[24:25], v[76:77] op_sel_hi:[1,0,1]
	v_pk_fma_f32 v[78:79], v[238:239], s[24:25], v[78:79] op_sel_hi:[1,0,1]
	v_cvt_pk_f32_fp8_e32 v[224:225], v180
	v_cvt_pk_f32_fp8_sdwa v[226:227], v180 src0_sel:WORD_1
	v_cvt_pk_f32_fp8_e32 v[228:229], v181
	v_cvt_pk_f32_fp8_sdwa v[230:231], v181 src0_sel:WORD_1
	v_cvt_pk_f32_fp8_e32 v[232:233], v182
	v_cvt_pk_f32_fp8_sdwa v[234:235], v182 src0_sel:WORD_1
	v_cvt_pk_f32_fp8_e32 v[236:237], v183
	v_cvt_pk_f32_fp8_sdwa v[238:239], v183 src0_sel:WORD_1
	v_pk_fma_f32 v[64:65], v[224:225], s[26:27], v[64:65] op_sel_hi:[1,0,1]
	v_pk_fma_f32 v[66:67], v[226:227], s[26:27], v[66:67] op_sel_hi:[1,0,1]
	v_pk_fma_f32 v[68:69], v[228:229], s[26:27], v[68:69] op_sel_hi:[1,0,1]
	v_pk_fma_f32 v[70:71], v[230:231], s[26:27], v[70:71] op_sel_hi:[1,0,1]
	v_pk_fma_f32 v[72:73], v[232:233], s[26:27], v[72:73] op_sel_hi:[1,0,1]
	v_pk_fma_f32 v[74:75], v[234:235], s[26:27], v[74:75] op_sel_hi:[1,0,1]
	v_pk_fma_f32 v[76:77], v[236:237], s[26:27], v[76:77] op_sel_hi:[1,0,1]
	v_pk_fma_f32 v[78:79], v[238:239], s[26:27], v[78:79] op_sel_hi:[1,0,1]
	v_cvt_pk_f32_fp8_e32 v[224:225], v184
	v_cvt_pk_f32_fp8_sdwa v[226:227], v184 src0_sel:WORD_1
	v_cvt_pk_f32_fp8_e32 v[228:229], v185
	v_cvt_pk_f32_fp8_sdwa v[230:231], v185 src0_sel:WORD_1
	v_cvt_pk_f32_fp8_e32 v[232:233], v186
	v_cvt_pk_f32_fp8_sdwa v[234:235], v186 src0_sel:WORD_1
	v_cvt_pk_f32_fp8_e32 v[236:237], v187
	v_cvt_pk_f32_fp8_sdwa v[238:239], v187 src0_sel:WORD_1
	v_pk_fma_f32 v[64:65], v[224:225], s[28:29], v[64:65] op_sel_hi:[1,0,1]
	v_pk_fma_f32 v[66:67], v[226:227], s[28:29], v[66:67] op_sel_hi:[1,0,1]
	v_pk_fma_f32 v[68:69], v[228:229], s[28:29], v[68:69] op_sel_hi:[1,0,1]
	v_pk_fma_f32 v[70:71], v[230:231], s[28:29], v[70:71] op_sel_hi:[1,0,1]
	v_pk_fma_f32 v[72:73], v[232:233], s[28:29], v[72:73] op_sel_hi:[1,0,1]
	v_pk_fma_f32 v[74:75], v[234:235], s[28:29], v[74:75] op_sel_hi:[1,0,1]
	v_pk_fma_f32 v[76:77], v[236:237], s[28:29], v[76:77] op_sel_hi:[1,0,1]
	v_pk_fma_f32 v[78:79], v[238:239], s[28:29], v[78:79] op_sel_hi:[1,0,1]
	v_cvt_pk_f32_fp8_e32 v[224:225], v188
	v_cvt_pk_f32_fp8_sdwa v[226:227], v188 src0_sel:WORD_1
	v_cvt_pk_f32_fp8_e32 v[228:229], v189
	v_cvt_pk_f32_fp8_sdwa v[230:231], v189 src0_sel:WORD_1
	v_cvt_pk_f32_fp8_e32 v[232:233], v190
	v_cvt_pk_f32_fp8_sdwa v[234:235], v190 src0_sel:WORD_1
	v_cvt_pk_f32_fp8_e32 v[236:237], v191
	v_cvt_pk_f32_fp8_sdwa v[238:239], v191 src0_sel:WORD_1
	v_pk_fma_f32 v[64:65], v[224:225], s[30:31], v[64:65] op_sel_hi:[1,0,1]
	v_pk_fma_f32 v[66:67], v[226:227], s[30:31], v[66:67] op_sel_hi:[1,0,1]
	v_pk_fma_f32 v[68:69], v[228:229], s[30:31], v[68:69] op_sel_hi:[1,0,1]
	v_pk_fma_f32 v[70:71], v[230:231], s[30:31], v[70:71] op_sel_hi:[1,0,1]
	v_pk_fma_f32 v[72:73], v[232:233], s[30:31], v[72:73] op_sel_hi:[1,0,1]
	v_pk_fma_f32 v[74:75], v[234:235], s[30:31], v[74:75] op_sel_hi:[1,0,1]
	v_pk_fma_f32 v[76:77], v[236:237], s[30:31], v[76:77] op_sel_hi:[1,0,1]
	v_pk_fma_f32 v[78:79], v[238:239], s[30:31], v[78:79] op_sel_hi:[1,0,1]
	v_readlane_b32 s16, v150, s72
	v_readlane_b32 s18, v150, s73
	v_readlane_b32 s20, v150, s74
	v_readlane_b32 s22, v150, s75
	v_readlane_b32 s24, v150, s76
	v_readlane_b32 s26, v150, s77
	v_readlane_b32 s28, v150, s78
	v_readlane_b32 s30, v150, s79
	v_readlane_b32 s48, v152, s72
	v_readlane_b32 s49, v152, s73
	v_readlane_b32 s50, v152, s74
	v_readlane_b32 s51, v152, s75
	v_readlane_b32 s52, v152, s76
	v_readlane_b32 s53, v152, s77
	v_readlane_b32 s54, v152, s78
	v_readlane_b32 s55, v152, s79
	s_add_u32 s32, s0, s48
	s_addc_u32 s33, s1, 0
	s_add_u32 s34, s0, s49
	s_addc_u32 s35, s1, 0
	s_add_u32 s36, s0, s50
	s_addc_u32 s37, s1, 0
	s_add_u32 s38, s0, s51
	s_addc_u32 s39, s1, 0
	s_add_u32 s40, s0, s52
	s_addc_u32 s41, s1, 0
	s_add_u32 s42, s0, s53
	s_addc_u32 s43, s1, 0
	s_add_u32 s44, s0, s54
	s_addc_u32 s45, s1, 0
	s_add_u32 s46, s0, s55
	s_addc_u32 s47, s1, 0
	global_load_dwordx4 v[160:163], v240, s[32:33]
	global_load_dwordx4 v[164:167], v240, s[34:35]
	global_load_dwordx4 v[168:171], v240, s[36:37]
	global_load_dwordx4 v[172:175], v240, s[38:39]
	global_load_dwordx4 v[176:179], v240, s[40:41]
	global_load_dwordx4 v[180:183], v240, s[42:43]
	global_load_dwordx4 v[184:187], v240, s[44:45]
	global_load_dwordx4 v[188:191], v240, s[46:47]
	s_waitcnt vmcnt(8)
	v_cvt_pk_f32_fp8_e32 v[224:225], v192
	v_cvt_pk_f32_fp8_sdwa v[226:227], v192 src0_sel:WORD_1
	v_cvt_pk_f32_fp8_e32 v[228:229], v193
	v_cvt_pk_f32_fp8_sdwa v[230:231], v193 src0_sel:WORD_1
	v_cvt_pk_f32_fp8_e32 v[232:233], v194
	v_cvt_pk_f32_fp8_sdwa v[234:235], v194 src0_sel:WORD_1
	v_cvt_pk_f32_fp8_e32 v[236:237], v195
	v_cvt_pk_f32_fp8_sdwa v[238:239], v195 src0_sel:WORD_1
	v_pk_fma_f32 v[80:81], v[224:225], s[16:17], v[80:81] op_sel_hi:[1,0,1]
	v_pk_fma_f32 v[82:83], v[226:227], s[16:17], v[82:83] op_sel_hi:[1,0,1]
	v_pk_fma_f32 v[84:85], v[228:229], s[16:17], v[84:85] op_sel_hi:[1,0,1]
	v_pk_fma_f32 v[86:87], v[230:231], s[16:17], v[86:87] op_sel_hi:[1,0,1]
	v_pk_fma_f32 v[88:89], v[232:233], s[16:17], v[88:89] op_sel_hi:[1,0,1]
	v_pk_fma_f32 v[90:91], v[234:235], s[16:17], v[90:91] op_sel_hi:[1,0,1]
	v_pk_fma_f32 v[92:93], v[236:237], s[16:17], v[92:93] op_sel_hi:[1,0,1]
	v_pk_fma_f32 v[94:95], v[238:239], s[16:17], v[94:95] op_sel_hi:[1,0,1]
	v_cvt_pk_f32_fp8_e32 v[224:225], v196
	v_cvt_pk_f32_fp8_sdwa v[226:227], v196 src0_sel:WORD_1
	v_cvt_pk_f32_fp8_e32 v[228:229], v197
	v_cvt_pk_f32_fp8_sdwa v[230:231], v197 src0_sel:WORD_1
	v_cvt_pk_f32_fp8_e32 v[232:233], v198
	v_cvt_pk_f32_fp8_sdwa v[234:235], v198 src0_sel:WORD_1
	v_cvt_pk_f32_fp8_e32 v[236:237], v199
	v_cvt_pk_f32_fp8_sdwa v[238:239], v199 src0_sel:WORD_1
	v_pk_fma_f32 v[80:81], v[224:225], s[18:19], v[80:81] op_sel_hi:[1,0,1]
	v_pk_fma_f32 v[82:83], v[226:227], s[18:19], v[82:83] op_sel_hi:[1,0,1]
	v_pk_fma_f32 v[84:85], v[228:229], s[18:19], v[84:85] op_sel_hi:[1,0,1]
	v_pk_fma_f32 v[86:87], v[230:231], s[18:19], v[86:87] op_sel_hi:[1,0,1]
	v_pk_fma_f32 v[88:89], v[232:233], s[18:19], v[88:89] op_sel_hi:[1,0,1]
	v_pk_fma_f32 v[90:91], v[234:235], s[18:19], v[90:91] op_sel_hi:[1,0,1]
	v_pk_fma_f32 v[92:93], v[236:237], s[18:19], v[92:93] op_sel_hi:[1,0,1]
	v_pk_fma_f32 v[94:95], v[238:239], s[18:19], v[94:95] op_sel_hi:[1,0,1]
	v_cvt_pk_f32_fp8_e32 v[224:225], v200
	v_cvt_pk_f32_fp8_sdwa v[226:227], v200 src0_sel:WORD_1
	v_cvt_pk_f32_fp8_e32 v[228:229], v201
	v_cvt_pk_f32_fp8_sdwa v[230:231], v201 src0_sel:WORD_1
	v_cvt_pk_f32_fp8_e32 v[232:233], v202
	v_cvt_pk_f32_fp8_sdwa v[234:235], v202 src0_sel:WORD_1
	v_cvt_pk_f32_fp8_e32 v[236:237], v203
	v_cvt_pk_f32_fp8_sdwa v[238:239], v203 src0_sel:WORD_1
	v_pk_fma_f32 v[80:81], v[224:225], s[20:21], v[80:81] op_sel_hi:[1,0,1]
	v_pk_fma_f32 v[82:83], v[226:227], s[20:21], v[82:83] op_sel_hi:[1,0,1]
	v_pk_fma_f32 v[84:85], v[228:229], s[20:21], v[84:85] op_sel_hi:[1,0,1]
	v_pk_fma_f32 v[86:87], v[230:231], s[20:21], v[86:87] op_sel_hi:[1,0,1]
	v_pk_fma_f32 v[88:89], v[232:233], s[20:21], v[88:89] op_sel_hi:[1,0,1]
	v_pk_fma_f32 v[90:91], v[234:235], s[20:21], v[90:91] op_sel_hi:[1,0,1]
	v_pk_fma_f32 v[92:93], v[236:237], s[20:21], v[92:93] op_sel_hi:[1,0,1]
	v_pk_fma_f32 v[94:95], v[238:239], s[20:21], v[94:95] op_sel_hi:[1,0,1]
	v_cvt_pk_f32_fp8_e32 v[224:225], v204
	v_cvt_pk_f32_fp8_sdwa v[226:227], v204 src0_sel:WORD_1
	v_cvt_pk_f32_fp8_e32 v[228:229], v205
	v_cvt_pk_f32_fp8_sdwa v[230:231], v205 src0_sel:WORD_1
	v_cvt_pk_f32_fp8_e32 v[232:233], v206
	v_cvt_pk_f32_fp8_sdwa v[234:235], v206 src0_sel:WORD_1
	v_cvt_pk_f32_fp8_e32 v[236:237], v207
	v_cvt_pk_f32_fp8_sdwa v[238:239], v207 src0_sel:WORD_1
	v_pk_fma_f32 v[80:81], v[224:225], s[22:23], v[80:81] op_sel_hi:[1,0,1]
	v_pk_fma_f32 v[82:83], v[226:227], s[22:23], v[82:83] op_sel_hi:[1,0,1]
	v_pk_fma_f32 v[84:85], v[228:229], s[22:23], v[84:85] op_sel_hi:[1,0,1]
	v_pk_fma_f32 v[86:87], v[230:231], s[22:23], v[86:87] op_sel_hi:[1,0,1]
	v_pk_fma_f32 v[88:89], v[232:233], s[22:23], v[88:89] op_sel_hi:[1,0,1]
	v_pk_fma_f32 v[90:91], v[234:235], s[22:23], v[90:91] op_sel_hi:[1,0,1]
	v_pk_fma_f32 v[92:93], v[236:237], s[22:23], v[92:93] op_sel_hi:[1,0,1]
	v_pk_fma_f32 v[94:95], v[238:239], s[22:23], v[94:95] op_sel_hi:[1,0,1]
	v_cvt_pk_f32_fp8_e32 v[224:225], v208
	v_cvt_pk_f32_fp8_sdwa v[226:227], v208 src0_sel:WORD_1
	v_cvt_pk_f32_fp8_e32 v[228:229], v209
	v_cvt_pk_f32_fp8_sdwa v[230:231], v209 src0_sel:WORD_1
	v_cvt_pk_f32_fp8_e32 v[232:233], v210
	v_cvt_pk_f32_fp8_sdwa v[234:235], v210 src0_sel:WORD_1
	v_cvt_pk_f32_fp8_e32 v[236:237], v211
	v_cvt_pk_f32_fp8_sdwa v[238:239], v211 src0_sel:WORD_1
	v_pk_fma_f32 v[80:81], v[224:225], s[24:25], v[80:81] op_sel_hi:[1,0,1]
	v_pk_fma_f32 v[82:83], v[226:227], s[24:25], v[82:83] op_sel_hi:[1,0,1]
	v_pk_fma_f32 v[84:85], v[228:229], s[24:25], v[84:85] op_sel_hi:[1,0,1]
	v_pk_fma_f32 v[86:87], v[230:231], s[24:25], v[86:87] op_sel_hi:[1,0,1]
	v_pk_fma_f32 v[88:89], v[232:233], s[24:25], v[88:89] op_sel_hi:[1,0,1]
	v_pk_fma_f32 v[90:91], v[234:235], s[24:25], v[90:91] op_sel_hi:[1,0,1]
	v_pk_fma_f32 v[92:93], v[236:237], s[24:25], v[92:93] op_sel_hi:[1,0,1]
	v_pk_fma_f32 v[94:95], v[238:239], s[24:25], v[94:95] op_sel_hi:[1,0,1]
	v_cvt_pk_f32_fp8_e32 v[224:225], v212
	v_cvt_pk_f32_fp8_sdwa v[226:227], v212 src0_sel:WORD_1
	v_cvt_pk_f32_fp8_e32 v[228:229], v213
	v_cvt_pk_f32_fp8_sdwa v[230:231], v213 src0_sel:WORD_1
	v_cvt_pk_f32_fp8_e32 v[232:233], v214
	v_cvt_pk_f32_fp8_sdwa v[234:235], v214 src0_sel:WORD_1
	v_cvt_pk_f32_fp8_e32 v[236:237], v215
	v_cvt_pk_f32_fp8_sdwa v[238:239], v215 src0_sel:WORD_1
	v_pk_fma_f32 v[80:81], v[224:225], s[26:27], v[80:81] op_sel_hi:[1,0,1]
	v_pk_fma_f32 v[82:83], v[226:227], s[26:27], v[82:83] op_sel_hi:[1,0,1]
	v_pk_fma_f32 v[84:85], v[228:229], s[26:27], v[84:85] op_sel_hi:[1,0,1]
	v_pk_fma_f32 v[86:87], v[230:231], s[26:27], v[86:87] op_sel_hi:[1,0,1]
	v_pk_fma_f32 v[88:89], v[232:233], s[26:27], v[88:89] op_sel_hi:[1,0,1]
	v_pk_fma_f32 v[90:91], v[234:235], s[26:27], v[90:91] op_sel_hi:[1,0,1]
	v_pk_fma_f32 v[92:93], v[236:237], s[26:27], v[92:93] op_sel_hi:[1,0,1]
	v_pk_fma_f32 v[94:95], v[238:239], s[26:27], v[94:95] op_sel_hi:[1,0,1]
	v_cvt_pk_f32_fp8_e32 v[224:225], v216
	v_cvt_pk_f32_fp8_sdwa v[226:227], v216 src0_sel:WORD_1
	v_cvt_pk_f32_fp8_e32 v[228:229], v217
	v_cvt_pk_f32_fp8_sdwa v[230:231], v217 src0_sel:WORD_1
	v_cvt_pk_f32_fp8_e32 v[232:233], v218
	v_cvt_pk_f32_fp8_sdwa v[234:235], v218 src0_sel:WORD_1
	v_cvt_pk_f32_fp8_e32 v[236:237], v219
	v_cvt_pk_f32_fp8_sdwa v[238:239], v219 src0_sel:WORD_1
	v_pk_fma_f32 v[80:81], v[224:225], s[28:29], v[80:81] op_sel_hi:[1,0,1]
	v_pk_fma_f32 v[82:83], v[226:227], s[28:29], v[82:83] op_sel_hi:[1,0,1]
	v_pk_fma_f32 v[84:85], v[228:229], s[28:29], v[84:85] op_sel_hi:[1,0,1]
	v_pk_fma_f32 v[86:87], v[230:231], s[28:29], v[86:87] op_sel_hi:[1,0,1]
	v_pk_fma_f32 v[88:89], v[232:233], s[28:29], v[88:89] op_sel_hi:[1,0,1]
	v_pk_fma_f32 v[90:91], v[234:235], s[28:29], v[90:91] op_sel_hi:[1,0,1]
	v_pk_fma_f32 v[92:93], v[236:237], s[28:29], v[92:93] op_sel_hi:[1,0,1]
	v_pk_fma_f32 v[94:95], v[238:239], s[28:29], v[94:95] op_sel_hi:[1,0,1]
	v_cvt_pk_f32_fp8_e32 v[224:225], v220
	v_cvt_pk_f32_fp8_sdwa v[226:227], v220 src0_sel:WORD_1
	v_cvt_pk_f32_fp8_e32 v[228:229], v221
	v_cvt_pk_f32_fp8_sdwa v[230:231], v221 src0_sel:WORD_1
	v_cvt_pk_f32_fp8_e32 v[232:233], v222
	v_cvt_pk_f32_fp8_sdwa v[234:235], v222 src0_sel:WORD_1
	v_cvt_pk_f32_fp8_e32 v[236:237], v223
	v_cvt_pk_f32_fp8_sdwa v[238:239], v223 src0_sel:WORD_1
	v_pk_fma_f32 v[80:81], v[224:225], s[30:31], v[80:81] op_sel_hi:[1,0,1]
	v_pk_fma_f32 v[82:83], v[226:227], s[30:31], v[82:83] op_sel_hi:[1,0,1]
	v_pk_fma_f32 v[84:85], v[228:229], s[30:31], v[84:85] op_sel_hi:[1,0,1]
	v_pk_fma_f32 v[86:87], v[230:231], s[30:31], v[86:87] op_sel_hi:[1,0,1]
	v_pk_fma_f32 v[88:89], v[232:233], s[30:31], v[88:89] op_sel_hi:[1,0,1]
	v_pk_fma_f32 v[90:91], v[234:235], s[30:31], v[90:91] op_sel_hi:[1,0,1]
	v_pk_fma_f32 v[92:93], v[236:237], s[30:31], v[92:93] op_sel_hi:[1,0,1]
	v_pk_fma_f32 v[94:95], v[238:239], s[30:31], v[94:95] op_sel_hi:[1,0,1]
	v_readlane_b32 s16, v154, s72
	v_readlane_b32 s18, v154, s73
	v_readlane_b32 s20, v154, s74
	v_readlane_b32 s22, v154, s75
	v_readlane_b32 s24, v154, s76
	v_readlane_b32 s26, v154, s77
	v_readlane_b32 s28, v154, s78
	v_readlane_b32 s30, v154, s79
	v_readlane_b32 s48, v156, s72
	v_readlane_b32 s49, v156, s73
	v_readlane_b32 s50, v156, s74
	v_readlane_b32 s51, v156, s75
	v_readlane_b32 s52, v156, s76
	v_readlane_b32 s53, v156, s77
	v_readlane_b32 s54, v156, s78
	v_readlane_b32 s55, v156, s79
	s_add_u32 s32, s0, s48
	s_addc_u32 s33, s1, 0
	s_add_u32 s34, s0, s49
	s_addc_u32 s35, s1, 0
	s_add_u32 s36, s0, s50
	s_addc_u32 s37, s1, 0
	s_add_u32 s38, s0, s51
	s_addc_u32 s39, s1, 0
	s_add_u32 s40, s0, s52
	s_addc_u32 s41, s1, 0
	s_add_u32 s42, s0, s53
	s_addc_u32 s43, s1, 0
	s_add_u32 s44, s0, s54
	s_addc_u32 s45, s1, 0
	s_add_u32 s46, s0, s55
	s_addc_u32 s47, s1, 0
	global_load_dwordx4 v[192:195], v240, s[32:33]
	global_load_dwordx4 v[196:199], v240, s[34:35]
	global_load_dwordx4 v[200:203], v240, s[36:37]
	global_load_dwordx4 v[204:207], v240, s[38:39]
	global_load_dwordx4 v[208:211], v240, s[40:41]
	global_load_dwordx4 v[212:215], v240, s[42:43]
	global_load_dwordx4 v[216:219], v240, s[44:45]
	global_load_dwordx4 v[220:223], v240, s[46:47]
	s_waitcnt vmcnt(8)
	v_cvt_pk_f32_fp8_e32 v[224:225], v160
	v_cvt_pk_f32_fp8_sdwa v[226:227], v160 src0_sel:WORD_1
	v_cvt_pk_f32_fp8_e32 v[228:229], v161
	v_cvt_pk_f32_fp8_sdwa v[230:231], v161 src0_sel:WORD_1
	v_cvt_pk_f32_fp8_e32 v[232:233], v162
	v_cvt_pk_f32_fp8_sdwa v[234:235], v162 src0_sel:WORD_1
	v_cvt_pk_f32_fp8_e32 v[236:237], v163
	v_cvt_pk_f32_fp8_sdwa v[238:239], v163 src0_sel:WORD_1
	v_pk_fma_f32 v[96:97], v[224:225], s[16:17], v[96:97] op_sel_hi:[1,0,1]
	v_pk_fma_f32 v[98:99], v[226:227], s[16:17], v[98:99] op_sel_hi:[1,0,1]
	v_pk_fma_f32 v[100:101], v[228:229], s[16:17], v[100:101] op_sel_hi:[1,0,1]
	v_pk_fma_f32 v[102:103], v[230:231], s[16:17], v[102:103] op_sel_hi:[1,0,1]
	v_pk_fma_f32 v[104:105], v[232:233], s[16:17], v[104:105] op_sel_hi:[1,0,1]
	v_pk_fma_f32 v[106:107], v[234:235], s[16:17], v[106:107] op_sel_hi:[1,0,1]
	v_pk_fma_f32 v[108:109], v[236:237], s[16:17], v[108:109] op_sel_hi:[1,0,1]
	v_pk_fma_f32 v[110:111], v[238:239], s[16:17], v[110:111] op_sel_hi:[1,0,1]
	v_cvt_pk_f32_fp8_e32 v[224:225], v164
	v_cvt_pk_f32_fp8_sdwa v[226:227], v164 src0_sel:WORD_1
	v_cvt_pk_f32_fp8_e32 v[228:229], v165
	v_cvt_pk_f32_fp8_sdwa v[230:231], v165 src0_sel:WORD_1
	v_cvt_pk_f32_fp8_e32 v[232:233], v166
	v_cvt_pk_f32_fp8_sdwa v[234:235], v166 src0_sel:WORD_1
	v_cvt_pk_f32_fp8_e32 v[236:237], v167
	v_cvt_pk_f32_fp8_sdwa v[238:239], v167 src0_sel:WORD_1
	v_pk_fma_f32 v[96:97], v[224:225], s[18:19], v[96:97] op_sel_hi:[1,0,1]
	v_pk_fma_f32 v[98:99], v[226:227], s[18:19], v[98:99] op_sel_hi:[1,0,1]
	v_pk_fma_f32 v[100:101], v[228:229], s[18:19], v[100:101] op_sel_hi:[1,0,1]
	v_pk_fma_f32 v[102:103], v[230:231], s[18:19], v[102:103] op_sel_hi:[1,0,1]
	v_pk_fma_f32 v[104:105], v[232:233], s[18:19], v[104:105] op_sel_hi:[1,0,1]
	v_pk_fma_f32 v[106:107], v[234:235], s[18:19], v[106:107] op_sel_hi:[1,0,1]
	v_pk_fma_f32 v[108:109], v[236:237], s[18:19], v[108:109] op_sel_hi:[1,0,1]
	v_pk_fma_f32 v[110:111], v[238:239], s[18:19], v[110:111] op_sel_hi:[1,0,1]
	v_cvt_pk_f32_fp8_e32 v[224:225], v168
	v_cvt_pk_f32_fp8_sdwa v[226:227], v168 src0_sel:WORD_1
	v_cvt_pk_f32_fp8_e32 v[228:229], v169
	v_cvt_pk_f32_fp8_sdwa v[230:231], v169 src0_sel:WORD_1
	v_cvt_pk_f32_fp8_e32 v[232:233], v170
	v_cvt_pk_f32_fp8_sdwa v[234:235], v170 src0_sel:WORD_1
	v_cvt_pk_f32_fp8_e32 v[236:237], v171
	v_cvt_pk_f32_fp8_sdwa v[238:239], v171 src0_sel:WORD_1
	v_pk_fma_f32 v[96:97], v[224:225], s[20:21], v[96:97] op_sel_hi:[1,0,1]
	v_pk_fma_f32 v[98:99], v[226:227], s[20:21], v[98:99] op_sel_hi:[1,0,1]
	v_pk_fma_f32 v[100:101], v[228:229], s[20:21], v[100:101] op_sel_hi:[1,0,1]
	v_pk_fma_f32 v[102:103], v[230:231], s[20:21], v[102:103] op_sel_hi:[1,0,1]
	v_pk_fma_f32 v[104:105], v[232:233], s[20:21], v[104:105] op_sel_hi:[1,0,1]
	v_pk_fma_f32 v[106:107], v[234:235], s[20:21], v[106:107] op_sel_hi:[1,0,1]
	v_pk_fma_f32 v[108:109], v[236:237], s[20:21], v[108:109] op_sel_hi:[1,0,1]
	v_pk_fma_f32 v[110:111], v[238:239], s[20:21], v[110:111] op_sel_hi:[1,0,1]
	v_cvt_pk_f32_fp8_e32 v[224:225], v172
	v_cvt_pk_f32_fp8_sdwa v[226:227], v172 src0_sel:WORD_1
	v_cvt_pk_f32_fp8_e32 v[228:229], v173
	v_cvt_pk_f32_fp8_sdwa v[230:231], v173 src0_sel:WORD_1
	v_cvt_pk_f32_fp8_e32 v[232:233], v174
	v_cvt_pk_f32_fp8_sdwa v[234:235], v174 src0_sel:WORD_1
	v_cvt_pk_f32_fp8_e32 v[236:237], v175
	v_cvt_pk_f32_fp8_sdwa v[238:239], v175 src0_sel:WORD_1
	v_pk_fma_f32 v[96:97], v[224:225], s[22:23], v[96:97] op_sel_hi:[1,0,1]
	v_pk_fma_f32 v[98:99], v[226:227], s[22:23], v[98:99] op_sel_hi:[1,0,1]
	v_pk_fma_f32 v[100:101], v[228:229], s[22:23], v[100:101] op_sel_hi:[1,0,1]
	v_pk_fma_f32 v[102:103], v[230:231], s[22:23], v[102:103] op_sel_hi:[1,0,1]
	v_pk_fma_f32 v[104:105], v[232:233], s[22:23], v[104:105] op_sel_hi:[1,0,1]
	v_pk_fma_f32 v[106:107], v[234:235], s[22:23], v[106:107] op_sel_hi:[1,0,1]
	v_pk_fma_f32 v[108:109], v[236:237], s[22:23], v[108:109] op_sel_hi:[1,0,1]
	v_pk_fma_f32 v[110:111], v[238:239], s[22:23], v[110:111] op_sel_hi:[1,0,1]
	v_cvt_pk_f32_fp8_e32 v[224:225], v176
	v_cvt_pk_f32_fp8_sdwa v[226:227], v176 src0_sel:WORD_1
	v_cvt_pk_f32_fp8_e32 v[228:229], v177
	v_cvt_pk_f32_fp8_sdwa v[230:231], v177 src0_sel:WORD_1
	v_cvt_pk_f32_fp8_e32 v[232:233], v178
	v_cvt_pk_f32_fp8_sdwa v[234:235], v178 src0_sel:WORD_1
	v_cvt_pk_f32_fp8_e32 v[236:237], v179
	v_cvt_pk_f32_fp8_sdwa v[238:239], v179 src0_sel:WORD_1
	v_pk_fma_f32 v[96:97], v[224:225], s[24:25], v[96:97] op_sel_hi:[1,0,1]
	v_pk_fma_f32 v[98:99], v[226:227], s[24:25], v[98:99] op_sel_hi:[1,0,1]
	v_pk_fma_f32 v[100:101], v[228:229], s[24:25], v[100:101] op_sel_hi:[1,0,1]
	v_pk_fma_f32 v[102:103], v[230:231], s[24:25], v[102:103] op_sel_hi:[1,0,1]
	v_pk_fma_f32 v[104:105], v[232:233], s[24:25], v[104:105] op_sel_hi:[1,0,1]
	v_pk_fma_f32 v[106:107], v[234:235], s[24:25], v[106:107] op_sel_hi:[1,0,1]
	v_pk_fma_f32 v[108:109], v[236:237], s[24:25], v[108:109] op_sel_hi:[1,0,1]
	v_pk_fma_f32 v[110:111], v[238:239], s[24:25], v[110:111] op_sel_hi:[1,0,1]
	v_cvt_pk_f32_fp8_e32 v[224:225], v180
	v_cvt_pk_f32_fp8_sdwa v[226:227], v180 src0_sel:WORD_1
	v_cvt_pk_f32_fp8_e32 v[228:229], v181
	v_cvt_pk_f32_fp8_sdwa v[230:231], v181 src0_sel:WORD_1
	v_cvt_pk_f32_fp8_e32 v[232:233], v182
	v_cvt_pk_f32_fp8_sdwa v[234:235], v182 src0_sel:WORD_1
	v_cvt_pk_f32_fp8_e32 v[236:237], v183
	v_cvt_pk_f32_fp8_sdwa v[238:239], v183 src0_sel:WORD_1
	v_pk_fma_f32 v[96:97], v[224:225], s[26:27], v[96:97] op_sel_hi:[1,0,1]
	v_pk_fma_f32 v[98:99], v[226:227], s[26:27], v[98:99] op_sel_hi:[1,0,1]
	v_pk_fma_f32 v[100:101], v[228:229], s[26:27], v[100:101] op_sel_hi:[1,0,1]
	v_pk_fma_f32 v[102:103], v[230:231], s[26:27], v[102:103] op_sel_hi:[1,0,1]
	v_pk_fma_f32 v[104:105], v[232:233], s[26:27], v[104:105] op_sel_hi:[1,0,1]
	v_pk_fma_f32 v[106:107], v[234:235], s[26:27], v[106:107] op_sel_hi:[1,0,1]
	v_pk_fma_f32 v[108:109], v[236:237], s[26:27], v[108:109] op_sel_hi:[1,0,1]
	v_pk_fma_f32 v[110:111], v[238:239], s[26:27], v[110:111] op_sel_hi:[1,0,1]
	v_cvt_pk_f32_fp8_e32 v[224:225], v184
	v_cvt_pk_f32_fp8_sdwa v[226:227], v184 src0_sel:WORD_1
	v_cvt_pk_f32_fp8_e32 v[228:229], v185
	v_cvt_pk_f32_fp8_sdwa v[230:231], v185 src0_sel:WORD_1
	v_cvt_pk_f32_fp8_e32 v[232:233], v186
	v_cvt_pk_f32_fp8_sdwa v[234:235], v186 src0_sel:WORD_1
	v_cvt_pk_f32_fp8_e32 v[236:237], v187
	v_cvt_pk_f32_fp8_sdwa v[238:239], v187 src0_sel:WORD_1
	v_pk_fma_f32 v[96:97], v[224:225], s[28:29], v[96:97] op_sel_hi:[1,0,1]
	v_pk_fma_f32 v[98:99], v[226:227], s[28:29], v[98:99] op_sel_hi:[1,0,1]
	v_pk_fma_f32 v[100:101], v[228:229], s[28:29], v[100:101] op_sel_hi:[1,0,1]
	v_pk_fma_f32 v[102:103], v[230:231], s[28:29], v[102:103] op_sel_hi:[1,0,1]
	v_pk_fma_f32 v[104:105], v[232:233], s[28:29], v[104:105] op_sel_hi:[1,0,1]
	v_pk_fma_f32 v[106:107], v[234:235], s[28:29], v[106:107] op_sel_hi:[1,0,1]
	v_pk_fma_f32 v[108:109], v[236:237], s[28:29], v[108:109] op_sel_hi:[1,0,1]
	v_pk_fma_f32 v[110:111], v[238:239], s[28:29], v[110:111] op_sel_hi:[1,0,1]
	v_cvt_pk_f32_fp8_e32 v[224:225], v188
	v_cvt_pk_f32_fp8_sdwa v[226:227], v188 src0_sel:WORD_1
	v_cvt_pk_f32_fp8_e32 v[228:229], v189
	v_cvt_pk_f32_fp8_sdwa v[230:231], v189 src0_sel:WORD_1
	v_cvt_pk_f32_fp8_e32 v[232:233], v190
	v_cvt_pk_f32_fp8_sdwa v[234:235], v190 src0_sel:WORD_1
	v_cvt_pk_f32_fp8_e32 v[236:237], v191
	v_cvt_pk_f32_fp8_sdwa v[238:239], v191 src0_sel:WORD_1
	v_pk_fma_f32 v[96:97], v[224:225], s[30:31], v[96:97] op_sel_hi:[1,0,1]
	v_pk_fma_f32 v[98:99], v[226:227], s[30:31], v[98:99] op_sel_hi:[1,0,1]
	v_pk_fma_f32 v[100:101], v[228:229], s[30:31], v[100:101] op_sel_hi:[1,0,1]
	v_pk_fma_f32 v[102:103], v[230:231], s[30:31], v[102:103] op_sel_hi:[1,0,1]
	v_pk_fma_f32 v[104:105], v[232:233], s[30:31], v[104:105] op_sel_hi:[1,0,1]
	v_pk_fma_f32 v[106:107], v[234:235], s[30:31], v[106:107] op_sel_hi:[1,0,1]
	v_pk_fma_f32 v[108:109], v[236:237], s[30:31], v[108:109] op_sel_hi:[1,0,1]
	v_pk_fma_f32 v[110:111], v[238:239], s[30:31], v[110:111] op_sel_hi:[1,0,1]
	v_readlane_b32 s16, v158, s72
	v_readlane_b32 s18, v158, s73
	v_readlane_b32 s20, v158, s74
	v_readlane_b32 s22, v158, s75
	v_readlane_b32 s24, v158, s76
	v_readlane_b32 s26, v158, s77
	v_readlane_b32 s28, v158, s78
	v_readlane_b32 s30, v158, s79
	v_readlane_b32 s48, v129, s72
	v_readlane_b32 s49, v129, s73
	v_readlane_b32 s50, v129, s74
	v_readlane_b32 s51, v129, s75
	v_readlane_b32 s52, v129, s76
	v_readlane_b32 s53, v129, s77
	v_readlane_b32 s54, v129, s78
	v_readlane_b32 s55, v129, s79
	s_add_u32 s32, s0, s48
	s_addc_u32 s33, s1, 0
	s_add_u32 s34, s0, s49
	s_addc_u32 s35, s1, 0
	s_add_u32 s36, s0, s50
	s_addc_u32 s37, s1, 0
	s_add_u32 s38, s0, s51
	s_addc_u32 s39, s1, 0
	s_add_u32 s40, s0, s52
	s_addc_u32 s41, s1, 0
	s_add_u32 s42, s0, s53
	s_addc_u32 s43, s1, 0
	s_add_u32 s44, s0, s54
	s_addc_u32 s45, s1, 0
	s_add_u32 s46, s0, s55
	s_addc_u32 s47, s1, 0
	global_load_dwordx4 v[160:163], v240, s[32:33]
	global_load_dwordx4 v[164:167], v240, s[34:35]
	global_load_dwordx4 v[168:171], v240, s[36:37]
	global_load_dwordx4 v[172:175], v240, s[38:39]
	global_load_dwordx4 v[176:179], v240, s[40:41]
	global_load_dwordx4 v[180:183], v240, s[42:43]
	global_load_dwordx4 v[184:187], v240, s[44:45]
	global_load_dwordx4 v[188:191], v240, s[46:47]
	s_waitcnt vmcnt(8)
	v_cvt_pk_f32_fp8_e32 v[224:225], v192
	v_cvt_pk_f32_fp8_sdwa v[226:227], v192 src0_sel:WORD_1
	v_cvt_pk_f32_fp8_e32 v[228:229], v193
	v_cvt_pk_f32_fp8_sdwa v[230:231], v193 src0_sel:WORD_1
	v_cvt_pk_f32_fp8_e32 v[232:233], v194
	v_cvt_pk_f32_fp8_sdwa v[234:235], v194 src0_sel:WORD_1
	v_cvt_pk_f32_fp8_e32 v[236:237], v195
	v_cvt_pk_f32_fp8_sdwa v[238:239], v195 src0_sel:WORD_1
	v_pk_fma_f32 v[112:113], v[224:225], s[16:17], v[112:113] op_sel_hi:[1,0,1]
	v_pk_fma_f32 v[114:115], v[226:227], s[16:17], v[114:115] op_sel_hi:[1,0,1]
	v_pk_fma_f32 v[116:117], v[228:229], s[16:17], v[116:117] op_sel_hi:[1,0,1]
	v_pk_fma_f32 v[118:119], v[230:231], s[16:17], v[118:119] op_sel_hi:[1,0,1]
	v_pk_fma_f32 v[120:121], v[232:233], s[16:17], v[120:121] op_sel_hi:[1,0,1]
	v_pk_fma_f32 v[122:123], v[234:235], s[16:17], v[122:123] op_sel_hi:[1,0,1]
	v_pk_fma_f32 v[124:125], v[236:237], s[16:17], v[124:125] op_sel_hi:[1,0,1]
	v_pk_fma_f32 v[126:127], v[238:239], s[16:17], v[126:127] op_sel_hi:[1,0,1]
	v_cvt_pk_f32_fp8_e32 v[224:225], v196
	v_cvt_pk_f32_fp8_sdwa v[226:227], v196 src0_sel:WORD_1
	v_cvt_pk_f32_fp8_e32 v[228:229], v197
	v_cvt_pk_f32_fp8_sdwa v[230:231], v197 src0_sel:WORD_1
	v_cvt_pk_f32_fp8_e32 v[232:233], v198
	v_cvt_pk_f32_fp8_sdwa v[234:235], v198 src0_sel:WORD_1
	v_cvt_pk_f32_fp8_e32 v[236:237], v199
	v_cvt_pk_f32_fp8_sdwa v[238:239], v199 src0_sel:WORD_1
	v_pk_fma_f32 v[112:113], v[224:225], s[18:19], v[112:113] op_sel_hi:[1,0,1]
	v_pk_fma_f32 v[114:115], v[226:227], s[18:19], v[114:115] op_sel_hi:[1,0,1]
	v_pk_fma_f32 v[116:117], v[228:229], s[18:19], v[116:117] op_sel_hi:[1,0,1]
	v_pk_fma_f32 v[118:119], v[230:231], s[18:19], v[118:119] op_sel_hi:[1,0,1]
	v_pk_fma_f32 v[120:121], v[232:233], s[18:19], v[120:121] op_sel_hi:[1,0,1]
	v_pk_fma_f32 v[122:123], v[234:235], s[18:19], v[122:123] op_sel_hi:[1,0,1]
	v_pk_fma_f32 v[124:125], v[236:237], s[18:19], v[124:125] op_sel_hi:[1,0,1]
	v_pk_fma_f32 v[126:127], v[238:239], s[18:19], v[126:127] op_sel_hi:[1,0,1]
	v_cvt_pk_f32_fp8_e32 v[224:225], v200
	v_cvt_pk_f32_fp8_sdwa v[226:227], v200 src0_sel:WORD_1
	v_cvt_pk_f32_fp8_e32 v[228:229], v201
	v_cvt_pk_f32_fp8_sdwa v[230:231], v201 src0_sel:WORD_1
	v_cvt_pk_f32_fp8_e32 v[232:233], v202
	v_cvt_pk_f32_fp8_sdwa v[234:235], v202 src0_sel:WORD_1
	v_cvt_pk_f32_fp8_e32 v[236:237], v203
	v_cvt_pk_f32_fp8_sdwa v[238:239], v203 src0_sel:WORD_1
	v_pk_fma_f32 v[112:113], v[224:225], s[20:21], v[112:113] op_sel_hi:[1,0,1]
	v_pk_fma_f32 v[114:115], v[226:227], s[20:21], v[114:115] op_sel_hi:[1,0,1]
	v_pk_fma_f32 v[116:117], v[228:229], s[20:21], v[116:117] op_sel_hi:[1,0,1]
	v_pk_fma_f32 v[118:119], v[230:231], s[20:21], v[118:119] op_sel_hi:[1,0,1]
	v_pk_fma_f32 v[120:121], v[232:233], s[20:21], v[120:121] op_sel_hi:[1,0,1]
	v_pk_fma_f32 v[122:123], v[234:235], s[20:21], v[122:123] op_sel_hi:[1,0,1]
	v_pk_fma_f32 v[124:125], v[236:237], s[20:21], v[124:125] op_sel_hi:[1,0,1]
	v_pk_fma_f32 v[126:127], v[238:239], s[20:21], v[126:127] op_sel_hi:[1,0,1]
	v_cvt_pk_f32_fp8_e32 v[224:225], v204
	v_cvt_pk_f32_fp8_sdwa v[226:227], v204 src0_sel:WORD_1
	v_cvt_pk_f32_fp8_e32 v[228:229], v205
	v_cvt_pk_f32_fp8_sdwa v[230:231], v205 src0_sel:WORD_1
	v_cvt_pk_f32_fp8_e32 v[232:233], v206
	v_cvt_pk_f32_fp8_sdwa v[234:235], v206 src0_sel:WORD_1
	v_cvt_pk_f32_fp8_e32 v[236:237], v207
	v_cvt_pk_f32_fp8_sdwa v[238:239], v207 src0_sel:WORD_1
	v_pk_fma_f32 v[112:113], v[224:225], s[22:23], v[112:113] op_sel_hi:[1,0,1]
	v_pk_fma_f32 v[114:115], v[226:227], s[22:23], v[114:115] op_sel_hi:[1,0,1]
	v_pk_fma_f32 v[116:117], v[228:229], s[22:23], v[116:117] op_sel_hi:[1,0,1]
	v_pk_fma_f32 v[118:119], v[230:231], s[22:23], v[118:119] op_sel_hi:[1,0,1]
	v_pk_fma_f32 v[120:121], v[232:233], s[22:23], v[120:121] op_sel_hi:[1,0,1]
	v_pk_fma_f32 v[122:123], v[234:235], s[22:23], v[122:123] op_sel_hi:[1,0,1]
	v_pk_fma_f32 v[124:125], v[236:237], s[22:23], v[124:125] op_sel_hi:[1,0,1]
	v_pk_fma_f32 v[126:127], v[238:239], s[22:23], v[126:127] op_sel_hi:[1,0,1]
	v_cvt_pk_f32_fp8_e32 v[224:225], v208
	v_cvt_pk_f32_fp8_sdwa v[226:227], v208 src0_sel:WORD_1
	v_cvt_pk_f32_fp8_e32 v[228:229], v209
	v_cvt_pk_f32_fp8_sdwa v[230:231], v209 src0_sel:WORD_1
	v_cvt_pk_f32_fp8_e32 v[232:233], v210
	v_cvt_pk_f32_fp8_sdwa v[234:235], v210 src0_sel:WORD_1
	v_cvt_pk_f32_fp8_e32 v[236:237], v211
	v_cvt_pk_f32_fp8_sdwa v[238:239], v211 src0_sel:WORD_1
	v_pk_fma_f32 v[112:113], v[224:225], s[24:25], v[112:113] op_sel_hi:[1,0,1]
	v_pk_fma_f32 v[114:115], v[226:227], s[24:25], v[114:115] op_sel_hi:[1,0,1]
	v_pk_fma_f32 v[116:117], v[228:229], s[24:25], v[116:117] op_sel_hi:[1,0,1]
	v_pk_fma_f32 v[118:119], v[230:231], s[24:25], v[118:119] op_sel_hi:[1,0,1]
	v_pk_fma_f32 v[120:121], v[232:233], s[24:25], v[120:121] op_sel_hi:[1,0,1]
	v_pk_fma_f32 v[122:123], v[234:235], s[24:25], v[122:123] op_sel_hi:[1,0,1]
	v_pk_fma_f32 v[124:125], v[236:237], s[24:25], v[124:125] op_sel_hi:[1,0,1]
	v_pk_fma_f32 v[126:127], v[238:239], s[24:25], v[126:127] op_sel_hi:[1,0,1]
	v_cvt_pk_f32_fp8_e32 v[224:225], v212
	v_cvt_pk_f32_fp8_sdwa v[226:227], v212 src0_sel:WORD_1
	v_cvt_pk_f32_fp8_e32 v[228:229], v213
	v_cvt_pk_f32_fp8_sdwa v[230:231], v213 src0_sel:WORD_1
	v_cvt_pk_f32_fp8_e32 v[232:233], v214
	v_cvt_pk_f32_fp8_sdwa v[234:235], v214 src0_sel:WORD_1
	v_cvt_pk_f32_fp8_e32 v[236:237], v215
	v_cvt_pk_f32_fp8_sdwa v[238:239], v215 src0_sel:WORD_1
	v_pk_fma_f32 v[112:113], v[224:225], s[26:27], v[112:113] op_sel_hi:[1,0,1]
	v_pk_fma_f32 v[114:115], v[226:227], s[26:27], v[114:115] op_sel_hi:[1,0,1]
	v_pk_fma_f32 v[116:117], v[228:229], s[26:27], v[116:117] op_sel_hi:[1,0,1]
	v_pk_fma_f32 v[118:119], v[230:231], s[26:27], v[118:119] op_sel_hi:[1,0,1]
	v_pk_fma_f32 v[120:121], v[232:233], s[26:27], v[120:121] op_sel_hi:[1,0,1]
	v_pk_fma_f32 v[122:123], v[234:235], s[26:27], v[122:123] op_sel_hi:[1,0,1]
	v_pk_fma_f32 v[124:125], v[236:237], s[26:27], v[124:125] op_sel_hi:[1,0,1]
	v_pk_fma_f32 v[126:127], v[238:239], s[26:27], v[126:127] op_sel_hi:[1,0,1]
	v_cvt_pk_f32_fp8_e32 v[224:225], v216
	v_cvt_pk_f32_fp8_sdwa v[226:227], v216 src0_sel:WORD_1
	v_cvt_pk_f32_fp8_e32 v[228:229], v217
	v_cvt_pk_f32_fp8_sdwa v[230:231], v217 src0_sel:WORD_1
	v_cvt_pk_f32_fp8_e32 v[232:233], v218
	v_cvt_pk_f32_fp8_sdwa v[234:235], v218 src0_sel:WORD_1
	v_cvt_pk_f32_fp8_e32 v[236:237], v219
	v_cvt_pk_f32_fp8_sdwa v[238:239], v219 src0_sel:WORD_1
	v_pk_fma_f32 v[112:113], v[224:225], s[28:29], v[112:113] op_sel_hi:[1,0,1]
	v_pk_fma_f32 v[114:115], v[226:227], s[28:29], v[114:115] op_sel_hi:[1,0,1]
	v_pk_fma_f32 v[116:117], v[228:229], s[28:29], v[116:117] op_sel_hi:[1,0,1]
	v_pk_fma_f32 v[118:119], v[230:231], s[28:29], v[118:119] op_sel_hi:[1,0,1]
	v_pk_fma_f32 v[120:121], v[232:233], s[28:29], v[120:121] op_sel_hi:[1,0,1]
	v_pk_fma_f32 v[122:123], v[234:235], s[28:29], v[122:123] op_sel_hi:[1,0,1]
	v_pk_fma_f32 v[124:125], v[236:237], s[28:29], v[124:125] op_sel_hi:[1,0,1]
	v_pk_fma_f32 v[126:127], v[238:239], s[28:29], v[126:127] op_sel_hi:[1,0,1]
	v_cvt_pk_f32_fp8_e32 v[224:225], v220
	v_cvt_pk_f32_fp8_sdwa v[226:227], v220 src0_sel:WORD_1
	v_cvt_pk_f32_fp8_e32 v[228:229], v221
	v_cvt_pk_f32_fp8_sdwa v[230:231], v221 src0_sel:WORD_1
	v_cvt_pk_f32_fp8_e32 v[232:233], v222
	v_cvt_pk_f32_fp8_sdwa v[234:235], v222 src0_sel:WORD_1
	v_cvt_pk_f32_fp8_e32 v[236:237], v223
	v_cvt_pk_f32_fp8_sdwa v[238:239], v223 src0_sel:WORD_1
	v_pk_fma_f32 v[112:113], v[224:225], s[30:31], v[112:113] op_sel_hi:[1,0,1]
	v_pk_fma_f32 v[114:115], v[226:227], s[30:31], v[114:115] op_sel_hi:[1,0,1]
	v_pk_fma_f32 v[116:117], v[228:229], s[30:31], v[116:117] op_sel_hi:[1,0,1]
	v_pk_fma_f32 v[118:119], v[230:231], s[30:31], v[118:119] op_sel_hi:[1,0,1]
	v_pk_fma_f32 v[120:121], v[232:233], s[30:31], v[120:121] op_sel_hi:[1,0,1]
	v_pk_fma_f32 v[122:123], v[234:235], s[30:31], v[122:123] op_sel_hi:[1,0,1]
	v_pk_fma_f32 v[124:125], v[236:237], s[30:31], v[124:125] op_sel_hi:[1,0,1]
	v_pk_fma_f32 v[126:127], v[238:239], s[30:31], v[126:127] op_sel_hi:[1,0,1]
	v_readlane_b32 s16, v131, s72
	v_readlane_b32 s18, v131, s73
	v_readlane_b32 s20, v131, s74
	v_readlane_b32 s22, v131, s75
	v_readlane_b32 s24, v131, s76
	v_readlane_b32 s26, v131, s77
	v_readlane_b32 s28, v131, s78
	v_readlane_b32 s30, v131, s79
	v_readlane_b32 s48, v133, s72
	v_readlane_b32 s49, v133, s73
	v_readlane_b32 s50, v133, s74
	v_readlane_b32 s51, v133, s75
	v_readlane_b32 s52, v133, s76
	v_readlane_b32 s53, v133, s77
	v_readlane_b32 s54, v133, s78
	v_readlane_b32 s55, v133, s79
	s_add_u32 s32, s0, s48
	s_addc_u32 s33, s1, 0
	s_add_u32 s34, s0, s49
	s_addc_u32 s35, s1, 0
	s_add_u32 s36, s0, s50
	s_addc_u32 s37, s1, 0
	s_add_u32 s38, s0, s51
	s_addc_u32 s39, s1, 0
	s_add_u32 s40, s0, s52
	s_addc_u32 s41, s1, 0
	s_add_u32 s42, s0, s53
	s_addc_u32 s43, s1, 0
	s_add_u32 s44, s0, s54
	s_addc_u32 s45, s1, 0
	s_add_u32 s46, s0, s55
	s_addc_u32 s47, s1, 0
	global_load_dwordx4 v[192:195], v240, s[32:33]
	global_load_dwordx4 v[196:199], v240, s[34:35]
	global_load_dwordx4 v[200:203], v240, s[36:37]
	global_load_dwordx4 v[204:207], v240, s[38:39]
	global_load_dwordx4 v[208:211], v240, s[40:41]
	global_load_dwordx4 v[212:215], v240, s[42:43]
	global_load_dwordx4 v[216:219], v240, s[44:45]
	global_load_dwordx4 v[220:223], v240, s[46:47]
	s_waitcnt vmcnt(8)
	v_cvt_pk_f32_fp8_e32 v[224:225], v160
	v_cvt_pk_f32_fp8_sdwa v[226:227], v160 src0_sel:WORD_1
	v_cvt_pk_f32_fp8_e32 v[228:229], v161
	v_cvt_pk_f32_fp8_sdwa v[230:231], v161 src0_sel:WORD_1
	v_cvt_pk_f32_fp8_e32 v[232:233], v162
	v_cvt_pk_f32_fp8_sdwa v[234:235], v162 src0_sel:WORD_1
	v_cvt_pk_f32_fp8_e32 v[236:237], v163
	v_cvt_pk_f32_fp8_sdwa v[238:239], v163 src0_sel:WORD_1
	v_pk_fma_f32 v[0:1], v[224:225], s[16:17], v[0:1] op_sel_hi:[1,0,1]
	v_pk_fma_f32 v[2:3], v[226:227], s[16:17], v[2:3] op_sel_hi:[1,0,1]
	v_pk_fma_f32 v[4:5], v[228:229], s[16:17], v[4:5] op_sel_hi:[1,0,1]
	v_pk_fma_f32 v[6:7], v[230:231], s[16:17], v[6:7] op_sel_hi:[1,0,1]
	v_pk_fma_f32 v[8:9], v[232:233], s[16:17], v[8:9] op_sel_hi:[1,0,1]
	v_pk_fma_f32 v[10:11], v[234:235], s[16:17], v[10:11] op_sel_hi:[1,0,1]
	v_pk_fma_f32 v[12:13], v[236:237], s[16:17], v[12:13] op_sel_hi:[1,0,1]
	v_pk_fma_f32 v[14:15], v[238:239], s[16:17], v[14:15] op_sel_hi:[1,0,1]
	v_cvt_pk_f32_fp8_e32 v[224:225], v164
	v_cvt_pk_f32_fp8_sdwa v[226:227], v164 src0_sel:WORD_1
	v_cvt_pk_f32_fp8_e32 v[228:229], v165
	v_cvt_pk_f32_fp8_sdwa v[230:231], v165 src0_sel:WORD_1
	v_cvt_pk_f32_fp8_e32 v[232:233], v166
	v_cvt_pk_f32_fp8_sdwa v[234:235], v166 src0_sel:WORD_1
	v_cvt_pk_f32_fp8_e32 v[236:237], v167
	v_cvt_pk_f32_fp8_sdwa v[238:239], v167 src0_sel:WORD_1
	v_pk_fma_f32 v[0:1], v[224:225], s[18:19], v[0:1] op_sel_hi:[1,0,1]
	v_pk_fma_f32 v[2:3], v[226:227], s[18:19], v[2:3] op_sel_hi:[1,0,1]
	v_pk_fma_f32 v[4:5], v[228:229], s[18:19], v[4:5] op_sel_hi:[1,0,1]
	v_pk_fma_f32 v[6:7], v[230:231], s[18:19], v[6:7] op_sel_hi:[1,0,1]
	v_pk_fma_f32 v[8:9], v[232:233], s[18:19], v[8:9] op_sel_hi:[1,0,1]
	v_pk_fma_f32 v[10:11], v[234:235], s[18:19], v[10:11] op_sel_hi:[1,0,1]
	v_pk_fma_f32 v[12:13], v[236:237], s[18:19], v[12:13] op_sel_hi:[1,0,1]
	v_pk_fma_f32 v[14:15], v[238:239], s[18:19], v[14:15] op_sel_hi:[1,0,1]
	v_cvt_pk_f32_fp8_e32 v[224:225], v168
	v_cvt_pk_f32_fp8_sdwa v[226:227], v168 src0_sel:WORD_1
	v_cvt_pk_f32_fp8_e32 v[228:229], v169
	v_cvt_pk_f32_fp8_sdwa v[230:231], v169 src0_sel:WORD_1
	v_cvt_pk_f32_fp8_e32 v[232:233], v170
	v_cvt_pk_f32_fp8_sdwa v[234:235], v170 src0_sel:WORD_1
	v_cvt_pk_f32_fp8_e32 v[236:237], v171
	v_cvt_pk_f32_fp8_sdwa v[238:239], v171 src0_sel:WORD_1
	v_pk_fma_f32 v[0:1], v[224:225], s[20:21], v[0:1] op_sel_hi:[1,0,1]
	v_pk_fma_f32 v[2:3], v[226:227], s[20:21], v[2:3] op_sel_hi:[1,0,1]
	v_pk_fma_f32 v[4:5], v[228:229], s[20:21], v[4:5] op_sel_hi:[1,0,1]
	v_pk_fma_f32 v[6:7], v[230:231], s[20:21], v[6:7] op_sel_hi:[1,0,1]
	v_pk_fma_f32 v[8:9], v[232:233], s[20:21], v[8:9] op_sel_hi:[1,0,1]
	v_pk_fma_f32 v[10:11], v[234:235], s[20:21], v[10:11] op_sel_hi:[1,0,1]
	v_pk_fma_f32 v[12:13], v[236:237], s[20:21], v[12:13] op_sel_hi:[1,0,1]
	v_pk_fma_f32 v[14:15], v[238:239], s[20:21], v[14:15] op_sel_hi:[1,0,1]
	v_cvt_pk_f32_fp8_e32 v[224:225], v172
	v_cvt_pk_f32_fp8_sdwa v[226:227], v172 src0_sel:WORD_1
	v_cvt_pk_f32_fp8_e32 v[228:229], v173
	v_cvt_pk_f32_fp8_sdwa v[230:231], v173 src0_sel:WORD_1
	v_cvt_pk_f32_fp8_e32 v[232:233], v174
	v_cvt_pk_f32_fp8_sdwa v[234:235], v174 src0_sel:WORD_1
	v_cvt_pk_f32_fp8_e32 v[236:237], v175
	v_cvt_pk_f32_fp8_sdwa v[238:239], v175 src0_sel:WORD_1
	v_pk_fma_f32 v[0:1], v[224:225], s[22:23], v[0:1] op_sel_hi:[1,0,1]
	v_pk_fma_f32 v[2:3], v[226:227], s[22:23], v[2:3] op_sel_hi:[1,0,1]
	v_pk_fma_f32 v[4:5], v[228:229], s[22:23], v[4:5] op_sel_hi:[1,0,1]
	v_pk_fma_f32 v[6:7], v[230:231], s[22:23], v[6:7] op_sel_hi:[1,0,1]
	v_pk_fma_f32 v[8:9], v[232:233], s[22:23], v[8:9] op_sel_hi:[1,0,1]
	v_pk_fma_f32 v[10:11], v[234:235], s[22:23], v[10:11] op_sel_hi:[1,0,1]
	v_pk_fma_f32 v[12:13], v[236:237], s[22:23], v[12:13] op_sel_hi:[1,0,1]
	v_pk_fma_f32 v[14:15], v[238:239], s[22:23], v[14:15] op_sel_hi:[1,0,1]
	v_cvt_pk_f32_fp8_e32 v[224:225], v176
	v_cvt_pk_f32_fp8_sdwa v[226:227], v176 src0_sel:WORD_1
	v_cvt_pk_f32_fp8_e32 v[228:229], v177
	v_cvt_pk_f32_fp8_sdwa v[230:231], v177 src0_sel:WORD_1
	v_cvt_pk_f32_fp8_e32 v[232:233], v178
	v_cvt_pk_f32_fp8_sdwa v[234:235], v178 src0_sel:WORD_1
	v_cvt_pk_f32_fp8_e32 v[236:237], v179
	v_cvt_pk_f32_fp8_sdwa v[238:239], v179 src0_sel:WORD_1
	v_pk_fma_f32 v[0:1], v[224:225], s[24:25], v[0:1] op_sel_hi:[1,0,1]
	v_pk_fma_f32 v[2:3], v[226:227], s[24:25], v[2:3] op_sel_hi:[1,0,1]
	v_pk_fma_f32 v[4:5], v[228:229], s[24:25], v[4:5] op_sel_hi:[1,0,1]
	v_pk_fma_f32 v[6:7], v[230:231], s[24:25], v[6:7] op_sel_hi:[1,0,1]
	v_pk_fma_f32 v[8:9], v[232:233], s[24:25], v[8:9] op_sel_hi:[1,0,1]
	v_pk_fma_f32 v[10:11], v[234:235], s[24:25], v[10:11] op_sel_hi:[1,0,1]
	v_pk_fma_f32 v[12:13], v[236:237], s[24:25], v[12:13] op_sel_hi:[1,0,1]
	v_pk_fma_f32 v[14:15], v[238:239], s[24:25], v[14:15] op_sel_hi:[1,0,1]
	v_cvt_pk_f32_fp8_e32 v[224:225], v180
	v_cvt_pk_f32_fp8_sdwa v[226:227], v180 src0_sel:WORD_1
	v_cvt_pk_f32_fp8_e32 v[228:229], v181
	v_cvt_pk_f32_fp8_sdwa v[230:231], v181 src0_sel:WORD_1
	v_cvt_pk_f32_fp8_e32 v[232:233], v182
	v_cvt_pk_f32_fp8_sdwa v[234:235], v182 src0_sel:WORD_1
	v_cvt_pk_f32_fp8_e32 v[236:237], v183
	v_cvt_pk_f32_fp8_sdwa v[238:239], v183 src0_sel:WORD_1
	v_pk_fma_f32 v[0:1], v[224:225], s[26:27], v[0:1] op_sel_hi:[1,0,1]
	v_pk_fma_f32 v[2:3], v[226:227], s[26:27], v[2:3] op_sel_hi:[1,0,1]
	v_pk_fma_f32 v[4:5], v[228:229], s[26:27], v[4:5] op_sel_hi:[1,0,1]
	v_pk_fma_f32 v[6:7], v[230:231], s[26:27], v[6:7] op_sel_hi:[1,0,1]
	v_pk_fma_f32 v[8:9], v[232:233], s[26:27], v[8:9] op_sel_hi:[1,0,1]
	v_pk_fma_f32 v[10:11], v[234:235], s[26:27], v[10:11] op_sel_hi:[1,0,1]
	v_pk_fma_f32 v[12:13], v[236:237], s[26:27], v[12:13] op_sel_hi:[1,0,1]
	v_pk_fma_f32 v[14:15], v[238:239], s[26:27], v[14:15] op_sel_hi:[1,0,1]
	v_cvt_pk_f32_fp8_e32 v[224:225], v184
	v_cvt_pk_f32_fp8_sdwa v[226:227], v184 src0_sel:WORD_1
	v_cvt_pk_f32_fp8_e32 v[228:229], v185
	v_cvt_pk_f32_fp8_sdwa v[230:231], v185 src0_sel:WORD_1
	v_cvt_pk_f32_fp8_e32 v[232:233], v186
	v_cvt_pk_f32_fp8_sdwa v[234:235], v186 src0_sel:WORD_1
	v_cvt_pk_f32_fp8_e32 v[236:237], v187
	v_cvt_pk_f32_fp8_sdwa v[238:239], v187 src0_sel:WORD_1
	v_pk_fma_f32 v[0:1], v[224:225], s[28:29], v[0:1] op_sel_hi:[1,0,1]
	v_pk_fma_f32 v[2:3], v[226:227], s[28:29], v[2:3] op_sel_hi:[1,0,1]
	v_pk_fma_f32 v[4:5], v[228:229], s[28:29], v[4:5] op_sel_hi:[1,0,1]
	v_pk_fma_f32 v[6:7], v[230:231], s[28:29], v[6:7] op_sel_hi:[1,0,1]
	v_pk_fma_f32 v[8:9], v[232:233], s[28:29], v[8:9] op_sel_hi:[1,0,1]
	v_pk_fma_f32 v[10:11], v[234:235], s[28:29], v[10:11] op_sel_hi:[1,0,1]
	v_pk_fma_f32 v[12:13], v[236:237], s[28:29], v[12:13] op_sel_hi:[1,0,1]
	v_pk_fma_f32 v[14:15], v[238:239], s[28:29], v[14:15] op_sel_hi:[1,0,1]
	v_cvt_pk_f32_fp8_e32 v[224:225], v188
	v_cvt_pk_f32_fp8_sdwa v[226:227], v188 src0_sel:WORD_1
	v_cvt_pk_f32_fp8_e32 v[228:229], v189
	v_cvt_pk_f32_fp8_sdwa v[230:231], v189 src0_sel:WORD_1
	v_cvt_pk_f32_fp8_e32 v[232:233], v190
	v_cvt_pk_f32_fp8_sdwa v[234:235], v190 src0_sel:WORD_1
	v_cvt_pk_f32_fp8_e32 v[236:237], v191
	v_cvt_pk_f32_fp8_sdwa v[238:239], v191 src0_sel:WORD_1
	v_pk_fma_f32 v[0:1], v[224:225], s[30:31], v[0:1] op_sel_hi:[1,0,1]
	v_pk_fma_f32 v[2:3], v[226:227], s[30:31], v[2:3] op_sel_hi:[1,0,1]
	v_pk_fma_f32 v[4:5], v[228:229], s[30:31], v[4:5] op_sel_hi:[1,0,1]
	v_pk_fma_f32 v[6:7], v[230:231], s[30:31], v[6:7] op_sel_hi:[1,0,1]
	v_pk_fma_f32 v[8:9], v[232:233], s[30:31], v[8:9] op_sel_hi:[1,0,1]
	v_pk_fma_f32 v[10:11], v[234:235], s[30:31], v[10:11] op_sel_hi:[1,0,1]
	v_pk_fma_f32 v[12:13], v[236:237], s[30:31], v[12:13] op_sel_hi:[1,0,1]
	v_pk_fma_f32 v[14:15], v[238:239], s[30:31], v[14:15] op_sel_hi:[1,0,1]
	v_readlane_b32 s16, v135, s72
	v_readlane_b32 s18, v135, s73
	v_readlane_b32 s20, v135, s74
	v_readlane_b32 s22, v135, s75
	v_readlane_b32 s24, v135, s76
	v_readlane_b32 s26, v135, s77
	v_readlane_b32 s28, v135, s78
	v_readlane_b32 s30, v135, s79
	v_readlane_b32 s48, v137, s72
	v_readlane_b32 s49, v137, s73
	v_readlane_b32 s50, v137, s74
	v_readlane_b32 s51, v137, s75
	v_readlane_b32 s52, v137, s76
	v_readlane_b32 s53, v137, s77
	v_readlane_b32 s54, v137, s78
	v_readlane_b32 s55, v137, s79
	s_add_u32 s32, s0, s48
	s_addc_u32 s33, s1, 0
	s_add_u32 s34, s0, s49
	s_addc_u32 s35, s1, 0
	s_add_u32 s36, s0, s50
	s_addc_u32 s37, s1, 0
	s_add_u32 s38, s0, s51
	s_addc_u32 s39, s1, 0
	s_add_u32 s40, s0, s52
	s_addc_u32 s41, s1, 0
	s_add_u32 s42, s0, s53
	s_addc_u32 s43, s1, 0
	s_add_u32 s44, s0, s54
	s_addc_u32 s45, s1, 0
	s_add_u32 s46, s0, s55
	s_addc_u32 s47, s1, 0
	global_load_dwordx4 v[160:163], v240, s[32:33]
	global_load_dwordx4 v[164:167], v240, s[34:35]
	global_load_dwordx4 v[168:171], v240, s[36:37]
	global_load_dwordx4 v[172:175], v240, s[38:39]
	global_load_dwordx4 v[176:179], v240, s[40:41]
	global_load_dwordx4 v[180:183], v240, s[42:43]
	global_load_dwordx4 v[184:187], v240, s[44:45]
	global_load_dwordx4 v[188:191], v240, s[46:47]
	s_waitcnt vmcnt(8)
	v_cvt_pk_f32_fp8_e32 v[224:225], v192
	v_cvt_pk_f32_fp8_sdwa v[226:227], v192 src0_sel:WORD_1
	v_cvt_pk_f32_fp8_e32 v[228:229], v193
	v_cvt_pk_f32_fp8_sdwa v[230:231], v193 src0_sel:WORD_1
	v_cvt_pk_f32_fp8_e32 v[232:233], v194
	v_cvt_pk_f32_fp8_sdwa v[234:235], v194 src0_sel:WORD_1
	v_cvt_pk_f32_fp8_e32 v[236:237], v195
	v_cvt_pk_f32_fp8_sdwa v[238:239], v195 src0_sel:WORD_1
	v_pk_fma_f32 v[16:17], v[224:225], s[16:17], v[16:17] op_sel_hi:[1,0,1]
	v_pk_fma_f32 v[18:19], v[226:227], s[16:17], v[18:19] op_sel_hi:[1,0,1]
	v_pk_fma_f32 v[20:21], v[228:229], s[16:17], v[20:21] op_sel_hi:[1,0,1]
	v_pk_fma_f32 v[22:23], v[230:231], s[16:17], v[22:23] op_sel_hi:[1,0,1]
	v_pk_fma_f32 v[24:25], v[232:233], s[16:17], v[24:25] op_sel_hi:[1,0,1]
	v_pk_fma_f32 v[26:27], v[234:235], s[16:17], v[26:27] op_sel_hi:[1,0,1]
	v_pk_fma_f32 v[28:29], v[236:237], s[16:17], v[28:29] op_sel_hi:[1,0,1]
	v_pk_fma_f32 v[30:31], v[238:239], s[16:17], v[30:31] op_sel_hi:[1,0,1]
	v_cvt_pk_f32_fp8_e32 v[224:225], v196
	v_cvt_pk_f32_fp8_sdwa v[226:227], v196 src0_sel:WORD_1
	v_cvt_pk_f32_fp8_e32 v[228:229], v197
	v_cvt_pk_f32_fp8_sdwa v[230:231], v197 src0_sel:WORD_1
	v_cvt_pk_f32_fp8_e32 v[232:233], v198
	v_cvt_pk_f32_fp8_sdwa v[234:235], v198 src0_sel:WORD_1
	v_cvt_pk_f32_fp8_e32 v[236:237], v199
	v_cvt_pk_f32_fp8_sdwa v[238:239], v199 src0_sel:WORD_1
	v_pk_fma_f32 v[16:17], v[224:225], s[18:19], v[16:17] op_sel_hi:[1,0,1]
	v_pk_fma_f32 v[18:19], v[226:227], s[18:19], v[18:19] op_sel_hi:[1,0,1]
	v_pk_fma_f32 v[20:21], v[228:229], s[18:19], v[20:21] op_sel_hi:[1,0,1]
	v_pk_fma_f32 v[22:23], v[230:231], s[18:19], v[22:23] op_sel_hi:[1,0,1]
	v_pk_fma_f32 v[24:25], v[232:233], s[18:19], v[24:25] op_sel_hi:[1,0,1]
	v_pk_fma_f32 v[26:27], v[234:235], s[18:19], v[26:27] op_sel_hi:[1,0,1]
	v_pk_fma_f32 v[28:29], v[236:237], s[18:19], v[28:29] op_sel_hi:[1,0,1]
	v_pk_fma_f32 v[30:31], v[238:239], s[18:19], v[30:31] op_sel_hi:[1,0,1]
	v_cvt_pk_f32_fp8_e32 v[224:225], v200
	v_cvt_pk_f32_fp8_sdwa v[226:227], v200 src0_sel:WORD_1
	v_cvt_pk_f32_fp8_e32 v[228:229], v201
	v_cvt_pk_f32_fp8_sdwa v[230:231], v201 src0_sel:WORD_1
	v_cvt_pk_f32_fp8_e32 v[232:233], v202
	v_cvt_pk_f32_fp8_sdwa v[234:235], v202 src0_sel:WORD_1
	v_cvt_pk_f32_fp8_e32 v[236:237], v203
	v_cvt_pk_f32_fp8_sdwa v[238:239], v203 src0_sel:WORD_1
	v_pk_fma_f32 v[16:17], v[224:225], s[20:21], v[16:17] op_sel_hi:[1,0,1]
	v_pk_fma_f32 v[18:19], v[226:227], s[20:21], v[18:19] op_sel_hi:[1,0,1]
	v_pk_fma_f32 v[20:21], v[228:229], s[20:21], v[20:21] op_sel_hi:[1,0,1]
	v_pk_fma_f32 v[22:23], v[230:231], s[20:21], v[22:23] op_sel_hi:[1,0,1]
	v_pk_fma_f32 v[24:25], v[232:233], s[20:21], v[24:25] op_sel_hi:[1,0,1]
	v_pk_fma_f32 v[26:27], v[234:235], s[20:21], v[26:27] op_sel_hi:[1,0,1]
	v_pk_fma_f32 v[28:29], v[236:237], s[20:21], v[28:29] op_sel_hi:[1,0,1]
	v_pk_fma_f32 v[30:31], v[238:239], s[20:21], v[30:31] op_sel_hi:[1,0,1]
	v_cvt_pk_f32_fp8_e32 v[224:225], v204
	v_cvt_pk_f32_fp8_sdwa v[226:227], v204 src0_sel:WORD_1
	v_cvt_pk_f32_fp8_e32 v[228:229], v205
	v_cvt_pk_f32_fp8_sdwa v[230:231], v205 src0_sel:WORD_1
	v_cvt_pk_f32_fp8_e32 v[232:233], v206
	v_cvt_pk_f32_fp8_sdwa v[234:235], v206 src0_sel:WORD_1
	v_cvt_pk_f32_fp8_e32 v[236:237], v207
	v_cvt_pk_f32_fp8_sdwa v[238:239], v207 src0_sel:WORD_1
	v_pk_fma_f32 v[16:17], v[224:225], s[22:23], v[16:17] op_sel_hi:[1,0,1]
	v_pk_fma_f32 v[18:19], v[226:227], s[22:23], v[18:19] op_sel_hi:[1,0,1]
	v_pk_fma_f32 v[20:21], v[228:229], s[22:23], v[20:21] op_sel_hi:[1,0,1]
	v_pk_fma_f32 v[22:23], v[230:231], s[22:23], v[22:23] op_sel_hi:[1,0,1]
	v_pk_fma_f32 v[24:25], v[232:233], s[22:23], v[24:25] op_sel_hi:[1,0,1]
	v_pk_fma_f32 v[26:27], v[234:235], s[22:23], v[26:27] op_sel_hi:[1,0,1]
	v_pk_fma_f32 v[28:29], v[236:237], s[22:23], v[28:29] op_sel_hi:[1,0,1]
	v_pk_fma_f32 v[30:31], v[238:239], s[22:23], v[30:31] op_sel_hi:[1,0,1]
	v_cvt_pk_f32_fp8_e32 v[224:225], v208
	v_cvt_pk_f32_fp8_sdwa v[226:227], v208 src0_sel:WORD_1
	v_cvt_pk_f32_fp8_e32 v[228:229], v209
	v_cvt_pk_f32_fp8_sdwa v[230:231], v209 src0_sel:WORD_1
	v_cvt_pk_f32_fp8_e32 v[232:233], v210
	v_cvt_pk_f32_fp8_sdwa v[234:235], v210 src0_sel:WORD_1
	v_cvt_pk_f32_fp8_e32 v[236:237], v211
	v_cvt_pk_f32_fp8_sdwa v[238:239], v211 src0_sel:WORD_1
	v_pk_fma_f32 v[16:17], v[224:225], s[24:25], v[16:17] op_sel_hi:[1,0,1]
	v_pk_fma_f32 v[18:19], v[226:227], s[24:25], v[18:19] op_sel_hi:[1,0,1]
	v_pk_fma_f32 v[20:21], v[228:229], s[24:25], v[20:21] op_sel_hi:[1,0,1]
	v_pk_fma_f32 v[22:23], v[230:231], s[24:25], v[22:23] op_sel_hi:[1,0,1]
	v_pk_fma_f32 v[24:25], v[232:233], s[24:25], v[24:25] op_sel_hi:[1,0,1]
	v_pk_fma_f32 v[26:27], v[234:235], s[24:25], v[26:27] op_sel_hi:[1,0,1]
	v_pk_fma_f32 v[28:29], v[236:237], s[24:25], v[28:29] op_sel_hi:[1,0,1]
	v_pk_fma_f32 v[30:31], v[238:239], s[24:25], v[30:31] op_sel_hi:[1,0,1]
	v_cvt_pk_f32_fp8_e32 v[224:225], v212
	v_cvt_pk_f32_fp8_sdwa v[226:227], v212 src0_sel:WORD_1
	v_cvt_pk_f32_fp8_e32 v[228:229], v213
	v_cvt_pk_f32_fp8_sdwa v[230:231], v213 src0_sel:WORD_1
	v_cvt_pk_f32_fp8_e32 v[232:233], v214
	v_cvt_pk_f32_fp8_sdwa v[234:235], v214 src0_sel:WORD_1
	v_cvt_pk_f32_fp8_e32 v[236:237], v215
	v_cvt_pk_f32_fp8_sdwa v[238:239], v215 src0_sel:WORD_1
	v_pk_fma_f32 v[16:17], v[224:225], s[26:27], v[16:17] op_sel_hi:[1,0,1]
	v_pk_fma_f32 v[18:19], v[226:227], s[26:27], v[18:19] op_sel_hi:[1,0,1]
	v_pk_fma_f32 v[20:21], v[228:229], s[26:27], v[20:21] op_sel_hi:[1,0,1]
	v_pk_fma_f32 v[22:23], v[230:231], s[26:27], v[22:23] op_sel_hi:[1,0,1]
	v_pk_fma_f32 v[24:25], v[232:233], s[26:27], v[24:25] op_sel_hi:[1,0,1]
	v_pk_fma_f32 v[26:27], v[234:235], s[26:27], v[26:27] op_sel_hi:[1,0,1]
	v_pk_fma_f32 v[28:29], v[236:237], s[26:27], v[28:29] op_sel_hi:[1,0,1]
	v_pk_fma_f32 v[30:31], v[238:239], s[26:27], v[30:31] op_sel_hi:[1,0,1]
	v_cvt_pk_f32_fp8_e32 v[224:225], v216
	v_cvt_pk_f32_fp8_sdwa v[226:227], v216 src0_sel:WORD_1
	v_cvt_pk_f32_fp8_e32 v[228:229], v217
	v_cvt_pk_f32_fp8_sdwa v[230:231], v217 src0_sel:WORD_1
	v_cvt_pk_f32_fp8_e32 v[232:233], v218
	v_cvt_pk_f32_fp8_sdwa v[234:235], v218 src0_sel:WORD_1
	v_cvt_pk_f32_fp8_e32 v[236:237], v219
	v_cvt_pk_f32_fp8_sdwa v[238:239], v219 src0_sel:WORD_1
	v_pk_fma_f32 v[16:17], v[224:225], s[28:29], v[16:17] op_sel_hi:[1,0,1]
	v_pk_fma_f32 v[18:19], v[226:227], s[28:29], v[18:19] op_sel_hi:[1,0,1]
	v_pk_fma_f32 v[20:21], v[228:229], s[28:29], v[20:21] op_sel_hi:[1,0,1]
	v_pk_fma_f32 v[22:23], v[230:231], s[28:29], v[22:23] op_sel_hi:[1,0,1]
	v_pk_fma_f32 v[24:25], v[232:233], s[28:29], v[24:25] op_sel_hi:[1,0,1]
	v_pk_fma_f32 v[26:27], v[234:235], s[28:29], v[26:27] op_sel_hi:[1,0,1]
	v_pk_fma_f32 v[28:29], v[236:237], s[28:29], v[28:29] op_sel_hi:[1,0,1]
	v_pk_fma_f32 v[30:31], v[238:239], s[28:29], v[30:31] op_sel_hi:[1,0,1]
	v_cvt_pk_f32_fp8_e32 v[224:225], v220
	v_cvt_pk_f32_fp8_sdwa v[226:227], v220 src0_sel:WORD_1
	v_cvt_pk_f32_fp8_e32 v[228:229], v221
	v_cvt_pk_f32_fp8_sdwa v[230:231], v221 src0_sel:WORD_1
	v_cvt_pk_f32_fp8_e32 v[232:233], v222
	v_cvt_pk_f32_fp8_sdwa v[234:235], v222 src0_sel:WORD_1
	v_cvt_pk_f32_fp8_e32 v[236:237], v223
	v_cvt_pk_f32_fp8_sdwa v[238:239], v223 src0_sel:WORD_1
	v_pk_fma_f32 v[16:17], v[224:225], s[30:31], v[16:17] op_sel_hi:[1,0,1]
	v_pk_fma_f32 v[18:19], v[226:227], s[30:31], v[18:19] op_sel_hi:[1,0,1]
	v_pk_fma_f32 v[20:21], v[228:229], s[30:31], v[20:21] op_sel_hi:[1,0,1]
	v_pk_fma_f32 v[22:23], v[230:231], s[30:31], v[22:23] op_sel_hi:[1,0,1]
	v_pk_fma_f32 v[24:25], v[232:233], s[30:31], v[24:25] op_sel_hi:[1,0,1]
	v_pk_fma_f32 v[26:27], v[234:235], s[30:31], v[26:27] op_sel_hi:[1,0,1]
	v_pk_fma_f32 v[28:29], v[236:237], s[30:31], v[28:29] op_sel_hi:[1,0,1]
	v_pk_fma_f32 v[30:31], v[238:239], s[30:31], v[30:31] op_sel_hi:[1,0,1]
	v_readlane_b32 s16, v139, s72
	v_readlane_b32 s18, v139, s73
	v_readlane_b32 s20, v139, s74
	v_readlane_b32 s22, v139, s75
	v_readlane_b32 s24, v139, s76
	v_readlane_b32 s26, v139, s77
	v_readlane_b32 s28, v139, s78
	v_readlane_b32 s30, v139, s79
	v_readlane_b32 s48, v141, s72
	v_readlane_b32 s49, v141, s73
	v_readlane_b32 s50, v141, s74
	v_readlane_b32 s51, v141, s75
	v_readlane_b32 s52, v141, s76
	v_readlane_b32 s53, v141, s77
	v_readlane_b32 s54, v141, s78
	v_readlane_b32 s55, v141, s79
	s_add_u32 s32, s0, s48
	s_addc_u32 s33, s1, 0
	s_add_u32 s34, s0, s49
	s_addc_u32 s35, s1, 0
	s_add_u32 s36, s0, s50
	s_addc_u32 s37, s1, 0
	s_add_u32 s38, s0, s51
	s_addc_u32 s39, s1, 0
	s_add_u32 s40, s0, s52
	s_addc_u32 s41, s1, 0
	s_add_u32 s42, s0, s53
	s_addc_u32 s43, s1, 0
	s_add_u32 s44, s0, s54
	s_addc_u32 s45, s1, 0
	s_add_u32 s46, s0, s55
	s_addc_u32 s47, s1, 0
	global_load_dwordx4 v[192:195], v240, s[32:33]
	global_load_dwordx4 v[196:199], v240, s[34:35]
	global_load_dwordx4 v[200:203], v240, s[36:37]
	global_load_dwordx4 v[204:207], v240, s[38:39]
	global_load_dwordx4 v[208:211], v240, s[40:41]
	global_load_dwordx4 v[212:215], v240, s[42:43]
	global_load_dwordx4 v[216:219], v240, s[44:45]
	global_load_dwordx4 v[220:223], v240, s[46:47]
	s_waitcnt vmcnt(8)
	v_cvt_pk_f32_fp8_e32 v[224:225], v160
	v_cvt_pk_f32_fp8_sdwa v[226:227], v160 src0_sel:WORD_1
	v_cvt_pk_f32_fp8_e32 v[228:229], v161
	v_cvt_pk_f32_fp8_sdwa v[230:231], v161 src0_sel:WORD_1
	v_cvt_pk_f32_fp8_e32 v[232:233], v162
	v_cvt_pk_f32_fp8_sdwa v[234:235], v162 src0_sel:WORD_1
	v_cvt_pk_f32_fp8_e32 v[236:237], v163
	v_cvt_pk_f32_fp8_sdwa v[238:239], v163 src0_sel:WORD_1
	v_pk_fma_f32 v[32:33], v[224:225], s[16:17], v[32:33] op_sel_hi:[1,0,1]
	v_pk_fma_f32 v[34:35], v[226:227], s[16:17], v[34:35] op_sel_hi:[1,0,1]
	v_pk_fma_f32 v[36:37], v[228:229], s[16:17], v[36:37] op_sel_hi:[1,0,1]
	v_pk_fma_f32 v[38:39], v[230:231], s[16:17], v[38:39] op_sel_hi:[1,0,1]
	v_pk_fma_f32 v[40:41], v[232:233], s[16:17], v[40:41] op_sel_hi:[1,0,1]
	v_pk_fma_f32 v[42:43], v[234:235], s[16:17], v[42:43] op_sel_hi:[1,0,1]
	v_pk_fma_f32 v[44:45], v[236:237], s[16:17], v[44:45] op_sel_hi:[1,0,1]
	v_pk_fma_f32 v[46:47], v[238:239], s[16:17], v[46:47] op_sel_hi:[1,0,1]
	v_cvt_pk_f32_fp8_e32 v[224:225], v164
	v_cvt_pk_f32_fp8_sdwa v[226:227], v164 src0_sel:WORD_1
	v_cvt_pk_f32_fp8_e32 v[228:229], v165
	v_cvt_pk_f32_fp8_sdwa v[230:231], v165 src0_sel:WORD_1
	v_cvt_pk_f32_fp8_e32 v[232:233], v166
	v_cvt_pk_f32_fp8_sdwa v[234:235], v166 src0_sel:WORD_1
	v_cvt_pk_f32_fp8_e32 v[236:237], v167
	v_cvt_pk_f32_fp8_sdwa v[238:239], v167 src0_sel:WORD_1
	v_pk_fma_f32 v[32:33], v[224:225], s[18:19], v[32:33] op_sel_hi:[1,0,1]
	v_pk_fma_f32 v[34:35], v[226:227], s[18:19], v[34:35] op_sel_hi:[1,0,1]
	v_pk_fma_f32 v[36:37], v[228:229], s[18:19], v[36:37] op_sel_hi:[1,0,1]
	v_pk_fma_f32 v[38:39], v[230:231], s[18:19], v[38:39] op_sel_hi:[1,0,1]
	v_pk_fma_f32 v[40:41], v[232:233], s[18:19], v[40:41] op_sel_hi:[1,0,1]
	v_pk_fma_f32 v[42:43], v[234:235], s[18:19], v[42:43] op_sel_hi:[1,0,1]
	v_pk_fma_f32 v[44:45], v[236:237], s[18:19], v[44:45] op_sel_hi:[1,0,1]
	v_pk_fma_f32 v[46:47], v[238:239], s[18:19], v[46:47] op_sel_hi:[1,0,1]
	v_cvt_pk_f32_fp8_e32 v[224:225], v168
	v_cvt_pk_f32_fp8_sdwa v[226:227], v168 src0_sel:WORD_1
	v_cvt_pk_f32_fp8_e32 v[228:229], v169
	v_cvt_pk_f32_fp8_sdwa v[230:231], v169 src0_sel:WORD_1
	v_cvt_pk_f32_fp8_e32 v[232:233], v170
	v_cvt_pk_f32_fp8_sdwa v[234:235], v170 src0_sel:WORD_1
	v_cvt_pk_f32_fp8_e32 v[236:237], v171
	v_cvt_pk_f32_fp8_sdwa v[238:239], v171 src0_sel:WORD_1
	v_pk_fma_f32 v[32:33], v[224:225], s[20:21], v[32:33] op_sel_hi:[1,0,1]
	v_pk_fma_f32 v[34:35], v[226:227], s[20:21], v[34:35] op_sel_hi:[1,0,1]
	v_pk_fma_f32 v[36:37], v[228:229], s[20:21], v[36:37] op_sel_hi:[1,0,1]
	v_pk_fma_f32 v[38:39], v[230:231], s[20:21], v[38:39] op_sel_hi:[1,0,1]
	v_pk_fma_f32 v[40:41], v[232:233], s[20:21], v[40:41] op_sel_hi:[1,0,1]
	v_pk_fma_f32 v[42:43], v[234:235], s[20:21], v[42:43] op_sel_hi:[1,0,1]
	v_pk_fma_f32 v[44:45], v[236:237], s[20:21], v[44:45] op_sel_hi:[1,0,1]
	v_pk_fma_f32 v[46:47], v[238:239], s[20:21], v[46:47] op_sel_hi:[1,0,1]
	v_cvt_pk_f32_fp8_e32 v[224:225], v172
	v_cvt_pk_f32_fp8_sdwa v[226:227], v172 src0_sel:WORD_1
	v_cvt_pk_f32_fp8_e32 v[228:229], v173
	v_cvt_pk_f32_fp8_sdwa v[230:231], v173 src0_sel:WORD_1
	v_cvt_pk_f32_fp8_e32 v[232:233], v174
	v_cvt_pk_f32_fp8_sdwa v[234:235], v174 src0_sel:WORD_1
	v_cvt_pk_f32_fp8_e32 v[236:237], v175
	v_cvt_pk_f32_fp8_sdwa v[238:239], v175 src0_sel:WORD_1
	v_pk_fma_f32 v[32:33], v[224:225], s[22:23], v[32:33] op_sel_hi:[1,0,1]
	v_pk_fma_f32 v[34:35], v[226:227], s[22:23], v[34:35] op_sel_hi:[1,0,1]
	v_pk_fma_f32 v[36:37], v[228:229], s[22:23], v[36:37] op_sel_hi:[1,0,1]
	v_pk_fma_f32 v[38:39], v[230:231], s[22:23], v[38:39] op_sel_hi:[1,0,1]
	v_pk_fma_f32 v[40:41], v[232:233], s[22:23], v[40:41] op_sel_hi:[1,0,1]
	v_pk_fma_f32 v[42:43], v[234:235], s[22:23], v[42:43] op_sel_hi:[1,0,1]
	v_pk_fma_f32 v[44:45], v[236:237], s[22:23], v[44:45] op_sel_hi:[1,0,1]
	v_pk_fma_f32 v[46:47], v[238:239], s[22:23], v[46:47] op_sel_hi:[1,0,1]
	v_cvt_pk_f32_fp8_e32 v[224:225], v176
	v_cvt_pk_f32_fp8_sdwa v[226:227], v176 src0_sel:WORD_1
	v_cvt_pk_f32_fp8_e32 v[228:229], v177
	v_cvt_pk_f32_fp8_sdwa v[230:231], v177 src0_sel:WORD_1
	v_cvt_pk_f32_fp8_e32 v[232:233], v178
	v_cvt_pk_f32_fp8_sdwa v[234:235], v178 src0_sel:WORD_1
	v_cvt_pk_f32_fp8_e32 v[236:237], v179
	v_cvt_pk_f32_fp8_sdwa v[238:239], v179 src0_sel:WORD_1
	v_pk_fma_f32 v[32:33], v[224:225], s[24:25], v[32:33] op_sel_hi:[1,0,1]
	v_pk_fma_f32 v[34:35], v[226:227], s[24:25], v[34:35] op_sel_hi:[1,0,1]
	v_pk_fma_f32 v[36:37], v[228:229], s[24:25], v[36:37] op_sel_hi:[1,0,1]
	v_pk_fma_f32 v[38:39], v[230:231], s[24:25], v[38:39] op_sel_hi:[1,0,1]
	v_pk_fma_f32 v[40:41], v[232:233], s[24:25], v[40:41] op_sel_hi:[1,0,1]
	v_pk_fma_f32 v[42:43], v[234:235], s[24:25], v[42:43] op_sel_hi:[1,0,1]
	v_pk_fma_f32 v[44:45], v[236:237], s[24:25], v[44:45] op_sel_hi:[1,0,1]
	v_pk_fma_f32 v[46:47], v[238:239], s[24:25], v[46:47] op_sel_hi:[1,0,1]
	v_cvt_pk_f32_fp8_e32 v[224:225], v180
	v_cvt_pk_f32_fp8_sdwa v[226:227], v180 src0_sel:WORD_1
	v_cvt_pk_f32_fp8_e32 v[228:229], v181
	v_cvt_pk_f32_fp8_sdwa v[230:231], v181 src0_sel:WORD_1
	v_cvt_pk_f32_fp8_e32 v[232:233], v182
	v_cvt_pk_f32_fp8_sdwa v[234:235], v182 src0_sel:WORD_1
	v_cvt_pk_f32_fp8_e32 v[236:237], v183
	v_cvt_pk_f32_fp8_sdwa v[238:239], v183 src0_sel:WORD_1
	v_pk_fma_f32 v[32:33], v[224:225], s[26:27], v[32:33] op_sel_hi:[1,0,1]
	v_pk_fma_f32 v[34:35], v[226:227], s[26:27], v[34:35] op_sel_hi:[1,0,1]
	v_pk_fma_f32 v[36:37], v[228:229], s[26:27], v[36:37] op_sel_hi:[1,0,1]
	v_pk_fma_f32 v[38:39], v[230:231], s[26:27], v[38:39] op_sel_hi:[1,0,1]
	v_pk_fma_f32 v[40:41], v[232:233], s[26:27], v[40:41] op_sel_hi:[1,0,1]
	v_pk_fma_f32 v[42:43], v[234:235], s[26:27], v[42:43] op_sel_hi:[1,0,1]
	v_pk_fma_f32 v[44:45], v[236:237], s[26:27], v[44:45] op_sel_hi:[1,0,1]
	v_pk_fma_f32 v[46:47], v[238:239], s[26:27], v[46:47] op_sel_hi:[1,0,1]
	v_cvt_pk_f32_fp8_e32 v[224:225], v184
	v_cvt_pk_f32_fp8_sdwa v[226:227], v184 src0_sel:WORD_1
	v_cvt_pk_f32_fp8_e32 v[228:229], v185
	v_cvt_pk_f32_fp8_sdwa v[230:231], v185 src0_sel:WORD_1
	v_cvt_pk_f32_fp8_e32 v[232:233], v186
	v_cvt_pk_f32_fp8_sdwa v[234:235], v186 src0_sel:WORD_1
	v_cvt_pk_f32_fp8_e32 v[236:237], v187
	v_cvt_pk_f32_fp8_sdwa v[238:239], v187 src0_sel:WORD_1
	v_pk_fma_f32 v[32:33], v[224:225], s[28:29], v[32:33] op_sel_hi:[1,0,1]
	v_pk_fma_f32 v[34:35], v[226:227], s[28:29], v[34:35] op_sel_hi:[1,0,1]
	v_pk_fma_f32 v[36:37], v[228:229], s[28:29], v[36:37] op_sel_hi:[1,0,1]
	v_pk_fma_f32 v[38:39], v[230:231], s[28:29], v[38:39] op_sel_hi:[1,0,1]
	v_pk_fma_f32 v[40:41], v[232:233], s[28:29], v[40:41] op_sel_hi:[1,0,1]
	v_pk_fma_f32 v[42:43], v[234:235], s[28:29], v[42:43] op_sel_hi:[1,0,1]
	v_pk_fma_f32 v[44:45], v[236:237], s[28:29], v[44:45] op_sel_hi:[1,0,1]
	v_pk_fma_f32 v[46:47], v[238:239], s[28:29], v[46:47] op_sel_hi:[1,0,1]
	v_cvt_pk_f32_fp8_e32 v[224:225], v188
	v_cvt_pk_f32_fp8_sdwa v[226:227], v188 src0_sel:WORD_1
	v_cvt_pk_f32_fp8_e32 v[228:229], v189
	v_cvt_pk_f32_fp8_sdwa v[230:231], v189 src0_sel:WORD_1
	v_cvt_pk_f32_fp8_e32 v[232:233], v190
	v_cvt_pk_f32_fp8_sdwa v[234:235], v190 src0_sel:WORD_1
	v_cvt_pk_f32_fp8_e32 v[236:237], v191
	v_cvt_pk_f32_fp8_sdwa v[238:239], v191 src0_sel:WORD_1
	v_pk_fma_f32 v[32:33], v[224:225], s[30:31], v[32:33] op_sel_hi:[1,0,1]
	v_pk_fma_f32 v[34:35], v[226:227], s[30:31], v[34:35] op_sel_hi:[1,0,1]
	v_pk_fma_f32 v[36:37], v[228:229], s[30:31], v[36:37] op_sel_hi:[1,0,1]
	v_pk_fma_f32 v[38:39], v[230:231], s[30:31], v[38:39] op_sel_hi:[1,0,1]
	v_pk_fma_f32 v[40:41], v[232:233], s[30:31], v[40:41] op_sel_hi:[1,0,1]
	v_pk_fma_f32 v[42:43], v[234:235], s[30:31], v[42:43] op_sel_hi:[1,0,1]
	v_pk_fma_f32 v[44:45], v[236:237], s[30:31], v[44:45] op_sel_hi:[1,0,1]
	v_pk_fma_f32 v[46:47], v[238:239], s[30:31], v[46:47] op_sel_hi:[1,0,1]
	v_readlane_b32 s16, v143, s72
	v_readlane_b32 s18, v143, s73
	v_readlane_b32 s20, v143, s74
	v_readlane_b32 s22, v143, s75
	v_readlane_b32 s24, v143, s76
	v_readlane_b32 s26, v143, s77
	v_readlane_b32 s28, v143, s78
	v_readlane_b32 s30, v143, s79
	v_readlane_b32 s48, v145, s72
	v_readlane_b32 s49, v145, s73
	v_readlane_b32 s50, v145, s74
	v_readlane_b32 s51, v145, s75
	v_readlane_b32 s52, v145, s76
	v_readlane_b32 s53, v145, s77
	v_readlane_b32 s54, v145, s78
	v_readlane_b32 s55, v145, s79
	s_add_u32 s32, s0, s48
	s_addc_u32 s33, s1, 0
	s_add_u32 s34, s0, s49
	s_addc_u32 s35, s1, 0
	s_add_u32 s36, s0, s50
	s_addc_u32 s37, s1, 0
	s_add_u32 s38, s0, s51
	s_addc_u32 s39, s1, 0
	s_add_u32 s40, s0, s52
	s_addc_u32 s41, s1, 0
	s_add_u32 s42, s0, s53
	s_addc_u32 s43, s1, 0
	s_add_u32 s44, s0, s54
	s_addc_u32 s45, s1, 0
	s_add_u32 s46, s0, s55
	s_addc_u32 s47, s1, 0
	global_load_dwordx4 v[160:163], v240, s[32:33]
	global_load_dwordx4 v[164:167], v240, s[34:35]
	global_load_dwordx4 v[168:171], v240, s[36:37]
	global_load_dwordx4 v[172:175], v240, s[38:39]
	global_load_dwordx4 v[176:179], v240, s[40:41]
	global_load_dwordx4 v[180:183], v240, s[42:43]
	global_load_dwordx4 v[184:187], v240, s[44:45]
	global_load_dwordx4 v[188:191], v240, s[46:47]
	s_waitcnt vmcnt(8)
	v_cvt_pk_f32_fp8_e32 v[224:225], v192
	v_cvt_pk_f32_fp8_sdwa v[226:227], v192 src0_sel:WORD_1
	v_cvt_pk_f32_fp8_e32 v[228:229], v193
	v_cvt_pk_f32_fp8_sdwa v[230:231], v193 src0_sel:WORD_1
	v_cvt_pk_f32_fp8_e32 v[232:233], v194
	v_cvt_pk_f32_fp8_sdwa v[234:235], v194 src0_sel:WORD_1
	v_cvt_pk_f32_fp8_e32 v[236:237], v195
	v_cvt_pk_f32_fp8_sdwa v[238:239], v195 src0_sel:WORD_1
	v_pk_fma_f32 v[48:49], v[224:225], s[16:17], v[48:49] op_sel_hi:[1,0,1]
	v_pk_fma_f32 v[50:51], v[226:227], s[16:17], v[50:51] op_sel_hi:[1,0,1]
	v_pk_fma_f32 v[52:53], v[228:229], s[16:17], v[52:53] op_sel_hi:[1,0,1]
	v_pk_fma_f32 v[54:55], v[230:231], s[16:17], v[54:55] op_sel_hi:[1,0,1]
	v_pk_fma_f32 v[56:57], v[232:233], s[16:17], v[56:57] op_sel_hi:[1,0,1]
	v_pk_fma_f32 v[58:59], v[234:235], s[16:17], v[58:59] op_sel_hi:[1,0,1]
	v_pk_fma_f32 v[60:61], v[236:237], s[16:17], v[60:61] op_sel_hi:[1,0,1]
	v_pk_fma_f32 v[62:63], v[238:239], s[16:17], v[62:63] op_sel_hi:[1,0,1]
	v_cvt_pk_f32_fp8_e32 v[224:225], v196
	v_cvt_pk_f32_fp8_sdwa v[226:227], v196 src0_sel:WORD_1
	v_cvt_pk_f32_fp8_e32 v[228:229], v197
	v_cvt_pk_f32_fp8_sdwa v[230:231], v197 src0_sel:WORD_1
	v_cvt_pk_f32_fp8_e32 v[232:233], v198
	v_cvt_pk_f32_fp8_sdwa v[234:235], v198 src0_sel:WORD_1
	v_cvt_pk_f32_fp8_e32 v[236:237], v199
	v_cvt_pk_f32_fp8_sdwa v[238:239], v199 src0_sel:WORD_1
	v_pk_fma_f32 v[48:49], v[224:225], s[18:19], v[48:49] op_sel_hi:[1,0,1]
	v_pk_fma_f32 v[50:51], v[226:227], s[18:19], v[50:51] op_sel_hi:[1,0,1]
	v_pk_fma_f32 v[52:53], v[228:229], s[18:19], v[52:53] op_sel_hi:[1,0,1]
	v_pk_fma_f32 v[54:55], v[230:231], s[18:19], v[54:55] op_sel_hi:[1,0,1]
	v_pk_fma_f32 v[56:57], v[232:233], s[18:19], v[56:57] op_sel_hi:[1,0,1]
	v_pk_fma_f32 v[58:59], v[234:235], s[18:19], v[58:59] op_sel_hi:[1,0,1]
	v_pk_fma_f32 v[60:61], v[236:237], s[18:19], v[60:61] op_sel_hi:[1,0,1]
	v_pk_fma_f32 v[62:63], v[238:239], s[18:19], v[62:63] op_sel_hi:[1,0,1]
	v_cvt_pk_f32_fp8_e32 v[224:225], v200
	v_cvt_pk_f32_fp8_sdwa v[226:227], v200 src0_sel:WORD_1
	v_cvt_pk_f32_fp8_e32 v[228:229], v201
	v_cvt_pk_f32_fp8_sdwa v[230:231], v201 src0_sel:WORD_1
	v_cvt_pk_f32_fp8_e32 v[232:233], v202
	v_cvt_pk_f32_fp8_sdwa v[234:235], v202 src0_sel:WORD_1
	v_cvt_pk_f32_fp8_e32 v[236:237], v203
	v_cvt_pk_f32_fp8_sdwa v[238:239], v203 src0_sel:WORD_1
	v_pk_fma_f32 v[48:49], v[224:225], s[20:21], v[48:49] op_sel_hi:[1,0,1]
	v_pk_fma_f32 v[50:51], v[226:227], s[20:21], v[50:51] op_sel_hi:[1,0,1]
	v_pk_fma_f32 v[52:53], v[228:229], s[20:21], v[52:53] op_sel_hi:[1,0,1]
	v_pk_fma_f32 v[54:55], v[230:231], s[20:21], v[54:55] op_sel_hi:[1,0,1]
	v_pk_fma_f32 v[56:57], v[232:233], s[20:21], v[56:57] op_sel_hi:[1,0,1]
	v_pk_fma_f32 v[58:59], v[234:235], s[20:21], v[58:59] op_sel_hi:[1,0,1]
	v_pk_fma_f32 v[60:61], v[236:237], s[20:21], v[60:61] op_sel_hi:[1,0,1]
	v_pk_fma_f32 v[62:63], v[238:239], s[20:21], v[62:63] op_sel_hi:[1,0,1]
	v_cvt_pk_f32_fp8_e32 v[224:225], v204
	v_cvt_pk_f32_fp8_sdwa v[226:227], v204 src0_sel:WORD_1
	v_cvt_pk_f32_fp8_e32 v[228:229], v205
	v_cvt_pk_f32_fp8_sdwa v[230:231], v205 src0_sel:WORD_1
	v_cvt_pk_f32_fp8_e32 v[232:233], v206
	v_cvt_pk_f32_fp8_sdwa v[234:235], v206 src0_sel:WORD_1
	v_cvt_pk_f32_fp8_e32 v[236:237], v207
	v_cvt_pk_f32_fp8_sdwa v[238:239], v207 src0_sel:WORD_1
	v_pk_fma_f32 v[48:49], v[224:225], s[22:23], v[48:49] op_sel_hi:[1,0,1]
	v_pk_fma_f32 v[50:51], v[226:227], s[22:23], v[50:51] op_sel_hi:[1,0,1]
	v_pk_fma_f32 v[52:53], v[228:229], s[22:23], v[52:53] op_sel_hi:[1,0,1]
	v_pk_fma_f32 v[54:55], v[230:231], s[22:23], v[54:55] op_sel_hi:[1,0,1]
	v_pk_fma_f32 v[56:57], v[232:233], s[22:23], v[56:57] op_sel_hi:[1,0,1]
	v_pk_fma_f32 v[58:59], v[234:235], s[22:23], v[58:59] op_sel_hi:[1,0,1]
	v_pk_fma_f32 v[60:61], v[236:237], s[22:23], v[60:61] op_sel_hi:[1,0,1]
	v_pk_fma_f32 v[62:63], v[238:239], s[22:23], v[62:63] op_sel_hi:[1,0,1]
	v_cvt_pk_f32_fp8_e32 v[224:225], v208
	v_cvt_pk_f32_fp8_sdwa v[226:227], v208 src0_sel:WORD_1
	v_cvt_pk_f32_fp8_e32 v[228:229], v209
	v_cvt_pk_f32_fp8_sdwa v[230:231], v209 src0_sel:WORD_1
	v_cvt_pk_f32_fp8_e32 v[232:233], v210
	v_cvt_pk_f32_fp8_sdwa v[234:235], v210 src0_sel:WORD_1
	v_cvt_pk_f32_fp8_e32 v[236:237], v211
	v_cvt_pk_f32_fp8_sdwa v[238:239], v211 src0_sel:WORD_1
	v_pk_fma_f32 v[48:49], v[224:225], s[24:25], v[48:49] op_sel_hi:[1,0,1]
	v_pk_fma_f32 v[50:51], v[226:227], s[24:25], v[50:51] op_sel_hi:[1,0,1]
	v_pk_fma_f32 v[52:53], v[228:229], s[24:25], v[52:53] op_sel_hi:[1,0,1]
	v_pk_fma_f32 v[54:55], v[230:231], s[24:25], v[54:55] op_sel_hi:[1,0,1]
	v_pk_fma_f32 v[56:57], v[232:233], s[24:25], v[56:57] op_sel_hi:[1,0,1]
	v_pk_fma_f32 v[58:59], v[234:235], s[24:25], v[58:59] op_sel_hi:[1,0,1]
	v_pk_fma_f32 v[60:61], v[236:237], s[24:25], v[60:61] op_sel_hi:[1,0,1]
	v_pk_fma_f32 v[62:63], v[238:239], s[24:25], v[62:63] op_sel_hi:[1,0,1]
	v_cvt_pk_f32_fp8_e32 v[224:225], v212
	v_cvt_pk_f32_fp8_sdwa v[226:227], v212 src0_sel:WORD_1
	v_cvt_pk_f32_fp8_e32 v[228:229], v213
	v_cvt_pk_f32_fp8_sdwa v[230:231], v213 src0_sel:WORD_1
	v_cvt_pk_f32_fp8_e32 v[232:233], v214
	v_cvt_pk_f32_fp8_sdwa v[234:235], v214 src0_sel:WORD_1
	v_cvt_pk_f32_fp8_e32 v[236:237], v215
	v_cvt_pk_f32_fp8_sdwa v[238:239], v215 src0_sel:WORD_1
	v_pk_fma_f32 v[48:49], v[224:225], s[26:27], v[48:49] op_sel_hi:[1,0,1]
	v_pk_fma_f32 v[50:51], v[226:227], s[26:27], v[50:51] op_sel_hi:[1,0,1]
	v_pk_fma_f32 v[52:53], v[228:229], s[26:27], v[52:53] op_sel_hi:[1,0,1]
	v_pk_fma_f32 v[54:55], v[230:231], s[26:27], v[54:55] op_sel_hi:[1,0,1]
	v_pk_fma_f32 v[56:57], v[232:233], s[26:27], v[56:57] op_sel_hi:[1,0,1]
	v_pk_fma_f32 v[58:59], v[234:235], s[26:27], v[58:59] op_sel_hi:[1,0,1]
; DI void peer_item_v(const Params& p, int item) {
;     ...
;     V_ISSUE(vqa, 0)
; #pragma unroll 1
;     for (int g = 0; g < 16; g += 2) {
;       V_ISSUE(vqb, g + 1)
;       V_CONSUME(vqa, g)
;       if (g + 2 < 16) V_ISSUE(vqa, g + 2)
;       V_CONSUME(vqb, g + 1)
;     }
	v_pk_fma_f32 v[60:61], v[236:237], s[26:27], v[60:61] op_sel_hi:[1,0,1]
	v_pk_fma_f32 v[62:63], v[238:239], s[26:27], v[62:63] op_sel_hi:[1,0,1]
	v_cvt_pk_f32_fp8_e32 v[224:225], v216
	v_cvt_pk_f32_fp8_sdwa v[226:227], v216 src0_sel:WORD_1
	v_cvt_pk_f32_fp8_e32 v[228:229], v217
	v_cvt_pk_f32_fp8_sdwa v[230:231], v217 src0_sel:WORD_1
	v_cvt_pk_f32_fp8_e32 v[232:233], v218
	v_cvt_pk_f32_fp8_sdwa v[234:235], v218 src0_sel:WORD_1
	v_cvt_pk_f32_fp8_e32 v[236:237], v219
	v_cvt_pk_f32_fp8_sdwa v[238:239], v219 src0_sel:WORD_1
	v_pk_fma_f32 v[48:49], v[224:225], s[28:29], v[48:49] op_sel_hi:[1,0,1]
	v_pk_fma_f32 v[50:51], v[226:227], s[28:29], v[50:51] op_sel_hi:[1,0,1]
	v_pk_fma_f32 v[52:53], v[228:229], s[28:29], v[52:53] op_sel_hi:[1,0,1]
	v_pk_fma_f32 v[54:55], v[230:231], s[28:29], v[54:55] op_sel_hi:[1,0,1]
	v_pk_fma_f32 v[56:57], v[232:233], s[28:29], v[56:57] op_sel_hi:[1,0,1]
	v_pk_fma_f32 v[58:59], v[234:235], s[28:29], v[58:59] op_sel_hi:[1,0,1]
	v_pk_fma_f32 v[60:61], v[236:237], s[28:29], v[60:61] op_sel_hi:[1,0,1]
	v_pk_fma_f32 v[62:63], v[238:239], s[28:29], v[62:63] op_sel_hi:[1,0,1]
	v_cvt_pk_f32_fp8_e32 v[224:225], v220
	v_cvt_pk_f32_fp8_sdwa v[226:227], v220 src0_sel:WORD_1
	v_cvt_pk_f32_fp8_e32 v[228:229], v221
	v_cvt_pk_f32_fp8_sdwa v[230:231], v221 src0_sel:WORD_1
	v_cvt_pk_f32_fp8_e32 v[232:233], v222
	v_cvt_pk_f32_fp8_sdwa v[234:235], v222 src0_sel:WORD_1
	v_cvt_pk_f32_fp8_e32 v[236:237], v223
	v_cvt_pk_f32_fp8_sdwa v[238:239], v223 src0_sel:WORD_1
	v_pk_fma_f32 v[48:49], v[224:225], s[30:31], v[48:49] op_sel_hi:[1,0,1]
	v_pk_fma_f32 v[50:51], v[226:227], s[30:31], v[50:51] op_sel_hi:[1,0,1]
	v_pk_fma_f32 v[52:53], v[228:229], s[30:31], v[52:53] op_sel_hi:[1,0,1]
	v_pk_fma_f32 v[54:55], v[230:231], s[30:31], v[54:55] op_sel_hi:[1,0,1]
	v_pk_fma_f32 v[56:57], v[232:233], s[30:31], v[56:57] op_sel_hi:[1,0,1]
	v_pk_fma_f32 v[58:59], v[234:235], s[30:31], v[58:59] op_sel_hi:[1,0,1]
	v_pk_fma_f32 v[60:61], v[236:237], s[30:31], v[60:61] op_sel_hi:[1,0,1]
	v_pk_fma_f32 v[62:63], v[238:239], s[30:31], v[62:63] op_sel_hi:[1,0,1]
	v_readlane_b32 s16, v147, s72
	v_readlane_b32 s18, v147, s73
	v_readlane_b32 s20, v147, s74
	v_readlane_b32 s22, v147, s75
	v_readlane_b32 s24, v147, s76
	v_readlane_b32 s26, v147, s77
	v_readlane_b32 s28, v147, s78
	v_readlane_b32 s30, v147, s79
	v_readlane_b32 s48, v149, s72
	v_readlane_b32 s49, v149, s73
	v_readlane_b32 s50, v149, s74
	v_readlane_b32 s51, v149, s75
	v_readlane_b32 s52, v149, s76
	v_readlane_b32 s53, v149, s77
	v_readlane_b32 s54, v149, s78
	v_readlane_b32 s55, v149, s79
	s_add_u32 s32, s0, s48
	s_addc_u32 s33, s1, 0
	s_add_u32 s34, s0, s49
	s_addc_u32 s35, s1, 0
	s_add_u32 s36, s0, s50
	s_addc_u32 s37, s1, 0
	s_add_u32 s38, s0, s51
	s_addc_u32 s39, s1, 0
	s_add_u32 s40, s0, s52
	s_addc_u32 s41, s1, 0
	s_add_u32 s42, s0, s53
	s_addc_u32 s43, s1, 0
	s_add_u32 s44, s0, s54
	s_addc_u32 s45, s1, 0
	s_add_u32 s46, s0, s55
	s_addc_u32 s47, s1, 0
	global_load_dwordx4 v[192:195], v240, s[32:33]
	global_load_dwordx4 v[196:199], v240, s[34:35]
	global_load_dwordx4 v[200:203], v240, s[36:37]
	global_load_dwordx4 v[204:207], v240, s[38:39]
	global_load_dwordx4 v[208:211], v240, s[40:41]
	global_load_dwordx4 v[212:215], v240, s[42:43]
	global_load_dwordx4 v[216:219], v240, s[44:45]
	global_load_dwordx4 v[220:223], v240, s[46:47]
	s_waitcnt vmcnt(8)
	v_cvt_pk_f32_fp8_e32 v[224:225], v160
	v_cvt_pk_f32_fp8_sdwa v[226:227], v160 src0_sel:WORD_1
	v_cvt_pk_f32_fp8_e32 v[228:229], v161
	v_cvt_pk_f32_fp8_sdwa v[230:231], v161 src0_sel:WORD_1
	v_cvt_pk_f32_fp8_e32 v[232:233], v162
	v_cvt_pk_f32_fp8_sdwa v[234:235], v162 src0_sel:WORD_1
	v_cvt_pk_f32_fp8_e32 v[236:237], v163
	v_cvt_pk_f32_fp8_sdwa v[238:239], v163 src0_sel:WORD_1
	v_pk_fma_f32 v[64:65], v[224:225], s[16:17], v[64:65] op_sel_hi:[1,0,1]
	v_pk_fma_f32 v[66:67], v[226:227], s[16:17], v[66:67] op_sel_hi:[1,0,1]
	v_pk_fma_f32 v[68:69], v[228:229], s[16:17], v[68:69] op_sel_hi:[1,0,1]
	v_pk_fma_f32 v[70:71], v[230:231], s[16:17], v[70:71] op_sel_hi:[1,0,1]
	v_pk_fma_f32 v[72:73], v[232:233], s[16:17], v[72:73] op_sel_hi:[1,0,1]
	v_pk_fma_f32 v[74:75], v[234:235], s[16:17], v[74:75] op_sel_hi:[1,0,1]
	v_pk_fma_f32 v[76:77], v[236:237], s[16:17], v[76:77] op_sel_hi:[1,0,1]
	v_pk_fma_f32 v[78:79], v[238:239], s[16:17], v[78:79] op_sel_hi:[1,0,1]
	v_cvt_pk_f32_fp8_e32 v[224:225], v164
	v_cvt_pk_f32_fp8_sdwa v[226:227], v164 src0_sel:WORD_1
	v_cvt_pk_f32_fp8_e32 v[228:229], v165
	v_cvt_pk_f32_fp8_sdwa v[230:231], v165 src0_sel:WORD_1
	v_cvt_pk_f32_fp8_e32 v[232:233], v166
	v_cvt_pk_f32_fp8_sdwa v[234:235], v166 src0_sel:WORD_1
	v_cvt_pk_f32_fp8_e32 v[236:237], v167
	v_cvt_pk_f32_fp8_sdwa v[238:239], v167 src0_sel:WORD_1
	v_pk_fma_f32 v[64:65], v[224:225], s[18:19], v[64:65] op_sel_hi:[1,0,1]
	v_pk_fma_f32 v[66:67], v[226:227], s[18:19], v[66:67] op_sel_hi:[1,0,1]
	v_pk_fma_f32 v[68:69], v[228:229], s[18:19], v[68:69] op_sel_hi:[1,0,1]
	v_pk_fma_f32 v[70:71], v[230:231], s[18:19], v[70:71] op_sel_hi:[1,0,1]
	v_pk_fma_f32 v[72:73], v[232:233], s[18:19], v[72:73] op_sel_hi:[1,0,1]
	v_pk_fma_f32 v[74:75], v[234:235], s[18:19], v[74:75] op_sel_hi:[1,0,1]
	v_pk_fma_f32 v[76:77], v[236:237], s[18:19], v[76:77] op_sel_hi:[1,0,1]
	v_pk_fma_f32 v[78:79], v[238:239], s[18:19], v[78:79] op_sel_hi:[1,0,1]
	v_cvt_pk_f32_fp8_e32 v[224:225], v168
	v_cvt_pk_f32_fp8_sdwa v[226:227], v168 src0_sel:WORD_1
	v_cvt_pk_f32_fp8_e32 v[228:229], v169
	v_cvt_pk_f32_fp8_sdwa v[230:231], v169 src0_sel:WORD_1
	v_cvt_pk_f32_fp8_e32 v[232:233], v170
	v_cvt_pk_f32_fp8_sdwa v[234:235], v170 src0_sel:WORD_1
	v_cvt_pk_f32_fp8_e32 v[236:237], v171
	v_cvt_pk_f32_fp8_sdwa v[238:239], v171 src0_sel:WORD_1
; DI void peer_item_v(const Params& p, int item) {
;     ...
;     V_ISSUE(vqa, 0)
; #pragma unroll 1
;     for (int g = 0; g < 16; g += 2) {
;       V_ISSUE(vqb, g + 1)
;       V_CONSUME(vqa, g)
;       if (g + 2 < 16) V_ISSUE(vqa, g + 2)
;       V_CONSUME(vqb, g + 1)
;     }
	v_pk_fma_f32 v[64:65], v[224:225], s[20:21], v[64:65] op_sel_hi:[1,0,1]
	v_pk_fma_f32 v[66:67], v[226:227], s[20:21], v[66:67] op_sel_hi:[1,0,1]
	v_pk_fma_f32 v[68:69], v[228:229], s[20:21], v[68:69] op_sel_hi:[1,0,1]
	v_pk_fma_f32 v[70:71], v[230:231], s[20:21], v[70:71] op_sel_hi:[1,0,1]
	v_pk_fma_f32 v[72:73], v[232:233], s[20:21], v[72:73] op_sel_hi:[1,0,1]
	v_pk_fma_f32 v[74:75], v[234:235], s[20:21], v[74:75] op_sel_hi:[1,0,1]
	v_pk_fma_f32 v[76:77], v[236:237], s[20:21], v[76:77] op_sel_hi:[1,0,1]
	v_pk_fma_f32 v[78:79], v[238:239], s[20:21], v[78:79] op_sel_hi:[1,0,1]
	v_cvt_pk_f32_fp8_e32 v[224:225], v172
	v_cvt_pk_f32_fp8_sdwa v[226:227], v172 src0_sel:WORD_1
	v_cvt_pk_f32_fp8_e32 v[228:229], v173
	v_cvt_pk_f32_fp8_sdwa v[230:231], v173 src0_sel:WORD_1
	v_cvt_pk_f32_fp8_e32 v[232:233], v174
	v_cvt_pk_f32_fp8_sdwa v[234:235], v174 src0_sel:WORD_1
	v_cvt_pk_f32_fp8_e32 v[236:237], v175
	v_cvt_pk_f32_fp8_sdwa v[238:239], v175 src0_sel:WORD_1
	v_pk_fma_f32 v[64:65], v[224:225], s[22:23], v[64:65] op_sel_hi:[1,0,1]
	v_pk_fma_f32 v[66:67], v[226:227], s[22:23], v[66:67] op_sel_hi:[1,0,1]
	v_pk_fma_f32 v[68:69], v[228:229], s[22:23], v[68:69] op_sel_hi:[1,0,1]
	v_pk_fma_f32 v[70:71], v[230:231], s[22:23], v[70:71] op_sel_hi:[1,0,1]
	v_pk_fma_f32 v[72:73], v[232:233], s[22:23], v[72:73] op_sel_hi:[1,0,1]
	v_pk_fma_f32 v[74:75], v[234:235], s[22:23], v[74:75] op_sel_hi:[1,0,1]
	v_pk_fma_f32 v[76:77], v[236:237], s[22:23], v[76:77] op_sel_hi:[1,0,1]
	v_pk_fma_f32 v[78:79], v[238:239], s[22:23], v[78:79] op_sel_hi:[1,0,1]
	v_cvt_pk_f32_fp8_e32 v[224:225], v176
	v_cvt_pk_f32_fp8_sdwa v[226:227], v176 src0_sel:WORD_1
	v_cvt_pk_f32_fp8_e32 v[228:229], v177
	v_cvt_pk_f32_fp8_sdwa v[230:231], v177 src0_sel:WORD_1
	v_cvt_pk_f32_fp8_e32 v[232:233], v178
	v_cvt_pk_f32_fp8_sdwa v[234:235], v178 src0_sel:WORD_1
	v_cvt_pk_f32_fp8_e32 v[236:237], v179
	v_cvt_pk_f32_fp8_sdwa v[238:239], v179 src0_sel:WORD_1
	v_pk_fma_f32 v[64:65], v[224:225], s[24:25], v[64:65] op_sel_hi:[1,0,1]
	v_pk_fma_f32 v[66:67], v[226:227], s[24:25], v[66:67] op_sel_hi:[1,0,1]
	v_pk_fma_f32 v[68:69], v[228:229], s[24:25], v[68:69] op_sel_hi:[1,0,1]
	v_pk_fma_f32 v[70:71], v[230:231], s[24:25], v[70:71] op_sel_hi:[1,0,1]
	v_pk_fma_f32 v[72:73], v[232:233], s[24:25], v[72:73] op_sel_hi:[1,0,1]
	v_pk_fma_f32 v[74:75], v[234:235], s[24:25], v[74:75] op_sel_hi:[1,0,1]
	v_pk_fma_f32 v[76:77], v[236:237], s[24:25], v[76:77] op_sel_hi:[1,0,1]
	v_pk_fma_f32 v[78:79], v[238:239], s[24:25], v[78:79] op_sel_hi:[1,0,1]
	v_cvt_pk_f32_fp8_e32 v[224:225], v180
	v_cvt_pk_f32_fp8_sdwa v[226:227], v180 src0_sel:WORD_1
	v_cvt_pk_f32_fp8_e32 v[228:229], v181
	v_cvt_pk_f32_fp8_sdwa v[230:231], v181 src0_sel:WORD_1
	v_cvt_pk_f32_fp8_e32 v[232:233], v182
	v_cvt_pk_f32_fp8_sdwa v[234:235], v182 src0_sel:WORD_1
	v_cvt_pk_f32_fp8_e32 v[236:237], v183
	v_cvt_pk_f32_fp8_sdwa v[238:239], v183 src0_sel:WORD_1
	v_pk_fma_f32 v[64:65], v[224:225], s[26:27], v[64:65] op_sel_hi:[1,0,1]
	v_pk_fma_f32 v[66:67], v[226:227], s[26:27], v[66:67] op_sel_hi:[1,0,1]
	v_pk_fma_f32 v[68:69], v[228:229], s[26:27], v[68:69] op_sel_hi:[1,0,1]
	v_pk_fma_f32 v[70:71], v[230:231], s[26:27], v[70:71] op_sel_hi:[1,0,1]
	v_pk_fma_f32 v[72:73], v[232:233], s[26:27], v[72:73] op_sel_hi:[1,0,1]
	v_pk_fma_f32 v[74:75], v[234:235], s[26:27], v[74:75] op_sel_hi:[1,0,1]
	v_pk_fma_f32 v[76:77], v[236:237], s[26:27], v[76:77] op_sel_hi:[1,0,1]
	v_pk_fma_f32 v[78:79], v[238:239], s[26:27], v[78:79] op_sel_hi:[1,0,1]
	v_cvt_pk_f32_fp8_e32 v[224:225], v184
	v_cvt_pk_f32_fp8_sdwa v[226:227], v184 src0_sel:WORD_1
	v_cvt_pk_f32_fp8_e32 v[228:229], v185
	v_cvt_pk_f32_fp8_sdwa v[230:231], v185 src0_sel:WORD_1
	v_cvt_pk_f32_fp8_e32 v[232:233], v186
	v_cvt_pk_f32_fp8_sdwa v[234:235], v186 src0_sel:WORD_1
	v_cvt_pk_f32_fp8_e32 v[236:237], v187
	v_cvt_pk_f32_fp8_sdwa v[238:239], v187 src0_sel:WORD_1
	v_pk_fma_f32 v[64:65], v[224:225], s[28:29], v[64:65] op_sel_hi:[1,0,1]
	v_pk_fma_f32 v[66:67], v[226:227], s[28:29], v[66:67] op_sel_hi:[1,0,1]
	v_pk_fma_f32 v[68:69], v[228:229], s[28:29], v[68:69] op_sel_hi:[1,0,1]
	v_pk_fma_f32 v[70:71], v[230:231], s[28:29], v[70:71] op_sel_hi:[1,0,1]
	v_pk_fma_f32 v[72:73], v[232:233], s[28:29], v[72:73] op_sel_hi:[1,0,1]
	v_pk_fma_f32 v[74:75], v[234:235], s[28:29], v[74:75] op_sel_hi:[1,0,1]
	v_pk_fma_f32 v[76:77], v[236:237], s[28:29], v[76:77] op_sel_hi:[1,0,1]
	v_pk_fma_f32 v[78:79], v[238:239], s[28:29], v[78:79] op_sel_hi:[1,0,1]
	v_cvt_pk_f32_fp8_e32 v[224:225], v188
	v_cvt_pk_f32_fp8_sdwa v[226:227], v188 src0_sel:WORD_1
	v_cvt_pk_f32_fp8_e32 v[228:229], v189
	v_cvt_pk_f32_fp8_sdwa v[230:231], v189 src0_sel:WORD_1
	v_cvt_pk_f32_fp8_e32 v[232:233], v190
	v_cvt_pk_f32_fp8_sdwa v[234:235], v190 src0_sel:WORD_1
	v_cvt_pk_f32_fp8_e32 v[236:237], v191
	v_cvt_pk_f32_fp8_sdwa v[238:239], v191 src0_sel:WORD_1
	v_pk_fma_f32 v[64:65], v[224:225], s[30:31], v[64:65] op_sel_hi:[1,0,1]
	v_pk_fma_f32 v[66:67], v[226:227], s[30:31], v[66:67] op_sel_hi:[1,0,1]
	v_pk_fma_f32 v[68:69], v[228:229], s[30:31], v[68:69] op_sel_hi:[1,0,1]
	v_pk_fma_f32 v[70:71], v[230:231], s[30:31], v[70:71] op_sel_hi:[1,0,1]
	v_pk_fma_f32 v[72:73], v[232:233], s[30:31], v[72:73] op_sel_hi:[1,0,1]
	v_pk_fma_f32 v[74:75], v[234:235], s[30:31], v[74:75] op_sel_hi:[1,0,1]
	v_pk_fma_f32 v[76:77], v[236:237], s[30:31], v[76:77] op_sel_hi:[1,0,1]
	v_pk_fma_f32 v[78:79], v[238:239], s[30:31], v[78:79] op_sel_hi:[1,0,1]
	v_readlane_b32 s16, v151, s72
	v_readlane_b32 s18, v151, s73
	v_readlane_b32 s20, v151, s74
	v_readlane_b32 s22, v151, s75
	v_readlane_b32 s24, v151, s76
	v_readlane_b32 s26, v151, s77
	v_readlane_b32 s28, v151, s78
	v_readlane_b32 s30, v151, s79
	v_readlane_b32 s48, v153, s72
	v_readlane_b32 s49, v153, s73
	v_readlane_b32 s50, v153, s74
	v_readlane_b32 s51, v153, s75
	v_readlane_b32 s52, v153, s76
	v_readlane_b32 s53, v153, s77
	v_readlane_b32 s54, v153, s78
	v_readlane_b32 s55, v153, s79
	s_add_u32 s32, s0, s48
	s_addc_u32 s33, s1, 0
	s_add_u32 s34, s0, s49
	s_addc_u32 s35, s1, 0
	s_add_u32 s36, s0, s50
	s_addc_u32 s37, s1, 0
	s_add_u32 s38, s0, s51
	s_addc_u32 s39, s1, 0
	s_add_u32 s40, s0, s52
	s_addc_u32 s41, s1, 0
	s_add_u32 s42, s0, s53
	s_addc_u32 s43, s1, 0
	s_add_u32 s44, s0, s54
	s_addc_u32 s45, s1, 0
	s_add_u32 s46, s0, s55
	s_addc_u32 s47, s1, 0
	global_load_dwordx4 v[160:163], v240, s[32:33]
	global_load_dwordx4 v[164:167], v240, s[34:35]
	global_load_dwordx4 v[168:171], v240, s[36:37]
	global_load_dwordx4 v[172:175], v240, s[38:39]
	global_load_dwordx4 v[176:179], v240, s[40:41]
	global_load_dwordx4 v[180:183], v240, s[42:43]
	global_load_dwordx4 v[184:187], v240, s[44:45]
	global_load_dwordx4 v[188:191], v240, s[46:47]
	s_waitcnt vmcnt(8)
; DI void peer_item_v(const Params& p, int item) {
;     ...
;     V_ISSUE(vqa, 0)
; #pragma unroll 1
;     for (int g = 0; g < 16; g += 2) {
;       V_ISSUE(vqb, g + 1)
;       V_CONSUME(vqa, g)
;       if (g + 2 < 16) V_ISSUE(vqa, g + 2)
;       V_CONSUME(vqb, g + 1)
;     }
	v_cvt_pk_f32_fp8_e32 v[224:225], v192
	v_cvt_pk_f32_fp8_sdwa v[226:227], v192 src0_sel:WORD_1
	v_cvt_pk_f32_fp8_e32 v[228:229], v193
	v_cvt_pk_f32_fp8_sdwa v[230:231], v193 src0_sel:WORD_1
	v_cvt_pk_f32_fp8_e32 v[232:233], v194
	v_cvt_pk_f32_fp8_sdwa v[234:235], v194 src0_sel:WORD_1
	v_cvt_pk_f32_fp8_e32 v[236:237], v195
	v_cvt_pk_f32_fp8_sdwa v[238:239], v195 src0_sel:WORD_1
	v_pk_fma_f32 v[80:81], v[224:225], s[16:17], v[80:81] op_sel_hi:[1,0,1]
	v_pk_fma_f32 v[82:83], v[226:227], s[16:17], v[82:83] op_sel_hi:[1,0,1]
	v_pk_fma_f32 v[84:85], v[228:229], s[16:17], v[84:85] op_sel_hi:[1,0,1]
	v_pk_fma_f32 v[86:87], v[230:231], s[16:17], v[86:87] op_sel_hi:[1,0,1]
	v_pk_fma_f32 v[88:89], v[232:233], s[16:17], v[88:89] op_sel_hi:[1,0,1]
	v_pk_fma_f32 v[90:91], v[234:235], s[16:17], v[90:91] op_sel_hi:[1,0,1]
	v_pk_fma_f32 v[92:93], v[236:237], s[16:17], v[92:93] op_sel_hi:[1,0,1]
	v_pk_fma_f32 v[94:95], v[238:239], s[16:17], v[94:95] op_sel_hi:[1,0,1]
	v_cvt_pk_f32_fp8_e32 v[224:225], v196
	v_cvt_pk_f32_fp8_sdwa v[226:227], v196 src0_sel:WORD_1
	v_cvt_pk_f32_fp8_e32 v[228:229], v197
	v_cvt_pk_f32_fp8_sdwa v[230:231], v197 src0_sel:WORD_1
	v_cvt_pk_f32_fp8_e32 v[232:233], v198
	v_cvt_pk_f32_fp8_sdwa v[234:235], v198 src0_sel:WORD_1
	v_cvt_pk_f32_fp8_e32 v[236:237], v199
	v_cvt_pk_f32_fp8_sdwa v[238:239], v199 src0_sel:WORD_1
	v_pk_fma_f32 v[80:81], v[224:225], s[18:19], v[80:81] op_sel_hi:[1,0,1]
	v_pk_fma_f32 v[82:83], v[226:227], s[18:19], v[82:83] op_sel_hi:[1,0,1]
	v_pk_fma_f32 v[84:85], v[228:229], s[18:19], v[84:85] op_sel_hi:[1,0,1]
	v_pk_fma_f32 v[86:87], v[230:231], s[18:19], v[86:87] op_sel_hi:[1,0,1]
	v_pk_fma_f32 v[88:89], v[232:233], s[18:19], v[88:89] op_sel_hi:[1,0,1]
	v_pk_fma_f32 v[90:91], v[234:235], s[18:19], v[90:91] op_sel_hi:[1,0,1]
	v_pk_fma_f32 v[92:93], v[236:237], s[18:19], v[92:93] op_sel_hi:[1,0,1]
	v_pk_fma_f32 v[94:95], v[238:239], s[18:19], v[94:95] op_sel_hi:[1,0,1]
	v_cvt_pk_f32_fp8_e32 v[224:225], v200
	v_cvt_pk_f32_fp8_sdwa v[226:227], v200 src0_sel:WORD_1
	v_cvt_pk_f32_fp8_e32 v[228:229], v201
	v_cvt_pk_f32_fp8_sdwa v[230:231], v201 src0_sel:WORD_1
	v_cvt_pk_f32_fp8_e32 v[232:233], v202
	v_cvt_pk_f32_fp8_sdwa v[234:235], v202 src0_sel:WORD_1
	v_cvt_pk_f32_fp8_e32 v[236:237], v203
	v_cvt_pk_f32_fp8_sdwa v[238:239], v203 src0_sel:WORD_1
	v_pk_fma_f32 v[80:81], v[224:225], s[20:21], v[80:81] op_sel_hi:[1,0,1]
	v_pk_fma_f32 v[82:83], v[226:227], s[20:21], v[82:83] op_sel_hi:[1,0,1]
	v_pk_fma_f32 v[84:85], v[228:229], s[20:21], v[84:85] op_sel_hi:[1,0,1]
	v_pk_fma_f32 v[86:87], v[230:231], s[20:21], v[86:87] op_sel_hi:[1,0,1]
	v_pk_fma_f32 v[88:89], v[232:233], s[20:21], v[88:89] op_sel_hi:[1,0,1]
	v_pk_fma_f32 v[90:91], v[234:235], s[20:21], v[90:91] op_sel_hi:[1,0,1]
	v_pk_fma_f32 v[92:93], v[236:237], s[20:21], v[92:93] op_sel_hi:[1,0,1]
	v_pk_fma_f32 v[94:95], v[238:239], s[20:21], v[94:95] op_sel_hi:[1,0,1]
	v_cvt_pk_f32_fp8_e32 v[224:225], v204
	v_cvt_pk_f32_fp8_sdwa v[226:227], v204 src0_sel:WORD_1
	v_cvt_pk_f32_fp8_e32 v[228:229], v205
	v_cvt_pk_f32_fp8_sdwa v[230:231], v205 src0_sel:WORD_1
	v_cvt_pk_f32_fp8_e32 v[232:233], v206
	v_cvt_pk_f32_fp8_sdwa v[234:235], v206 src0_sel:WORD_1
	v_cvt_pk_f32_fp8_e32 v[236:237], v207
	v_cvt_pk_f32_fp8_sdwa v[238:239], v207 src0_sel:WORD_1
	v_pk_fma_f32 v[80:81], v[224:225], s[22:23], v[80:81] op_sel_hi:[1,0,1]
	v_pk_fma_f32 v[82:83], v[226:227], s[22:23], v[82:83] op_sel_hi:[1,0,1]
	v_pk_fma_f32 v[84:85], v[228:229], s[22:23], v[84:85] op_sel_hi:[1,0,1]
	v_pk_fma_f32 v[86:87], v[230:231], s[22:23], v[86:87] op_sel_hi:[1,0,1]
	v_pk_fma_f32 v[88:89], v[232:233], s[22:23], v[88:89] op_sel_hi:[1,0,1]
	v_pk_fma_f32 v[90:91], v[234:235], s[22:23], v[90:91] op_sel_hi:[1,0,1]
	v_pk_fma_f32 v[92:93], v[236:237], s[22:23], v[92:93] op_sel_hi:[1,0,1]
	v_pk_fma_f32 v[94:95], v[238:239], s[22:23], v[94:95] op_sel_hi:[1,0,1]
	v_cvt_pk_f32_fp8_e32 v[224:225], v208
	v_cvt_pk_f32_fp8_sdwa v[226:227], v208 src0_sel:WORD_1
	v_cvt_pk_f32_fp8_e32 v[228:229], v209
	v_cvt_pk_f32_fp8_sdwa v[230:231], v209 src0_sel:WORD_1
	v_cvt_pk_f32_fp8_e32 v[232:233], v210
	v_cvt_pk_f32_fp8_sdwa v[234:235], v210 src0_sel:WORD_1
	v_cvt_pk_f32_fp8_e32 v[236:237], v211
	v_cvt_pk_f32_fp8_sdwa v[238:239], v211 src0_sel:WORD_1
	v_pk_fma_f32 v[80:81], v[224:225], s[24:25], v[80:81] op_sel_hi:[1,0,1]
	v_pk_fma_f32 v[82:83], v[226:227], s[24:25], v[82:83] op_sel_hi:[1,0,1]
	v_pk_fma_f32 v[84:85], v[228:229], s[24:25], v[84:85] op_sel_hi:[1,0,1]
	v_pk_fma_f32 v[86:87], v[230:231], s[24:25], v[86:87] op_sel_hi:[1,0,1]
	v_pk_fma_f32 v[88:89], v[232:233], s[24:25], v[88:89] op_sel_hi:[1,0,1]
	v_pk_fma_f32 v[90:91], v[234:235], s[24:25], v[90:91] op_sel_hi:[1,0,1]
	v_pk_fma_f32 v[92:93], v[236:237], s[24:25], v[92:93] op_sel_hi:[1,0,1]
	v_pk_fma_f32 v[94:95], v[238:239], s[24:25], v[94:95] op_sel_hi:[1,0,1]
	v_cvt_pk_f32_fp8_e32 v[224:225], v212
	v_cvt_pk_f32_fp8_sdwa v[226:227], v212 src0_sel:WORD_1
	v_cvt_pk_f32_fp8_e32 v[228:229], v213
	v_cvt_pk_f32_fp8_sdwa v[230:231], v213 src0_sel:WORD_1
	v_cvt_pk_f32_fp8_e32 v[232:233], v214
	v_cvt_pk_f32_fp8_sdwa v[234:235], v214 src0_sel:WORD_1
	v_cvt_pk_f32_fp8_e32 v[236:237], v215
	v_cvt_pk_f32_fp8_sdwa v[238:239], v215 src0_sel:WORD_1
	v_pk_fma_f32 v[80:81], v[224:225], s[26:27], v[80:81] op_sel_hi:[1,0,1]
	v_pk_fma_f32 v[82:83], v[226:227], s[26:27], v[82:83] op_sel_hi:[1,0,1]
	v_pk_fma_f32 v[84:85], v[228:229], s[26:27], v[84:85] op_sel_hi:[1,0,1]
	v_pk_fma_f32 v[86:87], v[230:231], s[26:27], v[86:87] op_sel_hi:[1,0,1]
	v_pk_fma_f32 v[88:89], v[232:233], s[26:27], v[88:89] op_sel_hi:[1,0,1]
	v_pk_fma_f32 v[90:91], v[234:235], s[26:27], v[90:91] op_sel_hi:[1,0,1]
; DI void peer_item_v(const Params& p, int item) {
;     ...
;     V_ISSUE(vqa, 0)
; #pragma unroll 1
;     for (int g = 0; g < 16; g += 2) {
;       V_ISSUE(vqb, g + 1)
;       V_CONSUME(vqa, g)
;       if (g + 2 < 16) V_ISSUE(vqa, g + 2)
;       V_CONSUME(vqb, g + 1)
;     }
	v_pk_fma_f32 v[92:93], v[236:237], s[26:27], v[92:93] op_sel_hi:[1,0,1]
	v_pk_fma_f32 v[94:95], v[238:239], s[26:27], v[94:95] op_sel_hi:[1,0,1]
	v_cvt_pk_f32_fp8_e32 v[224:225], v216
	v_cvt_pk_f32_fp8_sdwa v[226:227], v216 src0_sel:WORD_1
	v_cvt_pk_f32_fp8_e32 v[228:229], v217
	v_cvt_pk_f32_fp8_sdwa v[230:231], v217 src0_sel:WORD_1
	v_cvt_pk_f32_fp8_e32 v[232:233], v218
	v_cvt_pk_f32_fp8_sdwa v[234:235], v218 src0_sel:WORD_1
	v_cvt_pk_f32_fp8_e32 v[236:237], v219
	v_cvt_pk_f32_fp8_sdwa v[238:239], v219 src0_sel:WORD_1
	v_pk_fma_f32 v[80:81], v[224:225], s[28:29], v[80:81] op_sel_hi:[1,0,1]
	v_pk_fma_f32 v[82:83], v[226:227], s[28:29], v[82:83] op_sel_hi:[1,0,1]
	v_pk_fma_f32 v[84:85], v[228:229], s[28:29], v[84:85] op_sel_hi:[1,0,1]
	v_pk_fma_f32 v[86:87], v[230:231], s[28:29], v[86:87] op_sel_hi:[1,0,1]
	v_pk_fma_f32 v[88:89], v[232:233], s[28:29], v[88:89] op_sel_hi:[1,0,1]
	v_pk_fma_f32 v[90:91], v[234:235], s[28:29], v[90:91] op_sel_hi:[1,0,1]
	v_pk_fma_f32 v[92:93], v[236:237], s[28:29], v[92:93] op_sel_hi:[1,0,1]
	v_pk_fma_f32 v[94:95], v[238:239], s[28:29], v[94:95] op_sel_hi:[1,0,1]
	v_cvt_pk_f32_fp8_e32 v[224:225], v220
	v_cvt_pk_f32_fp8_sdwa v[226:227], v220 src0_sel:WORD_1
	v_cvt_pk_f32_fp8_e32 v[228:229], v221
	v_cvt_pk_f32_fp8_sdwa v[230:231], v221 src0_sel:WORD_1
	v_cvt_pk_f32_fp8_e32 v[232:233], v222
	v_cvt_pk_f32_fp8_sdwa v[234:235], v222 src0_sel:WORD_1
	v_cvt_pk_f32_fp8_e32 v[236:237], v223
	v_cvt_pk_f32_fp8_sdwa v[238:239], v223 src0_sel:WORD_1
	v_pk_fma_f32 v[80:81], v[224:225], s[30:31], v[80:81] op_sel_hi:[1,0,1]
	v_pk_fma_f32 v[82:83], v[226:227], s[30:31], v[82:83] op_sel_hi:[1,0,1]
	v_pk_fma_f32 v[84:85], v[228:229], s[30:31], v[84:85] op_sel_hi:[1,0,1]
	v_pk_fma_f32 v[86:87], v[230:231], s[30:31], v[86:87] op_sel_hi:[1,0,1]
	v_pk_fma_f32 v[88:89], v[232:233], s[30:31], v[88:89] op_sel_hi:[1,0,1]
	v_pk_fma_f32 v[90:91], v[234:235], s[30:31], v[90:91] op_sel_hi:[1,0,1]
	v_pk_fma_f32 v[92:93], v[236:237], s[30:31], v[92:93] op_sel_hi:[1,0,1]
	v_pk_fma_f32 v[94:95], v[238:239], s[30:31], v[94:95] op_sel_hi:[1,0,1]
	v_readlane_b32 s16, v155, s72
	v_readlane_b32 s18, v155, s73
	v_readlane_b32 s20, v155, s74
	v_readlane_b32 s22, v155, s75
	v_readlane_b32 s24, v155, s76
	v_readlane_b32 s26, v155, s77
	v_readlane_b32 s28, v155, s78
	v_readlane_b32 s30, v155, s79
	v_readlane_b32 s48, v157, s72
	v_readlane_b32 s49, v157, s73
	v_readlane_b32 s50, v157, s74
	v_readlane_b32 s51, v157, s75
	v_readlane_b32 s52, v157, s76
	v_readlane_b32 s53, v157, s77
	v_readlane_b32 s54, v157, s78
	v_readlane_b32 s55, v157, s79
	s_add_u32 s32, s0, s48
	s_addc_u32 s33, s1, 0
	s_add_u32 s34, s0, s49
	s_addc_u32 s35, s1, 0
	s_add_u32 s36, s0, s50
	s_addc_u32 s37, s1, 0
	s_add_u32 s38, s0, s51
	s_addc_u32 s39, s1, 0
	s_add_u32 s40, s0, s52
	s_addc_u32 s41, s1, 0
	s_add_u32 s42, s0, s53
	s_addc_u32 s43, s1, 0
	s_add_u32 s44, s0, s54
	s_addc_u32 s45, s1, 0
	s_add_u32 s46, s0, s55
	s_addc_u32 s47, s1, 0
	global_load_dwordx4 v[192:195], v240, s[32:33]
	global_load_dwordx4 v[196:199], v240, s[34:35]
	global_load_dwordx4 v[200:203], v240, s[36:37]
	global_load_dwordx4 v[204:207], v240, s[38:39]
	global_load_dwordx4 v[208:211], v240, s[40:41]
	global_load_dwordx4 v[212:215], v240, s[42:43]
	global_load_dwordx4 v[216:219], v240, s[44:45]
	global_load_dwordx4 v[220:223], v240, s[46:47]
	s_waitcnt vmcnt(8)
	v_cvt_pk_f32_fp8_e32 v[224:225], v160
	v_cvt_pk_f32_fp8_sdwa v[226:227], v160 src0_sel:WORD_1
	v_cvt_pk_f32_fp8_e32 v[228:229], v161
	v_cvt_pk_f32_fp8_sdwa v[230:231], v161 src0_sel:WORD_1
	v_cvt_pk_f32_fp8_e32 v[232:233], v162
	v_cvt_pk_f32_fp8_sdwa v[234:235], v162 src0_sel:WORD_1
	v_cvt_pk_f32_fp8_e32 v[236:237], v163
	v_cvt_pk_f32_fp8_sdwa v[238:239], v163 src0_sel:WORD_1
	v_pk_fma_f32 v[96:97], v[224:225], s[16:17], v[96:97] op_sel_hi:[1,0,1]
	v_pk_fma_f32 v[98:99], v[226:227], s[16:17], v[98:99] op_sel_hi:[1,0,1]
	v_pk_fma_f32 v[100:101], v[228:229], s[16:17], v[100:101] op_sel_hi:[1,0,1]
	v_pk_fma_f32 v[102:103], v[230:231], s[16:17], v[102:103] op_sel_hi:[1,0,1]
	v_pk_fma_f32 v[104:105], v[232:233], s[16:17], v[104:105] op_sel_hi:[1,0,1]
	v_pk_fma_f32 v[106:107], v[234:235], s[16:17], v[106:107] op_sel_hi:[1,0,1]
	v_pk_fma_f32 v[108:109], v[236:237], s[16:17], v[108:109] op_sel_hi:[1,0,1]
	v_pk_fma_f32 v[110:111], v[238:239], s[16:17], v[110:111] op_sel_hi:[1,0,1]
	v_cvt_pk_f32_fp8_e32 v[224:225], v164
	v_cvt_pk_f32_fp8_sdwa v[226:227], v164 src0_sel:WORD_1
	v_cvt_pk_f32_fp8_e32 v[228:229], v165
	v_cvt_pk_f32_fp8_sdwa v[230:231], v165 src0_sel:WORD_1
	v_cvt_pk_f32_fp8_e32 v[232:233], v166
	v_cvt_pk_f32_fp8_sdwa v[234:235], v166 src0_sel:WORD_1
	v_cvt_pk_f32_fp8_e32 v[236:237], v167
	v_cvt_pk_f32_fp8_sdwa v[238:239], v167 src0_sel:WORD_1
	v_pk_fma_f32 v[96:97], v[224:225], s[18:19], v[96:97] op_sel_hi:[1,0,1]
	v_pk_fma_f32 v[98:99], v[226:227], s[18:19], v[98:99] op_sel_hi:[1,0,1]
	v_pk_fma_f32 v[100:101], v[228:229], s[18:19], v[100:101] op_sel_hi:[1,0,1]
	v_pk_fma_f32 v[102:103], v[230:231], s[18:19], v[102:103] op_sel_hi:[1,0,1]
	v_pk_fma_f32 v[104:105], v[232:233], s[18:19], v[104:105] op_sel_hi:[1,0,1]
	v_pk_fma_f32 v[106:107], v[234:235], s[18:19], v[106:107] op_sel_hi:[1,0,1]
	v_pk_fma_f32 v[108:109], v[236:237], s[18:19], v[108:109] op_sel_hi:[1,0,1]
	v_pk_fma_f32 v[110:111], v[238:239], s[18:19], v[110:111] op_sel_hi:[1,0,1]
	v_cvt_pk_f32_fp8_e32 v[224:225], v168
	v_cvt_pk_f32_fp8_sdwa v[226:227], v168 src0_sel:WORD_1
	v_cvt_pk_f32_fp8_e32 v[228:229], v169
	v_cvt_pk_f32_fp8_sdwa v[230:231], v169 src0_sel:WORD_1
	v_cvt_pk_f32_fp8_e32 v[232:233], v170
	v_cvt_pk_f32_fp8_sdwa v[234:235], v170 src0_sel:WORD_1
	v_cvt_pk_f32_fp8_e32 v[236:237], v171
; DI void peer_item_v(const Params& p, int item) {
;     ...
;     V_ISSUE(vqa, 0)
; #pragma unroll 1
;     for (int g = 0; g < 16; g += 2) {
;       V_ISSUE(vqb, g + 1)
;       V_CONSUME(vqa, g)
;       if (g + 2 < 16) V_ISSUE(vqa, g + 2)
;       V_CONSUME(vqb, g + 1)
;     }
	v_cvt_pk_f32_fp8_sdwa v[238:239], v171 src0_sel:WORD_1
	v_pk_fma_f32 v[96:97], v[224:225], s[20:21], v[96:97] op_sel_hi:[1,0,1]
	v_pk_fma_f32 v[98:99], v[226:227], s[20:21], v[98:99] op_sel_hi:[1,0,1]
	v_pk_fma_f32 v[100:101], v[228:229], s[20:21], v[100:101] op_sel_hi:[1,0,1]
	v_pk_fma_f32 v[102:103], v[230:231], s[20:21], v[102:103] op_sel_hi:[1,0,1]
	v_pk_fma_f32 v[104:105], v[232:233], s[20:21], v[104:105] op_sel_hi:[1,0,1]
	v_pk_fma_f32 v[106:107], v[234:235], s[20:21], v[106:107] op_sel_hi:[1,0,1]
	v_pk_fma_f32 v[108:109], v[236:237], s[20:21], v[108:109] op_sel_hi:[1,0,1]
	v_pk_fma_f32 v[110:111], v[238:239], s[20:21], v[110:111] op_sel_hi:[1,0,1]
	v_cvt_pk_f32_fp8_e32 v[224:225], v172
	v_cvt_pk_f32_fp8_sdwa v[226:227], v172 src0_sel:WORD_1
	v_cvt_pk_f32_fp8_e32 v[228:229], v173
	v_cvt_pk_f32_fp8_sdwa v[230:231], v173 src0_sel:WORD_1
	v_cvt_pk_f32_fp8_e32 v[232:233], v174
	v_cvt_pk_f32_fp8_sdwa v[234:235], v174 src0_sel:WORD_1
	v_cvt_pk_f32_fp8_e32 v[236:237], v175
	v_cvt_pk_f32_fp8_sdwa v[238:239], v175 src0_sel:WORD_1
	v_pk_fma_f32 v[96:97], v[224:225], s[22:23], v[96:97] op_sel_hi:[1,0,1]
	v_pk_fma_f32 v[98:99], v[226:227], s[22:23], v[98:99] op_sel_hi:[1,0,1]
	v_pk_fma_f32 v[100:101], v[228:229], s[22:23], v[100:101] op_sel_hi:[1,0,1]
	v_pk_fma_f32 v[102:103], v[230:231], s[22:23], v[102:103] op_sel_hi:[1,0,1]
	v_pk_fma_f32 v[104:105], v[232:233], s[22:23], v[104:105] op_sel_hi:[1,0,1]
	v_pk_fma_f32 v[106:107], v[234:235], s[22:23], v[106:107] op_sel_hi:[1,0,1]
	v_pk_fma_f32 v[108:109], v[236:237], s[22:23], v[108:109] op_sel_hi:[1,0,1]
	v_pk_fma_f32 v[110:111], v[238:239], s[22:23], v[110:111] op_sel_hi:[1,0,1]
	v_cvt_pk_f32_fp8_e32 v[224:225], v176
	v_cvt_pk_f32_fp8_sdwa v[226:227], v176 src0_sel:WORD_1
	v_cvt_pk_f32_fp8_e32 v[228:229], v177
	v_cvt_pk_f32_fp8_sdwa v[230:231], v177 src0_sel:WORD_1
	v_cvt_pk_f32_fp8_e32 v[232:233], v178
	v_cvt_pk_f32_fp8_sdwa v[234:235], v178 src0_sel:WORD_1
	v_cvt_pk_f32_fp8_e32 v[236:237], v179
	v_cvt_pk_f32_fp8_sdwa v[238:239], v179 src0_sel:WORD_1
	v_pk_fma_f32 v[96:97], v[224:225], s[24:25], v[96:97] op_sel_hi:[1,0,1]
	v_pk_fma_f32 v[98:99], v[226:227], s[24:25], v[98:99] op_sel_hi:[1,0,1]
	v_pk_fma_f32 v[100:101], v[228:229], s[24:25], v[100:101] op_sel_hi:[1,0,1]
	v_pk_fma_f32 v[102:103], v[230:231], s[24:25], v[102:103] op_sel_hi:[1,0,1]
	v_pk_fma_f32 v[104:105], v[232:233], s[24:25], v[104:105] op_sel_hi:[1,0,1]
	v_pk_fma_f32 v[106:107], v[234:235], s[24:25], v[106:107] op_sel_hi:[1,0,1]
	v_pk_fma_f32 v[108:109], v[236:237], s[24:25], v[108:109] op_sel_hi:[1,0,1]
	v_pk_fma_f32 v[110:111], v[238:239], s[24:25], v[110:111] op_sel_hi:[1,0,1]
	v_cvt_pk_f32_fp8_e32 v[224:225], v180
	v_cvt_pk_f32_fp8_sdwa v[226:227], v180 src0_sel:WORD_1
	v_cvt_pk_f32_fp8_e32 v[228:229], v181
	v_cvt_pk_f32_fp8_sdwa v[230:231], v181 src0_sel:WORD_1
	v_cvt_pk_f32_fp8_e32 v[232:233], v182
	v_cvt_pk_f32_fp8_sdwa v[234:235], v182 src0_sel:WORD_1
	v_cvt_pk_f32_fp8_e32 v[236:237], v183
	v_cvt_pk_f32_fp8_sdwa v[238:239], v183 src0_sel:WORD_1
	v_pk_fma_f32 v[96:97], v[224:225], s[26:27], v[96:97] op_sel_hi:[1,0,1]
	v_pk_fma_f32 v[98:99], v[226:227], s[26:27], v[98:99] op_sel_hi:[1,0,1]
	v_pk_fma_f32 v[100:101], v[228:229], s[26:27], v[100:101] op_sel_hi:[1,0,1]
	v_pk_fma_f32 v[102:103], v[230:231], s[26:27], v[102:103] op_sel_hi:[1,0,1]
	v_pk_fma_f32 v[104:105], v[232:233], s[26:27], v[104:105] op_sel_hi:[1,0,1]
	v_pk_fma_f32 v[106:107], v[234:235], s[26:27], v[106:107] op_sel_hi:[1,0,1]
	v_pk_fma_f32 v[108:109], v[236:237], s[26:27], v[108:109] op_sel_hi:[1,0,1]
	v_pk_fma_f32 v[110:111], v[238:239], s[26:27], v[110:111] op_sel_hi:[1,0,1]
	v_cvt_pk_f32_fp8_e32 v[224:225], v184
	v_cvt_pk_f32_fp8_sdwa v[226:227], v184 src0_sel:WORD_1
	v_cvt_pk_f32_fp8_e32 v[228:229], v185
	v_cvt_pk_f32_fp8_sdwa v[230:231], v185 src0_sel:WORD_1
	v_cvt_pk_f32_fp8_e32 v[232:233], v186
	v_cvt_pk_f32_fp8_sdwa v[234:235], v186 src0_sel:WORD_1
	v_cvt_pk_f32_fp8_e32 v[236:237], v187
	v_cvt_pk_f32_fp8_sdwa v[238:239], v187 src0_sel:WORD_1
	v_pk_fma_f32 v[96:97], v[224:225], s[28:29], v[96:97] op_sel_hi:[1,0,1]
	v_pk_fma_f32 v[98:99], v[226:227], s[28:29], v[98:99] op_sel_hi:[1,0,1]
	v_pk_fma_f32 v[100:101], v[228:229], s[28:29], v[100:101] op_sel_hi:[1,0,1]
	v_pk_fma_f32 v[102:103], v[230:231], s[28:29], v[102:103] op_sel_hi:[1,0,1]
	v_pk_fma_f32 v[104:105], v[232:233], s[28:29], v[104:105] op_sel_hi:[1,0,1]
	v_pk_fma_f32 v[106:107], v[234:235], s[28:29], v[106:107] op_sel_hi:[1,0,1]
	v_pk_fma_f32 v[108:109], v[236:237], s[28:29], v[108:109] op_sel_hi:[1,0,1]
	v_pk_fma_f32 v[110:111], v[238:239], s[28:29], v[110:111] op_sel_hi:[1,0,1]
	v_cvt_pk_f32_fp8_e32 v[224:225], v188
	v_cvt_pk_f32_fp8_sdwa v[226:227], v188 src0_sel:WORD_1
	v_cvt_pk_f32_fp8_e32 v[228:229], v189
	v_cvt_pk_f32_fp8_sdwa v[230:231], v189 src0_sel:WORD_1
	v_cvt_pk_f32_fp8_e32 v[232:233], v190
	v_cvt_pk_f32_fp8_sdwa v[234:235], v190 src0_sel:WORD_1
	v_cvt_pk_f32_fp8_e32 v[236:237], v191
	v_cvt_pk_f32_fp8_sdwa v[238:239], v191 src0_sel:WORD_1
	v_pk_fma_f32 v[96:97], v[224:225], s[30:31], v[96:97] op_sel_hi:[1,0,1]
	v_pk_fma_f32 v[98:99], v[226:227], s[30:31], v[98:99] op_sel_hi:[1,0,1]
	v_pk_fma_f32 v[100:101], v[228:229], s[30:31], v[100:101] op_sel_hi:[1,0,1]
	v_pk_fma_f32 v[102:103], v[230:231], s[30:31], v[102:103] op_sel_hi:[1,0,1]
	v_pk_fma_f32 v[104:105], v[232:233], s[30:31], v[104:105] op_sel_hi:[1,0,1]
	v_pk_fma_f32 v[106:107], v[234:235], s[30:31], v[106:107] op_sel_hi:[1,0,1]
	v_pk_fma_f32 v[108:109], v[236:237], s[30:31], v[108:109] op_sel_hi:[1,0,1]
	v_pk_fma_f32 v[110:111], v[238:239], s[30:31], v[110:111] op_sel_hi:[1,0,1]
	v_readlane_b32 s16, v159, s72
; DI void peer_item_v(const Params& p, int item) {
;     ...
;     V_ISSUE(vqa, 0)
; #pragma unroll 1
;     for (int g = 0; g < 16; g += 2) {
;       V_ISSUE(vqb, g + 1)
;       V_CONSUME(vqa, g)
;       if (g + 2 < 16) V_ISSUE(vqa, g + 2)
;       V_CONSUME(vqb, g + 1)
;     }
	v_readlane_b32 s18, v159, s73
	v_readlane_b32 s20, v159, s74
	v_readlane_b32 s22, v159, s75
	v_readlane_b32 s24, v159, s76
	v_readlane_b32 s26, v159, s77
	v_readlane_b32 s28, v159, s78
	v_readlane_b32 s30, v159, s79
	s_add_u32 s72, s72, 8
	s_add_u32 s73, s73, 8
	s_add_u32 s74, s74, 8
	s_add_u32 s75, s75, 8
	s_add_u32 s76, s76, 8
	s_add_u32 s77, s77, 8
	s_add_u32 s78, s78, 8
	s_add_u32 s79, s79, 8
	s_and_b32 s72, s72, 63
	s_and_b32 s73, s73, 63
	s_and_b32 s74, s74, 63
	s_and_b32 s75, s75, 63
	s_and_b32 s76, s76, 63
	s_and_b32 s77, s77, 63
	s_and_b32 s78, s78, 63
	s_and_b32 s79, s79, 63
	v_readlane_b32 s48, v128, s72
	v_readlane_b32 s49, v128, s73
	v_readlane_b32 s50, v128, s74
	v_readlane_b32 s51, v128, s75
	v_readlane_b32 s52, v128, s76
	v_readlane_b32 s53, v128, s77
	v_readlane_b32 s54, v128, s78
	v_readlane_b32 s55, v128, s79
	s_add_u32 s32, s0, s48
	s_addc_u32 s33, s1, 0
	s_add_u32 s34, s0, s49
	s_addc_u32 s35, s1, 0
	s_add_u32 s36, s0, s50
	s_addc_u32 s37, s1, 0
	s_add_u32 s38, s0, s51
	s_addc_u32 s39, s1, 0
	s_add_u32 s40, s0, s52
	s_addc_u32 s41, s1, 0
	s_add_u32 s42, s0, s53
	s_addc_u32 s43, s1, 0
	s_add_u32 s44, s0, s54
	s_addc_u32 s45, s1, 0
	s_add_u32 s46, s0, s55
	s_addc_u32 s47, s1, 0
	global_load_dwordx4 v[160:163], v240, s[32:33]
	global_load_dwordx4 v[164:167], v240, s[34:35]
	global_load_dwordx4 v[168:171], v240, s[36:37]
	global_load_dwordx4 v[172:175], v240, s[38:39]
	global_load_dwordx4 v[176:179], v240, s[40:41]
	global_load_dwordx4 v[180:183], v240, s[42:43]
	global_load_dwordx4 v[184:187], v240, s[44:45]
	global_load_dwordx4 v[188:191], v240, s[46:47]
	s_waitcnt vmcnt(8)
	v_cvt_pk_f32_fp8_e32 v[224:225], v192
	v_cvt_pk_f32_fp8_sdwa v[226:227], v192 src0_sel:WORD_1
	v_cvt_pk_f32_fp8_e32 v[228:229], v193
	v_cvt_pk_f32_fp8_sdwa v[230:231], v193 src0_sel:WORD_1
	v_cvt_pk_f32_fp8_e32 v[232:233], v194
	v_cvt_pk_f32_fp8_sdwa v[234:235], v194 src0_sel:WORD_1
	v_cvt_pk_f32_fp8_e32 v[236:237], v195
	v_cvt_pk_f32_fp8_sdwa v[238:239], v195 src0_sel:WORD_1
	v_pk_fma_f32 v[112:113], v[224:225], s[16:17], v[112:113] op_sel_hi:[1,0,1]
	v_pk_fma_f32 v[114:115], v[226:227], s[16:17], v[114:115] op_sel_hi:[1,0,1]
	v_pk_fma_f32 v[116:117], v[228:229], s[16:17], v[116:117] op_sel_hi:[1,0,1]
	v_pk_fma_f32 v[118:119], v[230:231], s[16:17], v[118:119] op_sel_hi:[1,0,1]
	v_pk_fma_f32 v[120:121], v[232:233], s[16:17], v[120:121] op_sel_hi:[1,0,1]
	v_pk_fma_f32 v[122:123], v[234:235], s[16:17], v[122:123] op_sel_hi:[1,0,1]
	v_pk_fma_f32 v[124:125], v[236:237], s[16:17], v[124:125] op_sel_hi:[1,0,1]
	v_pk_fma_f32 v[126:127], v[238:239], s[16:17], v[126:127] op_sel_hi:[1,0,1]
	v_cvt_pk_f32_fp8_e32 v[224:225], v196
	v_cvt_pk_f32_fp8_sdwa v[226:227], v196 src0_sel:WORD_1
	v_cvt_pk_f32_fp8_e32 v[228:229], v197
	v_cvt_pk_f32_fp8_sdwa v[230:231], v197 src0_sel:WORD_1
	v_cvt_pk_f32_fp8_e32 v[232:233], v198
	v_cvt_pk_f32_fp8_sdwa v[234:235], v198 src0_sel:WORD_1
	v_cvt_pk_f32_fp8_e32 v[236:237], v199
	v_cvt_pk_f32_fp8_sdwa v[238:239], v199 src0_sel:WORD_1
	v_pk_fma_f32 v[112:113], v[224:225], s[18:19], v[112:113] op_sel_hi:[1,0,1]
	v_pk_fma_f32 v[114:115], v[226:227], s[18:19], v[114:115] op_sel_hi:[1,0,1]
	v_pk_fma_f32 v[116:117], v[228:229], s[18:19], v[116:117] op_sel_hi:[1,0,1]
	v_pk_fma_f32 v[118:119], v[230:231], s[18:19], v[118:119] op_sel_hi:[1,0,1]
	v_pk_fma_f32 v[120:121], v[232:233], s[18:19], v[120:121] op_sel_hi:[1,0,1]
	v_pk_fma_f32 v[122:123], v[234:235], s[18:19], v[122:123] op_sel_hi:[1,0,1]
	v_pk_fma_f32 v[124:125], v[236:237], s[18:19], v[124:125] op_sel_hi:[1,0,1]
	v_pk_fma_f32 v[126:127], v[238:239], s[18:19], v[126:127] op_sel_hi:[1,0,1]
	v_cvt_pk_f32_fp8_e32 v[224:225], v200
	v_cvt_pk_f32_fp8_sdwa v[226:227], v200 src0_sel:WORD_1
	v_cvt_pk_f32_fp8_e32 v[228:229], v201
	v_cvt_pk_f32_fp8_sdwa v[230:231], v201 src0_sel:WORD_1
	v_cvt_pk_f32_fp8_e32 v[232:233], v202
	v_cvt_pk_f32_fp8_sdwa v[234:235], v202 src0_sel:WORD_1
	v_cvt_pk_f32_fp8_e32 v[236:237], v203
	v_cvt_pk_f32_fp8_sdwa v[238:239], v203 src0_sel:WORD_1
	v_pk_fma_f32 v[112:113], v[224:225], s[20:21], v[112:113] op_sel_hi:[1,0,1]
	v_pk_fma_f32 v[114:115], v[226:227], s[20:21], v[114:115] op_sel_hi:[1,0,1]
	v_pk_fma_f32 v[116:117], v[228:229], s[20:21], v[116:117] op_sel_hi:[1,0,1]
	v_pk_fma_f32 v[118:119], v[230:231], s[20:21], v[118:119] op_sel_hi:[1,0,1]
	v_pk_fma_f32 v[120:121], v[232:233], s[20:21], v[120:121] op_sel_hi:[1,0,1]
	v_pk_fma_f32 v[122:123], v[234:235], s[20:21], v[122:123] op_sel_hi:[1,0,1]
	v_pk_fma_f32 v[124:125], v[236:237], s[20:21], v[124:125] op_sel_hi:[1,0,1]
	v_pk_fma_f32 v[126:127], v[238:239], s[20:21], v[126:127] op_sel_hi:[1,0,1]
	v_cvt_pk_f32_fp8_e32 v[224:225], v204
	v_cvt_pk_f32_fp8_sdwa v[226:227], v204 src0_sel:WORD_1
	v_cvt_pk_f32_fp8_e32 v[228:229], v205
	v_cvt_pk_f32_fp8_sdwa v[230:231], v205 src0_sel:WORD_1
	v_cvt_pk_f32_fp8_e32 v[232:233], v206
	v_cvt_pk_f32_fp8_sdwa v[234:235], v206 src0_sel:WORD_1
	v_cvt_pk_f32_fp8_e32 v[236:237], v207
	v_cvt_pk_f32_fp8_sdwa v[238:239], v207 src0_sel:WORD_1
	v_pk_fma_f32 v[112:113], v[224:225], s[22:23], v[112:113] op_sel_hi:[1,0,1]
	v_pk_fma_f32 v[114:115], v[226:227], s[22:23], v[114:115] op_sel_hi:[1,0,1]
	v_pk_fma_f32 v[116:117], v[228:229], s[22:23], v[116:117] op_sel_hi:[1,0,1]
	v_pk_fma_f32 v[118:119], v[230:231], s[22:23], v[118:119] op_sel_hi:[1,0,1]
	v_pk_fma_f32 v[120:121], v[232:233], s[22:23], v[120:121] op_sel_hi:[1,0,1]
	v_pk_fma_f32 v[122:123], v[234:235], s[22:23], v[122:123] op_sel_hi:[1,0,1]
	v_pk_fma_f32 v[124:125], v[236:237], s[22:23], v[124:125] op_sel_hi:[1,0,1]
	v_pk_fma_f32 v[126:127], v[238:239], s[22:23], v[126:127] op_sel_hi:[1,0,1]
	v_cvt_pk_f32_fp8_e32 v[224:225], v208
; DI void peer_item_v(const Params& p, int item) {
;     ...
;     V_ISSUE(vqa, 0)
; #pragma unroll 1
;     for (int g = 0; g < 16; g += 2) {
;       V_ISSUE(vqb, g + 1)
;       V_CONSUME(vqa, g)
;       if (g + 2 < 16) V_ISSUE(vqa, g + 2)
;       V_CONSUME(vqb, g + 1)
;     }
;     ...
;     float* orow = p.out + tok * 1024 + lane * 4;
;     float4 y[4];
;     float ss = 0.f;
; #pragma unroll
;     for (int i = 0; i < 4; ++i) {
;       y[i] = *(const float4*)(orow + 256 * i);
;       y[i].x += out[4 * i]; y[i].y += out[4 * i + 1]; y[i].z += out[4 * i + 2]; y[i].w += out[4 * i + 3];
;       ss += y[i].x * y[i].x + y[i].y * y[i].y + y[i].z * y[i].z + y[i].w * y[i].w;
;     }
;     ss = wave_sum(ss);
;     const float r = rsqrtf(ss * (1.f / 1024.f) + 1e-6f);
; #pragma unroll
;     for (int i = 0; i < 4; ++i) {
;       float4 g = *(const float4*)(p.g_final + 256 * i + lane * 4);
	v_cvt_pk_f32_fp8_sdwa v[226:227], v208 src0_sel:WORD_1
	v_cvt_pk_f32_fp8_e32 v[228:229], v209
	v_cvt_pk_f32_fp8_sdwa v[230:231], v209 src0_sel:WORD_1
	v_cvt_pk_f32_fp8_e32 v[232:233], v210
	v_cvt_pk_f32_fp8_sdwa v[234:235], v210 src0_sel:WORD_1
	v_cvt_pk_f32_fp8_e32 v[236:237], v211
	v_cvt_pk_f32_fp8_sdwa v[238:239], v211 src0_sel:WORD_1
	v_pk_fma_f32 v[112:113], v[224:225], s[24:25], v[112:113] op_sel_hi:[1,0,1]
	v_pk_fma_f32 v[114:115], v[226:227], s[24:25], v[114:115] op_sel_hi:[1,0,1]
	v_pk_fma_f32 v[116:117], v[228:229], s[24:25], v[116:117] op_sel_hi:[1,0,1]
	v_pk_fma_f32 v[118:119], v[230:231], s[24:25], v[118:119] op_sel_hi:[1,0,1]
	v_pk_fma_f32 v[120:121], v[232:233], s[24:25], v[120:121] op_sel_hi:[1,0,1]
	v_pk_fma_f32 v[122:123], v[234:235], s[24:25], v[122:123] op_sel_hi:[1,0,1]
	v_pk_fma_f32 v[124:125], v[236:237], s[24:25], v[124:125] op_sel_hi:[1,0,1]
	v_pk_fma_f32 v[126:127], v[238:239], s[24:25], v[126:127] op_sel_hi:[1,0,1]
	v_cvt_pk_f32_fp8_e32 v[224:225], v212
	v_cvt_pk_f32_fp8_sdwa v[226:227], v212 src0_sel:WORD_1
	v_cvt_pk_f32_fp8_e32 v[228:229], v213
	v_cvt_pk_f32_fp8_sdwa v[230:231], v213 src0_sel:WORD_1
	v_cvt_pk_f32_fp8_e32 v[232:233], v214
	v_cvt_pk_f32_fp8_sdwa v[234:235], v214 src0_sel:WORD_1
	v_cvt_pk_f32_fp8_e32 v[236:237], v215
	v_cvt_pk_f32_fp8_sdwa v[238:239], v215 src0_sel:WORD_1
	v_pk_fma_f32 v[112:113], v[224:225], s[26:27], v[112:113] op_sel_hi:[1,0,1]
	v_pk_fma_f32 v[114:115], v[226:227], s[26:27], v[114:115] op_sel_hi:[1,0,1]
	v_pk_fma_f32 v[116:117], v[228:229], s[26:27], v[116:117] op_sel_hi:[1,0,1]
	v_pk_fma_f32 v[118:119], v[230:231], s[26:27], v[118:119] op_sel_hi:[1,0,1]
	v_pk_fma_f32 v[120:121], v[232:233], s[26:27], v[120:121] op_sel_hi:[1,0,1]
	v_pk_fma_f32 v[122:123], v[234:235], s[26:27], v[122:123] op_sel_hi:[1,0,1]
	v_pk_fma_f32 v[124:125], v[236:237], s[26:27], v[124:125] op_sel_hi:[1,0,1]
	v_pk_fma_f32 v[126:127], v[238:239], s[26:27], v[126:127] op_sel_hi:[1,0,1]
	v_cvt_pk_f32_fp8_e32 v[224:225], v216
	v_cvt_pk_f32_fp8_sdwa v[226:227], v216 src0_sel:WORD_1
	v_cvt_pk_f32_fp8_e32 v[228:229], v217
	v_cvt_pk_f32_fp8_sdwa v[230:231], v217 src0_sel:WORD_1
	v_cvt_pk_f32_fp8_e32 v[232:233], v218
	v_cvt_pk_f32_fp8_sdwa v[234:235], v218 src0_sel:WORD_1
	v_cvt_pk_f32_fp8_e32 v[236:237], v219
	v_cvt_pk_f32_fp8_sdwa v[238:239], v219 src0_sel:WORD_1
	v_pk_fma_f32 v[112:113], v[224:225], s[28:29], v[112:113] op_sel_hi:[1,0,1]
	v_pk_fma_f32 v[114:115], v[226:227], s[28:29], v[114:115] op_sel_hi:[1,0,1]
	v_pk_fma_f32 v[116:117], v[228:229], s[28:29], v[116:117] op_sel_hi:[1,0,1]
	v_pk_fma_f32 v[118:119], v[230:231], s[28:29], v[118:119] op_sel_hi:[1,0,1]
	v_pk_fma_f32 v[120:121], v[232:233], s[28:29], v[120:121] op_sel_hi:[1,0,1]
	v_pk_fma_f32 v[122:123], v[234:235], s[28:29], v[122:123] op_sel_hi:[1,0,1]
	v_pk_fma_f32 v[124:125], v[236:237], s[28:29], v[124:125] op_sel_hi:[1,0,1]
	v_pk_fma_f32 v[126:127], v[238:239], s[28:29], v[126:127] op_sel_hi:[1,0,1]
	v_cvt_pk_f32_fp8_e32 v[224:225], v220
	v_cvt_pk_f32_fp8_sdwa v[226:227], v220 src0_sel:WORD_1
	v_cvt_pk_f32_fp8_e32 v[228:229], v221
	v_cvt_pk_f32_fp8_sdwa v[230:231], v221 src0_sel:WORD_1
	v_cvt_pk_f32_fp8_e32 v[232:233], v222
	v_cvt_pk_f32_fp8_sdwa v[234:235], v222 src0_sel:WORD_1
	v_cvt_pk_f32_fp8_e32 v[236:237], v223
	v_cvt_pk_f32_fp8_sdwa v[238:239], v223 src0_sel:WORD_1
	v_pk_fma_f32 v[112:113], v[224:225], s[30:31], v[112:113] op_sel_hi:[1,0,1]
	v_pk_fma_f32 v[114:115], v[226:227], s[30:31], v[114:115] op_sel_hi:[1,0,1]
	v_pk_fma_f32 v[116:117], v[228:229], s[30:31], v[116:117] op_sel_hi:[1,0,1]
	v_pk_fma_f32 v[118:119], v[230:231], s[30:31], v[118:119] op_sel_hi:[1,0,1]
	v_pk_fma_f32 v[120:121], v[232:233], s[30:31], v[120:121] op_sel_hi:[1,0,1]
	v_pk_fma_f32 v[122:123], v[234:235], s[30:31], v[122:123] op_sel_hi:[1,0,1]
	v_pk_fma_f32 v[124:125], v[236:237], s[30:31], v[124:125] op_sel_hi:[1,0,1]
	v_pk_fma_f32 v[126:127], v[238:239], s[30:31], v[126:127] op_sel_hi:[1,0,1]
	s_add_u32 s12, s12, 1
	s_cmp_lt_u32 s12, 8
	s_cbranch_scc1 .Lvf_k
	s_waitcnt vmcnt(0)
	global_load_dwordx4 v[128:131], v240, s[8:9]
	global_load_dwordx4 v[132:135], v240, s[8:9] offset:1024
	global_load_dwordx4 v[136:139], v240, s[8:9] offset:2048
	global_load_dwordx4 v[140:143], v240, s[8:9] offset:3072
	s_lshl_b32 s15, s14, 12
	s_add_u32 s62, s6, s15
	s_addc_u32 s63, s7, 0
	s_add_u32 s32, s62, 0
	s_addc_u32 s33, s63, 0
	s_add_u32 s34, s62, 4096
	s_addc_u32 s35, s63, 0
	s_add_u32 s36, s62, 8192
	s_addc_u32 s37, s63, 0
	s_add_u32 s38, s62, 12288
	s_addc_u32 s39, s63, 0
	global_load_dwordx4 v[160:163], v240, s[32:33]
	global_load_dwordx4 v[164:167], v240, s[32:33] offset:1024
	global_load_dwordx4 v[168:171], v240, s[32:33] offset:2048
	global_load_dwordx4 v[172:175], v240, s[32:33] offset:3072
	global_load_dwordx4 v[176:179], v240, s[34:35]
	global_load_dwordx4 v[180:183], v240, s[34:35] offset:1024
	global_load_dwordx4 v[184:187], v240, s[34:35] offset:2048
	global_load_dwordx4 v[188:191], v240, s[34:35] offset:3072
	global_load_dwordx4 v[192:195], v240, s[36:37]
	global_load_dwordx4 v[196:199], v240, s[36:37] offset:1024
	global_load_dwordx4 v[200:203], v240, s[36:37] offset:2048
	global_load_dwordx4 v[204:207], v240, s[36:37] offset:3072
	global_load_dwordx4 v[208:211], v240, s[38:39]
	global_load_dwordx4 v[212:215], v240, s[38:39] offset:1024
	global_load_dwordx4 v[216:219], v240, s[38:39] offset:2048
	global_load_dwordx4 v[220:223], v240, s[38:39] offset:3072
	s_waitcnt vmcnt(0)
; DI float wave_sum(float v) {
; #pragma unroll
;   for (int o = 32; o > 0; o >>= 1) v += __shfl_xor(v, o);
;   return v;
; }
; DI void peer_item_v(const Params& p, int item) {
;     ...
;     float* orow = p.out + tok * 1024 + lane * 4;
;     float4 y[4];
;     float ss = 0.f;
; #pragma unroll
;     for (int i = 0; i < 4; ++i) {
;       y[i] = *(const float4*)(orow + 256 * i);
;       y[i].x += out[4 * i]; y[i].y += out[4 * i + 1]; y[i].z += out[4 * i + 2]; y[i].w += out[4 * i + 3];
;       ss += y[i].x * y[i].x + y[i].y * y[i].y + y[i].z * y[i].z + y[i].w * y[i].w;
;     }
;     ss = wave_sum(ss);
;     const float r = rsqrtf(ss * (1.f / 1024.f) + 1e-6f);
; #pragma unroll
;     for (int i = 0; i < 4; ++i) {
;       float4 g = *(const float4*)(p.g_final + 256 * i + lane * 4);
;       y[i].x *= r * g.x; y[i].y *= r * g.y; y[i].z *= r * g.z; y[i].w *= r * g.w;
;       *(float4*)(orow + 256 * i) = y[i];
;     }
	v_pk_add_f32 v[160:161], v[160:161], v[0:1]
	v_pk_add_f32 v[162:163], v[162:163], v[2:3]
	v_pk_add_f32 v[164:165], v[164:165], v[4:5]
	v_pk_add_f32 v[166:167], v[166:167], v[6:7]
	v_pk_add_f32 v[168:169], v[168:169], v[8:9]
	v_pk_add_f32 v[170:171], v[170:171], v[10:11]
	v_pk_add_f32 v[172:173], v[172:173], v[12:13]
	v_pk_add_f32 v[174:175], v[174:175], v[14:15]
	v_pk_mul_f32 v[224:225], v[160:161], v[160:161]
	v_pk_mul_f32 v[226:227], v[162:163], v[162:163]
	v_pk_fma_f32 v[224:225], v[164:165], v[164:165], v[224:225]
	v_pk_fma_f32 v[226:227], v[166:167], v[166:167], v[226:227]
	v_pk_fma_f32 v[224:225], v[168:169], v[168:169], v[224:225]
	v_pk_fma_f32 v[226:227], v[170:171], v[170:171], v[226:227]
	v_pk_fma_f32 v[224:225], v[172:173], v[172:173], v[224:225]
	v_pk_fma_f32 v[226:227], v[174:175], v[174:175], v[226:227]
	v_pk_add_f32 v[224:225], v[224:225], v[226:227]
	s_nop 0
	v_add_f32_e32 v224, v224, v225
	ds_bpermute_b32 v225, v242, v224
	s_waitcnt lgkmcnt(0)
	v_add_f32_e32 v224, v224, v225
	ds_bpermute_b32 v225, v243, v224
	s_waitcnt lgkmcnt(0)
	v_add_f32_e32 v224, v224, v225
	ds_bpermute_b32 v225, v244, v224
	s_waitcnt lgkmcnt(0)
	v_add_f32_e32 v224, v224, v225
	ds_bpermute_b32 v225, v245, v224
	s_waitcnt lgkmcnt(0)
	v_add_f32_e32 v224, v224, v225
	ds_bpermute_b32 v225, v246, v224
	s_waitcnt lgkmcnt(0)
	v_add_f32_e32 v224, v224, v225
	ds_bpermute_b32 v225, v247, v224
	s_waitcnt lgkmcnt(0)
	v_add_f32_e32 v224, v224, v225
	v_fmamk_f32 v224, v224, 0x3a800000, v248
	v_rsq_f32_e32 v224, v224
	s_nop 1
	v_pk_mul_f32 v[226:227], v[128:129], v[224:225] op_sel_hi:[1,0]
	v_pk_mul_f32 v[160:161], v[160:161], v[226:227]
	v_pk_mul_f32 v[228:229], v[130:131], v[224:225] op_sel_hi:[1,0]
	v_pk_mul_f32 v[162:163], v[162:163], v[228:229]
	v_pk_mul_f32 v[230:231], v[132:133], v[224:225] op_sel_hi:[1,0]
	v_pk_mul_f32 v[164:165], v[164:165], v[230:231]
	v_pk_mul_f32 v[232:233], v[134:135], v[224:225] op_sel_hi:[1,0]
	v_pk_mul_f32 v[166:167], v[166:167], v[232:233]
	v_pk_mul_f32 v[226:227], v[136:137], v[224:225] op_sel_hi:[1,0]
	v_pk_mul_f32 v[168:169], v[168:169], v[226:227]
	v_pk_mul_f32 v[228:229], v[138:139], v[224:225] op_sel_hi:[1,0]
	v_pk_mul_f32 v[170:171], v[170:171], v[228:229]
	v_pk_mul_f32 v[230:231], v[140:141], v[224:225] op_sel_hi:[1,0]
	v_pk_mul_f32 v[172:173], v[172:173], v[230:231]
	v_pk_mul_f32 v[232:233], v[142:143], v[224:225] op_sel_hi:[1,0]
	v_pk_mul_f32 v[174:175], v[174:175], v[232:233]
	v_pk_add_f32 v[176:177], v[176:177], v[16:17]
	v_pk_add_f32 v[178:179], v[178:179], v[18:19]
	v_pk_add_f32 v[180:181], v[180:181], v[20:21]
	v_pk_add_f32 v[182:183], v[182:183], v[22:23]
	v_pk_add_f32 v[184:185], v[184:185], v[24:25]
	v_pk_add_f32 v[186:187], v[186:187], v[26:27]
	v_pk_add_f32 v[188:189], v[188:189], v[28:29]
	v_pk_add_f32 v[190:191], v[190:191], v[30:31]
	v_pk_mul_f32 v[224:225], v[176:177], v[176:177]
	v_pk_mul_f32 v[226:227], v[178:179], v[178:179]
	v_pk_fma_f32 v[224:225], v[180:181], v[180:181], v[224:225]
	v_pk_fma_f32 v[226:227], v[182:183], v[182:183], v[226:227]
	v_pk_fma_f32 v[224:225], v[184:185], v[184:185], v[224:225]
	v_pk_fma_f32 v[226:227], v[186:187], v[186:187], v[226:227]
	v_pk_fma_f32 v[224:225], v[188:189], v[188:189], v[224:225]
	v_pk_fma_f32 v[226:227], v[190:191], v[190:191], v[226:227]
	v_pk_add_f32 v[224:225], v[224:225], v[226:227]
	s_nop 0
	v_add_f32_e32 v224, v224, v225
	ds_bpermute_b32 v225, v242, v224
	s_waitcnt lgkmcnt(0)
	v_add_f32_e32 v224, v224, v225
	ds_bpermute_b32 v225, v243, v224
	s_waitcnt lgkmcnt(0)
	v_add_f32_e32 v224, v224, v225
	ds_bpermute_b32 v225, v244, v224
	s_waitcnt lgkmcnt(0)
	v_add_f32_e32 v224, v224, v225
	ds_bpermute_b32 v225, v245, v224
	s_waitcnt lgkmcnt(0)
	v_add_f32_e32 v224, v224, v225
	ds_bpermute_b32 v225, v246, v224
	s_waitcnt lgkmcnt(0)
	v_add_f32_e32 v224, v224, v225
	ds_bpermute_b32 v225, v247, v224
	s_waitcnt lgkmcnt(0)
	v_add_f32_e32 v224, v224, v225
	v_fmamk_f32 v224, v224, 0x3a800000, v248
	v_rsq_f32_e32 v224, v224
	s_nop 1
	v_pk_mul_f32 v[226:227], v[128:129], v[224:225] op_sel_hi:[1,0]
	v_pk_mul_f32 v[176:177], v[176:177], v[226:227]
	v_pk_mul_f32 v[228:229], v[130:131], v[224:225] op_sel_hi:[1,0]
	v_pk_mul_f32 v[178:179], v[178:179], v[228:229]
	v_pk_mul_f32 v[230:231], v[132:133], v[224:225] op_sel_hi:[1,0]
	v_pk_mul_f32 v[180:181], v[180:181], v[230:231]
	v_pk_mul_f32 v[232:233], v[134:135], v[224:225] op_sel_hi:[1,0]
	v_pk_mul_f32 v[182:183], v[182:183], v[232:233]
	v_pk_mul_f32 v[226:227], v[136:137], v[224:225] op_sel_hi:[1,0]
	v_pk_mul_f32 v[184:185], v[184:185], v[226:227]
	v_pk_mul_f32 v[228:229], v[138:139], v[224:225] op_sel_hi:[1,0]
	v_pk_mul_f32 v[186:187], v[186:187], v[228:229]
	v_pk_mul_f32 v[230:231], v[140:141], v[224:225] op_sel_hi:[1,0]
	v_pk_mul_f32 v[188:189], v[188:189], v[230:231]
	v_pk_mul_f32 v[232:233], v[142:143], v[224:225] op_sel_hi:[1,0]
	v_pk_mul_f32 v[190:191], v[190:191], v[232:233]
	v_pk_add_f32 v[192:193], v[192:193], v[32:33]
	v_pk_add_f32 v[194:195], v[194:195], v[34:35]
	v_pk_add_f32 v[196:197], v[196:197], v[36:37]
	v_pk_add_f32 v[198:199], v[198:199], v[38:39]
	v_pk_add_f32 v[200:201], v[200:201], v[40:41]
	v_pk_add_f32 v[202:203], v[202:203], v[42:43]
	v_pk_add_f32 v[204:205], v[204:205], v[44:45]
	v_pk_add_f32 v[206:207], v[206:207], v[46:47]
	v_pk_mul_f32 v[224:225], v[192:193], v[192:193]
	v_pk_mul_f32 v[226:227], v[194:195], v[194:195]
	v_pk_fma_f32 v[224:225], v[196:197], v[196:197], v[224:225]
	v_pk_fma_f32 v[226:227], v[198:199], v[198:199], v[226:227]
	v_pk_fma_f32 v[224:225], v[200:201], v[200:201], v[224:225]
	v_pk_fma_f32 v[226:227], v[202:203], v[202:203], v[226:227]
	v_pk_fma_f32 v[224:225], v[204:205], v[204:205], v[224:225]
	v_pk_fma_f32 v[226:227], v[206:207], v[206:207], v[226:227]
	v_pk_add_f32 v[224:225], v[224:225], v[226:227]
	s_nop 0
	v_add_f32_e32 v224, v224, v225
	ds_bpermute_b32 v225, v242, v224
	s_waitcnt lgkmcnt(0)
; DI void peer_item_v(const Params& p, int item) {
;     ...
;     float* orow = p.out + tok * 1024 + lane * 4;
;     float4 y[4];
;     float ss = 0.f;
; #pragma unroll
;     for (int i = 0; i < 4; ++i) {
;       y[i] = *(const float4*)(orow + 256 * i);
;       y[i].x += out[4 * i]; y[i].y += out[4 * i + 1]; y[i].z += out[4 * i + 2]; y[i].w += out[4 * i + 3];
;       ss += y[i].x * y[i].x + y[i].y * y[i].y + y[i].z * y[i].z + y[i].w * y[i].w;
;     }
;     ss = wave_sum(ss);
;     const float r = rsqrtf(ss * (1.f / 1024.f) + 1e-6f);
; #pragma unroll
;     for (int i = 0; i < 4; ++i) {
;       float4 g = *(const float4*)(p.g_final + 256 * i + lane * 4);
;       y[i].x *= r * g.x; y[i].y *= r * g.y; y[i].z *= r * g.z; y[i].w *= r * g.w;
;       *(float4*)(orow + 256 * i) = y[i];
;     }
	v_add_f32_e32 v224, v224, v225
	ds_bpermute_b32 v225, v243, v224
	s_waitcnt lgkmcnt(0)
	v_add_f32_e32 v224, v224, v225
	ds_bpermute_b32 v225, v244, v224
	s_waitcnt lgkmcnt(0)
	v_add_f32_e32 v224, v224, v225
	ds_bpermute_b32 v225, v245, v224
	s_waitcnt lgkmcnt(0)
	v_add_f32_e32 v224, v224, v225
	ds_bpermute_b32 v225, v246, v224
	s_waitcnt lgkmcnt(0)
	v_add_f32_e32 v224, v224, v225
	ds_bpermute_b32 v225, v247, v224
	s_waitcnt lgkmcnt(0)
	v_add_f32_e32 v224, v224, v225
	v_fmamk_f32 v224, v224, 0x3a800000, v248
	v_rsq_f32_e32 v224, v224
	s_nop 1
	v_pk_mul_f32 v[226:227], v[128:129], v[224:225] op_sel_hi:[1,0]
	v_pk_mul_f32 v[192:193], v[192:193], v[226:227]
	v_pk_mul_f32 v[228:229], v[130:131], v[224:225] op_sel_hi:[1,0]
	v_pk_mul_f32 v[194:195], v[194:195], v[228:229]
	v_pk_mul_f32 v[230:231], v[132:133], v[224:225] op_sel_hi:[1,0]
	v_pk_mul_f32 v[196:197], v[196:197], v[230:231]
	v_pk_mul_f32 v[232:233], v[134:135], v[224:225] op_sel_hi:[1,0]
	v_pk_mul_f32 v[198:199], v[198:199], v[232:233]
	v_pk_mul_f32 v[226:227], v[136:137], v[224:225] op_sel_hi:[1,0]
	v_pk_mul_f32 v[200:201], v[200:201], v[226:227]
	v_pk_mul_f32 v[228:229], v[138:139], v[224:225] op_sel_hi:[1,0]
	v_pk_mul_f32 v[202:203], v[202:203], v[228:229]
	v_pk_mul_f32 v[230:231], v[140:141], v[224:225] op_sel_hi:[1,0]
	v_pk_mul_f32 v[204:205], v[204:205], v[230:231]
	v_pk_mul_f32 v[232:233], v[142:143], v[224:225] op_sel_hi:[1,0]
	v_pk_mul_f32 v[206:207], v[206:207], v[232:233]
	v_pk_add_f32 v[208:209], v[208:209], v[48:49]
	v_pk_add_f32 v[210:211], v[210:211], v[50:51]
	v_pk_add_f32 v[212:213], v[212:213], v[52:53]
	v_pk_add_f32 v[214:215], v[214:215], v[54:55]
	v_pk_add_f32 v[216:217], v[216:217], v[56:57]
	v_pk_add_f32 v[218:219], v[218:219], v[58:59]
	v_pk_add_f32 v[220:221], v[220:221], v[60:61]
	v_pk_add_f32 v[222:223], v[222:223], v[62:63]
	v_pk_mul_f32 v[224:225], v[208:209], v[208:209]
	v_pk_mul_f32 v[226:227], v[210:211], v[210:211]
	v_pk_fma_f32 v[224:225], v[212:213], v[212:213], v[224:225]
	v_pk_fma_f32 v[226:227], v[214:215], v[214:215], v[226:227]
	v_pk_fma_f32 v[224:225], v[216:217], v[216:217], v[224:225]
	v_pk_fma_f32 v[226:227], v[218:219], v[218:219], v[226:227]
	v_pk_fma_f32 v[224:225], v[220:221], v[220:221], v[224:225]
	v_pk_fma_f32 v[226:227], v[222:223], v[222:223], v[226:227]
	v_pk_add_f32 v[224:225], v[224:225], v[226:227]
	s_nop 0
	v_add_f32_e32 v224, v224, v225
	ds_bpermute_b32 v225, v242, v224
	s_waitcnt lgkmcnt(0)
	v_add_f32_e32 v224, v224, v225
	ds_bpermute_b32 v225, v243, v224
	s_waitcnt lgkmcnt(0)
	v_add_f32_e32 v224, v224, v225
	ds_bpermute_b32 v225, v244, v224
	s_waitcnt lgkmcnt(0)
	v_add_f32_e32 v224, v224, v225
	ds_bpermute_b32 v225, v245, v224
	s_waitcnt lgkmcnt(0)
	v_add_f32_e32 v224, v224, v225
	ds_bpermute_b32 v225, v246, v224
	s_waitcnt lgkmcnt(0)
	v_add_f32_e32 v224, v224, v225
	ds_bpermute_b32 v225, v247, v224
	s_waitcnt lgkmcnt(0)
	v_add_f32_e32 v224, v224, v225
	v_fmamk_f32 v224, v224, 0x3a800000, v248
	v_rsq_f32_e32 v224, v224
	s_nop 1
	v_pk_mul_f32 v[226:227], v[128:129], v[224:225] op_sel_hi:[1,0]
	v_pk_mul_f32 v[208:209], v[208:209], v[226:227]
	v_pk_mul_f32 v[228:229], v[130:131], v[224:225] op_sel_hi:[1,0]
	v_pk_mul_f32 v[210:211], v[210:211], v[228:229]
	v_pk_mul_f32 v[230:231], v[132:133], v[224:225] op_sel_hi:[1,0]
	v_pk_mul_f32 v[212:213], v[212:213], v[230:231]
	v_pk_mul_f32 v[232:233], v[134:135], v[224:225] op_sel_hi:[1,0]
	v_pk_mul_f32 v[214:215], v[214:215], v[232:233]
	v_pk_mul_f32 v[226:227], v[136:137], v[224:225] op_sel_hi:[1,0]
	v_pk_mul_f32 v[216:217], v[216:217], v[226:227]
	v_pk_mul_f32 v[228:229], v[138:139], v[224:225] op_sel_hi:[1,0]
	v_pk_mul_f32 v[218:219], v[218:219], v[228:229]
	v_pk_mul_f32 v[230:231], v[140:141], v[224:225] op_sel_hi:[1,0]
	v_pk_mul_f32 v[220:221], v[220:221], v[230:231]
	v_pk_mul_f32 v[232:233], v[142:143], v[224:225] op_sel_hi:[1,0]
	v_pk_mul_f32 v[222:223], v[222:223], v[232:233]
	global_store_dwordx4 v240, v[160:163], s[32:33]
	global_store_dwordx4 v240, v[164:167], s[32:33] offset:1024
	global_store_dwordx4 v240, v[168:171], s[32:33] offset:2048
	global_store_dwordx4 v240, v[172:175], s[32:33] offset:3072
	global_store_dwordx4 v240, v[176:179], s[34:35]
	global_store_dwordx4 v240, v[180:183], s[34:35] offset:1024
	global_store_dwordx4 v240, v[184:187], s[34:35] offset:2048
	global_store_dwordx4 v240, v[188:191], s[34:35] offset:3072
	global_store_dwordx4 v240, v[192:195], s[36:37]
	global_store_dwordx4 v240, v[196:199], s[36:37] offset:1024
	global_store_dwordx4 v240, v[200:203], s[36:37] offset:2048
	global_store_dwordx4 v240, v[204:207], s[36:37] offset:3072
	global_store_dwordx4 v240, v[208:211], s[38:39]
	global_store_dwordx4 v240, v[212:215], s[38:39] offset:1024
	global_store_dwordx4 v240, v[216:219], s[38:39] offset:2048
	global_store_dwordx4 v240, v[220:223], s[38:39] offset:3072
	s_nop 1
	s_add_u32 s32, s62, 16384
	s_addc_u32 s33, s63, 0
	s_add_u32 s34, s62, 20480
	s_addc_u32 s35, s63, 0
	s_add_u32 s36, s62, 24576
	s_addc_u32 s37, s63, 0
	s_add_u32 s38, s62, 28672
	s_addc_u32 s39, s63, 0
	global_load_dwordx4 v[160:163], v240, s[32:33]
	global_load_dwordx4 v[164:167], v240, s[32:33] offset:1024
	global_load_dwordx4 v[168:171], v240, s[32:33] offset:2048
	global_load_dwordx4 v[172:175], v240, s[32:33] offset:3072
	global_load_dwordx4 v[176:179], v240, s[34:35]
	global_load_dwordx4 v[180:183], v240, s[34:35] offset:1024
	global_load_dwordx4 v[184:187], v240, s[34:35] offset:2048
	global_load_dwordx4 v[188:191], v240, s[34:35] offset:3072
	global_load_dwordx4 v[192:195], v240, s[36:37]
	global_load_dwordx4 v[196:199], v240, s[36:37] offset:1024
	global_load_dwordx4 v[200:203], v240, s[36:37] offset:2048
	global_load_dwordx4 v[204:207], v240, s[36:37] offset:3072
	global_load_dwordx4 v[208:211], v240, s[38:39]
	global_load_dwordx4 v[212:215], v240, s[38:39] offset:1024
	global_load_dwordx4 v[216:219], v240, s[38:39] offset:2048
	global_load_dwordx4 v[220:223], v240, s[38:39] offset:3072
	s_waitcnt vmcnt(0)
; DI float wave_sum(float v) {
; #pragma unroll
;   for (int o = 32; o > 0; o >>= 1) v += __shfl_xor(v, o);
;   return v;
; }
; DI void peer_item_v(const Params& p, int item) {
;     ...
;     float* orow = p.out + tok * 1024 + lane * 4;
;     float4 y[4];
;     float ss = 0.f;
; #pragma unroll
;     for (int i = 0; i < 4; ++i) {
;       y[i] = *(const float4*)(orow + 256 * i);
;       y[i].x += out[4 * i]; y[i].y += out[4 * i + 1]; y[i].z += out[4 * i + 2]; y[i].w += out[4 * i + 3];
;       ss += y[i].x * y[i].x + y[i].y * y[i].y + y[i].z * y[i].z + y[i].w * y[i].w;
;     }
;     ss = wave_sum(ss);
;     const float r = rsqrtf(ss * (1.f / 1024.f) + 1e-6f);
; #pragma unroll
;     for (int i = 0; i < 4; ++i) {
;       float4 g = *(const float4*)(p.g_final + 256 * i + lane * 4);
;       y[i].x *= r * g.x; y[i].y *= r * g.y; y[i].z *= r * g.z; y[i].w *= r * g.w;
;       *(float4*)(orow + 256 * i) = y[i];
;     }
	v_pk_add_f32 v[160:161], v[160:161], v[64:65]
	v_pk_add_f32 v[162:163], v[162:163], v[66:67]
	v_pk_add_f32 v[164:165], v[164:165], v[68:69]
	v_pk_add_f32 v[166:167], v[166:167], v[70:71]
	v_pk_add_f32 v[168:169], v[168:169], v[72:73]
	v_pk_add_f32 v[170:171], v[170:171], v[74:75]
	v_pk_add_f32 v[172:173], v[172:173], v[76:77]
	v_pk_add_f32 v[174:175], v[174:175], v[78:79]
	v_pk_mul_f32 v[224:225], v[160:161], v[160:161]
	v_pk_mul_f32 v[226:227], v[162:163], v[162:163]
	v_pk_fma_f32 v[224:225], v[164:165], v[164:165], v[224:225]
	v_pk_fma_f32 v[226:227], v[166:167], v[166:167], v[226:227]
	v_pk_fma_f32 v[224:225], v[168:169], v[168:169], v[224:225]
	v_pk_fma_f32 v[226:227], v[170:171], v[170:171], v[226:227]
	v_pk_fma_f32 v[224:225], v[172:173], v[172:173], v[224:225]
	v_pk_fma_f32 v[226:227], v[174:175], v[174:175], v[226:227]
	v_pk_add_f32 v[224:225], v[224:225], v[226:227]
	s_nop 0
	v_add_f32_e32 v224, v224, v225
	ds_bpermute_b32 v225, v242, v224
	s_waitcnt lgkmcnt(0)
	v_add_f32_e32 v224, v224, v225
	ds_bpermute_b32 v225, v243, v224
	s_waitcnt lgkmcnt(0)
	v_add_f32_e32 v224, v224, v225
	ds_bpermute_b32 v225, v244, v224
	s_waitcnt lgkmcnt(0)
	v_add_f32_e32 v224, v224, v225
	ds_bpermute_b32 v225, v245, v224
	s_waitcnt lgkmcnt(0)
	v_add_f32_e32 v224, v224, v225
	ds_bpermute_b32 v225, v246, v224
	s_waitcnt lgkmcnt(0)
	v_add_f32_e32 v224, v224, v225
	ds_bpermute_b32 v225, v247, v224
	s_waitcnt lgkmcnt(0)
	v_add_f32_e32 v224, v224, v225
	v_fmamk_f32 v224, v224, 0x3a800000, v248
	v_rsq_f32_e32 v224, v224
	s_nop 1
	v_pk_mul_f32 v[226:227], v[128:129], v[224:225] op_sel_hi:[1,0]
	v_pk_mul_f32 v[160:161], v[160:161], v[226:227]
	v_pk_mul_f32 v[228:229], v[130:131], v[224:225] op_sel_hi:[1,0]
	v_pk_mul_f32 v[162:163], v[162:163], v[228:229]
	v_pk_mul_f32 v[230:231], v[132:133], v[224:225] op_sel_hi:[1,0]
	v_pk_mul_f32 v[164:165], v[164:165], v[230:231]
	v_pk_mul_f32 v[232:233], v[134:135], v[224:225] op_sel_hi:[1,0]
	v_pk_mul_f32 v[166:167], v[166:167], v[232:233]
	v_pk_mul_f32 v[226:227], v[136:137], v[224:225] op_sel_hi:[1,0]
	v_pk_mul_f32 v[168:169], v[168:169], v[226:227]
	v_pk_mul_f32 v[228:229], v[138:139], v[224:225] op_sel_hi:[1,0]
	v_pk_mul_f32 v[170:171], v[170:171], v[228:229]
	v_pk_mul_f32 v[230:231], v[140:141], v[224:225] op_sel_hi:[1,0]
	v_pk_mul_f32 v[172:173], v[172:173], v[230:231]
	v_pk_mul_f32 v[232:233], v[142:143], v[224:225] op_sel_hi:[1,0]
	v_pk_mul_f32 v[174:175], v[174:175], v[232:233]
	v_pk_add_f32 v[176:177], v[176:177], v[80:81]
	v_pk_add_f32 v[178:179], v[178:179], v[82:83]
	v_pk_add_f32 v[180:181], v[180:181], v[84:85]
	v_pk_add_f32 v[182:183], v[182:183], v[86:87]
	v_pk_add_f32 v[184:185], v[184:185], v[88:89]
	v_pk_add_f32 v[186:187], v[186:187], v[90:91]
	v_pk_add_f32 v[188:189], v[188:189], v[92:93]
	v_pk_add_f32 v[190:191], v[190:191], v[94:95]
	v_pk_mul_f32 v[224:225], v[176:177], v[176:177]
	v_pk_mul_f32 v[226:227], v[178:179], v[178:179]
	v_pk_fma_f32 v[224:225], v[180:181], v[180:181], v[224:225]
	v_pk_fma_f32 v[226:227], v[182:183], v[182:183], v[226:227]
	v_pk_fma_f32 v[224:225], v[184:185], v[184:185], v[224:225]
	v_pk_fma_f32 v[226:227], v[186:187], v[186:187], v[226:227]
	v_pk_fma_f32 v[224:225], v[188:189], v[188:189], v[224:225]
	v_pk_fma_f32 v[226:227], v[190:191], v[190:191], v[226:227]
	v_pk_add_f32 v[224:225], v[224:225], v[226:227]
	s_nop 0
	v_add_f32_e32 v224, v224, v225
	ds_bpermute_b32 v225, v242, v224
	s_waitcnt lgkmcnt(0)
	v_add_f32_e32 v224, v224, v225
	ds_bpermute_b32 v225, v243, v224
	s_waitcnt lgkmcnt(0)
	v_add_f32_e32 v224, v224, v225
	ds_bpermute_b32 v225, v244, v224
	s_waitcnt lgkmcnt(0)
	v_add_f32_e32 v224, v224, v225
	ds_bpermute_b32 v225, v245, v224
	s_waitcnt lgkmcnt(0)
	v_add_f32_e32 v224, v224, v225
	ds_bpermute_b32 v225, v246, v224
	s_waitcnt lgkmcnt(0)
	v_add_f32_e32 v224, v224, v225
	ds_bpermute_b32 v225, v247, v224
	s_waitcnt lgkmcnt(0)
	v_add_f32_e32 v224, v224, v225
	v_fmamk_f32 v224, v224, 0x3a800000, v248
	v_rsq_f32_e32 v224, v224
	s_nop 1
	v_pk_mul_f32 v[226:227], v[128:129], v[224:225] op_sel_hi:[1,0]
	v_pk_mul_f32 v[176:177], v[176:177], v[226:227]
	v_pk_mul_f32 v[228:229], v[130:131], v[224:225] op_sel_hi:[1,0]
	v_pk_mul_f32 v[178:179], v[178:179], v[228:229]
	v_pk_mul_f32 v[230:231], v[132:133], v[224:225] op_sel_hi:[1,0]
	v_pk_mul_f32 v[180:181], v[180:181], v[230:231]
	v_pk_mul_f32 v[232:233], v[134:135], v[224:225] op_sel_hi:[1,0]
	v_pk_mul_f32 v[182:183], v[182:183], v[232:233]
	v_pk_mul_f32 v[226:227], v[136:137], v[224:225] op_sel_hi:[1,0]
	v_pk_mul_f32 v[184:185], v[184:185], v[226:227]
	v_pk_mul_f32 v[228:229], v[138:139], v[224:225] op_sel_hi:[1,0]
	v_pk_mul_f32 v[186:187], v[186:187], v[228:229]
	v_pk_mul_f32 v[230:231], v[140:141], v[224:225] op_sel_hi:[1,0]
	v_pk_mul_f32 v[188:189], v[188:189], v[230:231]
	v_pk_mul_f32 v[232:233], v[142:143], v[224:225] op_sel_hi:[1,0]
	v_pk_mul_f32 v[190:191], v[190:191], v[232:233]
	v_pk_add_f32 v[192:193], v[192:193], v[96:97]
	v_pk_add_f32 v[194:195], v[194:195], v[98:99]
	v_pk_add_f32 v[196:197], v[196:197], v[100:101]
	v_pk_add_f32 v[198:199], v[198:199], v[102:103]
	v_pk_add_f32 v[200:201], v[200:201], v[104:105]
	v_pk_add_f32 v[202:203], v[202:203], v[106:107]
	v_pk_add_f32 v[204:205], v[204:205], v[108:109]
	v_pk_add_f32 v[206:207], v[206:207], v[110:111]
	v_pk_mul_f32 v[224:225], v[192:193], v[192:193]
	v_pk_mul_f32 v[226:227], v[194:195], v[194:195]
	v_pk_fma_f32 v[224:225], v[196:197], v[196:197], v[224:225]
	v_pk_fma_f32 v[226:227], v[198:199], v[198:199], v[226:227]
	v_pk_fma_f32 v[224:225], v[200:201], v[200:201], v[224:225]
	v_pk_fma_f32 v[226:227], v[202:203], v[202:203], v[226:227]
	v_pk_fma_f32 v[224:225], v[204:205], v[204:205], v[224:225]
	v_pk_fma_f32 v[226:227], v[206:207], v[206:207], v[226:227]
	v_pk_add_f32 v[224:225], v[224:225], v[226:227]
	s_nop 0
	v_add_f32_e32 v224, v224, v225
	ds_bpermute_b32 v225, v242, v224
	s_waitcnt lgkmcnt(0)
; DI void peer_item_v(const Params& p, int item) {
;     ...
;     ss = wave_sum(ss);
;     const float r = rsqrtf(ss * (1.f / 1024.f) + 1e-6f);
; #pragma unroll
;     for (int i = 0; i < 4; ++i) {
;       float4 g = *(const float4*)(p.g_final + 256 * i + lane * 4);
;       y[i].x *= r * g.x; y[i].y *= r * g.y; y[i].z *= r * g.z; y[i].w *= r * g.w;
;       *(float4*)(orow + 256 * i) = y[i];
;     }
	v_add_f32_e32 v224, v224, v225
	ds_bpermute_b32 v225, v243, v224
	s_waitcnt lgkmcnt(0)
	v_add_f32_e32 v224, v224, v225
	ds_bpermute_b32 v225, v244, v224
	s_waitcnt lgkmcnt(0)
	v_add_f32_e32 v224, v224, v225
	ds_bpermute_b32 v225, v245, v224
	s_waitcnt lgkmcnt(0)
	v_add_f32_e32 v224, v224, v225
	ds_bpermute_b32 v225, v246, v224
	s_waitcnt lgkmcnt(0)
	v_add_f32_e32 v224, v224, v225
	ds_bpermute_b32 v225, v247, v224
	s_waitcnt lgkmcnt(0)
	v_add_f32_e32 v224, v224, v225
	v_fmamk_f32 v224, v224, 0x3a800000, v248
	v_rsq_f32_e32 v224, v224
	s_nop 1
	v_pk_mul_f32 v[226:227], v[128:129], v[224:225] op_sel_hi:[1,0]
	v_pk_mul_f32 v[192:193], v[192:193], v[226:227]
	v_pk_mul_f32 v[228:229], v[130:131], v[224:225] op_sel_hi:[1,0]
	v_pk_mul_f32 v[194:195], v[194:195], v[228:229]
	v_pk_mul_f32 v[230:231], v[132:133], v[224:225] op_sel_hi:[1,0]
	v_pk_mul_f32 v[196:197], v[196:197], v[230:231]
	v_pk_mul_f32 v[232:233], v[134:135], v[224:225] op_sel_hi:[1,0]
	v_pk_mul_f32 v[198:199], v[198:199], v[232:233]
	v_pk_mul_f32 v[226:227], v[136:137], v[224:225] op_sel_hi:[1,0]
	v_pk_mul_f32 v[200:201], v[200:201], v[226:227]
	v_pk_mul_f32 v[228:229], v[138:139], v[224:225] op_sel_hi:[1,0]
	v_pk_mul_f32 v[202:203], v[202:203], v[228:229]
	v_pk_mul_f32 v[230:231], v[140:141], v[224:225] op_sel_hi:[1,0]
	v_pk_mul_f32 v[204:205], v[204:205], v[230:231]
	v_pk_mul_f32 v[232:233], v[142:143], v[224:225] op_sel_hi:[1,0]
	v_pk_mul_f32 v[206:207], v[206:207], v[232:233]
	v_pk_add_f32 v[208:209], v[208:209], v[112:113]
	v_pk_add_f32 v[210:211], v[210:211], v[114:115]
	v_pk_add_f32 v[212:213], v[212:213], v[116:117]
	v_pk_add_f32 v[214:215], v[214:215], v[118:119]
	v_pk_add_f32 v[216:217], v[216:217], v[120:121]
	v_pk_add_f32 v[218:219], v[218:219], v[122:123]
	v_pk_add_f32 v[220:221], v[220:221], v[124:125]
	v_pk_add_f32 v[222:223], v[222:223], v[126:127]
	v_pk_mul_f32 v[224:225], v[208:209], v[208:209]
	v_pk_mul_f32 v[226:227], v[210:211], v[210:211]
	v_pk_fma_f32 v[224:225], v[212:213], v[212:213], v[224:225]
	v_pk_fma_f32 v[226:227], v[214:215], v[214:215], v[226:227]
	v_pk_fma_f32 v[224:225], v[216:217], v[216:217], v[224:225]
	v_pk_fma_f32 v[226:227], v[218:219], v[218:219], v[226:227]
	v_pk_fma_f32 v[224:225], v[220:221], v[220:221], v[224:225]
	v_pk_fma_f32 v[226:227], v[222:223], v[222:223], v[226:227]
	v_pk_add_f32 v[224:225], v[224:225], v[226:227]
	s_nop 0
	v_add_f32_e32 v224, v224, v225
	ds_bpermute_b32 v225, v242, v224
	s_waitcnt lgkmcnt(0)
	v_add_f32_e32 v224, v224, v225
	ds_bpermute_b32 v225, v243, v224
	s_waitcnt lgkmcnt(0)
	v_add_f32_e32 v224, v224, v225
	ds_bpermute_b32 v225, v244, v224
	s_waitcnt lgkmcnt(0)
	v_add_f32_e32 v224, v224, v225
	ds_bpermute_b32 v225, v245, v224
	s_waitcnt lgkmcnt(0)
	v_add_f32_e32 v224, v224, v225
	ds_bpermute_b32 v225, v246, v224
	s_waitcnt lgkmcnt(0)
	v_add_f32_e32 v224, v224, v225
	ds_bpermute_b32 v225, v247, v224
	s_waitcnt lgkmcnt(0)
; DI void peer_item_v(const Params& p, int item) {
;     ...
;     ss = wave_sum(ss);
;     const float r = rsqrtf(ss * (1.f / 1024.f) + 1e-6f);
; #pragma unroll
;     for (int i = 0; i < 4; ++i) {
;       float4 g = *(const float4*)(p.g_final + 256 * i + lane * 4);
;       y[i].x *= r * g.x; y[i].y *= r * g.y; y[i].z *= r * g.z; y[i].w *= r * g.w;
;       *(float4*)(orow + 256 * i) = y[i];
;     }
	v_add_f32_e32 v224, v224, v225
	v_fmamk_f32 v224, v224, 0x3a800000, v248
	v_rsq_f32_e32 v224, v224
	s_nop 1
	v_pk_mul_f32 v[226:227], v[128:129], v[224:225] op_sel_hi:[1,0]
	v_pk_mul_f32 v[208:209], v[208:209], v[226:227]
	v_pk_mul_f32 v[228:229], v[130:131], v[224:225] op_sel_hi:[1,0]
	v_pk_mul_f32 v[210:211], v[210:211], v[228:229]
	v_pk_mul_f32 v[230:231], v[132:133], v[224:225] op_sel_hi:[1,0]
	v_pk_mul_f32 v[212:213], v[212:213], v[230:231]
	v_pk_mul_f32 v[232:233], v[134:135], v[224:225] op_sel_hi:[1,0]
	v_pk_mul_f32 v[214:215], v[214:215], v[232:233]
	v_pk_mul_f32 v[226:227], v[136:137], v[224:225] op_sel_hi:[1,0]
	v_pk_mul_f32 v[216:217], v[216:217], v[226:227]
	v_pk_mul_f32 v[228:229], v[138:139], v[224:225] op_sel_hi:[1,0]
	v_pk_mul_f32 v[218:219], v[218:219], v[228:229]
	v_pk_mul_f32 v[230:231], v[140:141], v[224:225] op_sel_hi:[1,0]
	v_pk_mul_f32 v[220:221], v[220:221], v[230:231]
	v_pk_mul_f32 v[232:233], v[142:143], v[224:225] op_sel_hi:[1,0]
	v_pk_mul_f32 v[222:223], v[222:223], v[232:233]
	global_store_dwordx4 v240, v[160:163], s[32:33]
	global_store_dwordx4 v240, v[164:167], s[32:33] offset:1024
	global_store_dwordx4 v240, v[168:171], s[32:33] offset:2048
	global_store_dwordx4 v240, v[172:175], s[32:33] offset:3072
	global_store_dwordx4 v240, v[176:179], s[34:35]
	global_store_dwordx4 v240, v[180:183], s[34:35] offset:1024
	global_store_dwordx4 v240, v[184:187], s[34:35] offset:2048
	global_store_dwordx4 v240, v[188:191], s[34:35] offset:3072
	global_store_dwordx4 v240, v[192:195], s[36:37]
	global_store_dwordx4 v240, v[196:199], s[36:37] offset:1024
	global_store_dwordx4 v240, v[200:203], s[36:37] offset:2048
	global_store_dwordx4 v240, v[204:207], s[36:37] offset:3072
	global_store_dwordx4 v240, v[208:211], s[38:39]
	global_store_dwordx4 v240, v[212:215], s[38:39] offset:1024
	global_store_dwordx4 v240, v[216:219], s[38:39] offset:2048
	global_store_dwordx4 v240, v[220:223], s[38:39] offset:3072
	s_nop 1
	s_waitcnt lgkmcnt(0)
	v_mbcnt_lo_u32_b32 v213, -1, 0
	v_mbcnt_hi_u32_b32 v213, -1, v213
	v_readlane_b32 s18, v254, 60
	v_lshlrev_b32_e32 v238, 2, v213
	s_nop 1
	v_add_u32_e32 v236, s18, v238
	ds_read_b32 v3, v236 offset:512
	ds_read_b32 v53, v236 offset:768
	ds_read_b32 v64, v236 offset:1024
	ds_read_b32 v65, v236 offset:1280
	ds_read_b32 v66, v236 offset:1536
	ds_read_b32 v67, v236 offset:1792
	ds_read_b32 v68, v236 offset:2048
	ds_read_b32 v69, v236 offset:2304
	ds_read_b32 v70, v236 offset:2560
	ds_read_b32 v71, v236 offset:2816
	ds_read_b32 v72, v236 offset:3072
	ds_read_b32 v73, v236 offset:3328
	ds_read_b32 v74, v236 offset:3584
	ds_read_b32 v75, v236 offset:3840
	ds_read_b32 v76, v236 offset:4096
	ds_read_b32 v77, v236 offset:4352
	ds_read_b32 v78, v236 offset:4608
	ds_read_b32 v79, v236 offset:4864
	ds_read_b32 v80, v236 offset:5120
	ds_read_b32 v81, v236 offset:5376
	ds_read_b32 v82, v236 offset:5632
	ds_read_b32 v83, v236 offset:5888
	ds_read_b32 v96, v236 offset:6144
	ds_read_b32 v210, v236 offset:6400
	ds_read_b32 v211, v236 offset:6656
	ds_read_b32 v212, v236 offset:6912
	v_readlane_b32 s6, v254, 0
	v_readlane_b32 s7, v254, 1
	v_readlane_b32 s12, v254, 2
	v_readlane_b32 s13, v254, 3
	v_readlane_b32 s14, v254, 4
	v_readlane_b32 s15, v254, 5
	v_readlane_b32 s16, v254, 6
	v_readlane_b32 s17, v254, 7
	v_readlane_b32 s18, v254, 8
	v_readlane_b32 s19, v254, 9
	v_readlane_b32 s20, v254, 10
	v_readlane_b32 s21, v254, 11
	v_readlane_b32 s22, v254, 12
	v_readlane_b32 s23, v254, 13
	v_readlane_b32 s24, v254, 14
	v_readlane_b32 s25, v254, 15
	v_readlane_b32 s26, v254, 16
	v_readlane_b32 s27, v254, 17
	v_readlane_b32 s28, v254, 18
	v_readlane_b32 s29, v254, 19
	v_readlane_b32 s30, v254, 20
	v_readlane_b32 s31, v254, 21
	v_readlane_b32 s33, v254, 22
	v_readlane_b32 s34, v254, 23
	v_readlane_b32 s35, v254, 24
	v_readlane_b32 s36, v254, 25
	v_readlane_b32 s37, v254, 26
	v_readlane_b32 s38, v254, 27
	v_readlane_b32 s39, v254, 28
	v_readlane_b32 s40, v254, 29
	v_readlane_b32 s41, v254, 30
	v_readlane_b32 s42, v254, 31
	v_readlane_b32 s44, v254, 32
	v_readlane_b32 s45, v254, 33
	v_readlane_b32 s48, v254, 34
	v_readlane_b32 s49, v254, 35
	v_readlane_b32 s50, v254, 36
	v_readlane_b32 s51, v254, 37
	v_readlane_b32 s52, v254, 38
	v_readlane_b32 s53, v254, 39
	v_readlane_b32 s55, v254, 40
	v_readlane_b32 s60, v254, 41
	v_readlane_b32 s61, v254, 42
	v_readlane_b32 s62, v254, 43
	v_readlane_b32 s63, v254, 44
	v_readlane_b32 s66, v254, 45
	v_readlane_b32 s67, v254, 46
	v_readlane_b32 s68, v254, 47
	v_readlane_b32 s69, v254, 48
	v_readlane_b32 s74, v254, 49
	v_readlane_b32 s75, v254, 50
	v_readlane_b32 s76, v254, 51
	v_readlane_b32 s77, v254, 52
	v_readlane_b32 s78, v254, 53
	v_readlane_b32 s79, v254, 54
	v_readlane_b32 s88, v254, 55
	s_waitcnt lgkmcnt(0)
	s_nop 3

; DI void hsync_impl(const bool INIT) {
;     ...
;     if (old == 3u) {
;       __hip_atomic_store(&hb[h2], 0u, __ATOMIC_RELAXED, __HIP_MEMORY_SCOPE_WORKGROUP);
;       asm volatile("s_waitcnt vmcnt(0) lgkmcnt(0)" ::: "memory");
;       __hip_atomic_fetch_add(&hb[h2 + 1], 1u, __ATOMIC_RELAXED, __HIP_MEMORY_SCOPE_WORKGROUP);
;     } else {
.LBB0_1080:
	s_andn2_saveexec_b64 s[2:3], s[2:3]
	s_cbranch_execz .LBB0_1035
	s_mov_b64 s[2:3], exec
	v_mov_b32_e32 v0, s8
	ds_write_b32 v0, v53
	v_mbcnt_lo_u32_b32 v0, s2, 0
	s_waitcnt vmcnt(0) lgkmcnt(0)
	v_mbcnt_hi_u32_b32 v0, s3, v0
	v_cmp_eq_u32_e32 vcc, 0, v0
	s_and_b64 s[4:5], exec, vcc
	s_mov_b64 exec, s[4:5]
	s_cbranch_execz .LBB0_1035
	s_bcnt1_i32_b64 s2, s[2:3]
	v_mov_b32_e32 v0, s8
	v_mov_b32_e32 v1, s2
	ds_add_u32 v0, v1 offset:4
	s_branch .LBB0_1035
.LBB0_1083:
.LBB0_1272:
	s_endpgm
